# all global stores write-through (sc1), grid barrier without buffer_wbl2
# speedup vs baseline: 1.0037x; 1.0037x over previous
; __device__ __forceinline__ unsigned cvt_pk_bf16(float lo, float hi) { f32x2_t v = {lo, hi}; bf16x2_t b = __builtin_convertvector(v, bf16x2_t); return __builtin_bit_cast(unsigned, b); }
; __device__ __forceinline__ float silu_f(float x) { return x * __builtin_amdgcn_rcpf(1.0f + __builtin_amdgcn_exp2f(-x * LOG2E)); }
; __device__ __forceinline__ void ffn_fixup(const Args& a, int layer, int nrows, int gt, int NT) {
;     typedef _Float16 sh4 __attribute__((ext_vector_type(4)));
;     const _Float16* SIDE = (const _Float16*)(a.ws + WS_SIDE); bf16_t* ACT = (bf16_t*)(a.ws + WS_BIG); const float* cw = a.in[16] + (size_t)layer * 3 * DFF;
;     const int nblk = nrows >> 6;
;     for (int idx = gt; idx < nblk * 2 * (DFF / 4); idx += NT) {
;         const int c4 = idx % (DFF / 4), bw = idx / (DFF / 4), blk = bw >> 1, which = bw & 1, col = 4 * c4;
;         const int row = blk * 64 + (which ? 63 : 0);
;         const int sb = row < MX ? (blk & 31) : ((blk - MX / 64) & 3), nsb = row < MX ? 32 : 4;
;         const _Float16* sp = SIDE + ((size_t)(blk * 2 + which) * 3) * DFF + col;
;         f32x4 cv = __builtin_convertvector(*(const sh4*)sp, f32x4); const f32x4 vv = __builtin_convertvector(*(const sh4*)(sp + 2 * DFF), f32x4);
;         if (which == 0 && sb > 0) { const f32x4 gl = __builtin_convertvector(*(const sh4*)(SIDE + ((size_t)((blk - 1) * 2 + 1) * 3 + 1) * DFF + col), f32x4); cv += *(const f32x4*)(cw + col) * gl; }
;         if (which == 1 && sb < nsb - 1) { const f32x4 gf = __builtin_convertvector(*(const sh4*)(SIDE + ((size_t)((blk + 1) * 2 + 0) * 3 + 1) * DFF + col), f32x4); cv += *(const f32x4*)(cw + 2 * DFF + col) * gf; }
;         const f32x4 vs = vv * (-LOG2E);
;         u32x2 w; w.x = cvt_pk_bf16(silu_f(cv[0]) * vs[0], silu_f(cv[1]) * vs[1]); w.y = cvt_pk_bf16(silu_f(cv[2]) * vs[2], silu_f(cv[3]) * vs[3]);
;         *(u32x2*)(ACT + (size_t)row * DFF + col) = w;
;     }
.LBB0_109:
	s_or_b64 exec, exec, s[12:13]
	v_mul_f32_e32 v11, 0xbfb8aa3b, v4
	v_exp_f32_e32 v11, v11
	s_waitcnt vmcnt(0)
	v_cvt_f32_f16_sdwa v15, v7 dst_sel:DWORD dst_unused:UNUSED_PAD src0_sel:WORD_1
	v_cvt_f32_f16_e32 v14, v7
	s_mov_b32 s12, 0xbfb8aa3b
	v_add_f32_e32 v11, 1.0, v11
	v_cvt_f32_f16_sdwa v13, v6 dst_sel:DWORD dst_unused:UNUSED_PAD src0_sel:WORD_1
	v_cvt_f32_f16_e32 v12, v6
	v_pk_mul_f32 v[6:7], v[14:15], s[12:13] op_sel_hi:[1,0]
	v_rcp_f32_e32 v14, v11
	v_mul_f32_e32 v11, 0xbfb8aa3b, v5
	v_exp_f32_e32 v11, v11
	v_pk_mul_f32 v[12:13], v[12:13], s[12:13] op_sel_hi:[1,0]
	v_readlane_b32 s12, v252, 21
	v_readlane_b32 s13, v252, 22
	v_add_f32_e32 v11, 1.0, v11
	v_rcp_f32_e32 v15, v11
	s_movk_i32 s20, 0x1600
	v_add_u32_e32 v8, s14, v8
	v_cmp_le_i32_e32 vcc, s5, v8
	v_pk_mul_f32 v[4:5], v[4:5], v[14:15]
	v_add_u32_e32 v9, s16, v9
	v_pk_mul_f32 v[4:5], v[12:13], v[4:5]
	s_or_b64 s[38:39], vcc, s[38:39]
	v_cvt_pk_bf16_f32 v4, v4, v5
	v_mul_f32_e32 v5, 0xbfb8aa3b, v2
	v_exp_f32_e32 v5, v5
	s_nop 0
	v_add_f32_e32 v5, 1.0, v5
	v_rcp_f32_e32 v12, v5
	v_mul_f32_e32 v5, 0xbfb8aa3b, v3
	v_exp_f32_e32 v5, v5
	s_nop 0
	v_add_f32_e32 v5, 1.0, v5
	v_rcp_f32_e32 v13, v5
	s_nop 0
	v_pk_mul_f32 v[2:3], v[2:3], v[12:13]
	s_nop 0
	v_pk_mul_f32 v[2:3], v[6:7], v[2:3]
	s_nop 0
	v_cvt_pk_bf16_f32 v5, v2, v3
	v_mov_b64_e32 v[2:3], s[12:13]
	v_mad_i64_i32 v[2:3], s[12:13], v10, s20, v[2:3]
	v_lshl_add_u64 v[0:1], v[0:1], 1, v[2:3]
	global_store_dwordx2 v[0:1], v[4:5], off sc1
	s_andn2_b64 exec, exec, s[38:39]
	s_cbranch_execz .LBB0_114

; __device__ __forceinline__ void unpack8(const u32x4& w, float (&f)[8]) { f[0] = bf_lo(w.x); f[1] = bf_hi(w.x); f[2] = bf_lo(w.y); f[3] = bf_hi(w.y); f[4] = bf_lo(w.z); f[5] = bf_hi(w.z); f[6] = bf_lo(w.w); f[7] = bf_hi(w.w); }
; template <int HW> __device__ __forceinline__ void pool_item(const bf16_t* UP, bf16_t* MIXo, int row, int c8, int g) {
;     const int t = row < MX ? (row & (SEQ - 1)) : ((row - MX) & (CTXL - 1)), T = row < MX ? SEQ : CTXL;
;     const bf16_t* up = UP + (size_t)row * 512 + 128 * g + c8;
;     u32x4 w[2 * HW];
; #pragma unroll
;     for (int j = 0; j < 2 * HW; ++j) { const int s = t - HW + j; const int sc = s < 0 ? 0 : (s >= T ? T - 1 : s); w[j] = ld16(up + (ptrdiff_t)(sc - t) * 512); }
;     float acc[8], f[8];
; #pragma unroll
;     for (int q = 0; q < 8; ++q) acc[q] = 0.f;
;     int cnt = 0;
; #pragma unroll
;     for (int j = 0; j < 2 * HW; ++j) { const int s = t - HW + j; const bool ok = s >= 0 && s < T; cnt += ok ? 1 : 0; unpack8(w[j], f);
; #pragma unroll
;         for (int q = 0; q < 8; ++q) acc[q] += ok ? f[q] : 0.f; }
; __device__ __forceinline__ void pool_pass(const Args& a, int nrows, int lane, int gw, int NGW) {
;     const bf16_t* UP = (const bf16_t*)(a.ws + WS_UPOOL); bf16_t* MIXo = (bf16_t*)(a.ws + WS_MIX);
;     for (int wi = gw; wi < nrows; wi += NGW) {
;         const int g = wi & 3, row = 4 * (wi >> 2) + (lane >> 4), c8 = 8 * (lane & 15);
;         if (g == 0) pool_item<1>(UP, MIXo, row, c8, 0); else if (g == 1) pool_item<2>(UP, MIXo, row, c8, 1); else if (g == 2) pool_item<4>(UP, MIXo, row, c8, 2); else pool_item<8>(UP, MIXo, row, c8, 3);
.LBB0_119:
	s_and_b32 s5, s4, -4
	v_or_b32_e32 v52, s5, v56
	s_movk_i32 s9, 0x4000
	v_cmp_gt_i32_e32 vcc, s9, v52
	v_mov_b32_e32 v0, 0x100
	v_mov_b32_e32 v1, 0x800
	v_cndmask_b32_e32 v57, v0, v1, vcc
	v_cndmask_b32_e32 v0, v229, v230, vcc
	v_ashrrev_i32_e32 v53, 31, v52
	v_bitop3_b32 v58, v0, s5, v56 bitop3:0xe0
	v_lshlrev_b64 v[54:55], 10, v[52:53]
	s_cmp_lt_i32 s1, 2
	s_mov_b64 s[12:13], -1
	s_cbranch_scc1 .LBB0_125
	s_cmp_gt_i32 s1, 2
	s_cbranch_scc0 .LBB0_122
	v_subrev_co_u32_e32 v59, vcc, 8, v58
	v_add_u32_e32 v76, -1, v57
	v_min_u32_e32 v2, v59, v76
	v_cndmask_b32_e64 v2, v2, 0, vcc
	v_sub_u32_e32 v2, v2, v58
	v_ashrrev_i32_e32 v3, 31, v2
	v_lshl_add_u64 v[0:1], v[48:49], 0, v[54:55]
	v_lshlrev_b64 v[2:3], 10, v[2:3]
	v_lshl_add_u64 v[2:3], v[0:1], 0, v[2:3]
	v_subrev_co_u32_e32 v77, vcc, 7, v58
	global_load_dwordx4 v[60:63], v[2:3], off offset:768
	v_min_u32_e32 v2, v77, v76
	v_cndmask_b32_e64 v2, v2, 0, vcc
	v_sub_u32_e32 v2, v2, v58
	v_ashrrev_i32_e32 v3, 31, v2
	v_lshlrev_b64 v[2:3], 10, v[2:3]
	v_lshl_add_u64 v[2:3], v[0:1], 0, v[2:3]
	v_subrev_co_u32_e32 v78, vcc, 6, v58
	global_load_dwordx4 v[64:67], v[2:3], off offset:768
	v_min_u32_e32 v2, v78, v76
	v_cndmask_b32_e64 v2, v2, 0, vcc
	v_sub_u32_e32 v2, v2, v58
	v_ashrrev_i32_e32 v3, 31, v2
	v_lshlrev_b64 v[2:3], 10, v[2:3]
	v_lshl_add_u64 v[2:3], v[0:1], 0, v[2:3]
	v_subrev_co_u32_e32 v79, vcc, 5, v58
	global_load_dwordx4 v[68:71], v[2:3], off offset:768
	v_min_u32_e32 v2, v79, v76
	v_cndmask_b32_e64 v2, v2, 0, vcc
	v_sub_u32_e32 v2, v2, v58
	v_ashrrev_i32_e32 v3, 31, v2
	v_lshlrev_b64 v[2:3], 10, v[2:3]
	v_lshl_add_u64 v[2:3], v[0:1], 0, v[2:3]
	v_subrev_co_u32_e32 v80, vcc, 4, v58
	global_load_dwordx4 v[72:75], v[2:3], off offset:768
	v_min_u32_e32 v2, v80, v76
	v_cndmask_b32_e64 v2, v2, 0, vcc
	v_sub_u32_e32 v2, v2, v58
	v_ashrrev_i32_e32 v3, 31, v2
	v_lshlrev_b64 v[2:3], 10, v[2:3]
	v_lshl_add_u64 v[2:3], v[0:1], 0, v[2:3]
	v_subrev_co_u32_e32 v82, vcc, 3, v58
	global_load_dwordx4 v[44:47], v[2:3], off offset:768
	v_min_u32_e32 v2, v82, v76
	v_cndmask_b32_e64 v2, v2, 0, vcc
	v_sub_u32_e32 v2, v2, v58
	v_ashrrev_i32_e32 v3, 31, v2
	v_lshlrev_b64 v[2:3], 10, v[2:3]
	v_lshl_add_u64 v[2:3], v[0:1], 0, v[2:3]
	v_subrev_co_u32_e32 v83, vcc, 2, v58
	global_load_dwordx4 v[40:43], v[2:3], off offset:768
	v_min_u32_e32 v2, v83, v76
	v_cndmask_b32_e64 v2, v2, 0, vcc
	v_sub_u32_e32 v2, v2, v58
	v_ashrrev_i32_e32 v3, 31, v2
	v_lshlrev_b64 v[2:3], 10, v[2:3]
	v_lshl_add_u64 v[2:3], v[0:1], 0, v[2:3]
	v_subrev_co_u32_e32 v85, vcc, 1, v58
	global_load_dwordx4 v[36:39], v[2:3], off offset:768
	v_min_u32_e32 v2, v85, v76
	v_cndmask_b32_e64 v2, v2, 0, vcc
	v_sub_u32_e32 v2, v2, v58
	v_ashrrev_i32_e32 v3, 31, v2
	v_lshlrev_b64 v[2:3], 10, v[2:3]
	v_lshl_add_u64 v[2:3], v[0:1], 0, v[2:3]
	global_load_dwordx4 v[32:35], v[2:3], off offset:768
	v_sub_u32_e64 v2, v58, v76 clamp
	v_sub_u32_e32 v2, 0, v2
	v_ashrrev_i32_e32 v3, 31, v2
	v_lshlrev_b64 v[2:3], 10, v[2:3]
	v_lshl_add_u64 v[2:3], v[0:1], 0, v[2:3]
	v_add_u32_e32 v86, 1, v58
	global_load_dwordx4 v[28:31], v[2:3], off offset:768
	v_min_u32_e32 v2, v86, v76
	v_sub_u32_e32 v2, v2, v58
	v_ashrrev_i32_e32 v3, 31, v2
	v_lshlrev_b64 v[2:3], 10, v[2:3]
	v_lshl_add_u64 v[2:3], v[0:1], 0, v[2:3]
	v_add_u32_e32 v87, 2, v58
	global_load_dwordx4 v[24:27], v[2:3], off offset:768
	v_min_u32_e32 v2, v87, v76
	v_sub_u32_e32 v2, v2, v58
	v_ashrrev_i32_e32 v3, 31, v2
	v_lshlrev_b64 v[2:3], 10, v[2:3]
	v_lshl_add_u64 v[2:3], v[0:1], 0, v[2:3]
	v_add_u32_e32 v88, 3, v58
	global_load_dwordx4 v[20:23], v[2:3], off offset:768
	v_min_u32_e32 v2, v88, v76
	v_sub_u32_e32 v2, v2, v58
	v_ashrrev_i32_e32 v3, 31, v2
	v_lshlrev_b64 v[2:3], 10, v[2:3]
	v_lshl_add_u64 v[2:3], v[0:1], 0, v[2:3]
	v_add_u32_e32 v89, 4, v58
	global_load_dwordx4 v[16:19], v[2:3], off offset:768
	v_min_u32_e32 v2, v89, v76
	v_sub_u32_e32 v2, v2, v58
	v_ashrrev_i32_e32 v3, 31, v2
	v_lshlrev_b64 v[2:3], 10, v[2:3]
	v_lshl_add_u64 v[2:3], v[0:1], 0, v[2:3]
	v_add_u32_e32 v90, 5, v58
	global_load_dwordx4 v[12:15], v[2:3], off offset:768
	v_min_u32_e32 v2, v90, v76
	v_sub_u32_e32 v2, v2, v58
	v_ashrrev_i32_e32 v3, 31, v2
	v_lshlrev_b64 v[2:3], 10, v[2:3]
	v_lshl_add_u64 v[2:3], v[0:1], 0, v[2:3]
	v_add_u32_e32 v91, 6, v58
	global_load_dwordx4 v[8:11], v[2:3], off offset:768
	v_min_u32_e32 v2, v91, v76
	v_sub_u32_e32 v2, v2, v58
	v_ashrrev_i32_e32 v3, 31, v2
	v_lshlrev_b64 v[2:3], 10, v[2:3]
	v_lshl_add_u64 v[2:3], v[0:1], 0, v[2:3]
	v_add_u32_e32 v92, 7, v58
	global_load_dwordx4 v[4:7], v[2:3], off offset:768
	v_min_u32_e32 v2, v92, v76
	v_sub_u32_e32 v2, v2, v58
	v_ashrrev_i32_e32 v3, 31, v2
	v_lshlrev_b64 v[2:3], 10, v[2:3]
	v_lshl_add_u64 v[0:1], v[0:1], 0, v[2:3]
	global_load_dwordx4 v[0:3], v[0:1], off offset:768
	s_waitcnt vmcnt(15)
	v_lshlrev_b32_e32 v76, 16, v60
	v_and_b32_e32 v60, 0xffff0000, v60
	v_lshlrev_b32_e32 v93, 16, v61
	v_and_b32_e32 v61, 0xffff0000, v61
	v_lshlrev_b32_e32 v94, 16, v62
	v_and_b32_e32 v62, 0xffff0000, v62
	v_lshlrev_b32_e32 v95, 16, v63
	v_and_b32_e32 v63, 0xffff0000, v63
	v_cmp_lt_u32_e32 vcc, v59, v57
	v_add_f32_e32 v76, 0, v76
	v_add_f32_e32 v60, 0, v60
	v_add_f32_e32 v93, 0, v93
	v_add_f32_e32 v61, 0, v61
	v_add_f32_e32 v94, 0, v94
	v_add_f32_e32 v62, 0, v62
	v_add_f32_e32 v95, 0, v95
	v_add_f32_e32 v63, 0, v63
	v_cndmask_b32_e64 v59, 0, 1, vcc
	v_cndmask_b32_e32 v76, 0, v76, vcc
	v_cndmask_b32_e32 v60, 0, v60, vcc
	v_cndmask_b32_e32 v93, 0, v93, vcc
	v_cndmask_b32_e32 v61, 0, v61, vcc
	v_cndmask_b32_e32 v94, 0, v94, vcc
	v_cndmask_b32_e32 v62, 0, v62, vcc
	v_cndmask_b32_e32 v95, 0, v95, vcc
	v_cndmask_b32_e32 v63, 0, v63, vcc
	v_cmp_lt_u32_e32 vcc, v77, v57
	s_waitcnt vmcnt(14)
; __device__ __forceinline__ void unpack8(const u32x4& w, float (&f)[8]) { f[0] = bf_lo(w.x); f[1] = bf_hi(w.x); f[2] = bf_lo(w.y); f[3] = bf_hi(w.y); f[4] = bf_lo(w.z); f[5] = bf_hi(w.z); f[6] = bf_lo(w.w); f[7] = bf_hi(w.w); }
; template <int HW> __device__ __forceinline__ void pool_item(const bf16_t* UP, bf16_t* MIXo, int row, int c8, int g) {
;     ...
;     for (int j = 0; j < 2 * HW; ++j) { const int s = t - HW + j; const bool ok = s >= 0 && s < T; cnt += ok ? 1 : 0; unpack8(w[j], f);
; #pragma unroll
;         for (int q = 0; q < 8; ++q) acc[q] += ok ? f[q] : 0.f; }
	v_lshlrev_b32_e32 v98, 16, v67
	v_and_b32_e32 v67, 0xffff0000, v67
	v_lshlrev_b32_e32 v77, 16, v64
	v_and_b32_e32 v64, 0xffff0000, v64
	v_cndmask_b32_e32 v67, 0, v67, vcc
	v_lshlrev_b32_e32 v96, 16, v65
	v_cndmask_b32_e32 v77, 0, v77, vcc
	v_cndmask_b32_e32 v64, 0, v64, vcc
	v_add_f32_e32 v63, v63, v67
	v_cmp_lt_u32_e64 s[34:35], v78, v57
	s_waitcnt vmcnt(13)
	v_lshlrev_b32_e32 v67, 16, v68
	v_and_b32_e32 v68, 0xffff0000, v68
	v_and_b32_e32 v65, 0xffff0000, v65
	v_add_f32_e32 v76, v76, v77
	v_add_f32_e32 v60, v60, v64
	v_cndmask_b32_e32 v64, 0, v96, vcc
	v_lshlrev_b32_e32 v77, 16, v69
	v_cndmask_b32_e64 v68, 0, v68, s[34:35]
	v_lshlrev_b32_e32 v97, 16, v66
	v_add_f32_e32 v64, v93, v64
	v_cndmask_b32_e32 v65, 0, v65, vcc
	v_and_b32_e32 v69, 0xffff0000, v69
	v_add_f32_e32 v60, v60, v68
	v_cndmask_b32_e64 v68, 0, v77, s[34:35]
	v_and_b32_e32 v66, 0xffff0000, v66
	v_add_f32_e32 v61, v61, v65
	v_cndmask_b32_e32 v65, 0, v97, vcc
	v_lshlrev_b32_e32 v78, 16, v70
	v_add_f32_e32 v64, v64, v68
	v_cndmask_b32_e64 v68, 0, v69, s[34:35]
	v_add_f32_e32 v65, v94, v65
	v_cndmask_b32_e32 v66, 0, v66, vcc
	v_and_b32_e32 v70, 0xffff0000, v70
	v_add_f32_e32 v61, v61, v68
	v_cndmask_b32_e64 v68, 0, v78, s[34:35]
	v_add_f32_e32 v62, v62, v66
	v_cndmask_b32_e32 v66, 0, v98, vcc
	v_lshlrev_b32_e32 v93, 16, v71
	v_cndmask_b32_e64 v67, 0, v67, s[34:35]
	v_add_f32_e32 v65, v65, v68
	v_cndmask_b32_e64 v68, 0, v70, s[34:35]
	v_cmp_lt_u32_e64 s[36:37], v79, v57
	s_waitcnt vmcnt(12)
	v_lshlrev_b32_e32 v69, 16, v72
	v_add_f32_e32 v66, v95, v66
	v_and_b32_e32 v71, 0xffff0000, v71
	v_add_f32_e32 v67, v76, v67
	v_add_f32_e32 v62, v62, v68
	v_cndmask_b32_e64 v68, 0, v93, s[34:35]
	v_and_b32_e32 v70, 0xffff0000, v72
	v_cndmask_b32_e64 v69, 0, v69, s[36:37]
	v_add_f32_e32 v66, v66, v68
	v_cndmask_b32_e64 v68, 0, v71, s[34:35]
	v_lshlrev_b32_e32 v71, 16, v73
	v_add_f32_e32 v67, v67, v69
	v_cndmask_b32_e64 v69, 0, v70, s[36:37]
	v_and_b32_e32 v72, 0xffff0000, v73
	v_add_f32_e32 v60, v60, v69
	v_cndmask_b32_e64 v69, 0, v71, s[36:37]
	v_lshlrev_b32_e32 v73, 16, v74
	v_add_f32_e32 v64, v64, v69
	v_cndmask_b32_e64 v69, 0, v72, s[36:37]
	v_and_b32_e32 v74, 0xffff0000, v74
	v_add_f32_e32 v61, v61, v69
	v_cndmask_b32_e64 v69, 0, v73, s[36:37]
	v_lshlrev_b32_e32 v76, 16, v75
	v_add_f32_e32 v65, v65, v69
	v_cndmask_b32_e64 v69, 0, v74, s[36:37]
	v_and_b32_e32 v75, 0xffff0000, v75
	v_add_f32_e32 v62, v62, v69
	v_cndmask_b32_e64 v69, 0, v76, s[36:37]
	v_add_f32_e32 v63, v63, v68
	v_add_f32_e32 v66, v66, v69
	v_cndmask_b32_e64 v69, 0, v75, s[36:37]
	v_cndmask_b32_e64 v68, 0, 1, s[36:37]
	v_add_f32_e32 v63, v63, v69
	v_cmp_lt_u32_e64 s[36:37], v80, v57
	s_waitcnt vmcnt(11)
	v_lshlrev_b32_e32 v69, 16, v44
	v_and_b32_e32 v44, 0xffff0000, v44
	v_lshlrev_b32_e32 v70, 16, v45
	v_and_b32_e32 v45, 0xffff0000, v45
	v_lshlrev_b32_e32 v71, 16, v46
	v_and_b32_e32 v46, 0xffff0000, v46
	v_lshlrev_b32_e32 v72, 16, v47
	v_cndmask_b32_e64 v44, 0, v44, s[36:37]
	v_cndmask_b32_e64 v45, 0, v45, s[36:37]
	v_cndmask_b32_e64 v46, 0, v46, s[36:37]
	v_and_b32_e32 v47, 0xffff0000, v47
	v_cndmask_b32_e64 v69, 0, v69, s[36:37]
	v_add_f32_e32 v44, v60, v44
	v_cndmask_b32_e64 v60, 0, v70, s[36:37]
	v_add_f32_e32 v45, v61, v45
	v_cndmask_b32_e64 v61, 0, v71, s[36:37]
	v_add_f32_e32 v46, v62, v46
	v_cndmask_b32_e64 v62, 0, v72, s[36:37]
	v_add_f32_e32 v67, v67, v69
	v_add_f32_e32 v60, v64, v60
	v_add_f32_e32 v61, v65, v61
	v_add_f32_e32 v62, v66, v62
	v_cndmask_b32_e64 v47, 0, v47, s[36:37]
	v_cmp_lt_u32_e64 s[38:39], v82, v57
	s_waitcnt vmcnt(10)
	v_lshlrev_b32_e32 v64, 16, v40
	v_and_b32_e32 v40, 0xffff0000, v40
	v_lshlrev_b32_e32 v65, 16, v41
	v_and_b32_e32 v41, 0xffff0000, v41
	v_lshlrev_b32_e32 v66, 16, v42
	v_and_b32_e32 v42, 0xffff0000, v42
	v_lshlrev_b32_e32 v69, 16, v43
	v_and_b32_e32 v43, 0xffff0000, v43
	v_add_f32_e32 v47, v63, v47
	v_cndmask_b32_e64 v40, 0, v40, s[38:39]
	v_cndmask_b32_e64 v41, 0, v41, s[38:39]
	v_cndmask_b32_e64 v42, 0, v42, s[38:39]
	v_cndmask_b32_e64 v43, 0, v43, s[38:39]
	v_cndmask_b32_e64 v63, 0, 1, s[38:39]
	v_cndmask_b32_e64 v64, 0, v64, s[38:39]
	v_add_f32_e32 v40, v44, v40
	v_cndmask_b32_e64 v44, 0, v65, s[38:39]
	v_add_f32_e32 v41, v45, v41
	v_cndmask_b32_e64 v45, 0, v66, s[38:39]
	v_add_f32_e32 v42, v46, v42
	v_cndmask_b32_e64 v46, 0, v69, s[38:39]
	v_add_f32_e32 v43, v47, v43
	v_cmp_lt_u32_e64 s[38:39], v83, v57
	s_waitcnt vmcnt(9)
	v_lshlrev_b32_e32 v47, 16, v36
	v_and_b32_e32 v36, 0xffff0000, v36
	v_add_f32_e32 v44, v60, v44
	v_add_f32_e32 v45, v61, v45
	v_lshlrev_b32_e32 v60, 16, v37
	v_and_b32_e32 v37, 0xffff0000, v37
	v_lshlrev_b32_e32 v61, 16, v38
	v_and_b32_e32 v38, 0xffff0000, v38
	v_cndmask_b32_e64 v36, 0, v36, s[38:39]
	v_add_f32_e32 v46, v62, v46
	v_lshlrev_b32_e32 v62, 16, v39
	v_add_f32_e32 v36, v40, v36
	v_cndmask_b32_e64 v40, 0, v60, s[38:39]
	v_cndmask_b32_e64 v37, 0, v37, s[38:39]
	v_cndmask_b32_e64 v38, 0, v38, s[38:39]
	v_add_f32_e32 v40, v44, v40
	v_add_f32_e32 v37, v41, v37
	v_cndmask_b32_e64 v41, 0, v61, s[38:39]
	v_add_f32_e32 v38, v42, v38
	v_cndmask_b32_e64 v42, 0, v62, s[38:39]
	v_cmp_lt_u32_e64 s[40:41], v85, v57
	s_waitcnt vmcnt(8)
; __device__ __forceinline__ void unpack8(const u32x4& w, float (&f)[8]) { f[0] = bf_lo(w.x); f[1] = bf_hi(w.x); f[2] = bf_lo(w.y); f[3] = bf_hi(w.y); f[4] = bf_lo(w.z); f[5] = bf_hi(w.z); f[6] = bf_lo(w.w); f[7] = bf_hi(w.w); }
; template <int HW> __device__ __forceinline__ void pool_item(const bf16_t* UP, bf16_t* MIXo, int row, int c8, int g) {
;     ...
;     for (int j = 0; j < 2 * HW; ++j) { const int s = t - HW + j; const bool ok = s >= 0 && s < T; cnt += ok ? 1 : 0; unpack8(w[j], f);
; #pragma unroll
;         for (int q = 0; q < 8; ++q) acc[q] += ok ? f[q] : 0.f; }
	v_lshlrev_b32_e32 v44, 16, v32
	v_and_b32_e32 v32, 0xffff0000, v32
	v_and_b32_e32 v39, 0xffff0000, v39
	v_add_f32_e32 v41, v45, v41
	v_add_f32_e32 v42, v46, v42
	v_lshlrev_b32_e32 v45, 16, v33
	v_and_b32_e32 v33, 0xffff0000, v33
	v_lshlrev_b32_e32 v46, 16, v34
	v_and_b32_e32 v34, 0xffff0000, v34
	v_cndmask_b32_e64 v32, 0, v32, s[40:41]
	v_add_f32_e32 v64, v67, v64
	v_cndmask_b32_e64 v47, 0, v47, s[38:39]
	v_cndmask_b32_e64 v39, 0, v39, s[38:39]
	v_lshlrev_b32_e32 v60, 16, v35
	v_and_b32_e32 v35, 0xffff0000, v35
	v_add_f32_e32 v32, v36, v32
	v_cndmask_b32_e64 v36, 0, v45, s[40:41]
	v_cndmask_b32_e64 v33, 0, v33, s[40:41]
	v_cndmask_b32_e64 v34, 0, v34, s[40:41]
	v_add_f32_e32 v47, v64, v47
	v_add_f32_e32 v39, v43, v39
	v_cndmask_b32_e64 v43, 0, 1, s[40:41]
	v_cndmask_b32_e64 v44, 0, v44, s[40:41]
	v_add_f32_e32 v36, v40, v36
	v_add_f32_e32 v33, v37, v33
	v_cndmask_b32_e64 v37, 0, v46, s[40:41]
	v_add_f32_e32 v34, v38, v34
	v_cndmask_b32_e64 v38, 0, v60, s[40:41]
	v_cndmask_b32_e64 v35, 0, v35, s[40:41]
	v_cmp_lt_u32_e64 s[40:41], v58, v57
	s_waitcnt vmcnt(7)
	v_lshlrev_b32_e32 v40, 16, v28
	v_add_f32_e32 v44, v47, v44
	v_and_b32_e32 v28, 0xffff0000, v28
	v_cndmask_b32_e64 v46, 0, v40, s[40:41]
	v_add_f32_e32 v37, v41, v37
	v_lshlrev_b32_e32 v41, 16, v29
	v_add_f32_e32 v44, v44, v46
	v_cndmask_b32_e64 v46, 0, v28, s[40:41]
	v_and_b32_e32 v29, 0xffff0000, v29
	v_add_f32_e32 v32, v32, v46
	v_cndmask_b32_e64 v46, 0, v41, s[40:41]
	v_add_f32_e32 v38, v42, v38
	v_lshlrev_b32_e32 v42, 16, v30
	v_add_f32_e32 v36, v36, v46
	v_cndmask_b32_e64 v46, 0, v29, s[40:41]
	v_and_b32_e32 v30, 0xffff0000, v30
	v_add_f32_e32 v33, v33, v46
	v_cndmask_b32_e64 v46, 0, v42, s[40:41]
	v_lshlrev_b32_e32 v45, 16, v31
	v_add_f32_e32 v37, v37, v46
	v_cndmask_b32_e64 v46, 0, v30, s[40:41]
	v_and_b32_e32 v31, 0xffff0000, v31
	v_add_f32_e32 v34, v34, v46
	v_cndmask_b32_e64 v46, 0, v45, s[40:41]
	v_add_f32_e32 v35, v39, v35
	v_add_f32_e32 v38, v38, v46
	v_cndmask_b32_e64 v46, 0, v31, s[40:41]
	v_cndmask_b32_e64 v39, 0, 1, s[40:41]
	v_add_f32_e32 v35, v35, v46
	v_cmp_lt_u32_e64 s[40:41], v86, v57
	s_waitcnt vmcnt(6)
	v_lshlrev_b32_e32 v46, 16, v24
	v_and_b32_e32 v24, 0xffff0000, v24
	v_lshlrev_b32_e32 v47, 16, v25
	v_and_b32_e32 v25, 0xffff0000, v25
	v_lshlrev_b32_e32 v60, 16, v26
	v_and_b32_e32 v26, 0xffff0000, v26
	v_cndmask_b32_e64 v24, 0, v24, s[40:41]
	v_lshlrev_b32_e32 v61, 16, v27
	v_add_f32_e32 v24, v32, v24
	v_cndmask_b32_e64 v32, 0, v47, s[40:41]
	v_cndmask_b32_e64 v25, 0, v25, s[40:41]
	v_cndmask_b32_e64 v26, 0, v26, s[40:41]
	v_add_f32_e32 v32, v36, v32
	v_add_f32_e32 v25, v33, v25
	v_cndmask_b32_e64 v33, 0, v60, s[40:41]
	v_add_f32_e32 v26, v34, v26
	v_cndmask_b32_e64 v34, 0, v61, s[40:41]
	v_cmp_lt_u32_e64 s[42:43], v87, v57
	s_waitcnt vmcnt(5)
	v_lshlrev_b32_e32 v36, 16, v20
	v_and_b32_e32 v20, 0xffff0000, v20
	v_and_b32_e32 v27, 0xffff0000, v27
	v_cndmask_b32_e64 v46, 0, v46, s[40:41]
	v_add_f32_e32 v33, v37, v33
	v_add_f32_e32 v34, v38, v34
	v_lshlrev_b32_e32 v37, 16, v21
	v_and_b32_e32 v21, 0xffff0000, v21
	v_lshlrev_b32_e32 v38, 16, v22
	v_and_b32_e32 v22, 0xffff0000, v22
	v_cndmask_b32_e64 v20, 0, v20, s[42:43]
	v_add_f32_e32 v44, v44, v46
	v_cndmask_b32_e64 v27, 0, v27, s[40:41]
	v_lshlrev_b32_e32 v46, 16, v23
	v_and_b32_e32 v23, 0xffff0000, v23
	v_add_f32_e32 v20, v24, v20
	v_cndmask_b32_e64 v24, 0, v37, s[42:43]
	v_cndmask_b32_e64 v21, 0, v21, s[42:43]
	v_cndmask_b32_e64 v22, 0, v22, s[42:43]
	v_add_f32_e32 v27, v35, v27
	v_cndmask_b32_e64 v35, 0, 1, s[42:43]
	v_cndmask_b32_e64 v36, 0, v36, s[42:43]
	v_add_f32_e32 v24, v32, v24
	v_add_f32_e32 v21, v25, v21
	v_cndmask_b32_e64 v25, 0, v38, s[42:43]
	v_add_f32_e32 v22, v26, v22
	v_cndmask_b32_e64 v26, 0, v46, s[42:43]
	v_cndmask_b32_e64 v23, 0, v23, s[42:43]
	v_cmp_lt_u32_e64 s[42:43], v88, v57
	s_waitcnt vmcnt(4)
	v_lshlrev_b32_e32 v32, 16, v17
	v_and_b32_e32 v17, 0xffff0000, v17
	v_add_f32_e32 v25, v33, v25
	v_add_f32_e32 v23, v27, v23
	v_lshlrev_b32_e32 v27, 16, v16
	v_and_b32_e32 v16, 0xffff0000, v16
	v_lshlrev_b32_e32 v33, 16, v18
	v_and_b32_e32 v18, 0xffff0000, v18
	v_cndmask_b32_e64 v17, 0, v17, s[42:43]
	v_add_f32_e32 v26, v34, v26
	v_lshlrev_b32_e32 v34, 16, v19
	v_cndmask_b32_e64 v16, 0, v16, s[42:43]
	v_add_f32_e32 v17, v21, v17
	v_cndmask_b32_e64 v21, 0, v33, s[42:43]
	v_cndmask_b32_e64 v18, 0, v18, s[42:43]
	v_add_f32_e32 v16, v20, v16
	v_cndmask_b32_e64 v20, 0, v32, s[42:43]
	v_add_f32_e32 v21, v25, v21
	v_add_f32_e32 v18, v22, v18
	v_cndmask_b32_e64 v22, 0, v34, s[42:43]
	v_cmp_lt_u32_e64 s[44:45], v89, v57
	s_waitcnt vmcnt(3)
	v_lshlrev_b32_e32 v25, 16, v13
	v_and_b32_e32 v13, 0xffff0000, v13
	v_and_b32_e32 v19, 0xffff0000, v19
	v_add_f32_e32 v20, v24, v20
	v_add_f32_e32 v22, v26, v22
	v_lshlrev_b32_e32 v24, 16, v12
	v_and_b32_e32 v12, 0xffff0000, v12
	v_lshlrev_b32_e32 v26, 16, v14
	v_and_b32_e32 v14, 0xffff0000, v14
	v_cndmask_b32_e64 v13, 0, v13, s[44:45]
	v_cndmask_b32_e64 v19, 0, v19, s[42:43]
	v_lshlrev_b32_e32 v32, 16, v15
	v_and_b32_e32 v15, 0xffff0000, v15
	v_cndmask_b32_e64 v12, 0, v12, s[44:45]
	v_add_f32_e32 v13, v17, v13
	v_cndmask_b32_e64 v17, 0, v26, s[44:45]
	v_cndmask_b32_e64 v14, 0, v14, s[44:45]
	v_add_f32_e32 v19, v23, v19
	v_cndmask_b32_e64 v23, 0, 1, s[44:45]
	v_cndmask_b32_e64 v24, 0, v24, s[44:45]
	v_add_f32_e32 v12, v16, v12
	v_cndmask_b32_e64 v16, 0, v25, s[44:45]
	v_add_f32_e32 v17, v21, v17
	v_add_f32_e32 v14, v18, v14
	v_cndmask_b32_e64 v18, 0, v32, s[44:45]
	v_cndmask_b32_e64 v15, 0, v15, s[44:45]
	v_cmp_lt_u32_e64 s[44:45], v90, v57
	s_waitcnt vmcnt(2)
; __device__ __forceinline__ unsigned cvt_pk_bf16(float lo, float hi) { f32x2_t v = {lo, hi}; bf16x2_t b = __builtin_convertvector(v, bf16x2_t); return __builtin_bit_cast(unsigned, b); }
; __device__ __forceinline__ void unpack8(const u32x4& w, float (&f)[8]) { f[0] = bf_lo(w.x); f[1] = bf_hi(w.x); f[2] = bf_lo(w.y); f[3] = bf_hi(w.y); f[4] = bf_lo(w.z); f[5] = bf_hi(w.z); f[6] = bf_lo(w.w); f[7] = bf_hi(w.w); }
; template <int HW> __device__ __forceinline__ void pool_item(const bf16_t* UP, bf16_t* MIXo, int row, int c8, int g) {
;     ...
;     for (int j = 0; j < 2 * HW; ++j) { const int s = t - HW + j; const int sc = s < 0 ? 0 : (s >= T ? T - 1 : s); w[j] = ld16(up + (ptrdiff_t)(sc - t) * 512); }
;     float acc[8], f[8];
; #pragma unroll
;     for (int q = 0; q < 8; ++q) acc[q] = 0.f;
;     int cnt = 0;
; #pragma unroll
;     for (int j = 0; j < 2 * HW; ++j) { const int s = t - HW + j; const bool ok = s >= 0 && s < T; cnt += ok ? 1 : 0; unpack8(w[j], f);
; #pragma unroll
;         for (int q = 0; q < 8; ++q) acc[q] += ok ? f[q] : 0.f; }
;     unpack8(w[HW], f);
;     const float inv = 1.0f / (float)cnt;
; #pragma unroll
;     for (int q = 0; q < 8; ++q) acc[q] = acc[q] * inv - f[q];
;     u32x4 o; o.x = cvt_pk_bf16(acc[0], acc[1]); o.y = cvt_pk_bf16(acc[2], acc[3]); o.z = cvt_pk_bf16(acc[4], acc[5]); o.w = cvt_pk_bf16(acc[6], acc[7]);
;     *(u32x4*)(MIXo + (size_t)row * KMO + 128 * g + c8) = o;
	v_lshlrev_b32_e32 v21, 16, v10
	v_and_b32_e32 v10, 0xffff0000, v10
	v_add_f32_e32 v16, v20, v16
	v_add_f32_e32 v18, v22, v18
	v_add_f32_e32 v15, v19, v15
	v_lshlrev_b32_e32 v19, 16, v8
	v_and_b32_e32 v8, 0xffff0000, v8
	v_lshlrev_b32_e32 v20, 16, v9
	v_and_b32_e32 v9, 0xffff0000, v9
	v_lshlrev_b32_e32 v22, 16, v11
	v_cndmask_b32_e64 v10, 0, v10, s[44:45]
	v_cndmask_b32_e64 v8, 0, v8, s[44:45]
	v_cndmask_b32_e64 v9, 0, v9, s[44:45]
	v_add_f32_e32 v10, v14, v10
	v_cndmask_b32_e64 v14, 0, v22, s[44:45]
	v_add_f32_e32 v8, v12, v8
	v_cndmask_b32_e64 v12, 0, v20, s[44:45]
	v_add_f32_e32 v9, v13, v9
	v_cndmask_b32_e64 v13, 0, v21, s[44:45]
	v_add_f32_e32 v14, v18, v14
	v_cmp_lt_u32_e64 s[46:47], v91, v57
	s_waitcnt vmcnt(1)
	v_lshlrev_b32_e32 v18, 16, v6
	v_and_b32_e32 v6, 0xffff0000, v6
	v_and_b32_e32 v11, 0xffff0000, v11
	v_add_f32_e32 v12, v16, v12
	v_add_f32_e32 v13, v17, v13
	v_lshlrev_b32_e32 v16, 16, v4
	v_and_b32_e32 v4, 0xffff0000, v4
	v_lshlrev_b32_e32 v17, 16, v5
	v_and_b32_e32 v5, 0xffff0000, v5
	v_lshlrev_b32_e32 v20, 16, v7
	v_cndmask_b32_e64 v6, 0, v6, s[46:47]
	v_cndmask_b32_e64 v11, 0, v11, s[44:45]
	v_and_b32_e32 v7, 0xffff0000, v7
	v_cndmask_b32_e64 v4, 0, v4, s[46:47]
	v_cndmask_b32_e64 v5, 0, v5, s[46:47]
	v_add_f32_e32 v6, v10, v6
	v_cndmask_b32_e64 v10, 0, v20, s[46:47]
	v_add_f32_e32 v11, v15, v11
	v_cndmask_b32_e64 v15, 0, 1, s[46:47]
	v_cndmask_b32_e64 v16, 0, v16, s[46:47]
	v_add_f32_e32 v4, v8, v4
	v_cndmask_b32_e64 v8, 0, v17, s[46:47]
	v_add_f32_e32 v5, v9, v5
	v_cndmask_b32_e64 v9, 0, v18, s[46:47]
	v_add_f32_e32 v10, v14, v10
	v_cndmask_b32_e64 v7, 0, v7, s[46:47]
	v_cmp_lt_u32_e64 s[46:47], v92, v57
	s_waitcnt vmcnt(0)
	v_lshlrev_b32_e32 v14, 16, v3
	v_and_b32_e32 v3, 0xffff0000, v3
	v_add_f32_e32 v7, v11, v7
	v_cndmask_b32_e64 v3, 0, v3, s[46:47]
	v_add_f32_e32 v3, v7, v3
	v_addc_co_u32_e32 v7, vcc, 0, v39, vcc
	v_addc_co_u32_e64 v7, vcc, v7, v59, s[34:35]
	v_addc_co_u32_e64 v7, vcc, v7, v68, s[36:37]
	v_addc_co_u32_e64 v7, vcc, v7, v63, s[38:39]
	v_addc_co_u32_e64 v7, vcc, v7, v43, s[40:41]
	v_addc_co_u32_e64 v7, vcc, v7, v35, s[42:43]
	v_addc_co_u32_e64 v7, vcc, v7, v23, s[44:45]
	v_addc_co_u32_e64 v7, vcc, v7, v15, s[46:47]
	v_cvt_f32_u32_e32 v7, v7
	v_lshlrev_b32_e32 v11, 16, v0
	v_and_b32_e32 v0, 0xffff0000, v0
	v_add_f32_e32 v8, v12, v8
	v_lshlrev_b32_e32 v12, 16, v1
	v_and_b32_e32 v1, 0xffff0000, v1
	v_cndmask_b32_e64 v0, 0, v0, s[46:47]
	v_add_f32_e32 v9, v13, v9
	v_lshlrev_b32_e32 v13, 16, v2
	v_add_f32_e32 v0, v4, v0
	v_cndmask_b32_e64 v4, 0, v12, s[46:47]
	v_cndmask_b32_e64 v1, 0, v1, s[46:47]
	v_add_f32_e32 v4, v8, v4
	v_add_f32_e32 v1, v5, v1
	v_cndmask_b32_e64 v5, 0, v13, s[46:47]
	v_div_scale_f32 v8, s[12:13], v7, v7, 1.0
	v_add_f32_e32 v5, v9, v5
	v_rcp_f32_e32 v9, v8
	v_and_b32_e32 v2, 0xffff0000, v2
	v_cndmask_b32_e64 v2, 0, v2, s[46:47]
	v_add_f32_e32 v2, v6, v2
	v_cndmask_b32_e64 v6, 0, v14, s[46:47]
	v_add_f32_e32 v6, v10, v6
	v_fma_f32 v10, -v8, v9, 1.0
	v_fmac_f32_e32 v9, v10, v9
	v_div_scale_f32 v10, vcc, 1.0, v7, 1.0
	v_mul_f32_e32 v12, v10, v9
	v_add_f32_e32 v36, v44, v36
	v_cndmask_b32_e64 v27, 0, v27, s[42:43]
	v_fma_f32 v13, -v8, v12, v10
	v_add_f32_e32 v27, v36, v27
	v_fmac_f32_e32 v12, v13, v9
	v_add_f32_e32 v24, v27, v24
	v_cndmask_b32_e64 v19, 0, v19, s[44:45]
	v_fma_f32 v8, -v8, v12, v10
	v_add_f32_e32 v19, v24, v19
	v_div_fmas_f32 v8, v8, v9, v12
	v_add_f32_e32 v16, v19, v16
	v_cndmask_b32_e64 v11, 0, v11, s[46:47]
	v_div_fixup_f32 v7, v8, v7, 1.0
	v_add_f32_e32 v11, v16, v11
	v_fma_f32 v4, v7, v4, -v41
	v_fma_f32 v1, v7, v1, -v29
	v_fma_f32 v5, v7, v5, -v42
	v_fma_f32 v2, v7, v2, -v30
	v_fma_f32 v8, v7, v11, -v40
	v_fma_f32 v0, v7, v0, -v28
	v_fma_f32 v6, v7, v6, -v45
	v_fma_f32 v3, v7, v3, -v31
	v_cvt_pk_bf16_f32 v1, v4, v1
	v_cvt_pk_bf16_f32 v2, v5, v2
	v_lshlrev_b64 v[4:5], 11, v[52:53]
	v_cvt_pk_bf16_f32 v0, v8, v0
	v_cvt_pk_bf16_f32 v3, v6, v3
	v_lshl_add_u64 v[4:5], v[50:51], 0, v[4:5]
	global_store_dwordx4 v[4:5], v[0:3], off offset:768 sc1
	s_mov_b64 s[12:13], 0
.LBB0_122:
	s_andn2_b64 vcc, exec, s[12:13]
	s_cbranch_vccnz .LBB0_124
	v_subrev_co_u32_e32 v32, vcc, 4, v58
	v_add_u32_e32 v26, -1, v57
	v_min_u32_e32 v0, v32, v26
	v_add_u32_e32 v36, 1, v58
	v_cndmask_b32_e64 v0, v0, 0, vcc
	v_min_u32_e32 v16, v36, v26
	v_sub_u32_e32 v0, v0, v58
	v_sub_u32_e32 v16, v16, v58
	v_ashrrev_i32_e32 v1, 31, v0
	v_ashrrev_i32_e32 v17, 31, v16
	v_lshl_add_u64 v[24:25], v[48:49], 0, v[54:55]
	v_lshlrev_b64 v[0:1], 10, v[0:1]
	v_lshlrev_b64 v[16:17], 10, v[16:17]
	v_lshl_add_u64 v[0:1], v[24:25], 0, v[0:1]
	v_subrev_co_u32_e32 v33, vcc, 3, v58
	v_lshl_add_u64 v[16:17], v[24:25], 0, v[16:17]
	global_load_dwordx4 v[28:31], v[0:1], off offset:512
	v_add_u32_e32 v37, 2, v58
	global_load_dwordx4 v[16:19], v[16:17], off offset:512
	v_min_u32_e32 v0, v33, v26
	v_cndmask_b32_e64 v0, v0, 0, vcc
	v_min_u32_e32 v20, v37, v26
	v_sub_u32_e32 v0, v0, v58
	v_sub_u32_e32 v20, v20, v58
	v_ashrrev_i32_e32 v1, 31, v0
	v_ashrrev_i32_e32 v21, 31, v20
	v_lshlrev_b64 v[0:1], 10, v[0:1]
	v_lshlrev_b64 v[20:21], 10, v[20:21]
	v_lshl_add_u64 v[0:1], v[24:25], 0, v[0:1]
	v_subrev_co_u32_e32 v34, vcc, 2, v58
	v_lshl_add_u64 v[20:21], v[24:25], 0, v[20:21]
	global_load_dwordx4 v[12:15], v[0:1], off offset:512
	v_add_u32_e32 v38, 3, v58
	global_load_dwordx4 v[20:23], v[20:21], off offset:512
	v_min_u32_e32 v0, v34, v26
	v_cndmask_b32_e64 v0, v0, 0, vcc
	v_sub_u32_e32 v0, v0, v58
	v_ashrrev_i32_e32 v1, 31, v0
	v_lshlrev_b64 v[0:1], 10, v[0:1]
	v_lshl_add_u64 v[0:1], v[24:25], 0, v[0:1]
	v_subrev_co_u32_e32 v35, vcc, 1, v58
	global_load_dwordx4 v[4:7], v[0:1], off offset:512
	v_min_u32_e32 v0, v35, v26
	v_cndmask_b32_e64 v0, v0, 0, vcc
	v_sub_u32_e32 v0, v0, v58
	v_ashrrev_i32_e32 v1, 31, v0
	v_lshlrev_b64 v[0:1], 10, v[0:1]
	v_lshl_add_u64 v[0:1], v[24:25], 0, v[0:1]
	global_load_dwordx4 v[8:11], v[0:1], off offset:512
	v_sub_u32_e64 v0, v58, v26 clamp
	v_sub_u32_e32 v0, 0, v0
	v_ashrrev_i32_e32 v1, 31, v0
	v_lshlrev_b64 v[0:1], 10, v[0:1]
	v_lshl_add_u64 v[0:1], v[24:25], 0, v[0:1]
	global_load_dwordx4 v[0:3], v[0:1], off offset:512
	v_min_u32_e32 v26, v38, v26
	v_sub_u32_e32 v26, v26, v58
	v_ashrrev_i32_e32 v27, 31, v26
	v_lshlrev_b64 v[26:27], 10, v[26:27]
	v_lshl_add_u64 v[24:25], v[24:25], 0, v[26:27]
	global_load_dwordx4 v[24:27], v[24:25], off offset:512
	v_cmp_lt_u32_e32 vcc, v32, v57
	v_cmp_lt_u32_e64 s[34:35], v34, v57
	v_cmp_lt_u32_e64 s[36:37], v35, v57
	v_cndmask_b32_e64 v32, 0, 1, vcc
	v_cmp_lt_u32_e64 s[38:39], v37, v57
	s_waitcnt vmcnt(7)
; __device__ __forceinline__ void unpack8(const u32x4& w, float (&f)[8]) { f[0] = bf_lo(w.x); f[1] = bf_hi(w.x); f[2] = bf_lo(w.y); f[3] = bf_hi(w.y); f[4] = bf_lo(w.z); f[5] = bf_hi(w.z); f[6] = bf_lo(w.w); f[7] = bf_hi(w.w); }
; template <int HW> __device__ __forceinline__ void pool_item(const bf16_t* UP, bf16_t* MIXo, int row, int c8, int g) {
;     ...
;     for (int j = 0; j < 2 * HW; ++j) { const int s = t - HW + j; const bool ok = s >= 0 && s < T; cnt += ok ? 1 : 0; unpack8(w[j], f);
; #pragma unroll
;         for (int q = 0; q < 8; ++q) acc[q] += ok ? f[q] : 0.f; }
	v_lshlrev_b32_e32 v39, 16, v28
	v_and_b32_e32 v28, 0xffff0000, v28
	v_lshlrev_b32_e32 v40, 16, v29
	v_and_b32_e32 v29, 0xffff0000, v29
	v_lshlrev_b32_e32 v41, 16, v30
	v_and_b32_e32 v30, 0xffff0000, v30
	v_lshlrev_b32_e32 v42, 16, v31
	v_and_b32_e32 v31, 0xffff0000, v31
	v_add_f32_e32 v39, 0, v39
	v_add_f32_e32 v28, 0, v28
	v_add_f32_e32 v40, 0, v40
	v_add_f32_e32 v29, 0, v29
	v_add_f32_e32 v41, 0, v41
	v_add_f32_e32 v30, 0, v30
	v_add_f32_e32 v42, 0, v42
	v_add_f32_e32 v31, 0, v31
	v_cndmask_b32_e32 v39, 0, v39, vcc
	v_cndmask_b32_e32 v28, 0, v28, vcc
	v_cndmask_b32_e32 v40, 0, v40, vcc
	v_cndmask_b32_e32 v29, 0, v29, vcc
	v_cndmask_b32_e32 v41, 0, v41, vcc
	v_cndmask_b32_e32 v30, 0, v30, vcc
	v_cndmask_b32_e32 v42, 0, v42, vcc
	v_cndmask_b32_e32 v31, 0, v31, vcc
	v_cmp_lt_u32_e32 vcc, v33, v57
	s_waitcnt vmcnt(5)
	v_lshlrev_b32_e32 v45, 16, v15
	v_and_b32_e32 v15, 0xffff0000, v15
	v_lshlrev_b32_e32 v33, 16, v12
	v_and_b32_e32 v12, 0xffff0000, v12
	v_cndmask_b32_e32 v15, 0, v15, vcc
	v_lshlrev_b32_e32 v43, 16, v13
	v_and_b32_e32 v13, 0xffff0000, v13
	v_lshlrev_b32_e32 v44, 16, v14
	v_and_b32_e32 v14, 0xffff0000, v14
	v_cndmask_b32_e32 v33, 0, v33, vcc
	v_cndmask_b32_e32 v12, 0, v12, vcc
	v_add_f32_e32 v15, v31, v15
	s_waitcnt vmcnt(3)
	v_lshlrev_b32_e32 v31, 16, v4
	v_and_b32_e32 v4, 0xffff0000, v4
	v_add_f32_e32 v33, v39, v33
	v_add_f32_e32 v12, v28, v12
	v_cndmask_b32_e32 v28, 0, v43, vcc
	v_cndmask_b32_e32 v13, 0, v13, vcc
	v_cndmask_b32_e32 v14, 0, v14, vcc
	v_lshlrev_b32_e32 v34, 16, v5
	v_and_b32_e32 v5, 0xffff0000, v5
	v_lshlrev_b32_e32 v39, 16, v6
	v_and_b32_e32 v6, 0xffff0000, v6
	v_cndmask_b32_e64 v4, 0, v4, s[34:35]
	v_add_f32_e32 v28, v40, v28
	v_add_f32_e32 v13, v29, v13
	v_cndmask_b32_e32 v29, 0, v44, vcc
	v_add_f32_e32 v14, v30, v14
	v_cndmask_b32_e32 v30, 0, v45, vcc
	v_lshlrev_b32_e32 v40, 16, v7
	v_add_f32_e32 v4, v12, v4
	v_cndmask_b32_e64 v12, 0, v34, s[34:35]
	v_cndmask_b32_e64 v5, 0, v5, s[34:35]
	v_cndmask_b32_e64 v6, 0, v6, s[34:35]
	v_add_f32_e32 v29, v41, v29
	v_add_f32_e32 v30, v42, v30
	v_add_f32_e32 v12, v28, v12
	v_add_f32_e32 v5, v13, v5
	v_cndmask_b32_e64 v13, 0, v39, s[34:35]
	v_add_f32_e32 v6, v14, v6
	v_cndmask_b32_e64 v14, 0, v40, s[34:35]
	s_waitcnt vmcnt(2)
	v_lshlrev_b32_e32 v28, 16, v8
	v_and_b32_e32 v8, 0xffff0000, v8
	v_and_b32_e32 v7, 0xffff0000, v7
	v_cndmask_b32_e64 v31, 0, v31, s[34:35]
	v_add_f32_e32 v13, v29, v13
	v_add_f32_e32 v14, v30, v14
	v_lshlrev_b32_e32 v29, 16, v9
	v_and_b32_e32 v9, 0xffff0000, v9
	v_lshlrev_b32_e32 v30, 16, v10
	v_and_b32_e32 v10, 0xffff0000, v10
	v_cndmask_b32_e64 v8, 0, v8, s[36:37]
	v_add_f32_e32 v31, v33, v31
	v_cndmask_b32_e64 v7, 0, v7, s[34:35]
	v_lshlrev_b32_e32 v33, 16, v11
	v_and_b32_e32 v11, 0xffff0000, v11
	v_add_f32_e32 v4, v4, v8
	v_cndmask_b32_e64 v8, 0, v29, s[36:37]
	v_cndmask_b32_e64 v9, 0, v9, s[36:37]
	v_cndmask_b32_e64 v10, 0, v10, s[36:37]
	v_add_f32_e32 v7, v15, v7
	v_cndmask_b32_e64 v15, 0, 1, s[36:37]
	v_cndmask_b32_e64 v28, 0, v28, s[36:37]
	v_add_f32_e32 v8, v12, v8
	v_add_f32_e32 v5, v5, v9
	v_cndmask_b32_e64 v9, 0, v30, s[36:37]
	v_add_f32_e32 v6, v6, v10
	v_cndmask_b32_e64 v10, 0, v33, s[36:37]
	v_cndmask_b32_e64 v11, 0, v11, s[36:37]
	v_cmp_lt_u32_e64 s[36:37], v58, v57
	s_waitcnt vmcnt(1)
; __device__ __forceinline__ unsigned cvt_pk_bf16(float lo, float hi) { f32x2_t v = {lo, hi}; bf16x2_t b = __builtin_convertvector(v, bf16x2_t); return __builtin_bit_cast(unsigned, b); }
; __device__ __forceinline__ void unpack8(const u32x4& w, float (&f)[8]) { f[0] = bf_lo(w.x); f[1] = bf_hi(w.x); f[2] = bf_lo(w.y); f[3] = bf_hi(w.y); f[4] = bf_lo(w.z); f[5] = bf_hi(w.z); f[6] = bf_lo(w.w); f[7] = bf_hi(w.w); }
; template <int HW> __device__ __forceinline__ void pool_item(const bf16_t* UP, bf16_t* MIXo, int row, int c8, int g) {
;     ...
;     for (int j = 0; j < 2 * HW; ++j) { const int s = t - HW + j; const bool ok = s >= 0 && s < T; cnt += ok ? 1 : 0; unpack8(w[j], f);
; #pragma unroll
;         for (int q = 0; q < 8; ++q) acc[q] += ok ? f[q] : 0.f; }
;     unpack8(w[HW], f);
;     const float inv = 1.0f / (float)cnt;
; #pragma unroll
;     for (int q = 0; q < 8; ++q) acc[q] = acc[q] * inv - f[q];
;     u32x4 o; o.x = cvt_pk_bf16(acc[0], acc[1]); o.y = cvt_pk_bf16(acc[2], acc[3]); o.z = cvt_pk_bf16(acc[4], acc[5]); o.w = cvt_pk_bf16(acc[6], acc[7]);
;     *(u32x4*)(MIXo + (size_t)row * KMO + 128 * g + c8) = o;
	v_lshlrev_b32_e32 v12, 16, v0
	v_add_f32_e32 v28, v31, v28
	v_and_b32_e32 v0, 0xffff0000, v0
	v_cndmask_b32_e64 v30, 0, v12, s[36:37]
	v_add_f32_e32 v9, v13, v9
	v_lshlrev_b32_e32 v13, 16, v1
	v_add_f32_e32 v28, v28, v30
	v_cndmask_b32_e64 v30, 0, v0, s[36:37]
	v_and_b32_e32 v1, 0xffff0000, v1
	v_add_f32_e32 v4, v4, v30
	v_cndmask_b32_e64 v30, 0, v13, s[36:37]
	v_add_f32_e32 v10, v14, v10
	v_lshlrev_b32_e32 v14, 16, v2
	v_add_f32_e32 v8, v8, v30
	v_cndmask_b32_e64 v30, 0, v1, s[36:37]
	v_and_b32_e32 v2, 0xffff0000, v2
	v_add_f32_e32 v5, v5, v30
	v_cndmask_b32_e64 v30, 0, v14, s[36:37]
	v_lshlrev_b32_e32 v29, 16, v3
	v_add_f32_e32 v9, v9, v30
	v_cndmask_b32_e64 v30, 0, v2, s[36:37]
	v_and_b32_e32 v3, 0xffff0000, v3
	v_add_f32_e32 v6, v6, v30
	v_cndmask_b32_e64 v30, 0, v29, s[36:37]
	v_add_f32_e32 v7, v7, v11
	v_add_f32_e32 v10, v10, v30
	v_cndmask_b32_e64 v30, 0, v3, s[36:37]
	v_cndmask_b32_e64 v11, 0, 1, s[36:37]
	v_add_f32_e32 v7, v7, v30
	v_cmp_lt_u32_e64 s[36:37], v36, v57
	v_lshlrev_b32_e32 v30, 16, v16
	v_and_b32_e32 v16, 0xffff0000, v16
	v_lshlrev_b32_e32 v31, 16, v17
	v_cndmask_b32_e64 v16, 0, v16, s[36:37]
	v_and_b32_e32 v17, 0xffff0000, v17
	v_add_f32_e32 v4, v4, v16
	v_cndmask_b32_e64 v16, 0, v31, s[36:37]
	v_lshlrev_b32_e32 v33, 16, v18
	v_add_f32_e32 v8, v8, v16
	v_cndmask_b32_e64 v16, 0, v17, s[36:37]
	v_and_b32_e32 v18, 0xffff0000, v18
	v_add_f32_e32 v5, v5, v16
	v_cndmask_b32_e64 v16, 0, v33, s[36:37]
	v_lshlrev_b32_e32 v34, 16, v19
	v_add_f32_e32 v9, v9, v16
	v_cndmask_b32_e64 v16, 0, v18, s[36:37]
	v_and_b32_e32 v19, 0xffff0000, v19
	v_add_f32_e32 v6, v6, v16
	v_cndmask_b32_e64 v16, 0, v34, s[36:37]
	v_and_b32_e32 v18, 0xffff0000, v20
	v_add_f32_e32 v10, v10, v16
	v_cndmask_b32_e64 v16, 0, v19, s[36:37]
	v_lshlrev_b32_e32 v19, 16, v21
	v_cndmask_b32_e64 v18, 0, v18, s[38:39]
	v_lshlrev_b32_e32 v17, 16, v20
	v_and_b32_e32 v20, 0xffff0000, v21
	v_add_f32_e32 v4, v4, v18
	v_cndmask_b32_e64 v18, 0, v19, s[38:39]
	v_lshlrev_b32_e32 v21, 16, v22
	v_add_f32_e32 v8, v8, v18
	v_cndmask_b32_e64 v18, 0, v20, s[38:39]
	v_cndmask_b32_e64 v30, 0, v30, s[36:37]
	v_and_b32_e32 v22, 0xffff0000, v22
	v_add_f32_e32 v5, v5, v18
	v_cndmask_b32_e64 v18, 0, v21, s[38:39]
	v_add_f32_e32 v28, v28, v30
	v_lshlrev_b32_e32 v30, 16, v23
	v_add_f32_e32 v9, v9, v18
	v_cndmask_b32_e64 v18, 0, v22, s[38:39]
	v_addc_co_u32_e32 v11, vcc, 0, v11, vcc
	v_and_b32_e32 v23, 0xffff0000, v23
	v_add_f32_e32 v6, v6, v18
	v_cndmask_b32_e64 v18, 0, v30, s[38:39]
	v_addc_co_u32_e64 v11, vcc, v11, v32, s[34:35]
	v_add_f32_e32 v7, v7, v16
	v_cndmask_b32_e64 v16, 0, 1, s[38:39]
	v_cndmask_b32_e64 v17, 0, v17, s[38:39]
	v_add_f32_e32 v10, v10, v18
	v_cndmask_b32_e64 v18, 0, v23, s[38:39]
	v_cmp_lt_u32_e64 s[38:39], v38, v57
	v_addc_co_u32_e64 v11, vcc, v11, v15, s[36:37]
	s_nop 0
	v_addc_co_u32_e64 v11, vcc, v11, v16, s[38:39]
	v_add_f32_e32 v7, v7, v18
	s_waitcnt vmcnt(0)
	v_lshlrev_b32_e32 v18, 16, v24
	v_cvt_f32_u32_e32 v11, v11
	v_add_f32_e32 v17, v28, v17
	v_and_b32_e32 v19, 0xffff0000, v24
	v_cndmask_b32_e64 v18, 0, v18, s[38:39]
	v_lshlrev_b32_e32 v20, 16, v25
	v_add_f32_e32 v17, v17, v18
	v_cndmask_b32_e64 v18, 0, v19, s[38:39]
	v_and_b32_e32 v21, 0xffff0000, v25
	v_add_f32_e32 v4, v4, v18
	v_cndmask_b32_e64 v18, 0, v20, s[38:39]
	v_lshlrev_b32_e32 v22, 16, v26
	v_add_f32_e32 v8, v8, v18
	v_cndmask_b32_e64 v18, 0, v21, s[38:39]
	v_div_scale_f32 v15, s[12:13], v11, v11, 1.0
	v_and_b32_e32 v23, 0xffff0000, v26
	v_add_f32_e32 v5, v5, v18
	v_cndmask_b32_e64 v18, 0, v22, s[38:39]
	v_rcp_f32_e32 v16, v15
	v_lshlrev_b32_e32 v24, 16, v27
	v_add_f32_e32 v9, v9, v18
	v_cndmask_b32_e64 v18, 0, v23, s[38:39]
	v_and_b32_e32 v25, 0xffff0000, v27
	v_add_f32_e32 v6, v6, v18
	v_cndmask_b32_e64 v18, 0, v24, s[38:39]
	v_add_f32_e32 v10, v10, v18
	v_cndmask_b32_e64 v18, 0, v25, s[38:39]
	v_add_f32_e32 v7, v7, v18
	v_fma_f32 v18, -v15, v16, 1.0
	v_fmac_f32_e32 v16, v18, v16
	v_div_scale_f32 v18, vcc, 1.0, v11, 1.0
	v_mul_f32_e32 v19, v18, v16
	v_fma_f32 v20, -v15, v19, v18
	v_fmac_f32_e32 v19, v20, v16
	v_fma_f32 v15, -v15, v19, v18
	v_div_fmas_f32 v15, v15, v16, v19
	v_div_fixup_f32 v11, v15, v11, 1.0
	v_fma_f32 v0, v11, v4, -v0
	v_fma_f32 v4, v11, v8, -v13
	v_fma_f32 v1, v11, v5, -v1
	v_fma_f32 v5, v11, v9, -v14
	v_fma_f32 v2, v11, v6, -v2
	v_fma_f32 v12, v11, v17, -v12
	v_fma_f32 v6, v11, v10, -v29
	v_fma_f32 v3, v11, v7, -v3
	v_cvt_pk_bf16_f32 v1, v4, v1
	v_cvt_pk_bf16_f32 v2, v5, v2
	v_lshlrev_b64 v[4:5], 11, v[52:53]
	v_cvt_pk_bf16_f32 v0, v12, v0
	v_cvt_pk_bf16_f32 v3, v6, v3
	v_lshl_add_u64 v[4:5], v[50:51], 0, v[4:5]
	global_store_dwordx4 v[4:5], v[0:3], off offset:512 sc1

; __device__ __forceinline__ unsigned cvt_pk_bf16(float lo, float hi) { f32x2_t v = {lo, hi}; bf16x2_t b = __builtin_convertvector(v, bf16x2_t); return __builtin_bit_cast(unsigned, b); }
; __device__ __forceinline__ void unpack8(const u32x4& w, float (&f)[8]) { f[0] = bf_lo(w.x); f[1] = bf_hi(w.x); f[2] = bf_lo(w.y); f[3] = bf_hi(w.y); f[4] = bf_lo(w.z); f[5] = bf_hi(w.z); f[6] = bf_lo(w.w); f[7] = bf_hi(w.w); }
; template <int HW> __device__ __forceinline__ void pool_item(const bf16_t* UP, bf16_t* MIXo, int row, int c8, int g) {
;     const int t = row < MX ? (row & (SEQ - 1)) : ((row - MX) & (CTXL - 1)), T = row < MX ? SEQ : CTXL;
;     const bf16_t* up = UP + (size_t)row * 512 + 128 * g + c8;
;     u32x4 w[2 * HW];
; #pragma unroll
;     for (int j = 0; j < 2 * HW; ++j) { const int s = t - HW + j; const int sc = s < 0 ? 0 : (s >= T ? T - 1 : s); w[j] = ld16(up + (ptrdiff_t)(sc - t) * 512); }
;     float acc[8], f[8];
; #pragma unroll
;     for (int q = 0; q < 8; ++q) acc[q] = 0.f;
;     int cnt = 0;
; #pragma unroll
;     for (int j = 0; j < 2 * HW; ++j) { const int s = t - HW + j; const bool ok = s >= 0 && s < T; cnt += ok ? 1 : 0; unpack8(w[j], f);
; #pragma unroll
;         for (int q = 0; q < 8; ++q) acc[q] += ok ? f[q] : 0.f; }
;     unpack8(w[HW], f);
;     const float inv = 1.0f / (float)cnt;
; #pragma unroll
;     for (int q = 0; q < 8; ++q) acc[q] = acc[q] * inv - f[q];
;     u32x4 o; o.x = cvt_pk_bf16(acc[0], acc[1]); o.y = cvt_pk_bf16(acc[2], acc[3]); o.z = cvt_pk_bf16(acc[4], acc[5]); o.w = cvt_pk_bf16(acc[6], acc[7]);
;     *(u32x4*)(MIXo + (size_t)row * KMO + 128 * g + c8) = o;
.LBB0_125:
	s_andn2_b64 vcc, exec, s[12:13]
	s_cbranch_vccnz .LBB0_118
	s_cmp_eq_u32 s1, 1
	s_mov_b64 s[12:13], -1
	s_cbranch_scc1 .LBB0_128
	v_subrev_co_u32_e32 v8, vcc, 1, v58
	v_add_u32_e32 v6, -1, v57
	v_min_u32_e32 v0, v8, v6
	v_cndmask_b32_e64 v0, v0, 0, vcc
	v_sub_u32_e32 v0, v0, v58
	v_sub_u32_e64 v6, v58, v6 clamp
	v_ashrrev_i32_e32 v1, 31, v0
	v_sub_u32_e32 v6, 0, v6
	v_lshl_add_u64 v[4:5], v[48:49], 0, v[54:55]
	v_lshlrev_b64 v[0:1], 10, v[0:1]
	v_ashrrev_i32_e32 v7, 31, v6
	v_lshl_add_u64 v[0:1], v[4:5], 0, v[0:1]
	v_lshlrev_b64 v[6:7], 10, v[6:7]
	global_load_dwordx4 v[0:3], v[0:1], off
	v_lshl_add_u64 v[4:5], v[4:5], 0, v[6:7]
	global_load_dwordx4 v[4:7], v[4:5], off
	v_cmp_lt_u32_e32 vcc, v8, v57
	v_cmp_lt_u32_e64 s[34:35], v58, v57
	s_waitcnt vmcnt(1)
	v_lshlrev_b32_e32 v8, 16, v0
	v_and_b32_e32 v0, 0xffff0000, v0
	v_add_f32_e32 v8, 0, v8
	s_waitcnt vmcnt(0)
	v_lshlrev_b32_e32 v13, 16, v4
	v_lshlrev_b32_e32 v9, 16, v1
	v_cndmask_b32_e32 v8, 0, v8, vcc
	v_add_f32_e32 v0, 0, v0
	v_and_b32_e32 v4, 0xffff0000, v4
	v_cndmask_b32_e64 v17, 0, v13, s[34:35]
	v_and_b32_e32 v1, 0xffff0000, v1
	v_cndmask_b32_e32 v0, 0, v0, vcc
	v_add_f32_e32 v9, 0, v9
	v_lshlrev_b32_e32 v14, 16, v5
	v_add_f32_e32 v8, v8, v17
	v_cndmask_b32_e64 v17, 0, v4, s[34:35]
	v_lshlrev_b32_e32 v10, 16, v2
	v_cndmask_b32_e32 v9, 0, v9, vcc
	v_add_f32_e32 v1, 0, v1
	v_and_b32_e32 v5, 0xffff0000, v5
	v_add_f32_e32 v0, v0, v17
	v_cndmask_b32_e64 v17, 0, v14, s[34:35]
	v_and_b32_e32 v2, 0xffff0000, v2
	v_cndmask_b32_e32 v1, 0, v1, vcc
	v_add_f32_e32 v10, 0, v10
	v_lshlrev_b32_e32 v15, 16, v6
	v_add_f32_e32 v9, v9, v17
	v_cndmask_b32_e64 v17, 0, v5, s[34:35]
	v_lshlrev_b32_e32 v11, 16, v3
	v_and_b32_e32 v3, 0xffff0000, v3
	v_cndmask_b32_e32 v10, 0, v10, vcc
	v_add_f32_e32 v2, 0, v2
	v_and_b32_e32 v6, 0xffff0000, v6
	v_add_f32_e32 v1, v1, v17
	v_cndmask_b32_e64 v17, 0, v15, s[34:35]
	v_cndmask_b32_e32 v2, 0, v2, vcc
	v_add_f32_e32 v11, 0, v11
	v_add_f32_e32 v3, 0, v3
	v_cndmask_b32_e64 v12, 0, 1, s[34:35]
	v_lshlrev_b32_e32 v16, 16, v7
	v_add_f32_e32 v10, v10, v17
	v_cndmask_b32_e64 v17, 0, v6, s[34:35]
	v_cndmask_b32_e32 v11, 0, v11, vcc
	v_cndmask_b32_e32 v3, 0, v3, vcc
	v_and_b32_e32 v7, 0xffff0000, v7
	v_add_f32_e32 v2, v2, v17
	v_cndmask_b32_e64 v17, 0, v16, s[34:35]
	v_addc_co_u32_e32 v12, vcc, 0, v12, vcc
	v_add_f32_e32 v11, v11, v17
	v_cndmask_b32_e64 v17, 0, v7, s[34:35]
	v_cvt_f32_ubyte0_e32 v12, v12
	v_add_f32_e32 v3, v3, v17
	v_div_scale_f32 v17, s[12:13], v12, v12, 1.0
	v_rcp_f32_e32 v18, v17
	s_mov_b64 s[12:13], 0
	v_fma_f32 v19, -v17, v18, 1.0
	v_fmac_f32_e32 v18, v19, v18
	v_div_scale_f32 v19, vcc, 1.0, v12, 1.0
	v_mul_f32_e32 v20, v19, v18
	v_fma_f32 v21, -v17, v20, v19
	v_fmac_f32_e32 v20, v21, v18
	v_fma_f32 v17, -v17, v20, v19
	v_div_fmas_f32 v17, v17, v18, v20
	v_div_fixup_f32 v12, v17, v12, 1.0
	v_fma_f32 v0, v12, v0, -v4
	v_fma_f32 v4, v12, v9, -v14
	v_fma_f32 v1, v12, v1, -v5
	v_fma_f32 v5, v12, v10, -v15
	v_fma_f32 v2, v12, v2, -v6
	v_fma_f32 v8, v12, v8, -v13
	v_fma_f32 v6, v12, v11, -v16
	v_fma_f32 v3, v12, v3, -v7
	v_cvt_pk_bf16_f32 v1, v4, v1
	v_cvt_pk_bf16_f32 v2, v5, v2
	v_lshlrev_b64 v[4:5], 11, v[52:53]
	v_cvt_pk_bf16_f32 v0, v8, v0
	v_cvt_pk_bf16_f32 v3, v6, v3
	v_lshl_add_u64 v[4:5], v[50:51], 0, v[4:5]
	global_store_dwordx4 v[4:5], v[0:3], off sc1
; __device__ __forceinline__ unsigned cvt_pk_bf16(float lo, float hi) { f32x2_t v = {lo, hi}; bf16x2_t b = __builtin_convertvector(v, bf16x2_t); return __builtin_bit_cast(unsigned, b); }
; __device__ __forceinline__ void unpack8(const u32x4& w, float (&f)[8]) { f[0] = bf_lo(w.x); f[1] = bf_hi(w.x); f[2] = bf_lo(w.y); f[3] = bf_hi(w.y); f[4] = bf_lo(w.z); f[5] = bf_hi(w.z); f[6] = bf_lo(w.w); f[7] = bf_hi(w.w); }
; template <int HW> __device__ __forceinline__ void pool_item(const bf16_t* UP, bf16_t* MIXo, int row, int c8, int g) {
;     const int t = row < MX ? (row & (SEQ - 1)) : ((row - MX) & (CTXL - 1)), T = row < MX ? SEQ : CTXL;
;     const bf16_t* up = UP + (size_t)row * 512 + 128 * g + c8;
;     u32x4 w[2 * HW];
; #pragma unroll
;     for (int j = 0; j < 2 * HW; ++j) { const int s = t - HW + j; const int sc = s < 0 ? 0 : (s >= T ? T - 1 : s); w[j] = ld16(up + (ptrdiff_t)(sc - t) * 512); }
;     float acc[8], f[8];
; #pragma unroll
;     for (int q = 0; q < 8; ++q) acc[q] = 0.f;
;     int cnt = 0;
; #pragma unroll
;     for (int j = 0; j < 2 * HW; ++j) { const int s = t - HW + j; const bool ok = s >= 0 && s < T; cnt += ok ? 1 : 0; unpack8(w[j], f);
; #pragma unroll
;         for (int q = 0; q < 8; ++q) acc[q] += ok ? f[q] : 0.f; }
;     unpack8(w[HW], f);
;     const float inv = 1.0f / (float)cnt;
; #pragma unroll
;     for (int q = 0; q < 8; ++q) acc[q] = acc[q] * inv - f[q];
;     u32x4 o; o.x = cvt_pk_bf16(acc[0], acc[1]); o.y = cvt_pk_bf16(acc[2], acc[3]); o.z = cvt_pk_bf16(acc[4], acc[5]); o.w = cvt_pk_bf16(acc[6], acc[7]);
;     *(u32x4*)(MIXo + (size_t)row * KMO + 128 * g + c8) = o;
.LBB0_128:
	s_andn2_b64 vcc, exec, s[12:13]
	s_cbranch_vccnz .LBB0_118
	v_subrev_co_u32_e32 v8, vcc, 2, v58
	v_add_u32_e32 v6, -1, v57
	v_min_u32_e32 v0, v8, v6
	v_cndmask_b32_e64 v0, v0, 0, vcc
	v_sub_u32_e32 v0, v0, v58
	v_ashrrev_i32_e32 v1, 31, v0
	v_lshl_add_u64 v[4:5], v[48:49], 0, v[54:55]
	v_lshlrev_b64 v[0:1], 10, v[0:1]
	v_lshl_add_u64 v[0:1], v[4:5], 0, v[0:1]
	v_subrev_co_u32_e32 v9, vcc, 1, v58
	global_load_dwordx4 v[10:13], v[0:1], off offset:256
	v_min_u32_e32 v0, v9, v6
	v_cndmask_b32_e64 v0, v0, 0, vcc
	v_sub_u32_e32 v0, v0, v58
	v_ashrrev_i32_e32 v1, 31, v0
	v_lshlrev_b64 v[0:1], 10, v[0:1]
	v_lshl_add_u64 v[0:1], v[4:5], 0, v[0:1]
	global_load_dwordx4 v[14:17], v[0:1], off offset:256
	v_sub_u32_e64 v0, v58, v6 clamp
	v_sub_u32_e32 v0, 0, v0
	v_ashrrev_i32_e32 v1, 31, v0
	v_lshlrev_b64 v[0:1], 10, v[0:1]
	v_lshl_add_u64 v[0:1], v[4:5], 0, v[0:1]
	global_load_dwordx4 v[0:3], v[0:1], off offset:256
	v_add_u32_e32 v18, 1, v58
	v_min_u32_e32 v6, v18, v6
	v_sub_u32_e32 v6, v6, v58
	v_ashrrev_i32_e32 v7, 31, v6
	v_lshlrev_b64 v[6:7], 10, v[6:7]
	v_lshl_add_u64 v[4:5], v[4:5], 0, v[6:7]
	global_load_dwordx4 v[4:7], v[4:5], off offset:256
	v_cmp_lt_u32_e32 vcc, v8, v57
	v_cmp_lt_u32_e64 s[34:35], v58, v57
	s_waitcnt vmcnt(3)
	v_lshlrev_b32_e32 v19, 16, v10
	v_and_b32_e32 v10, 0xffff0000, v10
	v_lshlrev_b32_e32 v20, 16, v11
	v_and_b32_e32 v11, 0xffff0000, v11
	v_lshlrev_b32_e32 v21, 16, v12
	v_and_b32_e32 v12, 0xffff0000, v12
	v_lshlrev_b32_e32 v22, 16, v13
	v_and_b32_e32 v13, 0xffff0000, v13
	v_add_f32_e32 v19, 0, v19
	v_add_f32_e32 v10, 0, v10
	v_add_f32_e32 v20, 0, v20
	v_add_f32_e32 v11, 0, v11
	v_add_f32_e32 v21, 0, v21
	v_add_f32_e32 v12, 0, v12
	v_add_f32_e32 v22, 0, v22
	v_add_f32_e32 v13, 0, v13
	v_cndmask_b32_e64 v8, 0, 1, vcc
	v_cndmask_b32_e32 v19, 0, v19, vcc
	v_cndmask_b32_e32 v10, 0, v10, vcc
	v_cndmask_b32_e32 v20, 0, v20, vcc
	v_cndmask_b32_e32 v11, 0, v11, vcc
	v_cndmask_b32_e32 v21, 0, v21, vcc
	v_cndmask_b32_e32 v12, 0, v12, vcc
	v_cndmask_b32_e32 v22, 0, v22, vcc
	v_cndmask_b32_e32 v13, 0, v13, vcc
	v_cmp_lt_u32_e32 vcc, v9, v57
	s_waitcnt vmcnt(2)
	v_lshlrev_b32_e32 v9, 16, v14
	v_and_b32_e32 v14, 0xffff0000, v14
	v_cndmask_b32_e32 v9, 0, v9, vcc
	v_lshlrev_b32_e32 v23, 16, v15
	v_add_f32_e32 v9, v19, v9
	v_cndmask_b32_e32 v14, 0, v14, vcc
	s_waitcnt vmcnt(1)
	v_lshlrev_b32_e32 v19, 16, v0
	v_and_b32_e32 v15, 0xffff0000, v15
	v_add_f32_e32 v10, v10, v14
	v_cndmask_b32_e32 v14, 0, v23, vcc
	v_and_b32_e32 v0, 0xffff0000, v0
	v_cndmask_b32_e64 v23, 0, v19, s[34:35]
	v_lshlrev_b32_e32 v24, 16, v16
	v_add_f32_e32 v14, v20, v14
	v_cndmask_b32_e32 v15, 0, v15, vcc
	v_lshlrev_b32_e32 v20, 16, v1
	v_add_f32_e32 v9, v9, v23
	v_cndmask_b32_e64 v23, 0, v0, s[34:35]
	v_and_b32_e32 v16, 0xffff0000, v16
	v_add_f32_e32 v11, v11, v15
	v_cndmask_b32_e32 v15, 0, v24, vcc
	v_and_b32_e32 v1, 0xffff0000, v1
	v_add_f32_e32 v10, v10, v23
	v_cndmask_b32_e64 v23, 0, v20, s[34:35]
	v_lshlrev_b32_e32 v25, 16, v17
	v_add_f32_e32 v15, v21, v15
	v_cndmask_b32_e32 v16, 0, v16, vcc
	v_lshlrev_b32_e32 v21, 16, v2
	v_add_f32_e32 v14, v14, v23
	v_cndmask_b32_e64 v23, 0, v1, s[34:35]
	v_add_f32_e32 v12, v12, v16
	v_cndmask_b32_e32 v16, 0, v25, vcc
	v_and_b32_e32 v2, 0xffff0000, v2
	v_add_f32_e32 v11, v11, v23
	v_cndmask_b32_e64 v23, 0, v21, s[34:35]
	v_and_b32_e32 v17, 0xffff0000, v17
	v_add_f32_e32 v16, v22, v16
	v_lshlrev_b32_e32 v22, 16, v3
	v_add_f32_e32 v15, v15, v23
	v_cndmask_b32_e64 v23, 0, v2, s[34:35]
	v_cndmask_b32_e32 v17, 0, v17, vcc
	v_and_b32_e32 v3, 0xffff0000, v3
	v_add_f32_e32 v12, v12, v23
	v_cndmask_b32_e64 v23, 0, v22, s[34:35]
	v_add_f32_e32 v13, v13, v17
	v_cndmask_b32_e64 v17, 0, 1, s[34:35]
	v_add_f32_e32 v16, v16, v23
	v_cndmask_b32_e64 v23, 0, v3, s[34:35]
	v_cmp_lt_u32_e64 s[34:35], v18, v57
	s_waitcnt vmcnt(0)
	v_lshlrev_b32_e32 v25, 16, v7
	v_and_b32_e32 v7, 0xffff0000, v7
	v_add_f32_e32 v13, v13, v23
	v_cndmask_b32_e64 v7, 0, v7, s[34:35]
	v_add_f32_e32 v7, v13, v7
	v_addc_co_u32_e32 v13, vcc, 0, v17, vcc
	v_lshlrev_b32_e32 v18, 16, v4
	v_and_b32_e32 v4, 0xffff0000, v4
	v_addc_co_u32_e64 v8, vcc, v13, v8, s[34:35]
	v_lshlrev_b32_e32 v23, 16, v5
	v_cndmask_b32_e64 v4, 0, v4, s[34:35]
	v_cvt_f32_ubyte0_e32 v8, v8
	v_add_f32_e32 v4, v10, v4
	v_cndmask_b32_e64 v10, 0, v23, s[34:35]
	v_div_scale_f32 v13, s[12:13], v8, v8, 1.0
	v_add_f32_e32 v10, v14, v10
	v_rcp_f32_e32 v14, v13
	v_and_b32_e32 v5, 0xffff0000, v5
	v_lshlrev_b32_e32 v24, 16, v6
	v_cndmask_b32_e64 v5, 0, v5, s[34:35]
	v_and_b32_e32 v6, 0xffff0000, v6
	v_add_f32_e32 v5, v11, v5
	v_cndmask_b32_e64 v11, 0, v24, s[34:35]
	v_add_f32_e32 v11, v15, v11
	v_cndmask_b32_e64 v6, 0, v6, s[34:35]
	v_fma_f32 v15, -v13, v14, 1.0
	v_add_f32_e32 v6, v12, v6
	v_cndmask_b32_e64 v12, 0, v25, s[34:35]
	v_fmac_f32_e32 v14, v15, v14
	v_div_scale_f32 v15, vcc, 1.0, v8, 1.0
	v_add_f32_e32 v12, v16, v12
	v_mul_f32_e32 v16, v15, v14
	v_fma_f32 v17, -v13, v16, v15
	v_fmac_f32_e32 v16, v17, v14
	v_fma_f32 v13, -v13, v16, v15
	v_div_fmas_f32 v13, v13, v14, v16
	v_cndmask_b32_e64 v18, 0, v18, s[34:35]
	v_div_fixup_f32 v8, v13, v8, 1.0
	v_add_f32_e32 v9, v9, v18
	v_fma_f32 v0, v8, v4, -v0
	v_fma_f32 v4, v8, v10, -v20
	v_fma_f32 v1, v8, v5, -v1
	v_fma_f32 v5, v8, v11, -v21
	v_fma_f32 v2, v8, v6, -v2
	v_fma_f32 v9, v8, v9, -v19
	v_fma_f32 v6, v8, v12, -v22
	v_fma_f32 v3, v8, v7, -v3
	v_cvt_pk_bf16_f32 v1, v4, v1
	v_cvt_pk_bf16_f32 v2, v5, v2
	v_lshlrev_b64 v[4:5], 11, v[52:53]
	v_cvt_pk_bf16_f32 v0, v9, v0
	v_cvt_pk_bf16_f32 v3, v6, v3
	v_lshl_add_u64 v[4:5], v[50:51], 0, v[4:5]
	global_store_dwordx4 v[4:5], v[0:3], off offset:256 sc1
	s_branch .LBB0_118

; __device__ __forceinline__ u32x4 pack8(const f32x4& a, const f32x4& b) { u32x4 w; w.x = cvt_pk_bf16(a[0], a[1]); w.y = cvt_pk_bf16(a[2], a[3]); w.z = cvt_pk_bf16(b[0], b[1]); w.w = cvt_pk_bf16(b[2], b[3]); return w; }
; __device__ __forceinline__ void dft_combine(const Args& a, int gt, int NT, int lane, int gw, int NGW) {
;     const _Float16* SL = (const _Float16*)(a.ws + WS_DSLAB); bf16_t* MIXo = (bf16_t*)(a.ws + WS_MIX); const size_t SS = (size_t)1024 * 4096;
;     for (int idx0 = gt; idx0 < 1024 * 512; idx0 += 2 * NT) {
;         typedef _Float16 h8 __attribute__((ext_vector_type(8))); typedef float f8 __attribute__((ext_vector_type(8)));
;         f32x4 v[2][8]; int kk[2], bb[2], cc8[2]; bool okk[2];
; #pragma unroll
;         for (int u = 0; u < 2; ++u) {
;             const int idx = idx0 + u * NT; okk[u] = idx < 1024 * 512; const int id = okk[u] ? idx : idx0;
;             kk[u] = id >> 9; const int cc = id & 511; bb[u] = cc >> 6; cc8[u] = (cc & 63) * 8;
;             const _Float16* p = SL + (size_t)kk[u] * 4096 + bb[u] * 512 + cc8[u];
; #pragma unroll
;             for (int q = 0; q < 4; ++q) { const f8 t = __builtin_convertvector(*(const h8*)(p + q * SS), f8); v[u][2 * q] = (f32x4){t[0], t[1], t[2], t[3]}; v[u][2 * q + 1] = (f32x4){t[4], t[5], t[6], t[7]}; }
;         }
; #pragma unroll
;         for (int u = 0; u < 2; ++u) {
;             if (!okk[u]) continue;
;             const f32x4 P0 = v[u][0] + v[u][2], P1 = v[u][1] + v[u][3], Q0 = v[u][4] + v[u][6], Q1 = v[u][5] + v[u][7];
;             *(u32x4*)(MIXo + (size_t)(bb[u] * SEQ + kk[u]) * KMO + 512 + cc8[u]) = gm::pack8(P0 + Q0, P1 + Q1);
;             if (kk[u] > 0) *(u32x4*)(MIXo + (size_t)(bb[u] * SEQ + SEQ - kk[u]) * KMO + 512 + cc8[u]) = gm::pack8(P0 - Q0, P1 - Q1);
;         }
;     }
.LBB0_133:
	v_add_u32_e32 v39, s1, v0
	s_mov_b32 s5, 0x80000
	v_cmp_gt_i32_e64 s[34:35], s5, v39
	v_ashrrev_i32_e32 v20, 9, v0
	v_readlane_b32 s12, v252, 6
	v_cndmask_b32_e64 v6, v0, v39, s[34:35]
	v_ashrrev_i32_e32 v16, 9, v6
	v_ashrrev_i32_e32 v17, 31, v16
	v_bfe_u32 v40, v6, 6, 3
	v_lshlrev_b64 v[2:3], 13, v[16:17]
	v_readlane_b32 s13, v252, 7
	v_ashrrev_i32_e32 v21, 31, v20
	v_lshlrev_b32_e32 v80, 10, v40
	v_lshl_add_u64 v[2:3], s[12:13], 0, v[2:3]
	v_lshlrev_b64 v[4:5], 13, v[20:21]
	v_bfe_u32 v17, v0, 6, 3
	v_lshl_add_u64 v[2:3], v[2:3], 0, v[80:81]
	v_lshl_add_u64 v[4:5], s[12:13], 0, v[4:5]
	v_lshlrev_b32_e32 v80, 10, v17
	v_lshl_add_u64 v[0:1], v[4:5], 0, v[80:81]
	v_and_b32_e32 v4, 0x1f8, v38
	v_lshlrev_b32_e32 v80, 1, v4
	v_lshl_add_u64 v[0:1], v[0:1], 0, v[80:81]
	s_mov_b32 s12, 0x1800000
	v_add_co_u32_e32 v4, vcc, s12, v0
	s_mov_b32 s9, 0x1000000
	s_nop 0
	v_addc_co_u32_e32 v5, vcc, 0, v1, vcc
	global_load_dwordx4 v[22:25], v[4:5], off
	v_add_co_u32_e32 v4, vcc, s9, v0
	s_mov_b32 s5, 0x800000
	s_nop 0
	v_addc_co_u32_e32 v5, vcc, 0, v1, vcc
	global_load_dwordx4 v[26:29], v[4:5], off
	v_add_co_u32_e32 v4, vcc, s5, v0
	v_mov_b32_e32 v19, v81
	s_nop 0
	v_addc_co_u32_e32 v5, vcc, 0, v1, vcc
	global_load_dwordx4 v[30:33], v[4:5], off
	global_load_dwordx4 v[34:37], v[0:1], off
	v_lshlrev_b32_e32 v0, 3, v6
	v_and_b32_e32 v0, 0x1f8, v0
	v_lshlrev_b32_e32 v18, 1, v0
	v_lshl_add_u64 v[0:1], v[2:3], 0, v[18:19]
	v_add_co_u32_e32 v2, vcc, s5, v0
	v_lshlrev_b32_e32 v17, 11, v17
	s_nop 0
	v_addc_co_u32_e32 v3, vcc, 0, v1, vcc
	v_add_co_u32_e32 v4, vcc, s9, v0
	s_waitcnt vmcnt(3)
	v_cvt_f32_f16_e32 v44, v23
	v_addc_co_u32_e32 v5, vcc, 0, v1, vcc
	v_add_co_u32_e32 v42, vcc, s12, v0
	v_cvt_f32_f16_sdwa v45, v23 dst_sel:DWORD dst_unused:UNUSED_PAD src0_sel:WORD_1
	s_nop 0
	v_addc_co_u32_e32 v43, vcc, 0, v1, vcc
	global_load_dwordx4 v[12:15], v[0:1], off
	global_load_dwordx4 v[8:11], v[2:3], off
	s_nop 0
	global_load_dwordx4 v[4:7], v[4:5], off
	s_nop 0
	global_load_dwordx4 v[0:3], v[42:43], off
	v_cvt_f32_f16_e32 v42, v22
	v_cvt_f32_f16_sdwa v43, v22 dst_sel:DWORD dst_unused:UNUSED_PAD src0_sel:WORD_1
	v_cvt_f32_f16_e32 v46, v24
	v_cvt_f32_f16_sdwa v47, v24 dst_sel:DWORD dst_unused:UNUSED_PAD src0_sel:WORD_1
	v_cvt_f32_f16_e32 v48, v25
	v_cvt_f32_f16_sdwa v49, v25 dst_sel:DWORD dst_unused:UNUSED_PAD src0_sel:WORD_1
	s_waitcnt vmcnt(6)
	v_cvt_f32_f16_e32 v50, v26
	v_cvt_f32_f16_sdwa v51, v26 dst_sel:DWORD dst_unused:UNUSED_PAD src0_sel:WORD_1
	v_cvt_f32_f16_e32 v52, v27
	v_cvt_f32_f16_sdwa v53, v27 dst_sel:DWORD dst_unused:UNUSED_PAD src0_sel:WORD_1
	v_cvt_f32_f16_e32 v54, v28
	v_cvt_f32_f16_sdwa v55, v28 dst_sel:DWORD dst_unused:UNUSED_PAD src0_sel:WORD_1
	v_cvt_f32_f16_e32 v56, v29
	v_cvt_f32_f16_sdwa v57, v29 dst_sel:DWORD dst_unused:UNUSED_PAD src0_sel:WORD_1
	s_waitcnt vmcnt(5)
	v_cvt_f32_f16_e32 v28, v30
	v_cvt_f32_f16_sdwa v29, v30 dst_sel:DWORD dst_unused:UNUSED_PAD src0_sel:WORD_1
	v_cvt_f32_f16_e32 v26, v31
	v_cvt_f32_f16_sdwa v27, v31 dst_sel:DWORD dst_unused:UNUSED_PAD src0_sel:WORD_1
	v_cvt_f32_f16_e32 v24, v32
	v_cvt_f32_f16_sdwa v25, v32 dst_sel:DWORD dst_unused:UNUSED_PAD src0_sel:WORD_1
	v_cvt_f32_f16_e32 v22, v33
	v_cvt_f32_f16_sdwa v23, v33 dst_sel:DWORD dst_unused:UNUSED_PAD src0_sel:WORD_1
	s_waitcnt vmcnt(4)
	v_cvt_f32_f16_e32 v30, v34
	v_cvt_f32_f16_e32 v32, v35
	v_cvt_f32_f16_e32 v60, v37
	v_cvt_f32_f16_sdwa v61, v37 dst_sel:DWORD dst_unused:UNUSED_PAD src0_sel:WORD_1
	v_cvt_f32_f16_sdwa v33, v35 dst_sel:DWORD dst_unused:UNUSED_PAD src0_sel:WORD_1
	v_cvt_f32_f16_sdwa v31, v34 dst_sel:DWORD dst_unused:UNUSED_PAD src0_sel:WORD_1
	v_cvt_f32_f16_e32 v58, v36
	v_cvt_f32_f16_sdwa v59, v36 dst_sel:DWORD dst_unused:UNUSED_PAD src0_sel:WORD_1
	v_pk_add_f32 v[22:23], v[22:23], v[60:61]
	v_pk_add_f32 v[26:27], v[26:27], v[32:33]
	v_pk_add_f32 v[28:29], v[28:29], v[30:31]
	v_pk_add_f32 v[30:31], v[48:49], v[56:57]
	v_pk_add_f32 v[34:35], v[44:45], v[52:53]
	v_pk_add_f32 v[36:37], v[42:43], v[50:51]
	v_pk_add_f32 v[32:33], v[46:47], v[54:55]
	v_pk_add_f32 v[44:45], v[34:35], v[26:27]
	v_pk_add_f32 v[42:43], v[36:37], v[28:29]
	v_pk_add_f32 v[46:47], v[30:31], v[22:23]
	v_cvt_pk_bf16_f32 v42, v42, v43
	v_cvt_pk_bf16_f32 v43, v44, v45
	v_cvt_pk_bf16_f32 v45, v46, v47
	v_add_u32_e32 v46, v17, v20
	v_ashrrev_i32_e32 v47, 31, v46
	v_readlane_b32 s12, v252, 4
	v_pk_add_f32 v[24:25], v[24:25], v[58:59]
	v_lshlrev_b64 v[46:47], 11, v[46:47]
	v_readlane_b32 s13, v252, 5
	v_pk_add_f32 v[48:49], v[32:33], v[24:25]
	v_cmp_lt_i32_e32 vcc, 0, v20
	v_lshl_add_u64 v[46:47], s[12:13], 0, v[46:47]
	v_cvt_pk_bf16_f32 v44, v48, v49
	v_lshl_add_u64 v[46:47], v[46:47], 0, v[80:81]
	global_store_dwordx4 v[46:47], v[42:45], off offset:1024 sc1
	s_and_saveexec_b64 s[12:13], vcc
	s_cbranch_execz .LBB0_135
	v_sub_u32_e32 v17, v17, v20
	v_sub_f32_e32 v19, v27, v35
	v_sub_f32_e32 v21, v26, v34
	v_lshlrev_b32_e32 v20, 11, v17
	v_readlane_b32 s16, v252, 4
	v_sub_f32_e32 v27, v28, v36
	v_sub_f32_e32 v28, v23, v31
	v_cvt_pk_bf16_f32 v23, v21, v19
	v_ashrrev_i32_e32 v21, 31, v20
	v_readlane_b32 s17, v252, 5
	v_sub_f32_e32 v26, v29, v37
	v_sub_f32_e32 v29, v22, v30
	v_lshl_add_u64 v[20:21], s[16:17], 0, v[20:21]
	v_lshl_add_u64 v[20:21], v[20:21], 0, v[80:81]
	v_sub_f32_e32 v25, v25, v33
	v_sub_f32_e32 v24, v24, v32
	v_add_co_u32_e32 v20, vcc, 0x400000, v20
	v_cvt_pk_bf16_f32 v22, v27, v26
	v_cvt_pk_bf16_f32 v24, v24, v25
	v_cvt_pk_bf16_f32 v25, v29, v28
	v_addc_co_u32_e32 v21, vcc, 0, v21, vcc
	global_store_dwordx4 v[20:21], v[22:25], off offset:1024 sc1
; __device__ __forceinline__ u32x4 pack8(const f32x4& a, const f32x4& b) { u32x4 w; w.x = cvt_pk_bf16(a[0], a[1]); w.y = cvt_pk_bf16(a[2], a[3]); w.z = cvt_pk_bf16(b[0], b[1]); w.w = cvt_pk_bf16(b[2], b[3]); return w; }
; __device__ __forceinline__ void dft_combine(const Args& a, int gt, int NT, int lane, int gw, int NGW) {
;     ...
; #pragma unroll
;         for (int u = 0; u < 2; ++u) {
;             if (!okk[u]) continue;
;             const f32x4 P0 = v[u][0] + v[u][2], P1 = v[u][1] + v[u][3], Q0 = v[u][4] + v[u][6], Q1 = v[u][5] + v[u][7];
;             *(u32x4*)(MIXo + (size_t)(bb[u] * SEQ + kk[u]) * KMO + 512 + cc8[u]) = gm::pack8(P0 + Q0, P1 + Q1);
;             if (kk[u] > 0) *(u32x4*)(MIXo + (size_t)(bb[u] * SEQ + SEQ - kk[u]) * KMO + 512 + cc8[u]) = gm::pack8(P0 - Q0, P1 - Q1);
;         }
.LBB0_135:
	s_or_b64 exec, exec, s[12:13]
	s_and_saveexec_b64 s[40:41], s[34:35]
	s_mov_b32 s5, 0x7ffff
	s_cbranch_execz .LBB0_132
	s_waitcnt vmcnt(4)
	v_cvt_f32_f16_sdwa v21, v12 dst_sel:DWORD dst_unused:UNUSED_PAD src0_sel:WORD_1
	v_cvt_f32_f16_sdwa v23, v13 dst_sel:DWORD dst_unused:UNUSED_PAD src0_sel:WORD_1
	v_cvt_f32_f16_sdwa v25, v14 dst_sel:DWORD dst_unused:UNUSED_PAD src0_sel:WORD_1
	v_cvt_f32_f16_sdwa v27, v15 dst_sel:DWORD dst_unused:UNUSED_PAD src0_sel:WORD_1
	v_cvt_f32_f16_e32 v20, v12
	v_cvt_f32_f16_e32 v22, v13
	v_cvt_f32_f16_e32 v24, v14
	v_cvt_f32_f16_e32 v26, v15
	s_waitcnt vmcnt(3)
	v_cvt_f32_f16_sdwa v13, v8 dst_sel:DWORD dst_unused:UNUSED_PAD src0_sel:WORD_1
	v_cvt_f32_f16_sdwa v15, v9 dst_sel:DWORD dst_unused:UNUSED_PAD src0_sel:WORD_1
	v_cvt_f32_f16_sdwa v31, v11 dst_sel:DWORD dst_unused:UNUSED_PAD src0_sel:WORD_1
	v_cvt_f32_f16_e32 v12, v8
	v_cvt_f32_f16_e32 v14, v9
	v_cvt_f32_f16_e32 v30, v11
	s_waitcnt vmcnt(2)
	v_cvt_f32_f16_sdwa v33, v4 dst_sel:DWORD dst_unused:UNUSED_PAD src0_sel:WORD_1
	v_cvt_f32_f16_sdwa v35, v5 dst_sel:DWORD dst_unused:UNUSED_PAD src0_sel:WORD_1
	v_cvt_f32_f16_sdwa v9, v7 dst_sel:DWORD dst_unused:UNUSED_PAD src0_sel:WORD_1
	v_cvt_f32_f16_e32 v32, v4
	v_cvt_f32_f16_e32 v34, v5
	v_cvt_f32_f16_e32 v8, v7
	s_waitcnt vmcnt(1)
	v_cvt_f32_f16_sdwa v37, v0 dst_sel:DWORD dst_unused:UNUSED_PAD src0_sel:WORD_1
	v_cvt_f32_f16_sdwa v43, v1 dst_sel:DWORD dst_unused:UNUSED_PAD src0_sel:WORD_1
	v_cvt_f32_f16_sdwa v47, v3 dst_sel:DWORD dst_unused:UNUSED_PAD src0_sel:WORD_1
	v_cvt_f32_f16_e32 v36, v0
	v_cvt_f32_f16_e32 v42, v1
	v_cvt_f32_f16_e32 v46, v3
	v_cvt_f32_f16_sdwa v29, v10 dst_sel:DWORD dst_unused:UNUSED_PAD src0_sel:WORD_1
	v_cvt_f32_f16_e32 v28, v10
	v_cvt_f32_f16_sdwa v11, v6 dst_sel:DWORD dst_unused:UNUSED_PAD src0_sel:WORD_1
	v_cvt_f32_f16_e32 v10, v6
	v_cvt_f32_f16_sdwa v45, v2 dst_sel:DWORD dst_unused:UNUSED_PAD src0_sel:WORD_1
	v_cvt_f32_f16_e32 v44, v2
	v_pk_add_f32 v[0:1], v[26:27], v[30:31]
	v_pk_add_f32 v[4:5], v[22:23], v[14:15]
	v_pk_add_f32 v[6:7], v[20:21], v[12:13]
	v_pk_add_f32 v[8:9], v[8:9], v[46:47]
	v_pk_add_f32 v[12:13], v[34:35], v[42:43]
	v_pk_add_f32 v[14:15], v[32:33], v[36:37]
	v_pk_add_f32 v[2:3], v[24:25], v[28:29]
	v_pk_add_f32 v[22:23], v[4:5], v[12:13]
	v_pk_add_f32 v[20:21], v[6:7], v[14:15]
	v_pk_add_f32 v[24:25], v[0:1], v[8:9]
	v_lshlrev_b32_e32 v17, 11, v40
	v_cvt_pk_bf16_f32 v20, v20, v21
	v_cvt_pk_bf16_f32 v21, v22, v23
	v_cvt_pk_bf16_f32 v23, v24, v25
	v_add_u32_e32 v24, v17, v16
	v_ashrrev_i32_e32 v25, 31, v24
	v_readlane_b32 s12, v252, 4
	v_pk_add_f32 v[10:11], v[10:11], v[44:45]
	v_lshlrev_b64 v[24:25], 11, v[24:25]
	v_readlane_b32 s13, v252, 5
	v_pk_add_f32 v[26:27], v[2:3], v[10:11]
	v_mov_b32_e32 v19, v81
	v_lshl_add_u64 v[24:25], s[12:13], 0, v[24:25]
	v_cvt_pk_bf16_f32 v22, v26, v27
	v_lshl_add_u64 v[24:25], v[24:25], 0, v[18:19]
	v_cmp_lt_i32_e32 vcc, 0, v16
	global_store_dwordx4 v[24:25], v[20:23], off offset:1024 sc1
	s_and_b64 exec, exec, vcc
	s_cbranch_execz .LBB0_132
	v_sub_f32_e32 v5, v5, v13
	v_sub_f32_e32 v4, v4, v12
	v_sub_f32_e32 v9, v1, v9
	v_cvt_pk_bf16_f32 v1, v4, v5
	v_sub_u32_e32 v4, v17, v16
	v_ashrrev_i32_e32 v5, 31, v4
	v_readlane_b32 s12, v252, 4
	v_lshlrev_b64 v[4:5], 11, v[4:5]
	v_readlane_b32 s13, v252, 5
	v_sub_f32_e32 v7, v7, v15
	v_sub_f32_e32 v6, v6, v14
	v_lshl_add_u64 v[4:5], s[12:13], 0, v[4:5]
	v_lshl_add_u64 v[4:5], v[4:5], 0, v[18:19]
	v_sub_f32_e32 v8, v0, v8
	v_sub_f32_e32 v3, v3, v11
	v_sub_f32_e32 v2, v2, v10
	v_add_co_u32_e32 v4, vcc, 0x400000, v4
	v_cvt_pk_bf16_f32 v0, v6, v7
	v_cvt_pk_bf16_f32 v2, v2, v3
	v_cvt_pk_bf16_f32 v3, v8, v9
	v_addc_co_u32_e32 v5, vcc, 0, v5, vcc
	global_store_dwordx4 v[4:5], v[0:3], off offset:1024 sc1
	s_branch .LBB0_132

; __device__ __forceinline__ unsigned cvt_pk_bf16(float lo, float hi) { f32x2_t v = {lo, hi}; bf16x2_t b = __builtin_convertvector(v, bf16x2_t); return __builtin_bit_cast(unsigned, b); }
; __device__ __forceinline__ void unpack8(const u32x4& w, float (&f)[8]) { f[0] = bf_lo(w.x); f[1] = bf_hi(w.x); f[2] = bf_lo(w.y); f[3] = bf_hi(w.y); f[4] = bf_lo(w.z); f[5] = bf_hi(w.z); f[6] = bf_lo(w.w); f[7] = bf_hi(w.w); }
; __device__ __forceinline__ void dft_combine(const Args& a, int gt, int NT, int lane, int gw, int NGW) {
;     ...
;     const bf16_t* VT = (const bf16_t*)(a.ws + WS_VT);
;     for (int r = gw; r < NBATCH * 512; r += NGW) {
;         const bf16_t* v = VT + (size_t)r * 2 * SEQ + 8 * lane; float s = 0.f;
;         u32x4 q[4];
; #pragma unroll
;         for (int j = 0; j < 4; ++j) q[j] = ld16(v + 512 * j);
;         __builtin_amdgcn_sched_barrier(0);
; #pragma unroll
;         for (int j = 0; j < 4; ++j) { float f[8]; unpack8(q[j], f); s += (f[0] - f[1]) + (f[2] - f[3]) + (f[4] - f[5]) + (f[6] - f[7]); }
;         s = wave_sum(s) * (1.0f / 512.0f);
;         if (lane == 0) MIXo[(size_t)((r >> 9) * SEQ + 1024) * KMO + 512 + (r & 511)] = (bf16_t)(cvt_pk_bf16(s, 0.f) & 0xffffu);
;     }
.LBB0_141:
	s_waitcnt lgkmcnt(0)
	global_load_dwordx4 v[8:11], v[0:1], off
	global_load_dwordx4 v[12:15], v[0:1], off offset:1024
	global_load_dwordx4 v[16:19], v[0:1], off offset:2048
	global_load_dwordx4 v[20:23], v[0:1], off offset:3072
	s_waitcnt vmcnt(3)
	v_lshlrev_b32_e32 v24, 16, v8
	v_and_b32_e32 v8, 0xffff0000, v8
	v_lshlrev_b32_e32 v25, 16, v9
	v_and_b32_e32 v9, 0xffff0000, v9
	v_lshlrev_b32_e32 v26, 16, v10
	v_and_b32_e32 v10, 0xffff0000, v10
	v_sub_f32_e32 v8, v24, v8
	v_sub_f32_e32 v9, v25, v9
	v_lshlrev_b32_e32 v27, 16, v11
	v_and_b32_e32 v11, 0xffff0000, v11
	v_add_f32_e32 v8, v8, v9
	v_sub_f32_e32 v9, v26, v10
	v_add_f32_e32 v8, v9, v8
	v_sub_f32_e32 v9, v27, v11
	v_add_f32_e32 v8, v9, v8
	s_waitcnt vmcnt(2)
	v_lshlrev_b32_e32 v9, 16, v12
	v_and_b32_e32 v10, 0xffff0000, v12
	v_lshlrev_b32_e32 v11, 16, v13
	v_and_b32_e32 v12, 0xffff0000, v13
	v_lshlrev_b32_e32 v13, 16, v14
	v_and_b32_e32 v14, 0xffff0000, v14
	v_sub_f32_e32 v9, v9, v10
	v_sub_f32_e32 v10, v11, v12
	v_lshlrev_b32_e32 v24, 16, v15
	v_and_b32_e32 v15, 0xffff0000, v15
	v_add_f32_e32 v9, v9, v10
	v_sub_f32_e32 v10, v13, v14
	v_add_f32_e32 v9, v10, v9
	v_sub_f32_e32 v10, v24, v15
	v_add_f32_e32 v8, 0, v8
	v_add_f32_e32 v9, v10, v9
	v_add_f32_e32 v8, v8, v9
	s_waitcnt vmcnt(1)
	v_lshlrev_b32_e32 v9, 16, v16
	v_and_b32_e32 v10, 0xffff0000, v16
	v_lshlrev_b32_e32 v11, 16, v17
	v_and_b32_e32 v12, 0xffff0000, v17
	v_lshlrev_b32_e32 v13, 16, v18
	v_and_b32_e32 v14, 0xffff0000, v18
	v_sub_f32_e32 v9, v9, v10
	v_sub_f32_e32 v10, v11, v12
	v_lshlrev_b32_e32 v15, 16, v19
	v_and_b32_e32 v16, 0xffff0000, v19
	v_add_f32_e32 v9, v9, v10
	v_sub_f32_e32 v10, v13, v14
	v_add_f32_e32 v9, v10, v9
	v_sub_f32_e32 v10, v15, v16
	v_add_f32_e32 v9, v10, v9
	v_add_f32_e32 v8, v8, v9
	s_waitcnt vmcnt(0)
	v_lshlrev_b32_e32 v9, 16, v20
	v_and_b32_e32 v10, 0xffff0000, v20
	v_lshlrev_b32_e32 v11, 16, v21
	v_and_b32_e32 v12, 0xffff0000, v21
	v_lshlrev_b32_e32 v13, 16, v22
	v_and_b32_e32 v14, 0xffff0000, v22
	v_sub_f32_e32 v9, v9, v10
	v_sub_f32_e32 v10, v11, v12
	v_lshlrev_b32_e32 v15, 16, v23
	v_and_b32_e32 v16, 0xffff0000, v23
	v_add_f32_e32 v9, v9, v10
	v_sub_f32_e32 v10, v13, v14
	v_add_f32_e32 v9, v10, v9
	v_sub_f32_e32 v10, v15, v16
	v_add_f32_e32 v9, v10, v9
	v_add_f32_e32 v8, v8, v9
	ds_bpermute_b32 v9, v2, v8
	s_waitcnt lgkmcnt(0)
	v_add_f32_e32 v8, v8, v9
	ds_bpermute_b32 v9, v3, v8
	s_waitcnt lgkmcnt(0)
	v_add_f32_e32 v8, v8, v9
	ds_bpermute_b32 v9, v4, v8
	s_waitcnt lgkmcnt(0)
	v_add_f32_e32 v8, v8, v9
	ds_bpermute_b32 v9, v5, v8
	s_waitcnt lgkmcnt(0)
	v_add_f32_e32 v8, v8, v9
	ds_bpermute_b32 v9, v6, v8
	s_waitcnt lgkmcnt(0)
	v_add_f32_e32 v8, v8, v9
	ds_bpermute_b32 v9, v7, v8
	s_and_saveexec_b64 s[12:13], vcc
	s_cbranch_execz .LBB0_140
	s_and_b32 s1, s4, 0xfffff800
	s_or_b32 s16, s1, 0x400
	s_ashr_i32 s17, s16, 31
	s_and_b32 s1, s0, 0x1ff
	s_lshl_b64 s[16:17], s[16:17], 11
	v_readlane_b32 s20, v252, 4
	s_waitcnt lgkmcnt(0)
	v_add_f32_e32 v8, v8, v9
	v_readlane_b32 s21, v252, 5
	s_add_u32 s16, s20, s16
	v_mul_f32_e32 v8, 0x3b000000, v8
	s_addc_u32 s17, s21, s17
	s_lshl_b32 s1, s1, 1
	v_cvt_pk_bf16_f32 v8, v8, s0
	v_mov_b32_e32 v9, s1
	global_store_short v9, v8, s[16:17] offset:1024 sc1
	s_branch .LBB0_140

; #define LAS __attribute__((address_space(3)))
; #define LDS_WAIT() asm volatile("s_waitcnt lgkmcnt(0)" ::: "memory")
; __device__ __forceinline__ unsigned cvt_pk_bf16(float lo, float hi) { f32x2_t v = {lo, hi}; bf16x2_t b = __builtin_convertvector(v, bf16x2_t); return __builtin_bit_cast(unsigned, b); }
; __device__ __forceinline__ int crow(int r, int hi) { return (r & 3) + 8 * (r >> 2) + 4 * hi; }
; __device__ __forceinline__ void attn_unit(LAS unsigned char* lds, const bf16_t* U, bf16_t* MIXo, const float* sink8, int b, int hk, int qrow0, int qpos0, bool latent, int tid) {
;     ...
;     {
;         const float lt = lsum + __shfl_xor(lsum, 32);
;         if (hi == 0) scr[r32] = 1.0f / lt;
;         LDS_WAIT();
;         LAS unsigned short* stg = (LAS unsigned short*)(lds + AT_STG + wid * AT_STGW);
; #pragma unroll
;         for (int r = 0; r < 16; ++r) { const int q = crow(r, hi); const float il = scr[q];
;             stg[q * 72 + r32] = (unsigned short)(cvt_pk_bf16(o0[r] * il, 0.f) & 0xffffu); stg[q * 72 + 32 + r32] = (unsigned short)(cvt_pk_bf16(o1[r] * il, 0.f) & 0xffffu); }
;         LDS_WAIT();
; #pragma unroll
;         for (int i = 0; i < 4; ++i) { const int row = i * 8 + (lane >> 3), ch = lane & 7; const u32x4 v = *(const LAS u32x4*)((const LAS unsigned char*)stg + row * 144 + ch * 16);
;             *(u32x4*)(MIXo + (size_t)(qrow0 + rowoff + row) * KMO + hq * 64 + 8 * ch) = v; }
;         LDS_WAIT();
;     }
.LBB0_147:
	s_or_b64 exec, exec, s[0:1]
	s_waitcnt lgkmcnt(0)
	v_lshl_add_u32 v16, v146, 2, s8
	ds_read_b32 v17, v16
	s_mulk_i32 s5, 0x1200
	s_add_i32 s0, s5, 0
	s_add_i32 s0, s0, 0x15000
	v_lshlrev_b32_e32 v19, 1, v83
	s_waitcnt lgkmcnt(0)
	v_mul_f32_e32 v18, v32, v17
	v_mul_f32_e32 v0, v0, v17
	v_cvt_pk_bf16_f32 v18, v18, s0
	v_add3_u32 v20, s0, v153, v19
	v_cvt_pk_bf16_f32 v0, v0, s0
	ds_write_b16 v20, v18
	ds_write_b16 v20, v0 offset:64
	ds_read_b32 v0, v16 offset:4
	v_add3_u32 v18, s0, v154, v19
	s_waitcnt lgkmcnt(0)
	v_mul_f32_e32 v17, v33, v0
	v_mul_f32_e32 v0, v1, v0
	v_cvt_pk_bf16_f32 v17, v17, s0
	v_cvt_pk_bf16_f32 v0, v0, s0
	ds_write_b16 v18, v17
	ds_write_b16 v18, v0 offset:64
	ds_read_b32 v0, v16 offset:8
	v_add3_u32 v17, s0, v155, v19
	s_waitcnt lgkmcnt(0)
	v_mul_f32_e32 v1, v34, v0
	v_mul_f32_e32 v0, v2, v0
	v_cvt_pk_bf16_f32 v1, v1, s0
	v_cvt_pk_bf16_f32 v0, v0, s0
	ds_write_b16 v17, v1
	ds_write_b16 v17, v0 offset:64
	ds_read_b32 v0, v16 offset:12
	v_add3_u32 v2, s0, v156, v19
	s_waitcnt lgkmcnt(0)
	v_mul_f32_e32 v1, v35, v0
	v_mul_f32_e32 v0, v3, v0
	v_cvt_pk_bf16_f32 v1, v1, s0
	v_cvt_pk_bf16_f32 v0, v0, s0
	ds_write_b16 v2, v1
	ds_write_b16 v2, v0 offset:64
	ds_read_b32 v0, v16 offset:32
	v_add3_u32 v2, s0, v157, v19
	s_waitcnt lgkmcnt(0)
	v_mul_f32_e32 v1, v36, v0
	v_mul_f32_e32 v0, v4, v0
	v_cvt_pk_bf16_f32 v1, v1, s0
	v_cvt_pk_bf16_f32 v0, v0, s0
	ds_write_b16 v2, v1
	ds_write_b16 v2, v0 offset:64
	ds_read_b32 v0, v16 offset:36
	v_add3_u32 v2, s0, v158, v19
	v_or_b32_e32 v4, s4, v169
	s_waitcnt lgkmcnt(0)
	v_mul_f32_e32 v1, v37, v0
	v_mul_f32_e32 v0, v5, v0
	v_cvt_pk_bf16_f32 v1, v1, s0
	v_cvt_pk_bf16_f32 v0, v0, s0
	ds_write_b16 v2, v1
	ds_write_b16 v2, v0 offset:64
	ds_read_b32 v0, v16 offset:40
	v_add3_u32 v2, s0, v159, v19
	v_ashrrev_i32_e32 v5, 31, v4
	v_lshlrev_b64 v[4:5], 11, v[4:5]
	s_waitcnt lgkmcnt(0)
	v_mul_f32_e32 v1, v38, v0
	v_mul_f32_e32 v0, v6, v0
	v_cvt_pk_bf16_f32 v1, v1, s0
	v_cvt_pk_bf16_f32 v0, v0, s0
	ds_write_b16 v2, v1
	ds_write_b16 v2, v0 offset:64
	ds_read_b32 v0, v16 offset:44
	v_add3_u32 v2, s0, v160, v19
	s_waitcnt lgkmcnt(0)
	v_mul_f32_e32 v1, v39, v0
	v_mul_f32_e32 v0, v7, v0
	v_cvt_pk_bf16_f32 v1, v1, s0
	v_cvt_pk_bf16_f32 v0, v0, s0
	ds_write_b16 v2, v1
	ds_write_b16 v2, v0 offset:64
	ds_read_b32 v0, v16 offset:64
	v_add3_u32 v2, s0, v161, v19
	s_waitcnt lgkmcnt(0)
	v_mul_f32_e32 v1, v40, v0
	v_mul_f32_e32 v0, v8, v0
	v_cvt_pk_bf16_f32 v1, v1, s0
	v_cvt_pk_bf16_f32 v0, v0, s0
	ds_write_b16 v2, v1
	ds_write_b16 v2, v0 offset:64
	ds_read_b32 v0, v16 offset:68
	v_add3_u32 v2, s0, v162, v19
	s_waitcnt lgkmcnt(0)
	v_mul_f32_e32 v1, v41, v0
	v_mul_f32_e32 v0, v9, v0
	v_cvt_pk_bf16_f32 v1, v1, s0
	v_cvt_pk_bf16_f32 v0, v0, s0
	ds_write_b16 v2, v1
	ds_write_b16 v2, v0 offset:64
	ds_read_b32 v0, v16 offset:72
	v_add3_u32 v2, s0, v163, v19
	v_lshl_add_u64 v[8:9], s[36:37], 1, v[142:143]
	s_waitcnt lgkmcnt(0)
	v_mul_f32_e32 v1, v42, v0
	v_mul_f32_e32 v0, v10, v0
	v_cvt_pk_bf16_f32 v1, v1, s0
	v_cvt_pk_bf16_f32 v0, v0, s0
	ds_write_b16 v2, v1
	ds_write_b16 v2, v0 offset:64
	ds_read_b32 v0, v16 offset:76
	v_add3_u32 v2, s0, v164, v19
	s_waitcnt lgkmcnt(0)
	v_mul_f32_e32 v1, v43, v0
	v_mul_f32_e32 v0, v11, v0
	v_cvt_pk_bf16_f32 v1, v1, s0
	v_cvt_pk_bf16_f32 v0, v0, s0
	ds_write_b16 v2, v1
	ds_write_b16 v2, v0 offset:64
	ds_read_b32 v0, v16 offset:96
	v_add3_u32 v2, s0, v165, v19
	v_lshl_add_u64 v[10:11], v[8:9], 0, v[4:5]
	s_waitcnt lgkmcnt(0)
	v_mul_f32_e32 v1, v44, v0
	v_mul_f32_e32 v0, v12, v0
	v_cvt_pk_bf16_f32 v1, v1, s0
	v_cvt_pk_bf16_f32 v0, v0, s0
	ds_write_b16 v2, v1
	ds_write_b16 v2, v0 offset:64
	ds_read_b32 v0, v16 offset:100
	v_add3_u32 v2, s0, v166, v19
	v_add3_u32 v12, s0, v138, v139
	s_waitcnt lgkmcnt(0)
	v_mul_f32_e32 v1, v45, v0
	v_mul_f32_e32 v0, v13, v0
	v_cvt_pk_bf16_f32 v1, v1, s0
	v_cvt_pk_bf16_f32 v0, v0, s0
	ds_write_b16 v2, v1
	ds_write_b16 v2, v0 offset:64
	ds_read_b32 v0, v16 offset:104
	v_add3_u32 v2, s0, v167, v19
	s_waitcnt lgkmcnt(0)
	v_mul_f32_e32 v1, v46, v0
	v_mul_f32_e32 v0, v14, v0
	v_cvt_pk_bf16_f32 v1, v1, s0
	v_cvt_pk_bf16_f32 v0, v0, s0
	ds_write_b16 v2, v1
	ds_write_b16 v2, v0 offset:64
	ds_read_b32 v0, v16 offset:108
	v_add3_u32 v2, s0, v168, v19
	s_waitcnt lgkmcnt(0)
	v_mul_f32_e32 v1, v47, v0
	v_mul_f32_e32 v0, v15, v0
	v_cvt_pk_bf16_f32 v1, v1, s0
	v_cvt_pk_bf16_f32 v0, v0, s0
	ds_write_b16 v2, v1
	ds_write_b16 v2, v0 offset:64
	s_waitcnt lgkmcnt(0)
	ds_read_b128 v[0:3], v12
	ds_read_b128 v[4:7], v12 offset:1152
	s_waitcnt lgkmcnt(1)
	global_store_dwordx4 v[10:11], v[0:3], off sc1
	s_nop 1
	v_or_b32_e32 v0, s4, v170
	v_ashrrev_i32_e32 v1, 31, v0
	v_lshlrev_b64 v[0:1], 11, v[0:1]
	v_lshl_add_u64 v[0:1], v[8:9], 0, v[0:1]
	s_waitcnt lgkmcnt(0)
	global_store_dwordx4 v[0:1], v[4:7], off sc1
	ds_read_b128 v[0:3], v12 offset:2304
	s_nop 0
	v_or_b32_e32 v4, s4, v171
	v_ashrrev_i32_e32 v5, 31, v4
	v_lshlrev_b64 v[4:5], 11, v[4:5]
	v_lshl_add_u64 v[10:11], v[8:9], 0, v[4:5]
	ds_read_b128 v[4:7], v12 offset:3456
	s_waitcnt lgkmcnt(1)
	global_store_dwordx4 v[10:11], v[0:3], off sc1
	s_nop 1
	v_or_b32_e32 v0, s4, v172
	v_ashrrev_i32_e32 v1, 31, v0
	v_lshlrev_b64 v[0:1], 11, v[0:1]
	v_lshl_add_u64 v[0:1], v[8:9], 0, v[0:1]
	s_waitcnt lgkmcnt(0)
	global_store_dwordx4 v[0:1], v[4:7], off sc1
	s_waitcnt lgkmcnt(0)

; #define LAS __attribute__((address_space(3)))
; #define LDS_WAIT() asm volatile("s_waitcnt lgkmcnt(0)" ::: "memory")
; __device__ __forceinline__ unsigned cvt_pk_bf16(float lo, float hi) { f32x2_t v = {lo, hi}; bf16x2_t b = __builtin_convertvector(v, bf16x2_t); return __builtin_bit_cast(unsigned, b); }
; __device__ __forceinline__ int crow(int r, int hi) { return (r & 3) + 8 * (r >> 2) + 4 * hi; }
; __device__ __forceinline__ void attn_unit(LAS unsigned char* lds, const bf16_t* U, bf16_t* MIXo, const float* sink8, int b, int hk, int qrow0, int qpos0, bool latent, int tid) {
;     ...
;     {
;         const float lt = lsum + __shfl_xor(lsum, 32);
;         if (hi == 0) scr[r32] = 1.0f / lt;
;         LDS_WAIT();
;         LAS unsigned short* stg = (LAS unsigned short*)(lds + AT_STG + wid * AT_STGW);
; #pragma unroll
;         for (int r = 0; r < 16; ++r) { const int q = crow(r, hi); const float il = scr[q];
;             stg[q * 72 + r32] = (unsigned short)(cvt_pk_bf16(o0[r] * il, 0.f) & 0xffffu); stg[q * 72 + 32 + r32] = (unsigned short)(cvt_pk_bf16(o1[r] * il, 0.f) & 0xffffu); }
;         LDS_WAIT();
; #pragma unroll
;         for (int i = 0; i < 4; ++i) { const int row = i * 8 + (lane >> 3), ch = lane & 7; const u32x4 v = *(const LAS u32x4*)((const LAS unsigned char*)stg + row * 144 + ch * 16);
;             *(u32x4*)(MIXo + (size_t)(qrow0 + rowoff + row) * KMO + hq * 64 + 8 * ch) = v; }
;         LDS_WAIT();
;     }
.LBB0_169:
	s_or_b64 exec, exec, s[8:9]
	s_waitcnt lgkmcnt(0)
	v_add_u32_e32 v16, s14, v141
	ds_read_b32 v17, v16
	s_mulk_i32 s5, 0x1200
	s_add_i32 s5, s5, 0
	s_add_i32 s5, s5, 0x15000
	v_lshlrev_b32_e32 v19, 1, v83
	s_waitcnt lgkmcnt(0)
	v_mul_f32_e32 v18, v32, v17
	v_mul_f32_e32 v0, v0, v17
	v_cvt_pk_bf16_f32 v18, v18, s0
	v_add3_u32 v20, s5, v153, v19
	v_cvt_pk_bf16_f32 v0, v0, s0
	ds_write_b16 v20, v18
	ds_write_b16 v20, v0 offset:64
	ds_read_b32 v0, v16 offset:4
	v_add3_u32 v18, s5, v154, v19
	s_waitcnt lgkmcnt(0)
	v_mul_f32_e32 v17, v33, v0
	v_mul_f32_e32 v0, v1, v0
	v_cvt_pk_bf16_f32 v17, v17, s0
	v_cvt_pk_bf16_f32 v0, v0, s0
	ds_write_b16 v18, v17
	ds_write_b16 v18, v0 offset:64
	ds_read_b32 v0, v16 offset:8
	v_add3_u32 v17, s5, v155, v19
	s_waitcnt lgkmcnt(0)
	v_mul_f32_e32 v1, v34, v0
	v_mul_f32_e32 v0, v2, v0
	v_cvt_pk_bf16_f32 v1, v1, s0
	v_cvt_pk_bf16_f32 v0, v0, s0
	ds_write_b16 v17, v1
	ds_write_b16 v17, v0 offset:64
	ds_read_b32 v0, v16 offset:12
	v_add3_u32 v2, s5, v156, v19
	s_waitcnt lgkmcnt(0)
	v_mul_f32_e32 v1, v35, v0
	v_mul_f32_e32 v0, v3, v0
	v_cvt_pk_bf16_f32 v1, v1, s0
	v_cvt_pk_bf16_f32 v0, v0, s0
	ds_write_b16 v2, v1
	ds_write_b16 v2, v0 offset:64
	ds_read_b32 v0, v16 offset:32
	v_add3_u32 v2, s5, v157, v19
	s_waitcnt lgkmcnt(0)
	v_mul_f32_e32 v1, v36, v0
	v_mul_f32_e32 v0, v4, v0
	v_cvt_pk_bf16_f32 v1, v1, s0
	v_cvt_pk_bf16_f32 v0, v0, s0
	ds_write_b16 v2, v1
	ds_write_b16 v2, v0 offset:64
	ds_read_b32 v0, v16 offset:36
	v_add3_u32 v2, s5, v158, v19
	v_or_b32_e32 v4, s4, v169
	s_waitcnt lgkmcnt(0)
	v_mul_f32_e32 v1, v37, v0
	v_mul_f32_e32 v0, v5, v0
	v_cvt_pk_bf16_f32 v1, v1, s0
	v_cvt_pk_bf16_f32 v0, v0, s0
	ds_write_b16 v2, v1
	ds_write_b16 v2, v0 offset:64
	ds_read_b32 v0, v16 offset:40
	v_add3_u32 v2, s5, v159, v19
	v_mov_b32_e32 v5, v81
	v_lshlrev_b64 v[4:5], 11, v[4:5]
	s_waitcnt lgkmcnt(0)
	v_mul_f32_e32 v1, v38, v0
	v_mul_f32_e32 v0, v6, v0
	v_cvt_pk_bf16_f32 v1, v1, s0
	v_cvt_pk_bf16_f32 v0, v0, s0
	ds_write_b16 v2, v1
	ds_write_b16 v2, v0 offset:64
	ds_read_b32 v0, v16 offset:44
	v_add3_u32 v2, s5, v160, v19
	s_waitcnt lgkmcnt(0)
	v_mul_f32_e32 v1, v39, v0
	v_mul_f32_e32 v0, v7, v0
	v_cvt_pk_bf16_f32 v1, v1, s0
	v_cvt_pk_bf16_f32 v0, v0, s0
	ds_write_b16 v2, v1
	ds_write_b16 v2, v0 offset:64
	ds_read_b32 v0, v16 offset:64
	v_add3_u32 v2, s5, v161, v19
	s_waitcnt lgkmcnt(0)
	v_mul_f32_e32 v1, v40, v0
	v_mul_f32_e32 v0, v8, v0
	v_cvt_pk_bf16_f32 v1, v1, s0
	v_cvt_pk_bf16_f32 v0, v0, s0
	ds_write_b16 v2, v1
	ds_write_b16 v2, v0 offset:64
	ds_read_b32 v0, v16 offset:68
	v_add3_u32 v2, s5, v162, v19
	s_waitcnt lgkmcnt(0)
	v_mul_f32_e32 v1, v41, v0
	v_mul_f32_e32 v0, v9, v0
	v_cvt_pk_bf16_f32 v1, v1, s0
	v_cvt_pk_bf16_f32 v0, v0, s0
	ds_write_b16 v2, v1
	ds_write_b16 v2, v0 offset:64
	ds_read_b32 v0, v16 offset:72
	v_add3_u32 v2, s5, v163, v19
	v_lshl_add_u64 v[8:9], s[0:1], 1, v[142:143]
	s_waitcnt lgkmcnt(0)
	v_mul_f32_e32 v1, v42, v0
	v_mul_f32_e32 v0, v10, v0
	v_cvt_pk_bf16_f32 v1, v1, s0
	v_cvt_pk_bf16_f32 v0, v0, s0
	ds_write_b16 v2, v1
	ds_write_b16 v2, v0 offset:64
	ds_read_b32 v0, v16 offset:76
	v_add3_u32 v2, s5, v164, v19
	s_waitcnt lgkmcnt(0)
	v_mul_f32_e32 v1, v43, v0
	v_mul_f32_e32 v0, v11, v0
	v_cvt_pk_bf16_f32 v1, v1, s0
	v_cvt_pk_bf16_f32 v0, v0, s0
	ds_write_b16 v2, v1
	ds_write_b16 v2, v0 offset:64
	ds_read_b32 v0, v16 offset:96
	v_add3_u32 v2, s5, v165, v19
	v_lshl_add_u64 v[10:11], v[8:9], 0, v[4:5]
	s_waitcnt lgkmcnt(0)
	v_mul_f32_e32 v1, v44, v0
	v_mul_f32_e32 v0, v12, v0
	v_cvt_pk_bf16_f32 v1, v1, s0
	v_cvt_pk_bf16_f32 v0, v0, s0
	ds_write_b16 v2, v1
	ds_write_b16 v2, v0 offset:64
	ds_read_b32 v0, v16 offset:100
	v_add3_u32 v2, s5, v166, v19
	v_add3_u32 v12, s5, v138, v139
	s_waitcnt lgkmcnt(0)
	v_mul_f32_e32 v1, v45, v0
	v_mul_f32_e32 v0, v13, v0
	v_cvt_pk_bf16_f32 v1, v1, s0
	v_cvt_pk_bf16_f32 v0, v0, s0
	ds_write_b16 v2, v1
	ds_write_b16 v2, v0 offset:64
	ds_read_b32 v0, v16 offset:104
	v_add3_u32 v2, s5, v167, v19
	s_waitcnt lgkmcnt(0)
	v_mul_f32_e32 v1, v46, v0
	v_mul_f32_e32 v0, v14, v0
	v_cvt_pk_bf16_f32 v1, v1, s0
	v_cvt_pk_bf16_f32 v0, v0, s0
	ds_write_b16 v2, v1
	ds_write_b16 v2, v0 offset:64
	ds_read_b32 v0, v16 offset:108
	v_add3_u32 v2, s5, v168, v19
	s_waitcnt lgkmcnt(0)
	v_mul_f32_e32 v1, v47, v0
	v_mul_f32_e32 v0, v15, v0
	v_cvt_pk_bf16_f32 v1, v1, s0
	v_cvt_pk_bf16_f32 v0, v0, s0
	ds_write_b16 v2, v1
	ds_write_b16 v2, v0 offset:64
	s_waitcnt lgkmcnt(0)
	ds_read_b128 v[0:3], v12
	ds_read_b128 v[4:7], v12 offset:1152
	s_mov_b64 s[0:1], 0
	s_waitcnt lgkmcnt(1)
	global_store_dwordx4 v[10:11], v[0:3], off sc1
	s_nop 1
	v_or_b32_e32 v0, s4, v170
	v_mov_b32_e32 v1, v81
	v_lshlrev_b64 v[0:1], 11, v[0:1]
	v_lshl_add_u64 v[0:1], v[8:9], 0, v[0:1]
	s_waitcnt lgkmcnt(0)
	global_store_dwordx4 v[0:1], v[4:7], off sc1
	ds_read_b128 v[0:3], v12 offset:2304
	s_nop 0
	v_or_b32_e32 v4, s4, v171
	v_mov_b32_e32 v5, v81
	v_lshlrev_b64 v[4:5], 11, v[4:5]
	v_lshl_add_u64 v[10:11], v[8:9], 0, v[4:5]
	ds_read_b128 v[4:7], v12 offset:3456
	s_waitcnt lgkmcnt(1)
	global_store_dwordx4 v[10:11], v[0:3], off sc1
	s_nop 1
	v_or_b32_e32 v0, s4, v172
	v_mov_b32_e32 v1, v81
	v_lshlrev_b64 v[0:1], 11, v[0:1]
	v_lshl_add_u64 v[0:1], v[8:9], 0, v[0:1]
	s_waitcnt lgkmcnt(0)
	global_store_dwordx4 v[0:1], v[4:7], off sc1
	s_waitcnt lgkmcnt(0)

; __device__ __forceinline__ void unpack8(const u32x4& w, float (&f)[8]) { f[0] = bf_lo(w.x); f[1] = bf_hi(w.x); f[2] = bf_lo(w.y); f[3] = bf_hi(w.y); f[4] = bf_lo(w.z); f[5] = bf_hi(w.z); f[6] = bf_lo(w.w); f[7] = bf_hi(w.w); }
; __device__ __forceinline__ void sconv_pass(const Args& a, int e, int nrows, int gt, int NT) {
;     const bf16_t* U = (const bf16_t*)(a.ws + WS_BIG); bf16_t* MIXo = (bf16_t*)(a.ws + WS_MIX); const float* cw = a.in[9] + (size_t)e * 3 * 512;
;     for (int idx0 = gt; idx0 < nrows * 64; idx0 += 2 * NT) {
;         u32x4 ld[2][7]; int rowi[2], chi[2]; float m0[2], m2[2]; bool ok[2];
; #pragma unroll
;         for (int u = 0; u < 2; ++u) {
;             const int idx = idx0 + u * NT; ok[u] = idx < nrows * 64; const int id = ok[u] ? idx : idx0;
;             const int row = id >> 6, ch = id & 63; rowi[u] = row; chi[u] = ch;
;             const int t = row < MX ? (row & (SEQ - 1)) : ((row - MX) & (CTXL - 1)), T = row < MX ? SEQ : CTXL;
;             m0[u] = t > 0 ? 1.f : 0.f; m2[u] = t < T - 1 ? 1.f : 0.f;
;             const bf16_t* up = U + (size_t)row * ATT_IN + 8 * ch; const ptrdiff_t dn = t > 0 ? -(ptrdiff_t)ATT_IN : 0, upo = t < T - 1 ? (ptrdiff_t)ATT_IN : 0;
;             ld[u][0] = ld16(up + 768);
;             ld[u][1] = ld16(up + dn + 1280); ld[u][2] = ld16(up + dn + 1792);
;             ld[u][3] = ld16(up + 1280); ld[u][4] = ld16(up + 1792);
;             ld[u][5] = ld16(up + upo + 1280); ld[u][6] = ld16(up + upo + 1792);
;         }
; #pragma unroll
;         for (int u = 0; u < 2; ++u) {
;             if (!ok[u]) continue;
;             const int ch = chi[u];
;             float bv[8], acc[8], cv[8], zv[8];
;             unpack8(ld[u][0], bv);
; #pragma unroll
;             for (int q = 0; q < 8; ++q) acc[q] = 0.f;
; #pragma unroll
;             for (int j = 0; j < 3; ++j) {
;                 unpack8(ld[u][1 + 2 * j], cv); unpack8(ld[u][2 + 2 * j], zv);
;                 const float mk = j == 0 ? m0[u] : (j == 2 ? m2[u] : 1.f);
;                 const f32x4 w0 = *(const f32x4*)(cw + j * 512 + 8 * ch) * mk, w1 = *(const f32x4*)(cw + j * 512 + 8 * ch + 4) * mk;
; #pragma unroll
;                 for (int q = 0; q < 4; ++q) { acc[q] += w0[q] * (cv[q] * zv[q]); acc[4 + q] += w1[q] * (cv[4 + q] * zv[4 + q]); }
;             }
.LBB0_246:
	v_ashrrev_i32_e32 v86, 6, v0
	s_movk_i32 s13, 0x4000
	v_cmp_gt_i32_e32 vcc, s13, v86
	v_readlane_b32 s16, v252, 21
	v_readlane_b32 s17, v252, 22
	v_cndmask_b32_e32 v1, v229, v230, vcc
	v_and_b32_e32 v2, v1, v86
	v_cmp_eq_u32_e32 vcc, 0, v2
	v_cmp_eq_u32_e64 s[34:35], v2, v1
	v_mov_b64_e32 v[2:3], s[16:17]
	v_and_b32_e32 v56, 0x1f8, v85
	v_mad_i64_i32 v[4:5], s[16:17], v86, s33, v[2:3]
	v_lshlrev_b32_e32 v90, 1, v56
	v_mov_b32_e32 v91, v81
	v_lshl_add_u64 v[44:45], v[4:5], 0, v[90:91]
	v_cndmask_b32_e64 v80, v233, 0, s[34:35]
	v_add_u32_e32 v89, s5, v0
	v_lshl_add_u64 v[4:5], v[44:45], 0, v[80:81]
	v_cmp_gt_i32_e64 s[36:37], s4, v89
	global_load_dwordx4 v[36:39], v[44:45], off offset:2560
	global_load_dwordx4 v[40:43], v[44:45], off offset:3584
	global_load_dwordx4 v[32:35], v[4:5], off offset:2560
	global_load_dwordx4 v[28:31], v[4:5], off offset:3584
	v_cndmask_b32_e64 v4, v0, v89, s[36:37]
	v_ashrrev_i32_e32 v82, 6, v4
	v_cndmask_b32_e64 v88, 1.0, 0, s[34:35]
	v_cmp_gt_i32_e64 s[34:35], s13, v82
	v_mov_b32_e32 v5, v81
	v_cndmask_b32_e64 v47, -1, 0, vcc
	v_cndmask_b32_e64 v0, v229, v230, s[34:35]
	v_and_b32_e32 v1, v0, v82
	v_cmp_eq_u32_e64 s[34:35], 0, v1
	v_cmp_eq_u32_e64 s[38:39], v1, v0
	v_mad_i64_i32 v[0:1], s[16:17], v82, s33, v[2:3]
	v_lshlrev_b32_e32 v2, 3, v4
	v_and_b32_e32 v93, 0x1f8, v2
	v_lshlrev_b32_e32 v80, 1, v93
	v_lshl_add_u64 v[0:1], v[0:1], 0, v[80:81]
	v_cndmask_b32_e64 v3, -1, 0, s[34:35]
	v_cndmask_b32_e64 v2, v238, 0, s[34:35]
	v_cndmask_b32_e64 v4, v233, 0, s[38:39]
	v_lshl_add_u64 v[2:3], v[0:1], 0, v[2:3]
	v_cndmask_b32_e64 v46, v238, 0, vcc
	global_load_dwordx4 v[24:27], v[0:1], off offset:1536
	global_load_dwordx4 v[20:23], v[2:3], off offset:2560
	global_load_dwordx4 v[16:19], v[2:3], off offset:3584
	s_waitcnt lgkmcnt(0)
	global_load_dwordx4 v[8:11], v[0:1], off offset:2560
	global_load_dwordx4 v[12:15], v[0:1], off offset:3584
	v_lshl_add_u64 v[0:1], v[0:1], 0, v[4:5]
	v_lshl_add_u64 v[46:47], v[44:45], 0, v[46:47]
	global_load_dwordx4 v[4:7], v[0:1], off offset:2560
	s_nop 0
	global_load_dwordx4 v[0:3], v[0:1], off offset:3584
	s_nop 0
	global_load_dwordx4 v[48:51], v[46:47], off offset:3584
	global_load_dwordx4 v[52:55], v[46:47], off offset:2560
	global_load_dwordx4 v[60:63], v[44:45], off offset:1536
	v_lshlrev_b32_e32 v64, 2, v56
	v_mov_b32_e32 v65, v81
	v_lshl_add_u64 v[72:73], s[8:9], 0, v[64:65]
	s_mov_b64 s[16:17], 0x1000
	v_cndmask_b32_e64 v92, 1.0, 0, vcc
	global_load_dwordx4 v[44:47], v64, s[8:9] offset:16
	global_load_dwordx4 v[68:71], v64, s[8:9]
	global_load_dwordx4 v[56:59], v64, s[8:9] offset:2064
	s_nop 0
	global_load_dwordx4 v[64:67], v64, s[8:9] offset:2048
	v_lshl_add_u64 v[76:77], v[72:73], 0, s[16:17]
	v_add_co_u32_e32 v72, vcc, s94, v72
	v_ashrrev_i32_e32 v87, 31, v86
	s_nop 0
	v_addc_co_u32_e32 v73, vcc, 0, v73, vcc
	global_load_dwordx4 v[72:75], v[72:73], off
	s_nop 0
	global_load_dwordx4 v[76:79], v[76:77], off offset:16
	s_waitcnt vmcnt(19)
	v_lshlrev_b32_e32 v102, 16, v36
	s_waitcnt vmcnt(18)
	v_lshlrev_b32_e32 v100, 16, v40
	v_and_b32_e32 v101, 0xffff0000, v40
	v_and_b32_e32 v103, 0xffff0000, v36
	v_lshlrev_b32_e32 v40, 16, v41
	v_and_b32_e32 v41, 0xffff0000, v41
	v_lshlrev_b32_e32 v36, 16, v37
	v_and_b32_e32 v37, 0xffff0000, v37
	v_pk_mul_f32 v[36:37], v[36:37], v[40:41]
	s_waitcnt vmcnt(16)
	v_lshlrev_b32_e32 v40, 16, v29
	v_and_b32_e32 v41, 0xffff0000, v29
	s_waitcnt vmcnt(8)
	v_lshlrev_b32_e32 v98, 16, v48
	s_waitcnt vmcnt(7)
	v_lshlrev_b32_e32 v96, 16, v52
	v_and_b32_e32 v97, 0xffff0000, v52
	v_and_b32_e32 v99, 0xffff0000, v48
	v_pk_mul_f32 v[96:97], v[98:99], v[96:97]
	s_waitcnt vmcnt(6)
	v_lshlrev_b32_e32 v94, 16, v60
	s_waitcnt vmcnt(4)
	v_pk_mul_f32 v[68:69], v[92:93], v[68:69] op_sel_hi:[0,1]
	v_pk_fma_f32 v[68:69], v[96:97], v[68:69], 0 op_sel_hi:[1,1,0]
	v_pk_mul_f32 v[96:97], v[102:103], v[100:101]
	v_and_b32_e32 v95, 0xffff0000, v60
	s_waitcnt vmcnt(2)
	v_pk_fma_f32 v[64:65], v[96:97], v[64:65], v[68:69]
	v_lshlrev_b32_e32 v68, 16, v32
	v_and_b32_e32 v69, 0xffff0000, v32
	v_lshlrev_b32_e32 v96, 16, v28
	v_and_b32_e32 v97, 0xffff0000, v28
	s_waitcnt vmcnt(1)
	v_pk_mul_f32 v[72:73], v[88:89], v[72:73] op_sel_hi:[0,1]
	v_pk_mul_f32 v[68:69], v[68:69], v[96:97]
	v_lshlrev_b32_e32 v52, 16, v53
	v_pk_fma_f32 v[64:65], v[68:69], v[72:73], v[64:65]
	v_and_b32_e32 v53, 0xffff0000, v53
	v_pk_mul_f32 v[64:65], v[64:65], v[94:95]
	v_lshlrev_b32_e32 v48, 16, v49
	v_and_b32_e32 v49, 0xffff0000, v49
	v_cvt_pk_bf16_f32 v28, v64, v65
	v_pk_mul_f32 v[64:65], v[92:93], v[70:71] op_sel_hi:[0,1]
	v_pk_mul_f32 v[48:49], v[48:49], v[52:53]
	v_lshlrev_b32_e32 v32, 16, v33
	v_pk_fma_f32 v[48:49], v[48:49], v[64:65], 0 op_sel_hi:[1,1,0]
	v_and_b32_e32 v33, 0xffff0000, v33
	v_pk_fma_f32 v[36:37], v[36:37], v[66:67], v[48:49]
	v_pk_mul_f32 v[48:49], v[88:89], v[74:75] op_sel_hi:[0,1]
	v_pk_mul_f32 v[32:33], v[32:33], v[40:41]
	v_lshlrev_b32_e32 v40, 16, v50
	v_pk_fma_f32 v[32:33], v[32:33], v[48:49], v[36:37]
	v_lshlrev_b32_e32 v36, 16, v54
	v_and_b32_e32 v37, 0xffff0000, v54
	v_and_b32_e32 v41, 0xffff0000, v50
	v_lshlrev_b32_e32 v48, 16, v42
	v_and_b32_e32 v49, 0xffff0000, v42
	v_lshlrev_b32_e32 v52, 16, v38
	v_and_b32_e32 v53, 0xffff0000, v38
	v_pk_mul_f32 v[44:45], v[92:93], v[44:45] op_sel_hi:[0,1]
	v_pk_mul_f32 v[36:37], v[40:41], v[36:37]
	v_pk_mul_f32 v[40:41], v[52:53], v[48:49]
	v_pk_fma_f32 v[36:37], v[44:45], v[36:37], 0 op_sel_hi:[1,1,0]
	v_lshlrev_b32_e32 v60, 16, v61
	v_and_b32_e32 v61, 0xffff0000, v61
	v_pk_fma_f32 v[36:37], v[40:41], v[56:57], v[36:37]
	v_lshlrev_b32_e32 v40, 16, v34
	v_and_b32_e32 v41, 0xffff0000, v34
	v_lshlrev_b32_e32 v44, 16, v30
	v_and_b32_e32 v45, 0xffff0000, v30
	v_pk_mul_f32 v[32:33], v[32:33], v[60:61]
	s_waitcnt vmcnt(0)
; __device__ __forceinline__ unsigned cvt_pk_bf16(float lo, float hi) { f32x2_t v = {lo, hi}; bf16x2_t b = __builtin_convertvector(v, bf16x2_t); return __builtin_bit_cast(unsigned, b); }
; __device__ __forceinline__ void unpack8(const u32x4& w, float (&f)[8]) { f[0] = bf_lo(w.x); f[1] = bf_hi(w.x); f[2] = bf_lo(w.y); f[3] = bf_hi(w.y); f[4] = bf_lo(w.z); f[5] = bf_hi(w.z); f[6] = bf_lo(w.w); f[7] = bf_hi(w.w); }
; __device__ __forceinline__ void sconv_pass(const Args& a, int e, int nrows, int gt, int NT) {
;     ...
;             for (int j = 0; j < 3; ++j) {
;                 unpack8(ld[u][1 + 2 * j], cv); unpack8(ld[u][2 + 2 * j], zv);
;                 const float mk = j == 0 ? m0[u] : (j == 2 ? m2[u] : 1.f);
;                 const f32x4 w0 = *(const f32x4*)(cw + j * 512 + 8 * ch) * mk, w1 = *(const f32x4*)(cw + j * 512 + 8 * ch + 4) * mk;
; #pragma unroll
;                 for (int q = 0; q < 4; ++q) { acc[q] += w0[q] * (cv[q] * zv[q]); acc[4 + q] += w1[q] * (cv[4 + q] * zv[4 + q]); }
;             }
;             u32x4 w; w.x = cvt_pk_bf16(bv[0] * acc[0], bv[1] * acc[1]); w.y = cvt_pk_bf16(bv[2] * acc[2], bv[3] * acc[3]); w.z = cvt_pk_bf16(bv[4] * acc[4], bv[5] * acc[5]); w.w = cvt_pk_bf16(bv[6] * acc[6], bv[7] * acc[7]);
;             *(u32x4*)(MIXo + (size_t)rowi[u] * KMO + 512 + 8 * ch) = w;
;         }
	v_pk_mul_f32 v[48:49], v[88:89], v[76:77] op_sel_hi:[0,1]
	v_pk_mul_f32 v[40:41], v[40:41], v[44:45]
	v_cvt_pk_bf16_f32 v29, v32, v33
	v_lshlrev_b32_e32 v32, 16, v62
	v_and_b32_e32 v33, 0xffff0000, v62
	v_pk_fma_f32 v[36:37], v[40:41], v[48:49], v[36:37]
	v_lshlrev_b32_e32 v40, 16, v51
	v_pk_mul_f32 v[32:33], v[36:37], v[32:33]
	v_lshlrev_b32_e32 v36, 16, v55
	v_and_b32_e32 v37, 0xffff0000, v55
	v_and_b32_e32 v41, 0xffff0000, v51
	v_lshlrev_b32_e32 v42, 16, v43
	v_and_b32_e32 v43, 0xffff0000, v43
	v_lshlrev_b32_e32 v38, 16, v39
	v_and_b32_e32 v39, 0xffff0000, v39
	v_pk_mul_f32 v[44:45], v[92:93], v[46:47] op_sel_hi:[0,1]
	v_pk_mul_f32 v[36:37], v[40:41], v[36:37]
	v_pk_mul_f32 v[38:39], v[38:39], v[42:43]
	v_pk_fma_f32 v[36:37], v[44:45], v[36:37], 0 op_sel_hi:[1,1,0]
	v_lshlrev_b32_e32 v34, 16, v35
	v_pk_fma_f32 v[36:37], v[38:39], v[58:59], v[36:37]
	v_and_b32_e32 v35, 0xffff0000, v35
	v_lshlrev_b32_e32 v38, 16, v31
	v_and_b32_e32 v39, 0xffff0000, v31
	v_pk_mul_f32 v[40:41], v[88:89], v[78:79] op_sel_hi:[0,1]
	v_pk_mul_f32 v[34:35], v[34:35], v[38:39]
	v_cvt_pk_bf16_f32 v30, v32, v33
	v_lshlrev_b32_e32 v32, 16, v63
	v_and_b32_e32 v33, 0xffff0000, v63
	v_pk_fma_f32 v[34:35], v[34:35], v[40:41], v[36:37]
	s_nop 0
	v_pk_mul_f32 v[32:33], v[34:35], v[32:33]
	s_nop 0
	v_cvt_pk_bf16_f32 v31, v32, v33
	v_lshlrev_b64 v[32:33], 11, v[86:87]
	v_lshl_add_u64 v[32:33], s[86:87], 0, v[32:33]
	v_lshl_add_u64 v[32:33], v[32:33], 0, v[90:91]
	v_add_co_u32_e32 v32, vcc, 0x12500000, v32
	s_nop 1
	v_addc_co_u32_e32 v33, vcc, 0, v33, vcc
	global_store_dwordx4 v[32:33], v[28:31], off offset:1024 sc1
	s_and_saveexec_b64 s[42:43], s[36:37]
	s_cbranch_execz .LBB0_245
	v_lshlrev_b32_e32 v36, 2, v93
	v_mov_b32_e32 v37, v81
	v_lshl_add_u64 v[38:39], s[8:9], 0, v[36:37]
	global_load_dwordx4 v[28:31], v36, s[8:9] offset:16
	global_load_dwordx4 v[44:47], v36, s[8:9]
	global_load_dwordx4 v[32:35], v36, s[8:9] offset:2064
	global_load_dwordx4 v[48:51], v36, s[8:9] offset:2048
	v_lshl_add_u64 v[36:37], v[38:39], 0, s[16:17]
	v_add_co_u32_e32 v38, vcc, s94, v38
	v_cndmask_b32_e64 v42, 1.0, 0, s[34:35]
	s_nop 0
	v_addc_co_u32_e32 v39, vcc, 0, v39, vcc
	global_load_dwordx4 v[52:55], v[38:39], off
	s_nop 0
	global_load_dwordx4 v[36:39], v[36:37], off offset:16
	v_lshlrev_b32_e32 v58, 16, v20
	v_and_b32_e32 v59, 0xffff0000, v20
	v_lshlrev_b32_e32 v60, 16, v16
	v_and_b32_e32 v61, 0xffff0000, v16
	v_lshlrev_b32_e32 v62, 16, v12
	v_and_b32_e32 v63, 0xffff0000, v12
	v_lshlrev_b32_e32 v64, 16, v8
	v_and_b32_e32 v65, 0xffff0000, v8
	v_pk_mul_f32 v[58:59], v[58:59], v[60:61]
	v_cndmask_b32_e64 v40, 1.0, 0, s[38:39]
	v_lshlrev_b32_e32 v56, 16, v24
	v_and_b32_e32 v57, 0xffff0000, v24
	v_lshlrev_b32_e32 v20, 16, v21
	v_and_b32_e32 v21, 0xffff0000, v21
	v_lshlrev_b32_e32 v16, 16, v17
	v_and_b32_e32 v17, 0xffff0000, v17
	v_lshlrev_b32_e32 v12, 16, v13
	v_and_b32_e32 v13, 0xffff0000, v13
	v_lshlrev_b32_e32 v8, 16, v9
	v_and_b32_e32 v9, 0xffff0000, v9
	v_pk_mul_f32 v[16:17], v[20:21], v[16:17]
	v_pk_mul_f32 v[8:9], v[8:9], v[12:13]
	v_lshlrev_b32_e32 v12, 16, v1
	v_and_b32_e32 v13, 0xffff0000, v1
	v_lshlrev_b32_e32 v24, 16, v25
	v_and_b32_e32 v25, 0xffff0000, v25
	v_lshlrev_b32_e32 v20, 16, v10
	v_and_b32_e32 v21, 0xffff0000, v10
	v_lshlrev_b32_e32 v10, 16, v11
	v_and_b32_e32 v11, 0xffff0000, v11
	v_ashrrev_i32_e32 v83, 31, v82
	s_waitcnt vmcnt(4)
	v_pk_mul_f32 v[44:45], v[42:43], v[44:45] op_sel_hi:[0,1]
	v_pk_fma_f32 v[44:45], v[58:59], v[44:45], 0 op_sel_hi:[1,1,0]
	v_pk_mul_f32 v[58:59], v[64:65], v[62:63]
	s_waitcnt vmcnt(1)
	v_pk_mul_f32 v[52:53], v[40:41], v[52:53] op_sel_hi:[0,1]
	v_pk_fma_f32 v[44:45], v[58:59], v[48:49], v[44:45]
	v_lshlrev_b32_e32 v48, 16, v4
	v_and_b32_e32 v49, 0xffff0000, v4
	v_lshlrev_b32_e32 v58, 16, v0
	v_and_b32_e32 v59, 0xffff0000, v0
	v_pk_mul_f32 v[48:49], v[48:49], v[58:59]
	v_lshlrev_b32_e32 v4, 16, v5
	v_pk_fma_f32 v[44:45], v[48:49], v[52:53], v[44:45]
	v_and_b32_e32 v5, 0xffff0000, v5
	v_pk_mul_f32 v[44:45], v[44:45], v[56:57]
	v_pk_mul_f32 v[4:5], v[4:5], v[12:13]
	v_cvt_pk_bf16_f32 v0, v44, v45
	v_pk_mul_f32 v[44:45], v[42:43], v[46:47] op_sel_hi:[0,1]
	v_pk_fma_f32 v[16:17], v[16:17], v[44:45], 0 op_sel_hi:[1,1,0]
	v_lshlrev_b32_e32 v12, 16, v18
	v_pk_fma_f32 v[8:9], v[8:9], v[50:51], v[16:17]
	v_pk_mul_f32 v[16:17], v[40:41], v[54:55] op_sel_hi:[0,1]
	v_pk_fma_f32 v[4:5], v[4:5], v[16:17], v[8:9]
	v_lshlrev_b32_e32 v8, 16, v22
	v_and_b32_e32 v9, 0xffff0000, v22
	v_and_b32_e32 v13, 0xffff0000, v18
	v_pk_mul_f32 v[4:5], v[4:5], v[24:25]
	v_lshlrev_b32_e32 v16, 16, v14
	v_and_b32_e32 v17, 0xffff0000, v14
	v_pk_mul_f32 v[24:25], v[42:43], v[28:29] op_sel_hi:[0,1]
	v_pk_mul_f32 v[8:9], v[8:9], v[12:13]
	v_pk_mul_f32 v[12:13], v[20:21], v[16:17]
	v_pk_fma_f32 v[8:9], v[8:9], v[24:25], 0 op_sel_hi:[1,1,0]
	v_lshlrev_b32_e32 v16, 16, v2
	v_pk_fma_f32 v[8:9], v[12:13], v[32:33], v[8:9]
	v_lshlrev_b32_e32 v12, 16, v6
	v_and_b32_e32 v13, 0xffff0000, v6
	v_and_b32_e32 v17, 0xffff0000, v2
	s_waitcnt vmcnt(0)
	v_pk_mul_f32 v[20:21], v[40:41], v[36:37] op_sel_hi:[0,1]
	v_pk_mul_f32 v[12:13], v[12:13], v[16:17]
	v_cvt_pk_bf16_f32 v1, v4, v5
	v_lshlrev_b32_e32 v4, 16, v26
	v_and_b32_e32 v5, 0xffff0000, v26
	v_pk_fma_f32 v[8:9], v[12:13], v[20:21], v[8:9]
	v_lshlrev_b32_e32 v12, 16, v19
	v_pk_mul_f32 v[4:5], v[8:9], v[4:5]
	v_lshlrev_b32_e32 v8, 16, v23
	v_and_b32_e32 v9, 0xffff0000, v23
	v_and_b32_e32 v13, 0xffff0000, v19
	v_lshlrev_b32_e32 v14, 16, v15
	v_and_b32_e32 v15, 0xffff0000, v15
	v_pk_mul_f32 v[16:17], v[42:43], v[30:31] op_sel_hi:[0,1]
	v_pk_mul_f32 v[8:9], v[8:9], v[12:13]
	v_pk_mul_f32 v[10:11], v[10:11], v[14:15]
	v_pk_fma_f32 v[8:9], v[8:9], v[16:17], 0 op_sel_hi:[1,1,0]
	v_lshlrev_b32_e32 v6, 16, v7
	v_pk_fma_f32 v[8:9], v[10:11], v[34:35], v[8:9]
	v_and_b32_e32 v7, 0xffff0000, v7
	v_lshlrev_b32_e32 v10, 16, v3
	v_and_b32_e32 v11, 0xffff0000, v3
	v_pk_mul_f32 v[12:13], v[40:41], v[38:39] op_sel_hi:[0,1]
	v_pk_mul_f32 v[6:7], v[6:7], v[10:11]
	v_cvt_pk_bf16_f32 v2, v4, v5
	v_lshlrev_b32_e32 v4, 16, v27
	v_and_b32_e32 v5, 0xffff0000, v27
	v_pk_fma_f32 v[6:7], v[6:7], v[12:13], v[8:9]
	s_nop 0
	v_pk_mul_f32 v[4:5], v[6:7], v[4:5]
	s_nop 0
	v_cvt_pk_bf16_f32 v3, v4, v5
	v_lshlrev_b64 v[4:5], 11, v[82:83]
	v_lshl_add_u64 v[4:5], s[86:87], 0, v[4:5]
	v_lshl_add_u64 v[4:5], v[4:5], 0, v[80:81]
	v_add_co_u32_e32 v4, vcc, 0x12500000, v4
	s_nop 1
	v_addc_co_u32_e32 v5, vcc, 0, v5, vcc
	global_store_dwordx4 v[4:5], v[0:3], off offset:1024 sc1
	s_branch .LBB0_245

; __device__ __forceinline__ void epi_slab_h(const f32x4 (&acc)[2][2][4][2], const Job& J, const Unit& u, int wr, int wc, int fr, int fq) {
;     const int ld = J.nN * BM;
;     _Float16* O = (_Float16*)J.slab + ((size_t)u.slice * J.cM * BM + (size_t)(u.pm - J.nM) * BM) * ld + u.pn * BM;
; #pragma unroll
;     for (int ai = 0; ai < 2; ++ai)
; #pragma unroll
;         for (int m = 0; m < 4; ++m) {
;             _Float16* rowp = O + (size_t)(ai * HALF + wr * 64 + m * 16 + fr) * ld + wc * 32 + 8 * fq;
; #pragma unroll
;             for (int bj = 0; bj < 2; ++bj) { typedef _Float16 f16x8s __attribute__((ext_vector_type(8)));
;                 const f16x4s h0 = __builtin_convertvector(acc[ai][bj][m][0], f16x4s), h1 = __builtin_convertvector(acc[ai][bj][m][1], f16x4s);
;                 *(f16x8s*)(rowp + bj * HALF) = (f16x8s){h0[0], h0[1], h0[2], h0[3], h1[0], h1[1], h1[2], h1[3]}; }
;         }
; }
.LBB0_310:
	s_and_b64 vcc, exec, s[0:1]
	s_cbranch_vccz .LBB0_495
	v_readlane_b32 s1, v254, 40
	s_sub_i32 s1, s90, s1
	s_mul_hi_u32 s0, s50, s47
	s_mul_i32 s50, s50, s47
	s_ashr_i32 s8, s1, 31
	s_add_u32 s9, s50, s1
	s_addc_u32 s0, s0, s8
	s_mul_i32 s0, s82, s0
	s_mul_hi_u32 s1, s82, s9
	s_add_i32 s0, s1, s0
	s_mul_i32 s1, s83, s9
	s_add_i32 s1, s0, s1
	s_mul_i32 s0, s82, s9
	s_lshl_b64 s[0:1], s[0:1], 1
	v_readlane_b32 s8, v254, 12
	v_readlane_b32 s9, v254, 13
	s_add_u32 s8, s8, s0
	s_addc_u32 s9, s9, s1
	s_lshl_b32 s0, s78, 8
	s_ashr_i32 s1, s0, 31
	s_lshl_b64 s[0:1], s[0:1], 1
	s_add_u32 s0, s8, s0
	v_readlane_b32 s8, v255, 8
	s_addc_u32 s1, s9, s1
	v_lshlrev_b32_e32 v82, 3, v247
	v_or_b32_e32 v80, s8, v248
	v_readlane_b32 s8, v254, 59
	s_lshl_b32 s8, s8, 1
	s_add_u32 s0, s0, s8
	s_addc_u32 s1, s1, 0
	v_ashrrev_i32_e32 v83, 31, v82
	v_lshl_add_u64 v[82:83], v[82:83], 1, s[0:1]
	v_mad_i64_i32 v[86:87], s[0:1], v80, s96, 0
	v_lshl_add_u64 v[86:87], v[86:87], 1, v[82:83]
	v_cvt_pk_f16_f32 v131, v130, v131
	v_cvt_pk_f16_f32 v130, v128, v129
	v_cvt_pk_f16_f32 v129, v134, v135
	v_cvt_pk_f16_f32 v128, v132, v133
	v_cvt_pk_f16_f32 v115, v114, v115
	v_cvt_pk_f16_f32 v114, v112, v113
	v_cvt_pk_f16_f32 v113, v118, v119
	v_cvt_pk_f16_f32 v112, v116, v117
	v_or_b32_e32 v85, 16, v80
	global_store_dwordx4 v[86:87], v[128:131], off sc1
	global_store_dwordx4 v[86:87], v[112:115], off offset:256 sc1
	v_mad_i64_i32 v[86:87], s[0:1], v85, s96, 0
	v_lshl_add_u64 v[86:87], v[86:87], 1, v[82:83]
	v_cvt_pk_f16_f32 v115, v122, v123
	v_cvt_pk_f16_f32 v114, v120, v121
	v_cvt_pk_f16_f32 v113, v126, v127
	v_cvt_pk_f16_f32 v112, v124, v125
	v_cvt_pk_f16_f32 v99, v98, v99
	v_cvt_pk_f16_f32 v98, v96, v97
	v_cvt_pk_f16_f32 v97, v102, v103
	v_cvt_pk_f16_f32 v96, v100, v101
	v_or_b32_e32 v85, 32, v80
	global_store_dwordx4 v[86:87], v[112:115], off sc1
	global_store_dwordx4 v[86:87], v[96:99], off offset:256 sc1
	v_mad_i64_i32 v[86:87], s[0:1], v85, s96, 0
	v_lshl_add_u64 v[86:87], v[86:87], 1, v[82:83]
	v_cvt_pk_f16_f32 v75, v74, v75
	v_cvt_pk_f16_f32 v74, v72, v73
	v_cvt_pk_f16_f32 v73, v78, v79
	v_cvt_pk_f16_f32 v72, v76, v77
	global_store_dwordx4 v[86:87], v[72:75], off offset:256 sc1
	v_cvt_pk_f16_f32 v99, v106, v107
	v_cvt_pk_f16_f32 v98, v104, v105
	v_or_b32_e32 v72, 48, v80
	v_mad_i64_i32 v[72:73], s[0:1], v72, s96, 0
	v_cvt_pk_f16_f32 v97, v110, v111
	v_cvt_pk_f16_f32 v96, v108, v109
	v_lshl_add_u64 v[76:77], v[72:73], 1, v[82:83]
	v_cvt_pk_f16_f32 v63, v62, v63
	v_cvt_pk_f16_f32 v62, v60, v61
	v_cvt_pk_f16_f32 v61, v70, v71
	v_cvt_pk_f16_f32 v60, v68, v69
	global_store_dwordx4 v[86:87], v[96:99], off sc1
	global_store_dwordx4 v[76:77], v[60:63], off offset:256 sc1
	v_cvt_pk_f16_f32 v75, v90, v91
	v_cvt_pk_f16_f32 v74, v88, v89
	v_add_u32_e32 v60, 0x80, v80
	v_mad_i64_i32 v[60:61], s[0:1], v60, s96, 0
	v_cvt_pk_f16_f32 v73, v94, v95
	v_cvt_pk_f16_f32 v72, v92, v93
	v_lshl_add_u64 v[60:61], v[60:61], 1, v[82:83]
	v_cvt_pk_f16_f32 v43, v42, v43
	v_cvt_pk_f16_f32 v42, v40, v41
	v_cvt_pk_f16_f32 v41, v46, v47
	v_cvt_pk_f16_f32 v40, v44, v45
	global_store_dwordx4 v[76:77], v[72:75], off sc1
	global_store_dwordx4 v[60:61], v[40:43], off offset:256 sc1
	v_cvt_pk_f16_f32 v59, v58, v59
	v_cvt_pk_f16_f32 v58, v56, v57
	v_add_u32_e32 v40, 0x90, v80
	v_mad_i64_i32 v[40:41], s[0:1], v40, s96, 0
	v_cvt_pk_f16_f32 v57, v66, v67
	v_cvt_pk_f16_f32 v56, v64, v65
	v_lshl_add_u64 v[44:45], v[40:41], 1, v[82:83]
	v_cvt_pk_f16_f32 v27, v26, v27
	v_cvt_pk_f16_f32 v26, v24, v25
	v_cvt_pk_f16_f32 v25, v30, v31
	v_cvt_pk_f16_f32 v24, v28, v29
	global_store_dwordx4 v[60:61], v[56:59], off sc1
	global_store_dwordx4 v[44:45], v[24:27], off offset:256 sc1
	v_cvt_pk_f16_f32 v43, v50, v51
	v_cvt_pk_f16_f32 v42, v48, v49
	v_add_u32_e32 v24, 0xa0, v80
	v_mad_i64_i32 v[24:25], s[0:1], v24, s96, 0
	v_cvt_pk_f16_f32 v41, v54, v55
	v_cvt_pk_f16_f32 v40, v52, v53
	v_lshl_add_u64 v[28:29], v[24:25], 1, v[82:83]
	v_cvt_pk_f16_f32 v11, v10, v11
	v_cvt_pk_f16_f32 v10, v8, v9
	v_cvt_pk_f16_f32 v9, v14, v15
	v_cvt_pk_f16_f32 v8, v12, v13
	global_store_dwordx4 v[44:45], v[40:43], off sc1
	global_store_dwordx4 v[28:29], v[8:11], off offset:256 sc1
	v_cvt_pk_f16_f32 v27, v34, v35
	v_cvt_pk_f16_f32 v26, v32, v33
	v_add_u32_e32 v8, 0xb0, v80
	v_mad_i64_i32 v[8:9], s[0:1], v8, s96, 0
	v_cvt_pk_f16_f32 v25, v38, v39
	v_cvt_pk_f16_f32 v24, v36, v37
	v_lshl_add_u64 v[12:13], v[8:9], 1, v[82:83]
	v_cvt_pk_f16_f32 v11, v18, v19
	v_cvt_pk_f16_f32 v10, v16, v17
	v_cvt_pk_f16_f32 v9, v22, v23
	v_cvt_pk_f16_f32 v8, v20, v21
	v_cvt_pk_f16_f32 v3, v2, v3
	v_cvt_pk_f16_f32 v2, v0, v1
	v_cvt_pk_f16_f32 v1, v6, v7
	v_cvt_pk_f16_f32 v0, v4, v5
	global_store_dwordx4 v[28:29], v[24:27], off sc1
	global_store_dwordx4 v[12:13], v[8:11], off sc1
	global_store_dwordx4 v[12:13], v[0:3], off offset:256 sc1
	s_and_b64 vcc, exec, s[36:37]
	s_cbranch_vccz .LBB0_496

; __device__ __forceinline__ void epi_fuse(const f32x4 (&acc)[2][2][4][2], const Args& a, const Job& J, int pm, int pn, int wr, int wc, int fr, int fq, int wid, int lane, LAS unsigned char* pst) {
;     ...
;     for (int bj = 0; bj < 2; ++bj) {
;         f32x4 bv[2], hv[2];
; #pragma unroll
;         for (int n = 0; n < 2; ++n) {
;             if (bj == 1 && do_norm) { mg[n] = *(const f32x4*)(gB + HALF + 4 * n); ms[n] = *(const f32x4*)(modn + so + col0 + HALF + 4 * n); mh[n] = *(const f32x4*)(modn + ho + col0 + HALF + 4 * n); } }
;         if (bj == 1) __builtin_amdgcn_sched_barrier(0);
; #pragma unroll
;         for (int n = 0; n < 2; ++n) { bv[n] = mg[n] * (ms[n] + 1.0f); hv[n] = mh[n]; }
; #pragma unroll
;         for (int h = 0; h < 4; ++h) {
;             const int stp = bj * 4 + h, ai = h >> 1, m0 = (h & 1) * 2;
;             if (stp + 1 < 8) { const int bj2 = (stp + 1) >> 2, h2 = (stp + 1) & 3, ai2 = h2 >> 1, m2 = (h2 & 1) * 2;
; #pragma unroll
;                 for (int mm = 0; mm < 2; ++mm) xq2[(stp + 1) & 1][mm] = *(const f16x8*)(xh + 2u * (e0 + (unsigned)((ai2 * HALF + (m2 + mm) * 16) * DM + bj2 * HALF))); }
;             __builtin_amdgcn_sched_barrier(0);
; #pragma unroll
;             for (int mm = 0; mm < 2; ++mm) {
;                 const int m = m0 + mm;
;                 const int rl = ai * HALF + wr * 64 + m * 16 + fr; const float rs1 = S[2 * rl], rs2 = S[2 * rl + 1];
;                 const unsigned eo = e0 + (unsigned)((ai * HALF + m * 16) * DM + bj * HALF);
;                 const f16x8 xq = xq2[stp & 1][mm];
;                 f32x4 x1[2];
;                 x1[0] = __builtin_convertvector((f16x4){xq[0], xq[1], xq[2], xq[3]}, f32x4) + gv[bj][0] * (acc[ai][bj][m][0] * rs1);
;                 x1[1] = __builtin_convertvector((f16x4){xq[4], xq[5], xq[6], xq[7]}, f32x4) + gv[bj][1] * (acc[ai][bj][m][1] * rs1);
;                 if (do_norm) {
;                     const f16x4 h0 = __builtin_convertvector(x1[0], f16x4), h1 = __builtin_convertvector(x1[1], f16x4);
;                     *(f16x8*)(xo16 + 2u * eo) = (f16x8){h0[0], h0[1], h0[2], h0[3], h1[0], h1[1], h1[2], h1[3]};
;                     *(u32x4*)(HXo + 2u * eo) = pack8(x1[0] * rs2 * bv[0] + hv[0], x1[1] * rs2 * bv[1] + hv[1]);
.LBB0_342:
	v_pk_add_f32 v[200:201], v[150:151], 1.0 op_sel_hi:[1,0]
	v_pk_add_f32 v[202:203], v[148:149], 1.0 op_sel_hi:[1,0]
	v_pk_mul_f32 v[220:221], v[146:147], v[200:201]
	v_pk_mul_f32 v[222:223], v[144:145], v[202:203]
	v_pk_mul_f32 v[210:211], v[162:163], v[210:211]
	s_andn2_b64 vcc, exec, s[12:13]
	v_pk_mul_f32 v[212:213], v[160:161], v[212:213]
	s_movk_i32 s46, 0x1600
	v_readlane_b32 s47, v254, 38
	v_readlane_b32 s55, v254, 15
	s_cbranch_vccnz .LBB0_344
	s_add_i32 s12, 0, 0x24400
	v_add_u32_e32 v160, s12, v189
	ds_read_b32 v200, v160 offset:4
	v_cvt_pk_f16_f32 v163, v170, v171
	v_cvt_pk_f16_f32 v162, v168, v169
	v_cvt_pk_f16_f32 v161, v174, v175
	v_cvt_pk_f16_f32 v160, v172, v173
	global_store_dwordx4 v[224:225], v[160:163], off sc1
	s_waitcnt lgkmcnt(0)
	v_pk_mul_f32 v[168:169], v[168:169], v[200:201] op_sel_hi:[1,0]
	v_readlane_b32 s12, v252, 6
	v_pk_mul_f32 v[160:161], v[174:175], v[200:201] op_sel_hi:[1,0]
	v_pk_mul_f32 v[162:163], v[172:173], v[200:201] op_sel_hi:[1,0]
	v_pk_fma_f32 v[172:173], v[220:221], v[160:161], v[138:139]
	v_pk_fma_f32 v[160:161], v[222:223], v[162:163], v[136:137]
	v_pk_mul_f32 v[162:163], v[170:171], v[200:201] op_sel_hi:[1,0]
	v_readlane_b32 s13, v252, 7
	v_pk_fma_f32 v[170:171], v[210:211], v[162:163], v[142:143]
	v_pk_fma_f32 v[162:163], v[212:213], v[168:169], v[140:141]
	v_cvt_pk_bf16_f32 v160, v160, v161
	v_cvt_pk_bf16_f32 v161, v172, v173
	v_cvt_pk_bf16_f32 v162, v162, v163
	v_cvt_pk_bf16_f32 v163, v170, v171
	v_lshl_add_u64 v[168:169], s[12:13], 0, v[80:81]
	global_store_dwordx4 v[168:169], v[160:163], off sc1

; __device__ __forceinline__ u32x4 pack8(const f32x4& a, const f32x4& b) { u32x4 w; w.x = cvt_pk_bf16(a[0], a[1]); w.y = cvt_pk_bf16(a[2], a[3]); w.z = cvt_pk_bf16(b[0], b[1]); w.w = cvt_pk_bf16(b[2], b[3]); return w; }
; __device__ __forceinline__ void epi_fuse(const f32x4 (&acc)[2][2][4][2], const Args& a, const Job& J, int pm, int pn, int wr, int wc, int fr, int fq, int wid, int lane, LAS unsigned char* pst) {
;     ...
;             for (int mm = 0; mm < 2; ++mm) {
;                 const int m = m0 + mm;
;                 const int rl = ai * HALF + wr * 64 + m * 16 + fr; const float rs1 = S[2 * rl], rs2 = S[2 * rl + 1];
;                 const unsigned eo = e0 + (unsigned)((ai * HALF + m * 16) * DM + bj * HALF);
;                 const f16x8 xq = xq2[stp & 1][mm];
;                 f32x4 x1[2];
;                 x1[0] = __builtin_convertvector((f16x4){xq[0], xq[1], xq[2], xq[3]}, f32x4) + gv[bj][0] * (acc[ai][bj][m][0] * rs1);
;                 x1[1] = __builtin_convertvector((f16x4){xq[4], xq[5], xq[6], xq[7]}, f32x4) + gv[bj][1] * (acc[ai][bj][m][1] * rs1);
;                 if (do_norm) {
;                     const f16x4 h0 = __builtin_convertvector(x1[0], f16x4), h1 = __builtin_convertvector(x1[1], f16x4);
;                     *(f16x8*)(xo16 + 2u * eo) = (f16x8){h0[0], h0[1], h0[2], h0[3], h1[0], h1[1], h1[2], h1[3]};
;                     *(u32x4*)(HXo + 2u * eo) = pack8(x1[0] * rs2 * bv[0] + hv[0], x1[1] * rs2 * bv[1] + hv[1]);
;                 } else { __builtin_nontemporal_store(x1[0], (f32x4*)(xo32 + 4u * eo)); __builtin_nontemporal_store(x1[1], (f32x4*)(xo32 + 4u * (eo + 4))); }
.LBB0_346:
	s_andn2_b64 vcc, exec, s[12:13]
	s_cbranch_vccnz .LBB0_348
	ds_read_b32 v174, v80 offset:132
	v_lshlrev_b32_e32 v175, 1, v168
	v_cvt_pk_f16_f32 v173, v154, v155
	v_cvt_pk_f16_f32 v172, v152, v153
	v_cvt_pk_f16_f32 v171, v162, v163
	v_cvt_pk_f16_f32 v170, v160, v161
	s_waitcnt lgkmcnt(0)
	v_pk_mul_f32 v[162:163], v[162:163], v[174:175] op_sel_hi:[1,0]
	v_pk_mul_f32 v[160:161], v[160:161], v[174:175] op_sel_hi:[1,0]
	v_pk_mul_f32 v[154:155], v[154:155], v[174:175] op_sel_hi:[1,0]
	v_pk_mul_f32 v[152:153], v[152:153], v[174:175] op_sel_hi:[1,0]
	v_pk_fma_f32 v[162:163], v[220:221], v[162:163], v[138:139]
	v_pk_fma_f32 v[160:161], v[222:223], v[160:161], v[136:137]
	v_pk_fma_f32 v[168:169], v[210:211], v[154:155], v[142:143]
	v_pk_fma_f32 v[154:155], v[212:213], v[152:153], v[140:141]
	v_readlane_b32 s12, v252, 6
	v_cvt_pk_bf16_f32 v152, v160, v161
	v_cvt_pk_bf16_f32 v153, v162, v163
	v_cvt_pk_bf16_f32 v154, v154, v155
	v_cvt_pk_bf16_f32 v155, v168, v169
	v_readlane_b32 s13, v252, 7
	global_store_dwordx4 v175, v[170:173], s[0:1] sc1
	s_nop 3
	global_store_dwordx4 v175, v[152:155], s[12:13] sc1

; __device__ __forceinline__ u32x4 pack8(const f32x4& a, const f32x4& b) { u32x4 w; w.x = cvt_pk_bf16(a[0], a[1]); w.y = cvt_pk_bf16(a[2], a[3]); w.z = cvt_pk_bf16(b[0], b[1]); w.w = cvt_pk_bf16(b[2], b[3]); return w; }
; __device__ __forceinline__ void epi_fuse(const f32x4 (&acc)[2][2][4][2], const Args& a, const Job& J, int pm, int pn, int wr, int wc, int fr, int fq, int wid, int lane, LAS unsigned char* pst) {
;     ...
;             for (int mm = 0; mm < 2; ++mm) {
;                 const int m = m0 + mm;
;                 const int rl = ai * HALF + wr * 64 + m * 16 + fr; const float rs1 = S[2 * rl], rs2 = S[2 * rl + 1];
;                 const unsigned eo = e0 + (unsigned)((ai * HALF + m * 16) * DM + bj * HALF);
;                 const f16x8 xq = xq2[stp & 1][mm];
;                 f32x4 x1[2];
;                 x1[0] = __builtin_convertvector((f16x4){xq[0], xq[1], xq[2], xq[3]}, f32x4) + gv[bj][0] * (acc[ai][bj][m][0] * rs1);
;                 x1[1] = __builtin_convertvector((f16x4){xq[4], xq[5], xq[6], xq[7]}, f32x4) + gv[bj][1] * (acc[ai][bj][m][1] * rs1);
;                 if (do_norm) {
;                     const f16x4 h0 = __builtin_convertvector(x1[0], f16x4), h1 = __builtin_convertvector(x1[1], f16x4);
;                     *(f16x8*)(xo16 + 2u * eo) = (f16x8){h0[0], h0[1], h0[2], h0[3], h1[0], h1[1], h1[2], h1[3]};
;                     *(u32x4*)(HXo + 2u * eo) = pack8(x1[0] * rs2 * bv[0] + hv[0], x1[1] * rs2 * bv[1] + hv[1]);
;                 } else { __builtin_nontemporal_store(x1[0], (f32x4*)(xo32 + 4u * eo)); __builtin_nontemporal_store(x1[1], (f32x4*)(xo32 + 4u * (eo + 4))); }
.LBB0_350:
	s_andn2_b64 vcc, exec, s[12:13]
	s_cbranch_vccnz .LBB0_352
	ds_read_b32 v174, v80 offset:260
	v_lshlrev_b32_e32 v175, 1, v172
	v_cvt_pk_f16_f32 v203, v166, v167
	v_cvt_pk_f16_f32 v202, v164, v165
	v_cvt_pk_f16_f32 v201, v170, v171
	v_cvt_pk_f16_f32 v200, v168, v169
	s_waitcnt lgkmcnt(0)
	v_pk_mul_f32 v[170:171], v[170:171], v[174:175] op_sel_hi:[1,0]
	v_pk_mul_f32 v[168:169], v[168:169], v[174:175] op_sel_hi:[1,0]
	v_pk_mul_f32 v[166:167], v[166:167], v[174:175] op_sel_hi:[1,0]
	v_pk_mul_f32 v[164:165], v[164:165], v[174:175] op_sel_hi:[1,0]
	v_pk_fma_f32 v[170:171], v[220:221], v[170:171], v[138:139]
	v_pk_fma_f32 v[168:169], v[222:223], v[168:169], v[136:137]
	v_pk_fma_f32 v[172:173], v[210:211], v[166:167], v[142:143]
	v_pk_fma_f32 v[166:167], v[212:213], v[164:165], v[140:141]
	v_readlane_b32 s12, v252, 6
	v_cvt_pk_bf16_f32 v164, v168, v169
	v_cvt_pk_bf16_f32 v165, v170, v171
	v_cvt_pk_bf16_f32 v166, v166, v167
	v_cvt_pk_bf16_f32 v167, v172, v173
	v_readlane_b32 s13, v252, 7
	global_store_dwordx4 v175, v[200:203], s[0:1] sc1
	s_nop 3
	global_store_dwordx4 v175, v[164:167], s[12:13] sc1

; __device__ __forceinline__ u32x4 pack8(const f32x4& a, const f32x4& b) { u32x4 w; w.x = cvt_pk_bf16(a[0], a[1]); w.y = cvt_pk_bf16(a[2], a[3]); w.z = cvt_pk_bf16(b[0], b[1]); w.w = cvt_pk_bf16(b[2], b[3]); return w; }
; __device__ __forceinline__ void epi_fuse(const f32x4 (&acc)[2][2][4][2], const Args& a, const Job& J, int pm, int pn, int wr, int wc, int fr, int fq, int wid, int lane, LAS unsigned char* pst) {
;     ...
;             for (int mm = 0; mm < 2; ++mm) {
;                 const int m = m0 + mm;
;                 const int rl = ai * HALF + wr * 64 + m * 16 + fr; const float rs1 = S[2 * rl], rs2 = S[2 * rl + 1];
;                 const unsigned eo = e0 + (unsigned)((ai * HALF + m * 16) * DM + bj * HALF);
;                 const f16x8 xq = xq2[stp & 1][mm];
;                 f32x4 x1[2];
;                 x1[0] = __builtin_convertvector((f16x4){xq[0], xq[1], xq[2], xq[3]}, f32x4) + gv[bj][0] * (acc[ai][bj][m][0] * rs1);
;                 x1[1] = __builtin_convertvector((f16x4){xq[4], xq[5], xq[6], xq[7]}, f32x4) + gv[bj][1] * (acc[ai][bj][m][1] * rs1);
;                 if (do_norm) {
;                     const f16x4 h0 = __builtin_convertvector(x1[0], f16x4), h1 = __builtin_convertvector(x1[1], f16x4);
;                     *(f16x8*)(xo16 + 2u * eo) = (f16x8){h0[0], h0[1], h0[2], h0[3], h1[0], h1[1], h1[2], h1[3]};
;                     *(u32x4*)(HXo + 2u * eo) = pack8(x1[0] * rs2 * bv[0] + hv[0], x1[1] * rs2 * bv[1] + hv[1]);
;                 } else { __builtin_nontemporal_store(x1[0], (f32x4*)(xo32 + 4u * eo)); __builtin_nontemporal_store(x1[1], (f32x4*)(xo32 + 4u * (eo + 4))); }
.LBB0_354:
	s_andn2_b64 vcc, exec, s[12:13]
	s_cbranch_vccnz .LBB0_356
	ds_read_b32 v174, v80 offset:388
	v_lshlrev_b32_e32 v175, 1, v168
	v_cvt_pk_f16_f32 v173, v158, v159
	v_cvt_pk_f16_f32 v172, v156, v157
	v_cvt_pk_f16_f32 v171, v166, v167
	v_cvt_pk_f16_f32 v170, v164, v165
	s_waitcnt lgkmcnt(0)
	v_pk_mul_f32 v[166:167], v[166:167], v[174:175] op_sel_hi:[1,0]
	v_pk_mul_f32 v[164:165], v[164:165], v[174:175] op_sel_hi:[1,0]
	v_pk_mul_f32 v[158:159], v[158:159], v[174:175] op_sel_hi:[1,0]
	v_pk_mul_f32 v[156:157], v[156:157], v[174:175] op_sel_hi:[1,0]
	v_pk_fma_f32 v[166:167], v[220:221], v[166:167], v[138:139]
	v_pk_fma_f32 v[164:165], v[222:223], v[164:165], v[136:137]
	v_pk_fma_f32 v[168:169], v[210:211], v[158:159], v[142:143]
	v_pk_fma_f32 v[158:159], v[212:213], v[156:157], v[140:141]
	v_readlane_b32 s12, v252, 6
	v_cvt_pk_bf16_f32 v156, v164, v165
	v_cvt_pk_bf16_f32 v157, v166, v167
	v_cvt_pk_bf16_f32 v158, v158, v159
	v_cvt_pk_bf16_f32 v159, v168, v169
	v_readlane_b32 s13, v252, 7
	global_store_dwordx4 v175, v[170:173], s[0:1] sc1
	s_nop 3
	global_store_dwordx4 v175, v[156:159], s[12:13] sc1

; __device__ __forceinline__ u32x4 pack8(const f32x4& a, const f32x4& b) { u32x4 w; w.x = cvt_pk_bf16(a[0], a[1]); w.y = cvt_pk_bf16(a[2], a[3]); w.z = cvt_pk_bf16(b[0], b[1]); w.w = cvt_pk_bf16(b[2], b[3]); return w; }
; __device__ __forceinline__ void epi_fuse(const f32x4 (&acc)[2][2][4][2], const Args& a, const Job& J, int pm, int pn, int wr, int wc, int fr, int fq, int wid, int lane, LAS unsigned char* pst) {
;     ...
;             for (int mm = 0; mm < 2; ++mm) {
;                 const int m = m0 + mm;
;                 const int rl = ai * HALF + wr * 64 + m * 16 + fr; const float rs1 = S[2 * rl], rs2 = S[2 * rl + 1];
;                 const unsigned eo = e0 + (unsigned)((ai * HALF + m * 16) * DM + bj * HALF);
;                 const f16x8 xq = xq2[stp & 1][mm];
;                 f32x4 x1[2];
;                 x1[0] = __builtin_convertvector((f16x4){xq[0], xq[1], xq[2], xq[3]}, f32x4) + gv[bj][0] * (acc[ai][bj][m][0] * rs1);
;                 x1[1] = __builtin_convertvector((f16x4){xq[4], xq[5], xq[6], xq[7]}, f32x4) + gv[bj][1] * (acc[ai][bj][m][1] * rs1);
;                 if (do_norm) {
;                     const f16x4 h0 = __builtin_convertvector(x1[0], f16x4), h1 = __builtin_convertvector(x1[1], f16x4);
;                     *(f16x8*)(xo16 + 2u * eo) = (f16x8){h0[0], h0[1], h0[2], h0[3], h1[0], h1[1], h1[2], h1[3]};
;                     *(u32x4*)(HXo + 2u * eo) = pack8(x1[0] * rs2 * bv[0] + hv[0], x1[1] * rs2 * bv[1] + hv[1]);
;                 } else { __builtin_nontemporal_store(x1[0], (f32x4*)(xo32 + 4u * eo)); __builtin_nontemporal_store(x1[1], (f32x4*)(xo32 + 4u * (eo + 4))); }
.LBB0_358:
	s_andn2_b64 vcc, exec, s[12:13]
	s_cbranch_vccnz .LBB0_360
	ds_read_b32 v174, v80 offset:1028
	v_cvt_pk_f16_f32 v203, v162, v163
	v_cvt_pk_f16_f32 v202, v160, v161
	v_cvt_pk_f16_f32 v201, v170, v171
	v_cvt_pk_f16_f32 v200, v168, v169
	s_waitcnt lgkmcnt(0)
	v_pk_mul_f32 v[170:171], v[170:171], v[174:175] op_sel_hi:[1,0]
	v_pk_mul_f32 v[168:169], v[168:169], v[174:175] op_sel_hi:[1,0]
	v_pk_mul_f32 v[162:163], v[162:163], v[174:175] op_sel_hi:[1,0]
	v_pk_mul_f32 v[160:161], v[160:161], v[174:175] op_sel_hi:[1,0]
	v_pk_fma_f32 v[170:171], v[220:221], v[170:171], v[138:139]
	v_pk_fma_f32 v[168:169], v[222:223], v[168:169], v[136:137]
	v_pk_fma_f32 v[174:175], v[210:211], v[162:163], v[142:143]
	v_pk_fma_f32 v[162:163], v[212:213], v[160:161], v[140:141]
	v_readlane_b32 s12, v252, 6
	v_cvt_pk_bf16_f32 v160, v168, v169
	v_cvt_pk_bf16_f32 v161, v170, v171
	v_cvt_pk_bf16_f32 v162, v162, v163
	v_cvt_pk_bf16_f32 v163, v174, v175
	v_readlane_b32 s13, v252, 7
	global_store_dwordx4 v172, v[200:203], s[0:1] sc1
	s_nop 3
	global_store_dwordx4 v172, v[160:163], s[12:13] sc1

; __device__ __forceinline__ u32x4 pack8(const f32x4& a, const f32x4& b) { u32x4 w; w.x = cvt_pk_bf16(a[0], a[1]); w.y = cvt_pk_bf16(a[2], a[3]); w.z = cvt_pk_bf16(b[0], b[1]); w.w = cvt_pk_bf16(b[2], b[3]); return w; }
; __device__ __forceinline__ void epi_fuse(const f32x4 (&acc)[2][2][4][2], const Args& a, const Job& J, int pm, int pn, int wr, int wc, int fr, int fq, int wid, int lane, LAS unsigned char* pst) {
;     ...
;             for (int mm = 0; mm < 2; ++mm) {
;                 const int m = m0 + mm;
;                 const int rl = ai * HALF + wr * 64 + m * 16 + fr; const float rs1 = S[2 * rl], rs2 = S[2 * rl + 1];
;                 const unsigned eo = e0 + (unsigned)((ai * HALF + m * 16) * DM + bj * HALF);
;                 const f16x8 xq = xq2[stp & 1][mm];
;                 f32x4 x1[2];
;                 x1[0] = __builtin_convertvector((f16x4){xq[0], xq[1], xq[2], xq[3]}, f32x4) + gv[bj][0] * (acc[ai][bj][m][0] * rs1);
;                 x1[1] = __builtin_convertvector((f16x4){xq[4], xq[5], xq[6], xq[7]}, f32x4) + gv[bj][1] * (acc[ai][bj][m][1] * rs1);
;                 if (do_norm) {
;                     const f16x4 h0 = __builtin_convertvector(x1[0], f16x4), h1 = __builtin_convertvector(x1[1], f16x4);
;                     *(f16x8*)(xo16 + 2u * eo) = (f16x8){h0[0], h0[1], h0[2], h0[3], h1[0], h1[1], h1[2], h1[3]};
;                     *(u32x4*)(HXo + 2u * eo) = pack8(x1[0] * rs2 * bv[0] + hv[0], x1[1] * rs2 * bv[1] + hv[1]);
;                 } else { __builtin_nontemporal_store(x1[0], (f32x4*)(xo32 + 4u * eo)); __builtin_nontemporal_store(x1[1], (f32x4*)(xo32 + 4u * (eo + 4))); }
.LBB0_362:
	s_andn2_b64 vcc, exec, s[12:13]
	s_cbranch_vccnz .LBB0_364
	ds_read_b32 v174, v80 offset:1156
	v_lshlrev_b32_e32 v175, 1, v168
	v_cvt_pk_f16_f32 v173, v154, v155
	v_cvt_pk_f16_f32 v172, v152, v153
	v_cvt_pk_f16_f32 v171, v162, v163
	v_cvt_pk_f16_f32 v170, v160, v161
	s_waitcnt lgkmcnt(0)
	v_pk_mul_f32 v[162:163], v[162:163], v[174:175] op_sel_hi:[1,0]
	v_pk_mul_f32 v[160:161], v[160:161], v[174:175] op_sel_hi:[1,0]
	v_pk_mul_f32 v[154:155], v[154:155], v[174:175] op_sel_hi:[1,0]
	v_pk_mul_f32 v[152:153], v[152:153], v[174:175] op_sel_hi:[1,0]
	v_pk_fma_f32 v[162:163], v[220:221], v[162:163], v[138:139]
	v_pk_fma_f32 v[160:161], v[222:223], v[160:161], v[136:137]
	v_pk_fma_f32 v[168:169], v[210:211], v[154:155], v[142:143]
	v_pk_fma_f32 v[154:155], v[212:213], v[152:153], v[140:141]
	v_readlane_b32 s12, v252, 6
	v_cvt_pk_bf16_f32 v152, v160, v161
	v_cvt_pk_bf16_f32 v153, v162, v163
	v_cvt_pk_bf16_f32 v154, v154, v155
	v_cvt_pk_bf16_f32 v155, v168, v169
	v_readlane_b32 s13, v252, 7
	global_store_dwordx4 v175, v[170:173], s[0:1] sc1
	s_nop 3
	global_store_dwordx4 v175, v[152:155], s[12:13] sc1

; __device__ __forceinline__ u32x4 pack8(const f32x4& a, const f32x4& b) { u32x4 w; w.x = cvt_pk_bf16(a[0], a[1]); w.y = cvt_pk_bf16(a[2], a[3]); w.z = cvt_pk_bf16(b[0], b[1]); w.w = cvt_pk_bf16(b[2], b[3]); return w; }
; __device__ __forceinline__ void epi_fuse(const f32x4 (&acc)[2][2][4][2], const Args& a, const Job& J, int pm, int pn, int wr, int wc, int fr, int fq, int wid, int lane, LAS unsigned char* pst) {
;     ...
;             for (int mm = 0; mm < 2; ++mm) {
;                 const int m = m0 + mm;
;                 const int rl = ai * HALF + wr * 64 + m * 16 + fr; const float rs1 = S[2 * rl], rs2 = S[2 * rl + 1];
;                 const unsigned eo = e0 + (unsigned)((ai * HALF + m * 16) * DM + bj * HALF);
;                 const f16x8 xq = xq2[stp & 1][mm];
;                 f32x4 x1[2];
;                 x1[0] = __builtin_convertvector((f16x4){xq[0], xq[1], xq[2], xq[3]}, f32x4) + gv[bj][0] * (acc[ai][bj][m][0] * rs1);
;                 x1[1] = __builtin_convertvector((f16x4){xq[4], xq[5], xq[6], xq[7]}, f32x4) + gv[bj][1] * (acc[ai][bj][m][1] * rs1);
;                 if (do_norm) {
;                     const f16x4 h0 = __builtin_convertvector(x1[0], f16x4), h1 = __builtin_convertvector(x1[1], f16x4);
;                     *(f16x8*)(xo16 + 2u * eo) = (f16x8){h0[0], h0[1], h0[2], h0[3], h1[0], h1[1], h1[2], h1[3]};
;                     *(u32x4*)(HXo + 2u * eo) = pack8(x1[0] * rs2 * bv[0] + hv[0], x1[1] * rs2 * bv[1] + hv[1]);
;                 } else { __builtin_nontemporal_store(x1[0], (f32x4*)(xo32 + 4u * eo)); __builtin_nontemporal_store(x1[1], (f32x4*)(xo32 + 4u * (eo + 4))); }
.LBB0_366:
	s_andn2_b64 vcc, exec, s[12:13]
	s_cbranch_vccnz .LBB0_368
	ds_read_b32 v174, v80 offset:1284
	v_lshlrev_b32_e32 v175, 1, v172
	v_cvt_pk_f16_f32 v191, v166, v167
	v_cvt_pk_f16_f32 v190, v164, v165
	v_cvt_pk_f16_f32 v189, v170, v171
	v_cvt_pk_f16_f32 v188, v168, v169
	s_waitcnt lgkmcnt(0)
	v_pk_mul_f32 v[170:171], v[170:171], v[174:175] op_sel_hi:[1,0]
	v_pk_mul_f32 v[168:169], v[168:169], v[174:175] op_sel_hi:[1,0]
	v_pk_mul_f32 v[166:167], v[166:167], v[174:175] op_sel_hi:[1,0]
	v_pk_mul_f32 v[164:165], v[164:165], v[174:175] op_sel_hi:[1,0]
	v_pk_fma_f32 v[170:171], v[220:221], v[170:171], v[138:139]
	v_pk_fma_f32 v[168:169], v[222:223], v[168:169], v[136:137]
	v_pk_fma_f32 v[172:173], v[210:211], v[166:167], v[142:143]
	v_pk_fma_f32 v[166:167], v[212:213], v[164:165], v[140:141]
	v_readlane_b32 s12, v252, 6
	v_cvt_pk_bf16_f32 v164, v168, v169
	v_cvt_pk_bf16_f32 v165, v170, v171
	v_cvt_pk_bf16_f32 v166, v166, v167
	v_cvt_pk_bf16_f32 v167, v172, v173
	v_readlane_b32 s13, v252, 7
	global_store_dwordx4 v175, v[188:191], s[0:1] sc1
	s_nop 3
	global_store_dwordx4 v175, v[164:167], s[12:13] sc1

; __device__ __forceinline__ u32x4 pack8(const f32x4& a, const f32x4& b) { u32x4 w; w.x = cvt_pk_bf16(a[0], a[1]); w.y = cvt_pk_bf16(a[2], a[3]); w.z = cvt_pk_bf16(b[0], b[1]); w.w = cvt_pk_bf16(b[2], b[3]); return w; }
; __device__ __forceinline__ void epi_fuse(const f32x4 (&acc)[2][2][4][2], const Args& a, const Job& J, int pm, int pn, int wr, int wc, int fr, int fq, int wid, int lane, LAS unsigned char* pst) {
;     ...
;             for (int mm = 0; mm < 2; ++mm) {
;                 const int m = m0 + mm;
;                 const int rl = ai * HALF + wr * 64 + m * 16 + fr; const float rs1 = S[2 * rl], rs2 = S[2 * rl + 1];
;                 const unsigned eo = e0 + (unsigned)((ai * HALF + m * 16) * DM + bj * HALF);
;                 const f16x8 xq = xq2[stp & 1][mm];
;                 f32x4 x1[2];
;                 x1[0] = __builtin_convertvector((f16x4){xq[0], xq[1], xq[2], xq[3]}, f32x4) + gv[bj][0] * (acc[ai][bj][m][0] * rs1);
;                 x1[1] = __builtin_convertvector((f16x4){xq[4], xq[5], xq[6], xq[7]}, f32x4) + gv[bj][1] * (acc[ai][bj][m][1] * rs1);
;                 if (do_norm) {
;                     const f16x4 h0 = __builtin_convertvector(x1[0], f16x4), h1 = __builtin_convertvector(x1[1], f16x4);
;                     *(f16x8*)(xo16 + 2u * eo) = (f16x8){h0[0], h0[1], h0[2], h0[3], h1[0], h1[1], h1[2], h1[3]};
;                     *(u32x4*)(HXo + 2u * eo) = pack8(x1[0] * rs2 * bv[0] + hv[0], x1[1] * rs2 * bv[1] + hv[1]);
;                 } else { __builtin_nontemporal_store(x1[0], (f32x4*)(xo32 + 4u * eo)); __builtin_nontemporal_store(x1[1], (f32x4*)(xo32 + 4u * (eo + 4))); }
.LBB0_370:
	s_andn2_b64 vcc, exec, s[12:13]
	s_cbranch_vccnz .LBB0_372
	ds_read_b32 v174, v80 offset:1412
	v_lshlrev_b32_e32 v175, 1, v168
	v_cvt_pk_f16_f32 v173, v158, v159
	v_cvt_pk_f16_f32 v172, v156, v157
	v_cvt_pk_f16_f32 v171, v166, v167
	v_cvt_pk_f16_f32 v170, v164, v165
	s_waitcnt lgkmcnt(0)
	v_pk_mul_f32 v[166:167], v[166:167], v[174:175] op_sel_hi:[1,0]
	v_pk_mul_f32 v[164:165], v[164:165], v[174:175] op_sel_hi:[1,0]
	v_pk_mul_f32 v[158:159], v[158:159], v[174:175] op_sel_hi:[1,0]
	v_pk_mul_f32 v[156:157], v[156:157], v[174:175] op_sel_hi:[1,0]
	v_pk_fma_f32 v[166:167], v[220:221], v[166:167], v[138:139]
	v_pk_fma_f32 v[164:165], v[222:223], v[164:165], v[136:137]
	v_pk_fma_f32 v[168:169], v[210:211], v[158:159], v[142:143]
	v_pk_fma_f32 v[158:159], v[212:213], v[156:157], v[140:141]
	v_readlane_b32 s12, v252, 6
	v_cvt_pk_bf16_f32 v156, v164, v165
	v_cvt_pk_bf16_f32 v157, v166, v167
	v_cvt_pk_bf16_f32 v158, v158, v159
	v_cvt_pk_bf16_f32 v159, v168, v169
	v_readlane_b32 s13, v252, 7
	global_store_dwordx4 v175, v[170:173], s[0:1] sc1
	s_nop 3
	global_store_dwordx4 v175, v[156:159], s[12:13] sc1

; __device__ __forceinline__ void epi_fuse(const f32x4 (&acc)[2][2][4][2], const Args& a, const Job& J, int pm, int pn, int wr, int wc, int fr, int fq, int wid, int lane, LAS unsigned char* pst) {
;     ...
;     for (int bj = 0; bj < 2; ++bj) {
;         f32x4 bv[2], hv[2];
; #pragma unroll
;         for (int n = 0; n < 2; ++n) {
;             if (bj == 1 && do_norm) { mg[n] = *(const f32x4*)(gB + HALF + 4 * n); ms[n] = *(const f32x4*)(modn + so + col0 + HALF + 4 * n); mh[n] = *(const f32x4*)(modn + ho + col0 + HALF + 4 * n); } }
;         if (bj == 1) __builtin_amdgcn_sched_barrier(0);
; #pragma unroll
;         for (int n = 0; n < 2; ++n) { bv[n] = mg[n] * (ms[n] + 1.0f); hv[n] = mh[n]; }
; #pragma unroll
;         for (int h = 0; h < 4; ++h) {
;             const int stp = bj * 4 + h, ai = h >> 1, m0 = (h & 1) * 2;
;             if (stp + 1 < 8) { const int bj2 = (stp + 1) >> 2, h2 = (stp + 1) & 3, ai2 = h2 >> 1, m2 = (h2 & 1) * 2;
; #pragma unroll
;                 for (int mm = 0; mm < 2; ++mm) xq2[(stp + 1) & 1][mm] = *(const f16x8*)(xh + 2u * (e0 + (unsigned)((ai2 * HALF + (m2 + mm) * 16) * DM + bj2 * HALF))); }
;             __builtin_amdgcn_sched_barrier(0);
; #pragma unroll
;             for (int mm = 0; mm < 2; ++mm) {
;                 const int m = m0 + mm;
;                 const int rl = ai * HALF + wr * 64 + m * 16 + fr; const float rs1 = S[2 * rl], rs2 = S[2 * rl + 1];
;                 const unsigned eo = e0 + (unsigned)((ai * HALF + m * 16) * DM + bj * HALF);
;                 const f16x8 xq = xq2[stp & 1][mm];
;                 f32x4 x1[2];
;                 x1[0] = __builtin_convertvector((f16x4){xq[0], xq[1], xq[2], xq[3]}, f32x4) + gv[bj][0] * (acc[ai][bj][m][0] * rs1);
;                 x1[1] = __builtin_convertvector((f16x4){xq[4], xq[5], xq[6], xq[7]}, f32x4) + gv[bj][1] * (acc[ai][bj][m][1] * rs1);
;                 if (do_norm) {
;                     const f16x4 h0 = __builtin_convertvector(x1[0], f16x4), h1 = __builtin_convertvector(x1[1], f16x4);
;                     *(f16x8*)(xo16 + 2u * eo) = (f16x8){h0[0], h0[1], h0[2], h0[3], h1[0], h1[1], h1[2], h1[3]};
;                     *(u32x4*)(HXo + 2u * eo) = pack8(x1[0] * rs2 * bv[0] + hv[0], x1[1] * rs2 * bv[1] + hv[1]);
.LBB0_378:
	v_pk_add_f32 v[150:151], v[150:151], 1.0 op_sel_hi:[1,0]
	v_pk_add_f32 v[148:149], v[148:149], 1.0 op_sel_hi:[1,0]
	v_pk_mul_f32 v[172:173], v[146:147], v[150:151]
	s_andn2_b64 vcc, exec, s[12:13]
	v_pk_mul_f32 v[174:175], v[144:145], v[148:149]
	s_cbranch_vccnz .LBB0_380
	ds_read_b32 v148, v80 offset:4
	v_cvt_pk_f16_f32 v147, v162, v163
	v_cvt_pk_f16_f32 v146, v160, v161
	v_cvt_pk_f16_f32 v145, v170, v171
	v_cvt_pk_f16_f32 v144, v168, v169
	global_store_dwordx4 v180, v[144:147], s[0:1] sc1
	v_readlane_b32 s12, v252, 6
	v_readlane_b32 s13, v252, 7
	s_waitcnt lgkmcnt(0)
	v_pk_mul_f32 v[144:145], v[170:171], v[148:149] op_sel_hi:[1,0]
	v_pk_mul_f32 v[146:147], v[168:169], v[148:149] op_sel_hi:[1,0]
	s_waitcnt vmcnt(3)
	v_pk_fma_f32 v[150:151], v[172:173], v[144:145], v[138:139]
	v_pk_fma_f32 v[144:145], v[174:175], v[146:147], v[136:137]
	v_pk_mul_f32 v[146:147], v[162:163], v[148:149] op_sel_hi:[1,0]
	v_pk_mul_f32 v[148:149], v[160:161], v[148:149] op_sel_hi:[1,0]
	v_pk_fma_f32 v[160:161], v[210:211], v[146:147], v[142:143]
	v_pk_fma_f32 v[146:147], v[212:213], v[148:149], v[140:141]
	v_cvt_pk_bf16_f32 v144, v144, v145
	v_cvt_pk_bf16_f32 v145, v150, v151
	v_cvt_pk_bf16_f32 v146, v146, v147
	v_cvt_pk_bf16_f32 v147, v160, v161
	global_store_dwordx4 v180, v[144:147], s[12:13] sc1

; __device__ __forceinline__ u32x4 pack8(const f32x4& a, const f32x4& b) { u32x4 w; w.x = cvt_pk_bf16(a[0], a[1]); w.y = cvt_pk_bf16(a[2], a[3]); w.z = cvt_pk_bf16(b[0], b[1]); w.w = cvt_pk_bf16(b[2], b[3]); return w; }
; __device__ __forceinline__ void epi_fuse(const f32x4 (&acc)[2][2][4][2], const Args& a, const Job& J, int pm, int pn, int wr, int wc, int fr, int fq, int wid, int lane, LAS unsigned char* pst) {
;     ...
;             for (int mm = 0; mm < 2; ++mm) {
;                 const int m = m0 + mm;
;                 const int rl = ai * HALF + wr * 64 + m * 16 + fr; const float rs1 = S[2 * rl], rs2 = S[2 * rl + 1];
;                 const unsigned eo = e0 + (unsigned)((ai * HALF + m * 16) * DM + bj * HALF);
;                 const f16x8 xq = xq2[stp & 1][mm];
;                 f32x4 x1[2];
;                 x1[0] = __builtin_convertvector((f16x4){xq[0], xq[1], xq[2], xq[3]}, f32x4) + gv[bj][0] * (acc[ai][bj][m][0] * rs1);
;                 x1[1] = __builtin_convertvector((f16x4){xq[4], xq[5], xq[6], xq[7]}, f32x4) + gv[bj][1] * (acc[ai][bj][m][1] * rs1);
;                 if (do_norm) {
;                     const f16x4 h0 = __builtin_convertvector(x1[0], f16x4), h1 = __builtin_convertvector(x1[1], f16x4);
;                     *(f16x8*)(xo16 + 2u * eo) = (f16x8){h0[0], h0[1], h0[2], h0[3], h1[0], h1[1], h1[2], h1[3]};
;                     *(u32x4*)(HXo + 2u * eo) = pack8(x1[0] * rs2 * bv[0] + hv[0], x1[1] * rs2 * bv[1] + hv[1]);
;                 } else { __builtin_nontemporal_store(x1[0], (f32x4*)(xo32 + 4u * eo)); __builtin_nontemporal_store(x1[1], (f32x4*)(xo32 + 4u * (eo + 4))); }
.LBB0_382:
	s_andn2_b64 vcc, exec, s[12:13]
	s_cbranch_vccnz .LBB0_384
	ds_read_b32 v162, v80 offset:132
	v_cvt_pk_f16_f32 v155, v150, v151
	v_cvt_pk_f16_f32 v154, v148, v149
	v_cvt_pk_f16_f32 v153, v146, v147
	v_cvt_pk_f16_f32 v152, v144, v145
	s_waitcnt lgkmcnt(0)
	v_pk_mul_f32 v[146:147], v[146:147], v[162:163] op_sel_hi:[1,0]
	v_pk_mul_f32 v[144:145], v[144:145], v[162:163] op_sel_hi:[1,0]
	v_pk_mul_f32 v[150:151], v[150:151], v[162:163] op_sel_hi:[1,0]
	v_pk_mul_f32 v[148:149], v[148:149], v[162:163] op_sel_hi:[1,0]
	v_pk_fma_f32 v[146:147], v[172:173], v[146:147], v[138:139]
	v_pk_fma_f32 v[144:145], v[174:175], v[144:145], v[136:137]
	v_pk_fma_f32 v[150:151], v[210:211], v[150:151], v[142:143]
	v_pk_fma_f32 v[148:149], v[212:213], v[148:149], v[140:141]
	v_readlane_b32 s12, v252, 6
	v_lshlrev_b32_e32 v160, 1, v160
	v_cvt_pk_bf16_f32 v144, v144, v145
	v_cvt_pk_bf16_f32 v145, v146, v147
	v_cvt_pk_bf16_f32 v146, v148, v149
	v_cvt_pk_bf16_f32 v147, v150, v151
	v_readlane_b32 s13, v252, 7
	global_store_dwordx4 v160, v[152:155], s[0:1] sc1
	s_nop 3
	global_store_dwordx4 v160, v[144:147], s[12:13] sc1

; __device__ __forceinline__ u32x4 pack8(const f32x4& a, const f32x4& b) { u32x4 w; w.x = cvt_pk_bf16(a[0], a[1]); w.y = cvt_pk_bf16(a[2], a[3]); w.z = cvt_pk_bf16(b[0], b[1]); w.w = cvt_pk_bf16(b[2], b[3]); return w; }
; __device__ __forceinline__ void epi_fuse(const f32x4 (&acc)[2][2][4][2], const Args& a, const Job& J, int pm, int pn, int wr, int wc, int fr, int fq, int wid, int lane, LAS unsigned char* pst) {
;     ...
;             for (int mm = 0; mm < 2; ++mm) {
;                 const int m = m0 + mm;
;                 const int rl = ai * HALF + wr * 64 + m * 16 + fr; const float rs1 = S[2 * rl], rs2 = S[2 * rl + 1];
;                 const unsigned eo = e0 + (unsigned)((ai * HALF + m * 16) * DM + bj * HALF);
;                 const f16x8 xq = xq2[stp & 1][mm];
;                 f32x4 x1[2];
;                 x1[0] = __builtin_convertvector((f16x4){xq[0], xq[1], xq[2], xq[3]}, f32x4) + gv[bj][0] * (acc[ai][bj][m][0] * rs1);
;                 x1[1] = __builtin_convertvector((f16x4){xq[4], xq[5], xq[6], xq[7]}, f32x4) + gv[bj][1] * (acc[ai][bj][m][1] * rs1);
;                 if (do_norm) {
;                     const f16x4 h0 = __builtin_convertvector(x1[0], f16x4), h1 = __builtin_convertvector(x1[1], f16x4);
;                     *(f16x8*)(xo16 + 2u * eo) = (f16x8){h0[0], h0[1], h0[2], h0[3], h1[0], h1[1], h1[2], h1[3]};
;                     *(u32x4*)(HXo + 2u * eo) = pack8(x1[0] * rs2 * bv[0] + hv[0], x1[1] * rs2 * bv[1] + hv[1]);
;                 } else { __builtin_nontemporal_store(x1[0], (f32x4*)(xo32 + 4u * eo)); __builtin_nontemporal_store(x1[1], (f32x4*)(xo32 + 4u * (eo + 4))); }
.LBB0_386:
	s_andn2_b64 vcc, exec, s[12:13]
	s_cbranch_vccnz .LBB0_388
	ds_read_b32 v170, v80 offset:260
	v_cvt_pk_f16_f32 v167, v162, v163
	v_cvt_pk_f16_f32 v166, v160, v161
	v_cvt_pk_f16_f32 v165, v150, v151
	v_cvt_pk_f16_f32 v164, v148, v149
	s_waitcnt lgkmcnt(0)
	v_pk_mul_f32 v[150:151], v[150:151], v[170:171] op_sel_hi:[1,0]
	v_pk_mul_f32 v[148:149], v[148:149], v[170:171] op_sel_hi:[1,0]
	v_pk_mul_f32 v[162:163], v[162:163], v[170:171] op_sel_hi:[1,0]
	v_pk_mul_f32 v[160:161], v[160:161], v[170:171] op_sel_hi:[1,0]
	v_pk_fma_f32 v[150:151], v[172:173], v[150:151], v[138:139]
	v_pk_fma_f32 v[148:149], v[174:175], v[148:149], v[136:137]
	v_pk_fma_f32 v[162:163], v[210:211], v[162:163], v[142:143]
	v_pk_fma_f32 v[160:161], v[212:213], v[160:161], v[140:141]
	v_readlane_b32 s12, v252, 6
	v_lshlrev_b32_e32 v168, 1, v168
	v_cvt_pk_bf16_f32 v148, v148, v149
	v_cvt_pk_bf16_f32 v149, v150, v151
	v_cvt_pk_bf16_f32 v150, v160, v161
	v_cvt_pk_bf16_f32 v151, v162, v163
	v_readlane_b32 s13, v252, 7
	global_store_dwordx4 v168, v[164:167], s[0:1] sc1
	s_nop 3
	global_store_dwordx4 v168, v[148:151], s[12:13] sc1

; __device__ __forceinline__ u32x4 pack8(const f32x4& a, const f32x4& b) { u32x4 w; w.x = cvt_pk_bf16(a[0], a[1]); w.y = cvt_pk_bf16(a[2], a[3]); w.z = cvt_pk_bf16(b[0], b[1]); w.w = cvt_pk_bf16(b[2], b[3]); return w; }
; __device__ __forceinline__ void epi_fuse(const f32x4 (&acc)[2][2][4][2], const Args& a, const Job& J, int pm, int pn, int wr, int wc, int fr, int fq, int wid, int lane, LAS unsigned char* pst) {
;     ...
;             for (int mm = 0; mm < 2; ++mm) {
;                 const int m = m0 + mm;
;                 const int rl = ai * HALF + wr * 64 + m * 16 + fr; const float rs1 = S[2 * rl], rs2 = S[2 * rl + 1];
;                 const unsigned eo = e0 + (unsigned)((ai * HALF + m * 16) * DM + bj * HALF);
;                 const f16x8 xq = xq2[stp & 1][mm];
;                 f32x4 x1[2];
;                 x1[0] = __builtin_convertvector((f16x4){xq[0], xq[1], xq[2], xq[3]}, f32x4) + gv[bj][0] * (acc[ai][bj][m][0] * rs1);
;                 x1[1] = __builtin_convertvector((f16x4){xq[4], xq[5], xq[6], xq[7]}, f32x4) + gv[bj][1] * (acc[ai][bj][m][1] * rs1);
;                 if (do_norm) {
;                     const f16x4 h0 = __builtin_convertvector(x1[0], f16x4), h1 = __builtin_convertvector(x1[1], f16x4);
;                     *(f16x8*)(xo16 + 2u * eo) = (f16x8){h0[0], h0[1], h0[2], h0[3], h1[0], h1[1], h1[2], h1[3]};
;                     *(u32x4*)(HXo + 2u * eo) = pack8(x1[0] * rs2 * bv[0] + hv[0], x1[1] * rs2 * bv[1] + hv[1]);
;                 } else { __builtin_nontemporal_store(x1[0], (f32x4*)(xo32 + 4u * eo)); __builtin_nontemporal_store(x1[1], (f32x4*)(xo32 + 4u * (eo + 4))); }
.LBB0_390:
	s_andn2_b64 vcc, exec, s[12:13]
	s_cbranch_vccnz .LBB0_392
	ds_read_b32 v166, v80 offset:388
	v_cvt_pk_f16_f32 v165, v158, v159
	v_cvt_pk_f16_f32 v164, v156, v157
	v_cvt_pk_f16_f32 v163, v150, v151
	v_cvt_pk_f16_f32 v162, v148, v149
	s_waitcnt lgkmcnt(0)
	v_pk_mul_f32 v[150:151], v[150:151], v[166:167] op_sel_hi:[1,0]
	v_pk_mul_f32 v[148:149], v[148:149], v[166:167] op_sel_hi:[1,0]
	v_pk_mul_f32 v[158:159], v[158:159], v[166:167] op_sel_hi:[1,0]
	v_pk_mul_f32 v[156:157], v[156:157], v[166:167] op_sel_hi:[1,0]
	v_pk_fma_f32 v[150:151], v[172:173], v[150:151], v[138:139]
	v_pk_fma_f32 v[148:149], v[174:175], v[148:149], v[136:137]
	v_pk_fma_f32 v[158:159], v[210:211], v[158:159], v[142:143]
	v_pk_fma_f32 v[156:157], v[212:213], v[156:157], v[140:141]
	v_readlane_b32 s12, v252, 6
	v_lshlrev_b32_e32 v160, 1, v160
	v_cvt_pk_bf16_f32 v148, v148, v149
	v_cvt_pk_bf16_f32 v149, v150, v151
	v_cvt_pk_bf16_f32 v150, v156, v157
	v_cvt_pk_bf16_f32 v151, v158, v159
	v_readlane_b32 s13, v252, 7
	global_store_dwordx4 v160, v[162:165], s[0:1] sc1
	s_nop 3
	global_store_dwordx4 v160, v[148:151], s[12:13] sc1

; __device__ __forceinline__ u32x4 pack8(const f32x4& a, const f32x4& b) { u32x4 w; w.x = cvt_pk_bf16(a[0], a[1]); w.y = cvt_pk_bf16(a[2], a[3]); w.z = cvt_pk_bf16(b[0], b[1]); w.w = cvt_pk_bf16(b[2], b[3]); return w; }
; __device__ __forceinline__ void epi_fuse(const f32x4 (&acc)[2][2][4][2], const Args& a, const Job& J, int pm, int pn, int wr, int wc, int fr, int fq, int wid, int lane, LAS unsigned char* pst) {
;     ...
;             for (int mm = 0; mm < 2; ++mm) {
;                 const int m = m0 + mm;
;                 const int rl = ai * HALF + wr * 64 + m * 16 + fr; const float rs1 = S[2 * rl], rs2 = S[2 * rl + 1];
;                 const unsigned eo = e0 + (unsigned)((ai * HALF + m * 16) * DM + bj * HALF);
;                 const f16x8 xq = xq2[stp & 1][mm];
;                 f32x4 x1[2];
;                 x1[0] = __builtin_convertvector((f16x4){xq[0], xq[1], xq[2], xq[3]}, f32x4) + gv[bj][0] * (acc[ai][bj][m][0] * rs1);
;                 x1[1] = __builtin_convertvector((f16x4){xq[4], xq[5], xq[6], xq[7]}, f32x4) + gv[bj][1] * (acc[ai][bj][m][1] * rs1);
;                 if (do_norm) {
;                     const f16x4 h0 = __builtin_convertvector(x1[0], f16x4), h1 = __builtin_convertvector(x1[1], f16x4);
;                     *(f16x8*)(xo16 + 2u * eo) = (f16x8){h0[0], h0[1], h0[2], h0[3], h1[0], h1[1], h1[2], h1[3]};
;                     *(u32x4*)(HXo + 2u * eo) = pack8(x1[0] * rs2 * bv[0] + hv[0], x1[1] * rs2 * bv[1] + hv[1]);
;                 } else { __builtin_nontemporal_store(x1[0], (f32x4*)(xo32 + 4u * eo)); __builtin_nontemporal_store(x1[1], (f32x4*)(xo32 + 4u * (eo + 4))); }
.LBB0_394:
	s_andn2_b64 vcc, exec, s[12:13]
	s_cbranch_vccnz .LBB0_396
	ds_read_b32 v170, v80 offset:1028
	v_lshlrev_b32_e32 v171, 1, v164
	v_cvt_pk_f16_f32 v169, v154, v155
	v_cvt_pk_f16_f32 v168, v152, v153
	v_cvt_pk_f16_f32 v167, v162, v163
	v_cvt_pk_f16_f32 v166, v160, v161
	s_waitcnt lgkmcnt(0)
	v_pk_mul_f32 v[162:163], v[162:163], v[170:171] op_sel_hi:[1,0]
	v_pk_mul_f32 v[160:161], v[160:161], v[170:171] op_sel_hi:[1,0]
	v_pk_mul_f32 v[154:155], v[154:155], v[170:171] op_sel_hi:[1,0]
	v_pk_mul_f32 v[152:153], v[152:153], v[170:171] op_sel_hi:[1,0]
	v_pk_fma_f32 v[162:163], v[172:173], v[162:163], v[138:139]
	v_pk_fma_f32 v[160:161], v[174:175], v[160:161], v[136:137]
	v_pk_fma_f32 v[164:165], v[210:211], v[154:155], v[142:143]
	v_pk_fma_f32 v[154:155], v[212:213], v[152:153], v[140:141]
	v_readlane_b32 s12, v252, 6
	v_cvt_pk_bf16_f32 v152, v160, v161
	v_cvt_pk_bf16_f32 v153, v162, v163
	v_cvt_pk_bf16_f32 v154, v154, v155
	v_cvt_pk_bf16_f32 v155, v164, v165
	v_readlane_b32 s13, v252, 7
	global_store_dwordx4 v171, v[166:169], s[0:1] sc1
	s_nop 3
	global_store_dwordx4 v171, v[152:155], s[12:13] sc1

; __device__ __forceinline__ u32x4 pack8(const f32x4& a, const f32x4& b) { u32x4 w; w.x = cvt_pk_bf16(a[0], a[1]); w.y = cvt_pk_bf16(a[2], a[3]); w.z = cvt_pk_bf16(b[0], b[1]); w.w = cvt_pk_bf16(b[2], b[3]); return w; }
; __device__ __forceinline__ void epi_fuse(const f32x4 (&acc)[2][2][4][2], const Args& a, const Job& J, int pm, int pn, int wr, int wc, int fr, int fq, int wid, int lane, LAS unsigned char* pst) {
;     ...
;             for (int mm = 0; mm < 2; ++mm) {
;                 const int m = m0 + mm;
;                 const int rl = ai * HALF + wr * 64 + m * 16 + fr; const float rs1 = S[2 * rl], rs2 = S[2 * rl + 1];
;                 const unsigned eo = e0 + (unsigned)((ai * HALF + m * 16) * DM + bj * HALF);
;                 const f16x8 xq = xq2[stp & 1][mm];
;                 f32x4 x1[2];
;                 x1[0] = __builtin_convertvector((f16x4){xq[0], xq[1], xq[2], xq[3]}, f32x4) + gv[bj][0] * (acc[ai][bj][m][0] * rs1);
;                 x1[1] = __builtin_convertvector((f16x4){xq[4], xq[5], xq[6], xq[7]}, f32x4) + gv[bj][1] * (acc[ai][bj][m][1] * rs1);
;                 if (do_norm) {
;                     const f16x4 h0 = __builtin_convertvector(x1[0], f16x4), h1 = __builtin_convertvector(x1[1], f16x4);
;                     *(f16x8*)(xo16 + 2u * eo) = (f16x8){h0[0], h0[1], h0[2], h0[3], h1[0], h1[1], h1[2], h1[3]};
;                     *(u32x4*)(HXo + 2u * eo) = pack8(x1[0] * rs2 * bv[0] + hv[0], x1[1] * rs2 * bv[1] + hv[1]);
;                 } else { __builtin_nontemporal_store(x1[0], (f32x4*)(xo32 + 4u * eo)); __builtin_nontemporal_store(x1[1], (f32x4*)(xo32 + 4u * (eo + 4))); }
.LBB0_398:
	s_andn2_b64 vcc, exec, s[12:13]
	s_cbranch_vccnz .LBB0_400
	ds_read_b32 v166, v80 offset:1156
	v_lshlrev_b32_e32 v167, 1, v160
	v_cvt_pk_f16_f32 v165, v146, v147
	v_cvt_pk_f16_f32 v164, v144, v145
	v_cvt_pk_f16_f32 v163, v154, v155
	v_cvt_pk_f16_f32 v162, v152, v153
	s_waitcnt lgkmcnt(0)
	v_pk_mul_f32 v[154:155], v[154:155], v[166:167] op_sel_hi:[1,0]
	v_pk_mul_f32 v[152:153], v[152:153], v[166:167] op_sel_hi:[1,0]
	v_pk_mul_f32 v[146:147], v[146:147], v[166:167] op_sel_hi:[1,0]
	v_pk_mul_f32 v[144:145], v[144:145], v[166:167] op_sel_hi:[1,0]
	v_pk_fma_f32 v[154:155], v[172:173], v[154:155], v[138:139]
	v_pk_fma_f32 v[152:153], v[174:175], v[152:153], v[136:137]
	v_pk_fma_f32 v[160:161], v[210:211], v[146:147], v[142:143]
	v_pk_fma_f32 v[146:147], v[212:213], v[144:145], v[140:141]
	v_readlane_b32 s12, v252, 6
	v_cvt_pk_bf16_f32 v144, v152, v153
	v_cvt_pk_bf16_f32 v145, v154, v155
	v_cvt_pk_bf16_f32 v146, v146, v147
	v_cvt_pk_bf16_f32 v147, v160, v161
	v_readlane_b32 s13, v252, 7
	global_store_dwordx4 v167, v[162:165], s[0:1] sc1
	s_nop 3
	global_store_dwordx4 v167, v[144:147], s[12:13] sc1

; __device__ __forceinline__ u32x4 pack8(const f32x4& a, const f32x4& b) { u32x4 w; w.x = cvt_pk_bf16(a[0], a[1]); w.y = cvt_pk_bf16(a[2], a[3]); w.z = cvt_pk_bf16(b[0], b[1]); w.w = cvt_pk_bf16(b[2], b[3]); return w; }
; __device__ __forceinline__ void epi_fuse(const f32x4 (&acc)[2][2][4][2], const Args& a, const Job& J, int pm, int pn, int wr, int wc, int fr, int fq, int wid, int lane, LAS unsigned char* pst) {
;     ...
;             for (int mm = 0; mm < 2; ++mm) {
;                 const int m = m0 + mm;
;                 const int rl = ai * HALF + wr * 64 + m * 16 + fr; const float rs1 = S[2 * rl], rs2 = S[2 * rl + 1];
;                 const unsigned eo = e0 + (unsigned)((ai * HALF + m * 16) * DM + bj * HALF);
;                 const f16x8 xq = xq2[stp & 1][mm];
;                 f32x4 x1[2];
;                 x1[0] = __builtin_convertvector((f16x4){xq[0], xq[1], xq[2], xq[3]}, f32x4) + gv[bj][0] * (acc[ai][bj][m][0] * rs1);
;                 x1[1] = __builtin_convertvector((f16x4){xq[4], xq[5], xq[6], xq[7]}, f32x4) + gv[bj][1] * (acc[ai][bj][m][1] * rs1);
;                 if (do_norm) {
;                     const f16x4 h0 = __builtin_convertvector(x1[0], f16x4), h1 = __builtin_convertvector(x1[1], f16x4);
;                     *(f16x8*)(xo16 + 2u * eo) = (f16x8){h0[0], h0[1], h0[2], h0[3], h1[0], h1[1], h1[2], h1[3]};
;                     *(u32x4*)(HXo + 2u * eo) = pack8(x1[0] * rs2 * bv[0] + hv[0], x1[1] * rs2 * bv[1] + hv[1]);
;                 } else { __builtin_nontemporal_store(x1[0], (f32x4*)(xo32 + 4u * eo)); __builtin_nontemporal_store(x1[1], (f32x4*)(xo32 + 4u * (eo + 4))); }
.LBB0_402:
	s_andn2_b64 vcc, exec, s[12:13]
	s_cbranch_vccnz .LBB0_404
	ds_read_b32 v162, v80 offset:1284
	v_cvt_pk_f16_f32 v159, v154, v155
	v_cvt_pk_f16_f32 v158, v152, v153
	v_cvt_pk_f16_f32 v157, v146, v147
	v_cvt_pk_f16_f32 v156, v144, v145
	s_waitcnt lgkmcnt(0)
	v_pk_mul_f32 v[146:147], v[146:147], v[162:163] op_sel_hi:[1,0]
	v_pk_mul_f32 v[144:145], v[144:145], v[162:163] op_sel_hi:[1,0]
	v_pk_mul_f32 v[154:155], v[154:155], v[162:163] op_sel_hi:[1,0]
	v_pk_mul_f32 v[152:153], v[152:153], v[162:163] op_sel_hi:[1,0]
	v_pk_fma_f32 v[146:147], v[172:173], v[146:147], v[138:139]
	v_pk_fma_f32 v[144:145], v[174:175], v[144:145], v[136:137]
	v_pk_fma_f32 v[154:155], v[210:211], v[154:155], v[142:143]
	v_pk_fma_f32 v[152:153], v[212:213], v[152:153], v[140:141]
	v_readlane_b32 s12, v252, 6
	v_lshlrev_b32_e32 v160, 1, v160
	v_cvt_pk_bf16_f32 v144, v144, v145
	v_cvt_pk_bf16_f32 v145, v146, v147
	v_cvt_pk_bf16_f32 v146, v152, v153
	v_cvt_pk_bf16_f32 v147, v154, v155
	v_readlane_b32 s13, v252, 7
	global_store_dwordx4 v160, v[156:159], s[0:1] sc1
	s_nop 3
	global_store_dwordx4 v160, v[144:147], s[12:13] sc1

; __device__ __forceinline__ u32x4 pack8(const f32x4& a, const f32x4& b) { u32x4 w; w.x = cvt_pk_bf16(a[0], a[1]); w.y = cvt_pk_bf16(a[2], a[3]); w.z = cvt_pk_bf16(b[0], b[1]); w.w = cvt_pk_bf16(b[2], b[3]); return w; }
; __device__ __forceinline__ void epi_fuse(const f32x4 (&acc)[2][2][4][2], const Args& a, const Job& J, int pm, int pn, int wr, int wc, int fr, int fq, int wid, int lane, LAS unsigned char* pst) {
;     ...
;             for (int mm = 0; mm < 2; ++mm) {
;                 const int m = m0 + mm;
;                 const int rl = ai * HALF + wr * 64 + m * 16 + fr; const float rs1 = S[2 * rl], rs2 = S[2 * rl + 1];
;                 const unsigned eo = e0 + (unsigned)((ai * HALF + m * 16) * DM + bj * HALF);
;                 const f16x8 xq = xq2[stp & 1][mm];
;                 f32x4 x1[2];
;                 x1[0] = __builtin_convertvector((f16x4){xq[0], xq[1], xq[2], xq[3]}, f32x4) + gv[bj][0] * (acc[ai][bj][m][0] * rs1);
;                 x1[1] = __builtin_convertvector((f16x4){xq[4], xq[5], xq[6], xq[7]}, f32x4) + gv[bj][1] * (acc[ai][bj][m][1] * rs1);
;                 if (do_norm) {
;                     const f16x4 h0 = __builtin_convertvector(x1[0], f16x4), h1 = __builtin_convertvector(x1[1], f16x4);
;                     *(f16x8*)(xo16 + 2u * eo) = (f16x8){h0[0], h0[1], h0[2], h0[3], h1[0], h1[1], h1[2], h1[3]};
;                     *(u32x4*)(HXo + 2u * eo) = pack8(x1[0] * rs2 * bv[0] + hv[0], x1[1] * rs2 * bv[1] + hv[1]);
;                 } else { __builtin_nontemporal_store(x1[0], (f32x4*)(xo32 + 4u * eo)); __builtin_nontemporal_store(x1[1], (f32x4*)(xo32 + 4u * (eo + 4))); }
.LBB0_406:
	s_andn2_b64 vcc, exec, s[12:13]
	s_mov_b64 s[12:13], 0
	s_cbranch_vccnz .LBB0_408
	ds_read_b32 v80, v80 offset:1412
	v_cvt_pk_f16_f32 v155, v150, v151
	v_cvt_pk_f16_f32 v154, v148, v149
	v_cvt_pk_f16_f32 v153, v146, v147
	v_cvt_pk_f16_f32 v152, v144, v145
	s_waitcnt lgkmcnt(0)
	v_pk_mul_f32 v[82:83], v[146:147], v[80:81] op_sel_hi:[1,0]
	v_pk_mul_f32 v[86:87], v[144:145], v[80:81] op_sel_hi:[1,0]
	v_lshlrev_b32_e32 v85, 1, v85
	v_pk_fma_f32 v[82:83], v[172:173], v[82:83], v[138:139]
	v_pk_fma_f32 v[86:87], v[174:175], v[86:87], v[136:137]
	v_pk_mul_f32 v[136:137], v[150:151], v[80:81] op_sel_hi:[1,0]
	v_pk_mul_f32 v[138:139], v[148:149], v[80:81] op_sel_hi:[1,0]
	global_store_dwordx4 v85, v[152:155], s[0:1] sc1
	v_pk_fma_f32 v[142:143], v[210:211], v[136:137], v[142:143]
	v_pk_fma_f32 v[138:139], v[212:213], v[138:139], v[140:141]
	v_readlane_b32 s0, v252, 6
	v_cvt_pk_bf16_f32 v136, v86, v87
	v_cvt_pk_bf16_f32 v137, v82, v83
	v_cvt_pk_bf16_f32 v138, v138, v139
	v_cvt_pk_bf16_f32 v139, v142, v143
	v_readlane_b32 s1, v252, 7
	s_nop 4
	global_store_dwordx4 v85, v[136:139], s[0:1] sc1

; __device__ __forceinline__ void epi_ffn(const f32x4 (&acc)[2][2][4][2], const Job& J, int rowt, int pn, int wr, int wc, int fr, int fq, int lane) {
;     bf16_t* O = (bf16_t*)J.out; _Float16* SIDE = (_Float16*)J.out2; const float* cw = J.aux;
;     const int col = 128 * pn + 32 * wc + 8 * fq;
;     f32x4 w0[2], w1[2], w2[2];
; #pragma unroll
;     for (int n = 0; n < 2; ++n) { w0[n] = *(const f32x4*)(cw + col + 4 * n) * (-LOG2E); w1[n] = *(const f32x4*)(cw + DFF + col + 4 * n) * (-LOG2E); w2[n] = *(const f32x4*)(cw + 2 * DFF + col + 4 * n) * (-LOG2E); }
; #pragma unroll
;     for (int ai = 0; ai < 2; ++ai) {
;         const int blk = (rowt + ai * HALF + wr * 64) >> 6;
;         f32x4 cv[4][2];
; #pragma unroll
;         for (int n = 0; n < 2; ++n)
; #pragma unroll
;             for (int e = 0; e < 4; ++e) {
;                 float g[4], dn[4], up[4];
; #pragma unroll
;                 for (int m = 0; m < 4; ++m) { g[m] = acc[ai][0][m][n][e];
;                     dn[m] = __int_as_float(__builtin_amdgcn_mov_dpp(__float_as_int(g[m]), 0x121, 0xF, 0xF, false));
;                     up[m] = __int_as_float(__builtin_amdgcn_mov_dpp(__float_as_int(g[m]), 0x12F, 0xF, 0xF, false)); }
.LBB0_411:
	s_lshl_b32 s0, s78, 7
	v_readlane_b32 s1, v254, 59
	s_or_b32 s0, s0, s1
	v_lshl_add_u32 v82, v247, 3, s0
	v_ashrrev_i32_e32 v83, 31, v82
	v_readlane_b32 s0, v254, 17
	v_lshlrev_b64 v[86:87], 2, v[82:83]
	v_readlane_b32 s1, v254, 18
	v_lshlrev_b64 v[152:153], 1, v[82:83]
	v_mov_b32_dpp v218, v132 row_ror:1 row_mask:0xf bank_mask:0xf
	v_lshl_add_u64 v[144:145], s[0:1], 0, v[86:87]
	v_readlane_b32 s0, v255, 21
	v_readlane_b32 s1, v255, 22
	global_load_dwordx4 v[136:139], v[144:145], off
	v_mov_b32_dpp v224, v133 row_ror:1 row_mask:0xf bank_mask:0xf
	v_lshl_add_u64 v[146:147], s[0:1], 0, v[86:87]
	v_readlane_b32 s0, v255, 23
	v_readlane_b32 s1, v255, 24
	global_load_dwordx4 v[140:143], v[146:147], off
	v_mov_b32_dpp v192, v134 row_ror:1 row_mask:0xf bank_mask:0xf
	v_lshl_add_u64 v[86:87], s[0:1], 0, v[86:87]
	global_load_dwordx4 v[160:163], v[86:87], off
	global_load_dwordx4 v[164:167], v[144:145], off offset:16
	global_load_dwordx4 v[198:201], v[146:147], off offset:16
	global_load_dwordx4 v[206:209], v[86:87], off offset:16
	s_lshl_b32 s0, s90, 8
	v_readlane_b32 s1, v255, 9
	s_add_i32 s8, s1, s0
	v_readlane_b32 s0, v254, 23
	v_readlane_b32 s1, v254, 24
	v_mov_b32_dpp v211, v135 row_ror:1 row_mask:0xf bank_mask:0xf
	v_mov_b32_dpp v184, v128 row_ror:1 row_mask:0xf bank_mask:0xf
	v_lshl_add_u64 v[82:83], s[0:1], 0, v[152:153]
	s_mov_b32 s0, 0xbfb8aa3b
	v_mov_b32_dpp v194, v129 row_ror:1 row_mask:0xf bank_mask:0xf
	v_cmp_eq_u32_e64 s[40:41], 0, v248
	v_mov_b32_dpp v80, v132 row_ror:15 row_mask:0xf bank_mask:0xf
	v_mov_b32_dpp v217, v124 row_ror:15 row_mask:0xf bank_mask:0xf
	v_mov_b32_dpp v86, v133 row_ror:15 row_mask:0xf bank_mask:0xf
	v_mov_b32_dpp v223, v125 row_ror:15 row_mask:0xf bank_mask:0xf
	v_mov_b32_dpp v87, v134 row_ror:15 row_mask:0xf bank_mask:0xf
	v_mov_b32_dpp v191, v126 row_ror:15 row_mask:0xf bank_mask:0xf
	v_mov_b32_dpp v144, v135 row_ror:15 row_mask:0xf bank_mask:0xf
	v_mov_b32_dpp v210, v127 row_ror:15 row_mask:0xf bank_mask:0xf
	v_mov_b32_dpp v196, v128 row_ror:15 row_mask:0xf bank_mask:0xf
	v_mov_b32_dpp v182, v120 row_ror:15 row_mask:0xf bank_mask:0xf
	v_mov_b32_dpp v216, v129 row_ror:15 row_mask:0xf bank_mask:0xf
	v_cndmask_b32_e64 v203, v224, 0, s[40:41]
	v_cndmask_b32_e64 v202, v218, 0, s[40:41]
	v_cmp_eq_u32_e64 s[42:43], 15, v248
	v_cndmask_b32_e64 v215, v211, 0, s[40:41]
	v_cndmask_b32_e64 v214, v192, 0, s[40:41]
	v_mov_b32_dpp v251, v121 row_ror:15 row_mask:0xf bank_mask:0xf
	v_cndmask_b32_e64 v213, v86, v223, s[42:43]
	v_cndmask_b32_e64 v212, v80, v217, s[42:43]
	v_cndmask_b32_e64 v221, v144, v210, s[42:43]
	v_cndmask_b32_e64 v220, v87, v191, s[42:43]
	v_mov_b32_dpp v222, v130 row_ror:1 row_mask:0xf bank_mask:0xf
	v_mov_b32_dpp v250, v131 row_ror:1 row_mask:0xf bank_mask:0xf
	v_mov_b32_dpp v80, v130 row_ror:15 row_mask:0xf bank_mask:0xf
	v_mov_b32_dpp v249, v123 row_ror:15 row_mask:0xf bank_mask:0xf
	v_cmp_ne_u32_e64 s[44:45], 0, v248
	v_cmp_ne_u32_e64 s[38:39], 15, v248
	v_mov_b32_dpp v193, v124 row_ror:1 row_mask:0xf bank_mask:0xf
	v_mov_b32_dpp v188, v108 row_ror:1 row_mask:0xf bank_mask:0xf
	v_mov_b32_dpp v195, v108 row_ror:15 row_mask:0xf bank_mask:0xf
	v_mov_b32_dpp v190, v92 row_ror:1 row_mask:0xf bank_mask:0xf
	v_mov_b32_dpp v186, v92 row_ror:15 row_mask:0xf bank_mask:0xf
	v_mov_b32_dpp v176, v125 row_ror:1 row_mask:0xf bank_mask:0xf
	v_mov_b32_dpp v179, v109 row_ror:1 row_mask:0xf bank_mask:0xf
	v_mov_b32_dpp v180, v109 row_ror:15 row_mask:0xf bank_mask:0xf
	v_mov_b32_dpp v197, v93 row_ror:1 row_mask:0xf bank_mask:0xf
	v_mov_b32_dpp v183, v93 row_ror:15 row_mask:0xf bank_mask:0xf
	v_mov_b32_dpp v185, v126 row_ror:1 row_mask:0xf bank_mask:0xf
	v_mov_b32_dpp v177, v110 row_ror:1 row_mask:0xf bank_mask:0xf
	v_mov_b32_dpp v187, v110 row_ror:15 row_mask:0xf bank_mask:0xf
	v_mov_b32_dpp v181, v94 row_ror:1 row_mask:0xf bank_mask:0xf
	v_mov_b32_dpp v175, v94 row_ror:15 row_mask:0xf bank_mask:0xf
	v_mov_b32_dpp v172, v127 row_ror:1 row_mask:0xf bank_mask:0xf
	v_mov_b32_dpp v173, v111 row_ror:1 row_mask:0xf bank_mask:0xf
	v_mov_b32_dpp v174, v111 row_ror:15 row_mask:0xf bank_mask:0xf
	v_mov_b32_dpp v189, v95 row_ror:1 row_mask:0xf bank_mask:0xf
	v_mov_b32_dpp v178, v95 row_ror:15 row_mask:0xf bank_mask:0xf
	v_mov_b32_dpp v170, v120 row_ror:1 row_mask:0xf bank_mask:0xf
	v_mov_b32_dpp v168, v104 row_ror:1 row_mask:0xf bank_mask:0xf
	v_mov_b32_dpp v171, v104 row_ror:15 row_mask:0xf bank_mask:0xf
	v_mov_b32_dpp v169, v88 row_ror:1 row_mask:0xf bank_mask:0xf
	v_mov_b32_dpp v85, v88 row_ror:15 row_mask:0xf bank_mask:0xf
	v_mov_b32_dpp v225, v89 row_ror:1 row_mask:0xf bank_mask:0xf
	v_mov_b32_dpp v219, v106 row_ror:15 row_mask:0xf bank_mask:0xf
	s_waitcnt vmcnt(0)
; __device__ __forceinline__ void epi_ffn(const f32x4 (&acc)[2][2][4][2], const Job& J, int rowt, int pn, int wr, int wc, int fr, int fq, int lane) {
;     ...
;     for (int n = 0; n < 2; ++n) { w0[n] = *(const f32x4*)(cw + col + 4 * n) * (-LOG2E); w1[n] = *(const f32x4*)(cw + DFF + col + 4 * n) * (-LOG2E); w2[n] = *(const f32x4*)(cw + 2 * DFF + col + 4 * n) * (-LOG2E); }
; #pragma unroll
;     for (int ai = 0; ai < 2; ++ai) {
;         const int blk = (rowt + ai * HALF + wr * 64) >> 6;
;         f32x4 cv[4][2];
; #pragma unroll
;         for (int n = 0; n < 2; ++n)
; #pragma unroll
;             for (int e = 0; e < 4; ++e) {
;                 float g[4], dn[4], up[4];
; #pragma unroll
;                 for (int m = 0; m < 4; ++m) { g[m] = acc[ai][0][m][n][e];
;                     dn[m] = __int_as_float(__builtin_amdgcn_mov_dpp(__float_as_int(g[m]), 0x121, 0xF, 0xF, false));
;                     up[m] = __int_as_float(__builtin_amdgcn_mov_dpp(__float_as_int(g[m]), 0x12F, 0xF, 0xF, false)); }
; #pragma unroll
;                 for (int m = 0; m < 4; ++m) {
;                     const float pv = fr > 0 ? dn[m] : (m > 0 ? dn[m - 1] : 0.f);
;                     const float nx = fr < 15 ? up[m] : (m < 3 ? up[m + 1] : 0.f);
;                     cv[m][n][e] = w0[n][e] * pv + w1[n][e] * g[m] + w2[n][e] * nx;
;                 }
;             }
; #pragma unroll
;         for (int m = 0; m < 4; ++m) {
;             const int grow = rowt + ai * HALF + wr * 64 + m * 16 + fr;
;             const bool first = (m == 0 && fr == 0), last = (m == 3 && fr == 15);
;             if (first || last) {
;                 typedef _Float16 sh4 __attribute__((ext_vector_type(4))); typedef _Float16 sh8 __attribute__((ext_vector_type(8)));
;                 _Float16* sp = SIDE + ((size_t)(blk * 2 + (last ? 1 : 0)) * 3) * DFF + col;
;                 auto pk = [](const f32x4& a, const f32x4& b) { const sh4 x = __builtin_convertvector(a, sh4), y = __builtin_convertvector(b, sh4); return (sh8){x[0], x[1], x[2], x[3], y[0], y[1], y[2], y[3]}; };
;                 *(sh8*)sp = pk(cv[m][0] * NEG_LN2, cv[m][1] * NEG_LN2); *(sh8*)(sp + DFF) = pk(acc[ai][0][m][0], acc[ai][0][m][1]); *(sh8*)(sp + 2 * DFF) = pk(acc[ai][1][m][0], acc[ai][1][m][1]);
;             } else {
;                 f32x4 a0, a1;
; #pragma unroll
	v_pk_mul_f32 v[146:147], v[138:139], s[0:1] op_sel_hi:[1,0]
	v_pk_mul_f32 v[154:155], v[136:137], s[0:1] op_sel_hi:[1,0]
	v_pk_mul_f32 v[150:151], v[142:143], s[0:1] op_sel_hi:[1,0]
	v_pk_mul_f32 v[158:159], v[140:141], s[0:1] op_sel_hi:[1,0]
	v_pk_mul_f32 v[142:143], v[198:199], s[0:1] op_sel_hi:[1,0]
	v_pk_mul_f32 v[148:149], v[162:163], s[0:1] op_sel_hi:[1,0]
	v_pk_mul_f32 v[156:157], v[160:161], s[0:1] op_sel_hi:[1,0]
	v_pk_mul_f32 v[140:141], v[164:165], s[0:1] op_sel_hi:[1,0]
	v_pk_mul_f32 v[160:161], v[134:135], v[150:151]
	v_pk_mul_f32 v[162:163], v[132:133], v[158:159]
	v_pk_mul_f32 v[164:165], v[128:129], v[142:143]
	v_cndmask_b32_e64 v199, v194, 0, s[40:41]
	v_cndmask_b32_e64 v198, v184, 0, s[40:41]
	v_pk_mul_f32 v[138:139], v[200:201], s[0:1] op_sel_hi:[1,0]
	v_pk_mul_f32 v[144:145], v[206:207], s[0:1] op_sel_hi:[1,0]
	v_pk_fma_f32 v[162:163], v[154:155], v[202:203], v[162:163]
	v_pk_fma_f32 v[160:161], v[146:147], v[214:215], v[160:161]
	v_cndmask_b32_e64 v201, v216, v251, s[42:43]
	v_cndmask_b32_e64 v200, v196, v182, s[42:43]
	v_pk_fma_f32 v[164:165], v[140:141], v[198:199], v[164:165]
	v_pk_mul_f32 v[136:137], v[166:167], s[0:1] op_sel_hi:[1,0]
	v_pk_fma_f32 v[166:167], v[156:157], v[212:213], v[162:163]
	v_pk_fma_f32 v[162:163], v[148:149], v[220:221], v[160:161]
	v_pk_mul_f32 v[160:161], v[130:131], v[138:139]
	v_pk_fma_f32 v[164:165], v[144:145], v[200:201], v[164:165]
	v_mov_b32_dpp v221, v122 row_ror:15 row_mask:0xf bank_mask:0xf
	v_mov_b32_dpp v202, v131 row_ror:15 row_mask:0xf bank_mask:0xf
	v_cndmask_b32_e64 v201, v250, 0, s[40:41]
	v_cndmask_b32_e64 v200, v222, 0, s[40:41]
	v_pk_mul_f32 v[86:87], v[208:209], s[0:1] op_sel_hi:[1,0]
	v_cndmask_b32_e64 v203, v202, v249, s[42:43]
	v_cndmask_b32_e64 v202, v80, v221, s[42:43]
	v_pk_fma_f32 v[160:161], v[136:137], v[200:201], v[160:161]
	v_mov_b32_dpp v207, v121 row_ror:1 row_mask:0xf bank_mask:0xf
	v_mov_b32_dpp v212, v105 row_ror:1 row_mask:0xf bank_mask:0xf
	v_mov_b32_dpp v213, v105 row_ror:15 row_mask:0xf bank_mask:0xf
	v_mov_b32_dpp v215, v89 row_ror:15 row_mask:0xf bank_mask:0xf
	v_mov_b32_dpp v216, v122 row_ror:1 row_mask:0xf bank_mask:0xf
	v_mov_b32_dpp v208, v106 row_ror:1 row_mask:0xf bank_mask:0xf
	v_mov_b32_dpp v214, v90 row_ror:1 row_mask:0xf bank_mask:0xf
	v_mov_b32_dpp v206, v90 row_ror:15 row_mask:0xf bank_mask:0xf
	v_mov_b32_dpp v196, v123 row_ror:1 row_mask:0xf bank_mask:0xf
	v_mov_b32_dpp v198, v107 row_ror:1 row_mask:0xf bank_mask:0xf
	v_mov_b32_dpp v199, v107 row_ror:15 row_mask:0xf bank_mask:0xf
	v_mov_b32_dpp v220, v91 row_ror:1 row_mask:0xf bank_mask:0xf
	v_mov_b32_dpp v209, v91 row_ror:15 row_mask:0xf bank_mask:0xf
	v_pk_fma_f32 v[160:161], v[86:87], v[202:203], v[160:161]
	v_or_b32_e32 v80, s8, v248
	s_and_saveexec_b64 s[0:1], s[44:45]
	s_xor_b64 s[0:1], exec, s[0:1]
	s_cbranch_execz .LBB0_413
	v_exp_f32_e32 v201, v164
	v_exp_f32_e32 v200, v166
	v_add_f32_e32 v201, 1.0, v201
	v_rcp_f32_e32 v202, v201
	v_exp_f32_e32 v201, v167
	v_add_f32_e32 v200, 1.0, v200
	v_rcp_f32_e32 v200, v200
	v_add_f32_e32 v201, 1.0, v201
	v_rcp_f32_e32 v201, v201
	s_nop 0
	v_pk_mul_f32 v[166:167], v[166:167], v[200:201]
	v_exp_f32_e32 v200, v165
	v_exp_f32_e32 v201, v160
	v_pk_mul_f32 v[166:167], v[116:117], v[166:167]
	v_add_f32_e32 v200, 1.0, v200
	v_rcp_f32_e32 v203, v200
	v_add_f32_e32 v201, 1.0, v201
	v_exp_f32_e32 v200, v162
	v_pk_mul_f32 v[164:165], v[164:165], v[202:203]
	v_rcp_f32_e32 v202, v201
	v_exp_f32_e32 v201, v163
	v_add_f32_e32 v200, 1.0, v200
	v_rcp_f32_e32 v200, v200
	v_pk_mul_f32 v[164:165], v[112:113], v[164:165]
	v_add_f32_e32 v201, 1.0, v201
	v_rcp_f32_e32 v201, v201
	s_nop 0
	v_pk_mul_f32 v[162:163], v[162:163], v[200:201]
	v_exp_f32_e32 v200, v161
	v_pk_mul_f32 v[162:163], v[118:119], v[162:163]
	v_add_f32_e32 v200, 1.0, v200
	v_rcp_f32_e32 v203, v200
	s_nop 0
	v_pk_mul_f32 v[160:161], v[160:161], v[202:203]
	s_nop 0
	v_pk_mul_f32 v[200:201], v[114:115], v[160:161]
	v_cvt_pk_bf16_f32 v160, v166, v167
	v_cvt_pk_bf16_f32 v161, v162, v163
	v_cvt_pk_bf16_f32 v162, v164, v165
	v_cvt_pk_bf16_f32 v163, v200, v201
	v_mad_i64_i32 v[164:165], s[12:13], v80, s46, v[82:83]
	global_store_dwordx4 v[164:165], v[160:163], off sc1
.LBB0_413:
	s_or_saveexec_b64 s[0:1], s[0:1]
	v_readlane_b32 s12, v254, 21
	v_readlane_b32 s13, v254, 22
	s_ashr_i32 s9, s8, 5
	s_nop 0
	v_lshl_add_u64 v[152:153], s[12:13], 0, v[152:153]
	s_xor_b64 exec, exec, s[0:1]
	s_cbranch_execz .LBB0_415
	s_mul_i32 s12, s9, 3
	v_mad_i64_i32 v[200:201], s[12:13], s12, v235, v[152:153]
	s_mov_b32 s12, 0xbf317218
	s_nop 0
	v_pk_mul_f32 v[166:167], v[166:167], s[12:13] op_sel_hi:[1,0]
	v_pk_mul_f32 v[202:203], v[162:163], s[12:13] op_sel_hi:[1,0]
	v_pk_mul_f32 v[164:165], v[164:165], s[12:13] op_sel_hi:[1,0]
	v_pk_mul_f32 v[160:161], v[160:161], s[12:13] op_sel_hi:[1,0]
	s_movk_i32 s12, 0x1000
	v_cvt_pk_f16_f32 v163, v160, v161
	v_cvt_pk_f16_f32 v162, v164, v165
	v_cvt_pk_f16_f32 v161, v202, v203
	v_cvt_pk_f16_f32 v160, v166, v167
	v_add_co_u32_e32 v164, vcc, s12, v200
	global_store_dwordx4 v[200:201], v[160:163], off sc1
	s_nop 0
	v_addc_co_u32_e32 v165, vcc, 0, v201, vcc
	v_cvt_pk_f16_f32 v163, v130, v131
	v_cvt_pk_f16_f32 v162, v128, v129
	v_cvt_pk_f16_f32 v161, v134, v135
	v_cvt_pk_f16_f32 v160, v132, v133
	global_store_dwordx4 v[164:165], v[160:163], off offset:1536 sc1
	v_add_co_u32_e32 v164, vcc, 0x2000, v200
	s_nop 0
	v_cvt_pk_f16_f32 v163, v114, v115
	v_cvt_pk_f16_f32 v162, v112, v113
	v_cvt_pk_f16_f32 v161, v118, v119
	v_cvt_pk_f16_f32 v160, v116, v117
	v_addc_co_u32_e32 v165, vcc, 0, v201, vcc
	global_store_dwordx4 v[164:165], v[160:163], off offset:3072 sc1
; __device__ __forceinline__ void epi_ffn(const f32x4 (&acc)[2][2][4][2], const Job& J, int rowt, int pn, int wr, int wc, int fr, int fq, int lane) {
;     bf16_t* O = (bf16_t*)J.out; _Float16* SIDE = (_Float16*)J.out2; const float* cw = J.aux;
;     const int col = 128 * pn + 32 * wc + 8 * fq;
;     f32x4 w0[2], w1[2], w2[2];
; #pragma unroll
;     for (int n = 0; n < 2; ++n) { w0[n] = *(const f32x4*)(cw + col + 4 * n) * (-LOG2E); w1[n] = *(const f32x4*)(cw + DFF + col + 4 * n) * (-LOG2E); w2[n] = *(const f32x4*)(cw + 2 * DFF + col + 4 * n) * (-LOG2E); }
; #pragma unroll
;     for (int ai = 0; ai < 2; ++ai) {
;         const int blk = (rowt + ai * HALF + wr * 64) >> 6;
;         f32x4 cv[4][2];
; #pragma unroll
;         for (int n = 0; n < 2; ++n)
; #pragma unroll
;             for (int e = 0; e < 4; ++e) {
;                 float g[4], dn[4], up[4];
; #pragma unroll
;                 for (int m = 0; m < 4; ++m) { g[m] = acc[ai][0][m][n][e];
;                     dn[m] = __int_as_float(__builtin_amdgcn_mov_dpp(__float_as_int(g[m]), 0x121, 0xF, 0xF, false));
;                     up[m] = __int_as_float(__builtin_amdgcn_mov_dpp(__float_as_int(g[m]), 0x12F, 0xF, 0xF, false)); }
; #pragma unroll
;                 for (int m = 0; m < 4; ++m) {
;                     const float pv = fr > 0 ? dn[m] : (m > 0 ? dn[m - 1] : 0.f);
;                     const float nx = fr < 15 ? up[m] : (m < 3 ? up[m + 1] : 0.f);
;                     cv[m][n][e] = w0[n][e] * pv + w1[n][e] * g[m] + w2[n][e] * nx;
;                 }
;             }
; #pragma unroll
;         for (int m = 0; m < 4; ++m) {
;             const int grow = rowt + ai * HALF + wr * 64 + m * 16 + fr;
;             const bool first = (m == 0 && fr == 0), last = (m == 3 && fr == 15);
;             if (first || last) {
;                 typedef _Float16 sh4 __attribute__((ext_vector_type(4))); typedef _Float16 sh8 __attribute__((ext_vector_type(8)));
;                 _Float16* sp = SIDE + ((size_t)(blk * 2 + (last ? 1 : 0)) * 3) * DFF + col;
;                 auto pk = [](const f32x4& a, const f32x4& b) { const sh4 x = __builtin_convertvector(a, sh4), y = __builtin_convertvector(b, sh4); return (sh8){x[0], x[1], x[2], x[3], y[0], y[1], y[2], y[3]}; };
.LBB0_415:
	s_or_b64 exec, exec, s[0:1]
	s_nop 0
	v_cndmask_b32_e64 v161, v176, v224, s[40:41]
	v_cndmask_b32_e64 v160, v193, v218, s[40:41]
	v_pk_mul_f32 v[164:165], v[124:125], v[158:159]
	v_cndmask_b32_e64 v163, v223, v180, s[42:43]
	v_cndmask_b32_e64 v162, v217, v195, s[42:43]
	v_pk_fma_f32 v[160:161], v[154:155], v[160:161], v[164:165]
	v_pk_mul_f32 v[164:165], v[92:93], v[158:159]
	v_pk_fma_f32 v[200:201], v[156:157], v[162:163], v[160:161]
	v_cndmask_b32_e64 v160, v188, v193, s[40:41]
	v_mul_f32_e32 v193, v154, v160
	v_cndmask_b32_e64 v161, v195, v186, s[42:43]
	v_fmac_f32_e32 v193, v108, v158
	v_fmac_f32_e32 v193, v156, v161
	v_cndmask_b32_e64 v160, v190, v188, s[40:41]
	v_cndmask_b32_e64 v161, v197, v179, s[40:41]
	v_cndmask_b32_e64 v162, v186, 0, s[42:43]
	v_cndmask_b32_e64 v163, v183, 0, s[42:43]
	v_pk_fma_f32 v[160:161], v[154:155], v[160:161], v[164:165]
	v_pk_mul_f32 v[166:167], v[126:127], v[150:151]
	v_pk_fma_f32 v[164:165], v[156:157], v[162:163], v[160:161]
	v_cndmask_b32_e64 v160, v179, v176, s[40:41]
	v_mul_f32_e32 v179, v155, v160
	v_cndmask_b32_e64 v161, v180, v183, s[42:43]
	v_fmac_f32_e32 v179, v109, v159
	v_fmac_f32_e32 v179, v157, v161
	v_cndmask_b32_e64 v161, v172, v211, s[40:41]
	v_cndmask_b32_e64 v160, v185, v192, s[40:41]
	v_cndmask_b32_e64 v163, v210, v174, s[42:43]
	v_cndmask_b32_e64 v162, v191, v187, s[42:43]
	v_pk_fma_f32 v[160:161], v[146:147], v[160:161], v[166:167]
	v_pk_mul_f32 v[202:203], v[94:95], v[150:151]
	v_pk_fma_f32 v[190:191], v[148:149], v[162:163], v[160:161]
	v_cndmask_b32_e64 v160, v177, v185, s[40:41]
	v_mul_f32_e32 v180, v146, v160
	v_cndmask_b32_e64 v161, v187, v175, s[42:43]
	v_fmac_f32_e32 v180, v110, v150
	v_fmac_f32_e32 v180, v148, v161
	v_cndmask_b32_e64 v160, v181, v177, s[40:41]
	v_cndmask_b32_e64 v161, v189, v173, s[40:41]
	v_cndmask_b32_e64 v162, v175, 0, s[42:43]
	v_cndmask_b32_e64 v163, v178, 0, s[42:43]
	v_pk_fma_f32 v[160:161], v[146:147], v[160:161], v[202:203]
	v_cndmask_b32_e64 v167, v251, v213, s[42:43]
	v_pk_fma_f32 v[160:161], v[148:149], v[162:163], v[160:161]
	v_cndmask_b32_e64 v162, v173, v172, s[40:41]
	v_cndmask_b32_e64 v163, v174, v178, s[42:43]
	v_mul_f32_e32 v178, v147, v162
	v_fmac_f32_e32 v178, v111, v151
	v_fmac_f32_e32 v178, v149, v163
	v_cndmask_b32_e64 v163, v207, v194, s[40:41]
	v_cndmask_b32_e64 v162, v170, v184, s[40:41]
	v_pk_mul_f32 v[174:175], v[120:121], v[142:143]
	v_cndmask_b32_e64 v166, v182, v171, s[42:43]
	v_pk_fma_f32 v[162:163], v[140:141], v[162:163], v[174:175]
	v_pk_mul_f32 v[172:173], v[122:123], v[138:139]
	v_pk_fma_f32 v[174:175], v[144:145], v[166:167], v[162:163]
	v_cndmask_b32_e64 v162, v168, v170, s[40:41]
	v_mul_f32_e32 v181, v140, v162
	v_cndmask_b32_e64 v163, v171, v85, s[42:43]
	v_fmac_f32_e32 v181, v104, v142
	v_fmac_f32_e32 v181, v144, v163
	v_cndmask_b32_e64 v162, v169, v168, s[40:41]
	v_cndmask_b32_e64 v163, v225, v212, s[40:41]
	v_cndmask_b32_e64 v166, v85, 0, s[42:43]
	v_pk_mul_f32 v[170:171], v[88:89], v[142:143]
	v_cndmask_b32_e64 v85, v212, v207, s[40:41]
	v_cndmask_b32_e64 v167, v215, 0, s[42:43]
	v_pk_fma_f32 v[162:163], v[140:141], v[162:163], v[170:171]
	v_mul_f32_e32 v85, v141, v85
	v_pk_fma_f32 v[166:167], v[144:145], v[166:167], v[162:163]
	v_cndmask_b32_e64 v162, v213, v215, s[42:43]
	v_fmac_f32_e32 v85, v105, v143
	v_fmac_f32_e32 v85, v145, v162
	v_cndmask_b32_e64 v163, v196, v250, s[40:41]
	v_cndmask_b32_e64 v162, v216, v222, s[40:41]
	v_cndmask_b32_e64 v171, v249, v199, s[42:43]
	v_cndmask_b32_e64 v170, v221, v219, s[42:43]
	v_pk_fma_f32 v[162:163], v[136:137], v[162:163], v[172:173]
	v_pk_mul_f32 v[168:169], v[90:91], v[138:139]
	v_pk_fma_f32 v[170:171], v[86:87], v[170:171], v[162:163]
	v_cndmask_b32_e64 v162, v208, v216, s[40:41]
	v_mul_f32_e32 v182, v136, v162
	v_cndmask_b32_e64 v163, v219, v206, s[42:43]
	v_fmac_f32_e32 v182, v106, v138
	v_fmac_f32_e32 v182, v86, v163
	v_cndmask_b32_e64 v162, v214, v208, s[40:41]
	v_cndmask_b32_e64 v163, v220, v198, s[40:41]
	v_pk_fma_f32 v[162:163], v[136:137], v[162:163], v[168:169]
	v_cndmask_b32_e64 v168, v198, v196, s[40:41]
	v_mul_f32_e32 v183, v137, v168
	v_cndmask_b32_e64 v169, v199, v209, s[42:43]
	v_fmac_f32_e32 v183, v107, v139
	v_cndmask_b32_e64 v172, v206, 0, s[42:43]
	v_cndmask_b32_e64 v173, v209, 0, s[42:43]
	v_fmac_f32_e32 v183, v87, v169
	v_exp_f32_e32 v169, v174
	v_pk_fma_f32 v[162:163], v[86:87], v[172:173], v[162:163]
	v_exp_f32_e32 v172, v201
	v_exp_f32_e32 v176, v175
	v_add_f32_e32 v173, 1.0, v169
	v_exp_f32_e32 v168, v200
	v_add_f32_e32 v169, 1.0, v172
	v_rcp_f32_e32 v172, v173
	v_add_f32_e32 v173, 1.0, v176
	v_rcp_f32_e32 v173, v173
	v_exp_f32_e32 v176, v190
	v_exp_f32_e32 v177, v191
	v_exp_f32_e32 v185, v171
	v_pk_mul_f32 v[172:173], v[174:175], v[172:173]
	v_exp_f32_e32 v175, v170
	v_add_f32_e32 v168, 1.0, v168
	v_add_f32_e32 v174, 1.0, v176
	v_rcp_f32_e32 v168, v168
	v_add_f32_e32 v175, 1.0, v175
	v_rcp_f32_e32 v176, v175
	v_add_f32_e32 v175, 1.0, v177
	v_add_f32_e32 v177, 1.0, v185
	v_rcp_f32_e32 v169, v169
	v_rcp_f32_e32 v174, v174
	v_rcp_f32_e32 v175, v175
	v_rcp_f32_e32 v177, v177
	v_pk_mul_f32 v[168:169], v[200:201], v[168:169]
	v_or_b32_e32 v184, 16, v80
	v_pk_mul_f32 v[174:175], v[190:191], v[174:175]
	v_pk_mul_f32 v[170:171], v[170:171], v[176:177]
	v_pk_mul_f32 v[168:169], v[100:101], v[168:169]
	v_pk_mul_f32 v[172:173], v[96:97], v[172:173]
	v_pk_mul_f32 v[174:175], v[102:103], v[174:175]
	v_pk_mul_f32 v[176:177], v[98:99], v[170:171]
	v_cvt_pk_bf16_f32 v168, v168, v169
	v_cvt_pk_bf16_f32 v169, v174, v175
	v_cvt_pk_bf16_f32 v170, v172, v173
	v_cvt_pk_bf16_f32 v171, v176, v177
	v_mad_i64_i32 v[172:173], s[0:1], v184, s46, v[82:83]
; __device__ __forceinline__ void epi_ffn(const f32x4 (&acc)[2][2][4][2], const Job& J, int rowt, int pn, int wr, int wc, int fr, int fq, int lane) {
;     bf16_t* O = (bf16_t*)J.out; _Float16* SIDE = (_Float16*)J.out2; const float* cw = J.aux;
;     const int col = 128 * pn + 32 * wc + 8 * fq;
;     f32x4 w0[2], w1[2], w2[2];
; #pragma unroll
;     for (int n = 0; n < 2; ++n) { w0[n] = *(const f32x4*)(cw + col + 4 * n) * (-LOG2E); w1[n] = *(const f32x4*)(cw + DFF + col + 4 * n) * (-LOG2E); w2[n] = *(const f32x4*)(cw + 2 * DFF + col + 4 * n) * (-LOG2E); }
; #pragma unroll
;     for (int ai = 0; ai < 2; ++ai) {
;         const int blk = (rowt + ai * HALF + wr * 64) >> 6;
;         f32x4 cv[4][2];
; #pragma unroll
;         for (int n = 0; n < 2; ++n)
; #pragma unroll
;             for (int e = 0; e < 4; ++e) {
;                 float g[4], dn[4], up[4];
; #pragma unroll
;                 for (int m = 0; m < 4; ++m) { g[m] = acc[ai][0][m][n][e];
;                     dn[m] = __int_as_float(__builtin_amdgcn_mov_dpp(__float_as_int(g[m]), 0x121, 0xF, 0xF, false));
;                     up[m] = __int_as_float(__builtin_amdgcn_mov_dpp(__float_as_int(g[m]), 0x12F, 0xF, 0xF, false)); }
; #pragma unroll
;                 for (int m = 0; m < 4; ++m) {
;                     const float pv = fr > 0 ? dn[m] : (m > 0 ? dn[m - 1] : 0.f);
;                     const float nx = fr < 15 ? up[m] : (m < 3 ? up[m + 1] : 0.f);
;                     cv[m][n][e] = w0[n][e] * pv + w1[n][e] * g[m] + w2[n][e] * nx;
;                 }
;             }
; #pragma unroll
;         for (int m = 0; m < 4; ++m) {
;             const int grow = rowt + ai * HALF + wr * 64 + m * 16 + fr;
;             const bool first = (m == 0 && fr == 0), last = (m == 3 && fr == 15);
;             if (first || last) {
;                 typedef _Float16 sh4 __attribute__((ext_vector_type(4))); typedef _Float16 sh8 __attribute__((ext_vector_type(8)));
;                 _Float16* sp = SIDE + ((size_t)(blk * 2 + (last ? 1 : 0)) * 3) * DFF + col;
;                 auto pk = [](const f32x4& a, const f32x4& b) { const sh4 x = __builtin_convertvector(a, sh4), y = __builtin_convertvector(b, sh4); return (sh8){x[0], x[1], x[2], x[3], y[0], y[1], y[2], y[3]}; };
	global_store_dwordx4 v[172:173], v[168:171], off sc1
	v_exp_f32_e32 v174, v193
	v_exp_f32_e32 v173, v180
	v_exp_f32_e32 v168, v181
	v_exp_f32_e32 v170, v179
	v_add_f32_e32 v174, 1.0, v174
	v_rcp_f32_e32 v174, v174
	v_add_f32_e32 v168, 1.0, v168
	v_rcp_f32_e32 v168, v168
	v_add_f32_e32 v173, 1.0, v173
	v_rcp_f32_e32 v173, v173
	v_mul_f32_e32 v169, v193, v174
	v_mul_f32_e32 v168, v181, v168
	v_mul_f32_e32 v171, v72, v168
	v_exp_f32_e32 v168, v85
	v_exp_f32_e32 v174, v182
	v_add_f32_e32 v170, 1.0, v170
	v_rcp_f32_e32 v170, v170
	v_add_f32_e32 v168, 1.0, v168
	v_rcp_f32_e32 v168, v168
	v_or_b32_e32 v172, 32, v80
	v_mul_f32_e32 v170, v179, v170
	v_mul_f32_e32 v169, v76, v169
	v_mul_f32_e32 v85, v85, v168
	v_mul_f32_e32 v168, v180, v173
	v_add_f32_e32 v173, 1.0, v174
	v_exp_f32_e32 v174, v178
	v_mul_f32_e32 v175, v78, v168
	v_exp_f32_e32 v168, v183
	v_rcp_f32_e32 v173, v173
	v_add_f32_e32 v174, 1.0, v174
	v_rcp_f32_e32 v174, v174
	v_add_f32_e32 v168, 1.0, v168
	v_rcp_f32_e32 v168, v168
	v_mul_f32_e32 v173, v182, v173
	v_mul_f32_e32 v174, v178, v174
	v_mul_f32_e32 v170, v77, v170
	v_mul_f32_e32 v168, v183, v168
	v_mul_f32_e32 v85, v73, v85
	v_mul_f32_e32 v173, v74, v173
	v_mul_f32_e32 v174, v79, v174
	v_mul_f32_e32 v176, v75, v168
	v_cvt_pk_bf16_f32 v168, v169, v170
	v_cvt_pk_bf16_f32 v169, v175, v174
	v_cvt_pk_bf16_f32 v170, v171, v85
	v_cvt_pk_bf16_f32 v171, v173, v176
	v_mad_i64_i32 v[172:173], s[0:1], v172, s46, v[82:83]
	global_store_dwordx4 v[172:173], v[168:171], off sc1
	s_and_saveexec_b64 s[0:1], s[38:39]
	s_xor_b64 s[0:1], exec, s[0:1]
	s_cbranch_execz .LBB0_417
	v_exp_f32_e32 v85, v164
	v_or_b32_e32 v80, 48, v80
	v_add_f32_e32 v85, 1.0, v85
	v_rcp_f32_e32 v168, v85
	v_exp_f32_e32 v85, v166
	s_nop 0
	v_add_f32_e32 v85, 1.0, v85
	v_rcp_f32_e32 v170, v85
	v_exp_f32_e32 v85, v165
	s_nop 0
	v_add_f32_e32 v85, 1.0, v85
	v_rcp_f32_e32 v169, v85
	v_exp_f32_e32 v85, v167
	v_pk_mul_f32 v[164:165], v[164:165], v[168:169]
	v_add_f32_e32 v85, 1.0, v85
	v_rcp_f32_e32 v171, v85
	v_exp_f32_e32 v85, v160
	v_pk_mul_f32 v[164:165], v[68:69], v[164:165]
	v_pk_mul_f32 v[166:167], v[166:167], v[170:171]
	v_add_f32_e32 v85, 1.0, v85
	v_rcp_f32_e32 v168, v85
	v_exp_f32_e32 v85, v162
	v_pk_mul_f32 v[166:167], v[60:61], v[166:167]
	v_add_f32_e32 v85, 1.0, v85
	v_rcp_f32_e32 v170, v85
	v_exp_f32_e32 v85, v161
	s_nop 0
	v_add_f32_e32 v85, 1.0, v85
	v_rcp_f32_e32 v169, v85
	v_exp_f32_e32 v85, v163
	v_pk_mul_f32 v[160:161], v[160:161], v[168:169]
	v_add_f32_e32 v85, 1.0, v85
	v_rcp_f32_e32 v171, v85
	v_pk_mul_f32 v[168:169], v[70:71], v[160:161]
	v_pk_mul_f32 v[160:161], v[162:163], v[170:171]
	s_nop 0
	v_pk_mul_f32 v[170:171], v[62:63], v[160:161]
	v_cvt_pk_bf16_f32 v160, v164, v165
	v_cvt_pk_bf16_f32 v161, v168, v169
	v_cvt_pk_bf16_f32 v162, v166, v167
	v_cvt_pk_bf16_f32 v163, v170, v171
	v_mad_i64_i32 v[164:165], s[12:13], v80, s46, v[82:83]
	global_store_dwordx4 v[164:165], v[160:163], off sc1
.LBB0_417:
	s_andn2_saveexec_b64 s[0:1], s[0:1]
	s_cbranch_execz .LBB0_419
	s_mul_i32 s9, s9, 3
	s_add_i32 s9, s9, 3
	v_mad_i64_i32 v[168:169], s[12:13], s9, v235, v[152:153]
	s_mov_b32 s12, 0xbf317218
	s_nop 0
	v_pk_mul_f32 v[164:165], v[164:165], s[12:13] op_sel_hi:[1,0]
	v_pk_mul_f32 v[160:161], v[160:161], s[12:13] op_sel_hi:[1,0]
	v_pk_mul_f32 v[166:167], v[166:167], s[12:13] op_sel_hi:[1,0]
	v_pk_mul_f32 v[162:163], v[162:163], s[12:13] op_sel_hi:[1,0]
	s_movk_i32 s9, 0x1000
	v_cvt_pk_f16_f32 v163, v162, v163
	v_cvt_pk_f16_f32 v162, v166, v167
	v_cvt_pk_f16_f32 v161, v160, v161
	v_cvt_pk_f16_f32 v160, v164, v165
	v_add_co_u32_e32 v164, vcc, s9, v168
	global_store_dwordx4 v[168:169], v[160:163], off sc1
	s_nop 0
	v_addc_co_u32_e32 v165, vcc, 0, v169, vcc
	v_cvt_pk_f16_f32 v163, v90, v91
	v_cvt_pk_f16_f32 v162, v88, v89
	v_cvt_pk_f16_f32 v161, v94, v95
	v_cvt_pk_f16_f32 v160, v92, v93
	global_store_dwordx4 v[164:165], v[160:163], off offset:1536 sc1
	v_add_co_u32_e32 v164, vcc, 0x2000, v168
	s_nop 0
	v_cvt_pk_f16_f32 v163, v62, v63
	v_cvt_pk_f16_f32 v162, v60, v61
	v_cvt_pk_f16_f32 v161, v70, v71
	v_cvt_pk_f16_f32 v160, v68, v69
	v_addc_co_u32_e32 v165, vcc, 0, v169, vcc
	global_store_dwordx4 v[164:165], v[160:163], off offset:3072 sc1
.LBB0_419:
	s_or_b64 exec, exec, s[0:1]
	v_mov_b32_dpp v249, v64 row_ror:1 row_mask:0xf bank_mask:0xf
	v_mov_b32_dpp v251, v65 row_ror:1 row_mask:0xf bank_mask:0xf
	v_mov_b32_dpp v80, v64 row_ror:15 row_mask:0xf bank_mask:0xf
	v_mov_b32_dpp v225, v52 row_ror:15 row_mask:0xf bank_mask:0xf
	v_mov_b32_dpp v85, v65 row_ror:15 row_mask:0xf bank_mask:0xf
	v_mov_b32_dpp v250, v53 row_ror:15 row_mask:0xf bank_mask:0xf
	v_pk_mul_f32 v[162:163], v[64:65], v[158:159]
	v_cndmask_b32_e64 v165, v251, 0, s[40:41]
	v_cndmask_b32_e64 v164, v249, 0, s[40:41]
	v_cndmask_b32_e64 v167, v85, v250, s[42:43]
	v_cndmask_b32_e64 v166, v80, v225, s[42:43]
	v_pk_fma_f32 v[162:163], v[154:155], v[164:165], v[162:163]
	v_mov_b32_dpp v218, v66 row_ror:1 row_mask:0xf bank_mask:0xf
	v_mov_b32_dpp v224, v67 row_ror:1 row_mask:0xf bank_mask:0xf
	v_pk_mul_f32 v[160:161], v[66:67], v[150:151]
	v_pk_fma_f32 v[164:165], v[156:157], v[166:167], v[162:163]
	v_mov_b32_dpp v80, v66 row_ror:15 row_mask:0xf bank_mask:0xf
	v_mov_b32_dpp v217, v54 row_ror:15 row_mask:0xf bank_mask:0xf
	v_mov_b32_dpp v85, v67 row_ror:15 row_mask:0xf bank_mask:0xf
	v_mov_b32_dpp v223, v55 row_ror:15 row_mask:0xf bank_mask:0xf
	v_cndmask_b32_e64 v163, v224, 0, s[40:41]
	v_cndmask_b32_e64 v162, v218, 0, s[40:41]
	v_cndmask_b32_e64 v167, v85, v223, s[42:43]
	v_cndmask_b32_e64 v166, v80, v217, s[42:43]
	v_pk_fma_f32 v[160:161], v[146:147], v[162:163], v[160:161]
	v_mov_b32_dpp v209, v56 row_ror:1 row_mask:0xf bank_mask:0xf
; __device__ __forceinline__ void epi_ffn(const f32x4 (&acc)[2][2][4][2], const Job& J, int rowt, int pn, int wr, int wc, int fr, int fq, int lane) {
;     bf16_t* O = (bf16_t*)J.out; _Float16* SIDE = (_Float16*)J.out2; const float* cw = J.aux;
;     const int col = 128 * pn + 32 * wc + 8 * fq;
;     f32x4 w0[2], w1[2], w2[2];
; #pragma unroll
;     for (int n = 0; n < 2; ++n) { w0[n] = *(const f32x4*)(cw + col + 4 * n) * (-LOG2E); w1[n] = *(const f32x4*)(cw + DFF + col + 4 * n) * (-LOG2E); w2[n] = *(const f32x4*)(cw + 2 * DFF + col + 4 * n) * (-LOG2E); }
; #pragma unroll
;     for (int ai = 0; ai < 2; ++ai) {
;         const int blk = (rowt + ai * HALF + wr * 64) >> 6;
;         f32x4 cv[4][2];
; #pragma unroll
;         for (int n = 0; n < 2; ++n)
; #pragma unroll
;             for (int e = 0; e < 4; ++e) {
;                 float g[4], dn[4], up[4];
; #pragma unroll
;                 for (int m = 0; m < 4; ++m) { g[m] = acc[ai][0][m][n][e];
;                     dn[m] = __int_as_float(__builtin_amdgcn_mov_dpp(__float_as_int(g[m]), 0x121, 0xF, 0xF, false));
;                     up[m] = __int_as_float(__builtin_amdgcn_mov_dpp(__float_as_int(g[m]), 0x12F, 0xF, 0xF, false)); }
; #pragma unroll
;                 for (int m = 0; m < 4; ++m) {
;                     const float pv = fr > 0 ? dn[m] : (m > 0 ? dn[m - 1] : 0.f);
;                     const float nx = fr < 15 ? up[m] : (m < 3 ? up[m + 1] : 0.f);
;                     cv[m][n][e] = w0[n][e] * pv + w1[n][e] * g[m] + w2[n][e] * nx;
;                 }
;             }
; #pragma unroll
;         for (int m = 0; m < 4; ++m) {
;             const int grow = rowt + ai * HALF + wr * 64 + m * 16 + fr;
;             const bool first = (m == 0 && fr == 0), last = (m == 3 && fr == 15);
;             if (first || last) {
;                 typedef _Float16 sh4 __attribute__((ext_vector_type(4))); typedef _Float16 sh8 __attribute__((ext_vector_type(8)));
;                 _Float16* sp = SIDE + ((size_t)(blk * 2 + (last ? 1 : 0)) * 3) * DFF + col;
;                 auto pk = [](const f32x4& a, const f32x4& b) { const sh4 x = __builtin_convertvector(a, sh4), y = __builtin_convertvector(b, sh4); return (sh8){x[0], x[1], x[2], x[3], y[0], y[1], y[2], y[3]}; };
	v_mov_b32_dpp v80, v56 row_ror:15 row_mask:0xf bank_mask:0xf
	v_mov_b32_dpp v208, v48 row_ror:15 row_mask:0xf bank_mask:0xf
	v_mov_b32_dpp v221, v57 row_ror:1 row_mask:0xf bank_mask:0xf
	v_mov_b32_dpp v186, v58 row_ror:1 row_mask:0xf bank_mask:0xf
	v_mov_b32_dpp v199, v59 row_ror:1 row_mask:0xf bank_mask:0xf
	v_pk_fma_f32 v[160:161], v[148:149], v[166:167], v[160:161]
	v_mov_b32_dpp v85, v57 row_ror:15 row_mask:0xf bank_mask:0xf
	v_mov_b32_dpp v219, v49 row_ror:15 row_mask:0xf bank_mask:0xf
	v_pk_mul_f32 v[162:163], v[58:59], v[138:139]
	v_pk_mul_f32 v[166:167], v[56:57], v[142:143]
	v_cndmask_b32_e64 v171, v221, 0, s[40:41]
	v_cndmask_b32_e64 v170, v209, 0, s[40:41]
	v_cndmask_b32_e64 v174, v80, v208, s[42:43]
	v_mov_b32_dpp v80, v58 row_ror:15 row_mask:0xf bank_mask:0xf
	v_mov_b32_dpp v185, v50 row_ror:15 row_mask:0xf bank_mask:0xf
	v_mov_b32_dpp v202, v59 row_ror:15 row_mask:0xf bank_mask:0xf
	v_mov_b32_dpp v198, v51 row_ror:15 row_mask:0xf bank_mask:0xf
	v_cndmask_b32_e64 v201, v199, 0, s[40:41]
	v_cndmask_b32_e64 v200, v186, 0, s[40:41]
	v_cndmask_b32_e64 v175, v85, v219, s[42:43]
	v_pk_fma_f32 v[166:167], v[140:141], v[170:171], v[166:167]
	v_cndmask_b32_e64 v203, v202, v198, s[42:43]
	v_cndmask_b32_e64 v202, v80, v185, s[42:43]
	v_pk_fma_f32 v[162:163], v[136:137], v[200:201], v[162:163]
	s_addk_i32 s8, 0x80
	v_mov_b32_dpp v216, v52 row_ror:1 row_mask:0xf bank_mask:0xf
	v_mov_b32_dpp v212, v36 row_ror:1 row_mask:0xf bank_mask:0xf
	v_mov_b32_dpp v220, v36 row_ror:15 row_mask:0xf bank_mask:0xf
	v_mov_b32_dpp v214, v20 row_ror:1 row_mask:0xf bank_mask:0xf
	v_mov_b32_dpp v210, v20 row_ror:15 row_mask:0xf bank_mask:0xf
	v_mov_b32_dpp v190, v53 row_ror:1 row_mask:0xf bank_mask:0xf
	v_mov_b32_dpp v194, v37 row_ror:1 row_mask:0xf bank_mask:0xf
	v_mov_b32_dpp v195, v37 row_ror:15 row_mask:0xf bank_mask:0xf
	v_mov_b32_dpp v222, v21 row_ror:1 row_mask:0xf bank_mask:0xf
	v_mov_b32_dpp v206, v21 row_ror:15 row_mask:0xf bank_mask:0xf
	v_mov_b32_dpp v211, v54 row_ror:1 row_mask:0xf bank_mask:0xf
	v_mov_b32_dpp v196, v38 row_ror:1 row_mask:0xf bank_mask:0xf
	v_mov_b32_dpp v213, v38 row_ror:15 row_mask:0xf bank_mask:0xf
	v_mov_b32_dpp v207, v22 row_ror:1 row_mask:0xf bank_mask:0xf
	v_mov_b32_dpp v193, v22 row_ror:15 row_mask:0xf bank_mask:0xf
	v_mov_b32_dpp v189, v55 row_ror:1 row_mask:0xf bank_mask:0xf
	v_mov_b32_dpp v191, v39 row_ror:1 row_mask:0xf bank_mask:0xf
	v_mov_b32_dpp v192, v39 row_ror:15 row_mask:0xf bank_mask:0xf
	v_mov_b32_dpp v215, v23 row_ror:1 row_mask:0xf bank_mask:0xf
	v_mov_b32_dpp v197, v23 row_ror:15 row_mask:0xf bank_mask:0xf
	v_mov_b32_dpp v184, v48 row_ror:1 row_mask:0xf bank_mask:0xf
	v_mov_b32_dpp v180, v32 row_ror:1 row_mask:0xf bank_mask:0xf
	v_mov_b32_dpp v187, v32 row_ror:15 row_mask:0xf bank_mask:0xf
	v_mov_b32_dpp v182, v16 row_ror:1 row_mask:0xf bank_mask:0xf
	v_mov_b32_dpp v178, v16 row_ror:15 row_mask:0xf bank_mask:0xf
	v_mov_b32_dpp v168, v49 row_ror:1 row_mask:0xf bank_mask:0xf
	v_mov_b32_dpp v172, v33 row_ror:1 row_mask:0xf bank_mask:0xf
	v_mov_b32_dpp v173, v33 row_ror:15 row_mask:0xf bank_mask:0xf
	v_mov_b32_dpp v188, v17 row_ror:1 row_mask:0xf bank_mask:0xf
	v_mov_b32_dpp v176, v17 row_ror:15 row_mask:0xf bank_mask:0xf
	v_pk_fma_f32 v[166:167], v[144:145], v[174:175], v[166:167]
	v_mov_b32_dpp v179, v50 row_ror:1 row_mask:0xf bank_mask:0xf
	v_mov_b32_dpp v174, v34 row_ror:1 row_mask:0xf bank_mask:0xf
	v_mov_b32_dpp v181, v34 row_ror:15 row_mask:0xf bank_mask:0xf
	v_mov_b32_dpp v177, v18 row_ror:1 row_mask:0xf bank_mask:0xf
	v_mov_b32_dpp v171, v18 row_ror:15 row_mask:0xf bank_mask:0xf
	v_mov_b32_dpp v85, v51 row_ror:1 row_mask:0xf bank_mask:0xf
	v_mov_b32_dpp v169, v35 row_ror:1 row_mask:0xf bank_mask:0xf
	v_mov_b32_dpp v170, v35 row_ror:15 row_mask:0xf bank_mask:0xf
	v_mov_b32_dpp v183, v19 row_ror:1 row_mask:0xf bank_mask:0xf
	v_mov_b32_dpp v175, v19 row_ror:15 row_mask:0xf bank_mask:0xf
	v_pk_fma_f32 v[162:163], v[86:87], v[202:203], v[162:163]
	v_or_b32_e32 v80, s8, v248
	s_and_saveexec_b64 s[0:1], s[44:45]
	s_xor_b64 s[0:1], exec, s[0:1]
	s_cbranch_execz .LBB0_421
	v_exp_f32_e32 v201, v166
	v_exp_f32_e32 v200, v164
	v_add_f32_e32 v201, 1.0, v201
	v_rcp_f32_e32 v202, v201
	v_exp_f32_e32 v201, v165
	v_add_f32_e32 v200, 1.0, v200
	v_rcp_f32_e32 v200, v200
	v_add_f32_e32 v201, 1.0, v201
	v_rcp_f32_e32 v201, v201
	s_nop 0
	v_pk_mul_f32 v[164:165], v[164:165], v[200:201]
	v_exp_f32_e32 v200, v167
	v_exp_f32_e32 v201, v162
	v_pk_mul_f32 v[164:165], v[44:45], v[164:165]
	v_add_f32_e32 v200, 1.0, v200
	v_rcp_f32_e32 v203, v200
	v_add_f32_e32 v201, 1.0, v201
	v_exp_f32_e32 v200, v160
	v_pk_mul_f32 v[166:167], v[166:167], v[202:203]
	v_rcp_f32_e32 v202, v201
	v_exp_f32_e32 v201, v161
	v_add_f32_e32 v200, 1.0, v200
	v_rcp_f32_e32 v200, v200
	v_pk_mul_f32 v[166:167], v[40:41], v[166:167]
	v_add_f32_e32 v201, 1.0, v201
	v_rcp_f32_e32 v201, v201
	s_nop 0
	v_pk_mul_f32 v[160:161], v[160:161], v[200:201]
	s_nop 0
	v_pk_mul_f32 v[200:201], v[46:47], v[160:161]
	v_exp_f32_e32 v160, v163
	s_nop 0
	v_add_f32_e32 v160, 1.0, v160
	v_rcp_f32_e32 v203, v160
	s_nop 0
	v_pk_mul_f32 v[160:161], v[162:163], v[202:203]
	s_nop 0
	v_pk_mul_f32 v[202:203], v[42:43], v[160:161]
	v_cvt_pk_bf16_f32 v160, v164, v165
	v_cvt_pk_bf16_f32 v161, v200, v201
	v_cvt_pk_bf16_f32 v162, v166, v167
	v_cvt_pk_bf16_f32 v163, v202, v203
	v_mad_i64_i32 v[164:165], s[12:13], v80, s46, v[82:83]
	global_store_dwordx4 v[164:165], v[160:163], off sc1
; __device__ __forceinline__ void epi_ffn(const f32x4 (&acc)[2][2][4][2], const Job& J, int rowt, int pn, int wr, int wc, int fr, int fq, int lane) {
;     bf16_t* O = (bf16_t*)J.out; _Float16* SIDE = (_Float16*)J.out2; const float* cw = J.aux;
;     const int col = 128 * pn + 32 * wc + 8 * fq;
;     f32x4 w0[2], w1[2], w2[2];
; #pragma unroll
;     for (int n = 0; n < 2; ++n) { w0[n] = *(const f32x4*)(cw + col + 4 * n) * (-LOG2E); w1[n] = *(const f32x4*)(cw + DFF + col + 4 * n) * (-LOG2E); w2[n] = *(const f32x4*)(cw + 2 * DFF + col + 4 * n) * (-LOG2E); }
; #pragma unroll
;     for (int ai = 0; ai < 2; ++ai) {
;         const int blk = (rowt + ai * HALF + wr * 64) >> 6;
;         f32x4 cv[4][2];
; #pragma unroll
;         for (int n = 0; n < 2; ++n)
; #pragma unroll
;             for (int e = 0; e < 4; ++e) {
;                 float g[4], dn[4], up[4];
; #pragma unroll
;                 for (int m = 0; m < 4; ++m) { g[m] = acc[ai][0][m][n][e];
;                     dn[m] = __int_as_float(__builtin_amdgcn_mov_dpp(__float_as_int(g[m]), 0x121, 0xF, 0xF, false));
;                     up[m] = __int_as_float(__builtin_amdgcn_mov_dpp(__float_as_int(g[m]), 0x12F, 0xF, 0xF, false)); }
; #pragma unroll
;                 for (int m = 0; m < 4; ++m) {
;                     const float pv = fr > 0 ? dn[m] : (m > 0 ? dn[m - 1] : 0.f);
;                     const float nx = fr < 15 ? up[m] : (m < 3 ? up[m + 1] : 0.f);
;                     cv[m][n][e] = w0[n][e] * pv + w1[n][e] * g[m] + w2[n][e] * nx;
;                 }
;             }
; #pragma unroll
;         for (int m = 0; m < 4; ++m) {
;             const int grow = rowt + ai * HALF + wr * 64 + m * 16 + fr;
;             const bool first = (m == 0 && fr == 0), last = (m == 3 && fr == 15);
;             if (first || last) {
;                 typedef _Float16 sh4 __attribute__((ext_vector_type(4))); typedef _Float16 sh8 __attribute__((ext_vector_type(8)));
;                 _Float16* sp = SIDE + ((size_t)(blk * 2 + (last ? 1 : 0)) * 3) * DFF + col;
;                 auto pk = [](const f32x4& a, const f32x4& b) { const sh4 x = __builtin_convertvector(a, sh4), y = __builtin_convertvector(b, sh4); return (sh8){x[0], x[1], x[2], x[3], y[0], y[1], y[2], y[3]}; };
.LBB0_421:
	s_or_saveexec_b64 s[0:1], s[0:1]
	s_ashr_i32 s8, s8, 5
	s_xor_b64 exec, exec, s[0:1]
	s_cbranch_execz .LBB0_423
	s_mul_i32 s9, s8, 3
	v_mad_i64_i32 v[200:201], s[12:13], s9, v235, v[152:153]
	s_mov_b32 s12, 0xbf317218
	s_nop 0
	v_pk_mul_f32 v[164:165], v[164:165], s[12:13] op_sel_hi:[1,0]
	v_pk_mul_f32 v[160:161], v[160:161], s[12:13] op_sel_hi:[1,0]
	v_pk_mul_f32 v[166:167], v[166:167], s[12:13] op_sel_hi:[1,0]
	v_pk_mul_f32 v[162:163], v[162:163], s[12:13] op_sel_hi:[1,0]
	s_movk_i32 s9, 0x1000
	v_cvt_pk_f16_f32 v163, v162, v163
	v_cvt_pk_f16_f32 v162, v166, v167
	v_cvt_pk_f16_f32 v161, v160, v161
	v_cvt_pk_f16_f32 v160, v164, v165
	v_add_co_u32_e32 v164, vcc, s9, v200
	global_store_dwordx4 v[200:201], v[160:163], off sc1
	s_nop 0
	v_addc_co_u32_e32 v165, vcc, 0, v201, vcc
	v_cvt_pk_f16_f32 v163, v58, v59
	v_cvt_pk_f16_f32 v162, v56, v57
	v_cvt_pk_f16_f32 v161, v66, v67
	v_cvt_pk_f16_f32 v160, v64, v65
	global_store_dwordx4 v[164:165], v[160:163], off offset:1536 sc1
	v_add_co_u32_e32 v164, vcc, 0x2000, v200
	s_nop 0
	v_cvt_pk_f16_f32 v163, v42, v43
	v_cvt_pk_f16_f32 v162, v40, v41
	v_cvt_pk_f16_f32 v161, v46, v47
	v_cvt_pk_f16_f32 v160, v44, v45
	v_addc_co_u32_e32 v165, vcc, 0, v201, vcc
	global_store_dwordx4 v[164:165], v[160:163], off offset:3072 sc1
.LBB0_423:
	s_or_b64 exec, exec, s[0:1]
	s_nop 0
	v_cndmask_b32_e64 v161, v190, v251, s[40:41]
	v_cndmask_b32_e64 v160, v216, v249, s[40:41]
	v_pk_mul_f32 v[166:167], v[52:53], v[158:159]
	v_cndmask_b32_e64 v163, v250, v195, s[42:43]
	v_cndmask_b32_e64 v162, v225, v220, s[42:43]
	v_pk_fma_f32 v[160:161], v[154:155], v[160:161], v[166:167]
	v_pk_mul_f32 v[202:203], v[20:21], v[158:159]
	v_pk_fma_f32 v[162:163], v[156:157], v[162:163], v[160:161]
	v_cndmask_b32_e64 v160, v212, v216, s[40:41]
	v_mul_f32_e32 v216, v154, v160
	v_cndmask_b32_e64 v161, v220, v210, s[42:43]
	v_fmac_f32_e32 v216, v36, v158
	v_fmac_f32_e32 v216, v156, v161
	v_cndmask_b32_e64 v160, v214, v212, s[40:41]
	v_cndmask_b32_e64 v161, v222, v194, s[40:41]
	v_pk_fma_f32 v[160:161], v[154:155], v[160:161], v[202:203]
	v_cndmask_b32_e64 v154, v194, v190, s[40:41]
	v_cndmask_b32_e64 v166, v210, 0, s[42:43]
	v_cndmask_b32_e64 v167, v206, 0, s[42:43]
	v_mul_f32_e32 v190, v155, v154
	v_pk_mul_f32 v[164:165], v[54:55], v[150:151]
	v_pk_fma_f32 v[160:161], v[156:157], v[166:167], v[160:161]
	v_cndmask_b32_e64 v156, v195, v206, s[42:43]
	v_fmac_f32_e32 v190, v37, v159
	v_cndmask_b32_e64 v155, v189, v224, s[40:41]
	v_cndmask_b32_e64 v154, v211, v218, s[40:41]
	v_fmac_f32_e32 v190, v157, v156
	v_cndmask_b32_e64 v157, v223, v192, s[42:43]
	v_cndmask_b32_e64 v156, v217, v213, s[42:43]
	v_pk_fma_f32 v[154:155], v[146:147], v[154:155], v[164:165]
	v_pk_mul_f32 v[200:201], v[22:23], v[150:151]
	v_pk_fma_f32 v[156:157], v[148:149], v[156:157], v[154:155]
	v_cndmask_b32_e64 v154, v196, v211, s[40:41]
	v_mul_f32_e32 v194, v146, v154
	v_cndmask_b32_e64 v155, v213, v193, s[42:43]
	v_fmac_f32_e32 v194, v38, v150
	v_fmac_f32_e32 v194, v148, v155
	v_cndmask_b32_e64 v154, v207, v196, s[40:41]
	v_cndmask_b32_e64 v155, v215, v191, s[40:41]
	v_pk_fma_f32 v[154:155], v[146:147], v[154:155], v[200:201]
	v_cndmask_b32_e64 v146, v191, v189, s[40:41]
	v_cndmask_b32_e64 v158, v193, 0, s[42:43]
	v_cndmask_b32_e64 v159, v197, 0, s[42:43]
	v_mul_f32_e32 v189, v147, v146
	v_pk_fma_f32 v[154:155], v[148:149], v[158:159], v[154:155]
	v_cndmask_b32_e64 v148, v192, v197, s[42:43]
	v_fmac_f32_e32 v189, v39, v151
	v_cndmask_b32_e64 v147, v168, v221, s[40:41]
	v_cndmask_b32_e64 v146, v184, v209, s[40:41]
	v_pk_mul_f32 v[158:159], v[48:49], v[142:143]
	v_fmac_f32_e32 v189, v149, v148
	v_cndmask_b32_e64 v149, v219, v173, s[42:43]
	v_cndmask_b32_e64 v148, v208, v187, s[42:43]
	v_pk_fma_f32 v[146:147], v[140:141], v[146:147], v[158:159]
	v_pk_mul_f32 v[166:167], v[16:17], v[142:143]
	v_pk_fma_f32 v[148:149], v[144:145], v[148:149], v[146:147]
	v_cndmask_b32_e64 v146, v180, v184, s[40:41]
	v_mul_f32_e32 v184, v140, v146
	v_cndmask_b32_e64 v147, v187, v178, s[42:43]
	v_fmac_f32_e32 v184, v32, v142
	v_fmac_f32_e32 v184, v144, v147
	v_cndmask_b32_e64 v146, v182, v180, s[40:41]
	v_cndmask_b32_e64 v147, v188, v172, s[40:41]
	v_cndmask_b32_e64 v158, v178, 0, s[42:43]
	v_cndmask_b32_e64 v159, v176, 0, s[42:43]
	v_pk_fma_f32 v[146:147], v[140:141], v[146:147], v[166:167]
	v_cndmask_b32_e64 v140, v172, v168, s[40:41]
	v_pk_fma_f32 v[146:147], v[144:145], v[158:159], v[146:147]
	v_mul_f32_e32 v158, v141, v140
	v_pk_mul_f32 v[150:151], v[50:51], v[138:139]
	v_cndmask_b32_e64 v142, v173, v176, s[42:43]
	v_fmac_f32_e32 v158, v33, v143
	v_cndmask_b32_e64 v141, v85, v199, s[40:41]
	v_cndmask_b32_e64 v140, v179, v186, s[40:41]
	v_fmac_f32_e32 v158, v145, v142
	v_cndmask_b32_e64 v143, v198, v170, s[42:43]
	v_cndmask_b32_e64 v142, v185, v181, s[42:43]
	v_pk_fma_f32 v[140:141], v[136:137], v[140:141], v[150:151]
	v_pk_mul_f32 v[164:165], v[18:19], v[138:139]
	v_pk_fma_f32 v[142:143], v[86:87], v[142:143], v[140:141]
	v_cndmask_b32_e64 v140, v174, v179, s[40:41]
	v_mul_f32_e32 v150, v136, v140
	v_cndmask_b32_e64 v141, v181, v171, s[42:43]
	v_fmac_f32_e32 v150, v34, v138
	v_fmac_f32_e32 v150, v86, v141
	v_cndmask_b32_e64 v140, v177, v174, s[40:41]
	v_cndmask_b32_e64 v141, v183, v169, s[40:41]
	v_pk_fma_f32 v[140:141], v[136:137], v[140:141], v[164:165]
	v_cndmask_b32_e64 v85, v169, v85, s[40:41]
	v_exp_f32_e32 v136, v162
	v_cndmask_b32_e64 v144, v171, 0, s[42:43]
	v_cndmask_b32_e64 v145, v175, 0, s[42:43]
	v_mul_f32_e32 v85, v137, v85
; __device__ __forceinline__ void epi_ffn(const f32x4 (&acc)[2][2][4][2], const Job& J, int rowt, int pn, int wr, int wc, int fr, int fq, int lane) {
;     bf16_t* O = (bf16_t*)J.out; _Float16* SIDE = (_Float16*)J.out2; const float* cw = J.aux;
;     const int col = 128 * pn + 32 * wc + 8 * fq;
;     f32x4 w0[2], w1[2], w2[2];
; #pragma unroll
;     for (int n = 0; n < 2; ++n) { w0[n] = *(const f32x4*)(cw + col + 4 * n) * (-LOG2E); w1[n] = *(const f32x4*)(cw + DFF + col + 4 * n) * (-LOG2E); w2[n] = *(const f32x4*)(cw + 2 * DFF + col + 4 * n) * (-LOG2E); }
; #pragma unroll
;     for (int ai = 0; ai < 2; ++ai) {
;         const int blk = (rowt + ai * HALF + wr * 64) >> 6;
;         f32x4 cv[4][2];
; #pragma unroll
;         for (int n = 0; n < 2; ++n)
; #pragma unroll
;             for (int e = 0; e < 4; ++e) {
;                 float g[4], dn[4], up[4];
; #pragma unroll
;                 for (int m = 0; m < 4; ++m) { g[m] = acc[ai][0][m][n][e];
;                     dn[m] = __int_as_float(__builtin_amdgcn_mov_dpp(__float_as_int(g[m]), 0x121, 0xF, 0xF, false));
;                     up[m] = __int_as_float(__builtin_amdgcn_mov_dpp(__float_as_int(g[m]), 0x12F, 0xF, 0xF, false)); }
; #pragma unroll
;                 for (int m = 0; m < 4; ++m) {
;                     const float pv = fr > 0 ? dn[m] : (m > 0 ? dn[m - 1] : 0.f);
;                     const float nx = fr < 15 ? up[m] : (m < 3 ? up[m + 1] : 0.f);
;                     cv[m][n][e] = w0[n][e] * pv + w1[n][e] * g[m] + w2[n][e] * nx;
;                 }
;             }
; #pragma unroll
;         for (int m = 0; m < 4; ++m) {
;             const int grow = rowt + ai * HALF + wr * 64 + m * 16 + fr;
;             const bool first = (m == 0 && fr == 0), last = (m == 3 && fr == 15);
;             if (first || last) {
;                 typedef _Float16 sh4 __attribute__((ext_vector_type(4))); typedef _Float16 sh8 __attribute__((ext_vector_type(8)));
;                 _Float16* sp = SIDE + ((size_t)(blk * 2 + (last ? 1 : 0)) * 3) * DFF + col;
;                 auto pk = [](const f32x4& a, const f32x4& b) { const sh4 x = __builtin_convertvector(a, sh4), y = __builtin_convertvector(b, sh4); return (sh8){x[0], x[1], x[2], x[3], y[0], y[1], y[2], y[3]}; };
	v_pk_fma_f32 v[140:141], v[86:87], v[144:145], v[140:141]
	v_cndmask_b32_e64 v86, v170, v175, s[42:43]
	v_fmac_f32_e32 v85, v35, v139
	v_fmac_f32_e32 v85, v87, v86
	v_exp_f32_e32 v87, v148
	v_add_f32_e32 v86, 1.0, v136
	v_exp_f32_e32 v136, v163
	v_exp_f32_e32 v138, v149
	v_add_f32_e32 v137, 1.0, v87
	v_exp_f32_e32 v139, v142
	v_add_f32_e32 v87, 1.0, v136
	v_rcp_f32_e32 v136, v137
	v_add_f32_e32 v137, 1.0, v138
	v_rcp_f32_e32 v137, v137
	v_exp_f32_e32 v138, v156
	v_exp_f32_e32 v145, v157
	v_add_f32_e32 v139, 1.0, v139
	v_pk_mul_f32 v[136:137], v[148:149], v[136:137]
	v_exp_f32_e32 v148, v143
	v_add_f32_e32 v138, 1.0, v138
	v_rcp_f32_e32 v144, v139
	v_add_f32_e32 v139, 1.0, v145
	v_rcp_f32_e32 v138, v138
	v_rcp_f32_e32 v139, v139
	v_add_f32_e32 v145, 1.0, v148
	v_rcp_f32_e32 v145, v145
	v_pk_mul_f32 v[148:149], v[24:25], v[136:137]
	v_pk_mul_f32 v[136:137], v[156:157], v[138:139]
	v_rcp_f32_e32 v86, v86
	v_pk_mul_f32 v[138:139], v[30:31], v[136:137]
	v_pk_mul_f32 v[136:137], v[142:143], v[144:145]
	v_exp_f32_e32 v144, v216
	v_rcp_f32_e32 v87, v87
	v_pk_mul_f32 v[142:143], v[26:27], v[136:137]
	v_cvt_pk_bf16_f32 v137, v138, v139
	v_cvt_pk_bf16_f32 v139, v142, v143
	v_add_f32_e32 v142, 1.0, v144
	v_rcp_f32_e32 v142, v142
	v_pk_mul_f32 v[86:87], v[162:163], v[86:87]
	v_or_b32_e32 v151, 16, v80
	v_pk_mul_f32 v[86:87], v[28:29], v[86:87]
	v_cvt_pk_bf16_f32 v138, v148, v149
	v_cvt_pk_bf16_f32 v136, v86, v87
	v_mad_i64_i32 v[86:87], s[0:1], v151, s46, v[82:83]
	global_store_dwordx4 v[86:87], v[136:139], off sc1
	v_exp_f32_e32 v86, v184
	v_exp_f32_e32 v143, v189
	v_mul_f32_e32 v136, v216, v142
	v_exp_f32_e32 v137, v190
	v_exp_f32_e32 v138, v158
	v_exp_f32_e32 v139, v194
	v_exp_f32_e32 v142, v150
	v_exp_f32_e32 v144, v85
	v_add_f32_e32 v86, 1.0, v86
	v_add_f32_e32 v137, 1.0, v137
	v_add_f32_e32 v138, 1.0, v138
	v_add_f32_e32 v139, 1.0, v139
	v_add_f32_e32 v142, 1.0, v142
	v_add_f32_e32 v143, 1.0, v143
	v_add_f32_e32 v144, 1.0, v144
	v_rcp_f32_e32 v86, v86
	v_rcp_f32_e32 v137, v137
	v_rcp_f32_e32 v138, v138
	v_rcp_f32_e32 v139, v139
	v_rcp_f32_e32 v142, v142
	v_rcp_f32_e32 v143, v143
	v_rcp_f32_e32 v144, v144
	v_mul_f32_e32 v86, v184, v86
	v_mul_f32_e32 v137, v190, v137
	v_mul_f32_e32 v138, v158, v138
	v_mul_f32_e32 v139, v194, v139
	v_mul_f32_e32 v142, v150, v142
	v_mul_f32_e32 v143, v189, v143
	v_mul_f32_e32 v85, v85, v144
	v_or_b32_e32 v87, 32, v80
	v_mul_f32_e32 v136, v12, v136
	v_mul_f32_e32 v86, v8, v86
	v_mul_f32_e32 v137, v13, v137
	v_mul_f32_e32 v138, v9, v138
	v_mul_f32_e32 v139, v14, v139
	v_mul_f32_e32 v142, v10, v142
	v_mul_f32_e32 v143, v15, v143
	v_mul_f32_e32 v85, v11, v85
	v_cvt_pk_bf16_f32 v136, v136, v137
	v_cvt_pk_bf16_f32 v137, v139, v143
	v_cvt_pk_bf16_f32 v138, v86, v138
	v_cvt_pk_bf16_f32 v139, v142, v85
	v_mad_i64_i32 v[86:87], s[0:1], v87, s46, v[82:83]
	global_store_dwordx4 v[86:87], v[136:139], off sc1
	s_and_saveexec_b64 s[0:1], s[38:39]
	s_xor_b64 s[0:1], exec, s[0:1]
	s_cbranch_execz .LBB0_425
	v_exp_f32_e32 v85, v160
	v_or_b32_e32 v80, 48, v80
	v_mad_i64_i32 v[82:83], s[12:13], v80, s46, v[82:83]
	v_add_f32_e32 v85, 1.0, v85
	v_rcp_f32_e32 v86, v85
	v_exp_f32_e32 v85, v146
	s_nop 0
	v_add_f32_e32 v85, 1.0, v85
	v_rcp_f32_e32 v136, v85
	v_exp_f32_e32 v85, v161
	s_nop 0
	v_add_f32_e32 v85, 1.0, v85
	v_rcp_f32_e32 v87, v85
	v_exp_f32_e32 v85, v147
	v_pk_mul_f32 v[86:87], v[160:161], v[86:87]
	v_add_f32_e32 v85, 1.0, v85
	v_rcp_f32_e32 v137, v85
	v_exp_f32_e32 v85, v154
	v_pk_mul_f32 v[86:87], v[4:5], v[86:87]
	v_pk_mul_f32 v[136:137], v[146:147], v[136:137]
	v_add_f32_e32 v85, 1.0, v85
	v_pk_mul_f32 v[138:139], v[0:1], v[136:137]
	v_rcp_f32_e32 v136, v85
	v_exp_f32_e32 v85, v140
	v_cvt_pk_bf16_f32 v138, v138, v139
	v_add_f32_e32 v85, 1.0, v85
	v_rcp_f32_e32 v142, v85
	v_exp_f32_e32 v85, v155
	s_nop 0
	v_add_f32_e32 v85, 1.0, v85
	v_rcp_f32_e32 v137, v85
	v_exp_f32_e32 v85, v141
	v_pk_mul_f32 v[136:137], v[154:155], v[136:137]
	v_add_f32_e32 v85, 1.0, v85
	v_rcp_f32_e32 v143, v85
	v_pk_mul_f32 v[144:145], v[6:7], v[136:137]
	v_pk_mul_f32 v[136:137], v[140:141], v[142:143]
	s_nop 0
	v_pk_mul_f32 v[140:141], v[2:3], v[136:137]
	v_cvt_pk_bf16_f32 v136, v86, v87
	v_cvt_pk_bf16_f32 v137, v144, v145
	v_cvt_pk_bf16_f32 v139, v140, v141
	global_store_dwordx4 v[82:83], v[136:139], off sc1
.LBB0_425:
	s_andn2_saveexec_b64 s[0:1], s[0:1]
	s_cbranch_execz .LBB0_427
	s_mul_i32 s8, s8, 3
	s_add_i32 s8, s8, 3
	v_mad_i64_i32 v[82:83], s[8:9], s8, v235, v[152:153]
	s_mov_b32 s8, 0xbf317218
	s_nop 0
	v_pk_mul_f32 v[86:87], v[160:161], s[8:9] op_sel_hi:[1,0]
	v_pk_mul_f32 v[136:137], v[154:155], s[8:9] op_sel_hi:[1,0]
	v_pk_mul_f32 v[142:143], v[146:147], s[8:9] op_sel_hi:[1,0]
	v_pk_mul_f32 v[138:139], v[140:141], s[8:9] op_sel_hi:[1,0]
	s_movk_i32 s8, 0x1000
	v_cvt_pk_f16_f32 v137, v136, v137
	v_cvt_pk_f16_f32 v136, v86, v87
	v_add_co_u32_e32 v86, vcc, s8, v82
	v_cvt_pk_f16_f32 v139, v138, v139
	v_cvt_pk_f16_f32 v138, v142, v143
	v_addc_co_u32_e32 v87, vcc, 0, v83, vcc
	global_store_dwordx4 v[82:83], v[136:139], off sc1
	v_add_co_u32_e32 v82, vcc, 0x2000, v82
	s_nop 0
	v_cvt_pk_f16_f32 v139, v18, v19
	v_cvt_pk_f16_f32 v138, v16, v17
	v_cvt_pk_f16_f32 v137, v22, v23
	v_cvt_pk_f16_f32 v136, v20, v21
	global_store_dwordx4 v[86:87], v[136:139], off offset:1536 sc1
	v_addc_co_u32_e32 v83, vcc, 0, v83, vcc
	s_nop 0
	v_cvt_pk_f16_f32 v139, v2, v3
	v_cvt_pk_f16_f32 v138, v0, v1
	v_cvt_pk_f16_f32 v137, v6, v7
	v_cvt_pk_f16_f32 v136, v4, v5
	global_store_dwordx4 v[82:83], v[136:139], off offset:3072 sc1

; __device__ __forceinline__ u32x4 pack8(const f32x4& a, const f32x4& b) { u32x4 w; w.x = cvt_pk_bf16(a[0], a[1]); w.y = cvt_pk_bf16(a[2], a[3]); w.z = cvt_pk_bf16(b[0], b[1]); w.w = cvt_pk_bf16(b[2], b[3]); return w; }
; __device__ __forceinline__ void epi_vt(const f32x4 (&acc)[2][2][4][2], const Job& J, int pm, int pn, int wr, int wc, int fr, int fq) {
;     const int s = pm >> 1, c0 = (pm & 1) * 256;
;     bf16_t* base; size_t cstride;
;     if (pn < MX / 256) { const int b = pn >> 3, t0 = (pn & 7) * 256; base = (bf16_t*)J.out + ((size_t)(b * 512) * 2 + s) * SEQ + t0; cstride = 2 * SEQ; }
;     else { const int b = pn - MX / 256; base = (bf16_t*)J.out2 + ((size_t)(b * 512) * 2 + s) * CTXL; cstride = 2 * CTXL; }
; #pragma unroll
;     for (int ai = 0; ai < 2; ++ai)
; #pragma unroll
;         for (int m = 0; m < 4; ++m) {
;             bf16_t* rowp = base + (size_t)(c0 + ai * HALF + wr * 64 + m * 16 + fr) * cstride + wc * 32 + 8 * fq;
; #pragma unroll
;             for (int bj = 0; bj < 2; ++bj) *(u32x4*)(rowp + bj * HALF) = pack8(acc[ai][bj][m][0], acc[ai][bj][m][1]);
;         }
; }
.LBB0_432:
	s_lshl_b32 s1, s90, 8
	s_and_b32 s1, s1, 0x100
	v_readlane_b32 s8, v255, 8
	s_add_i32 s1, s1, s8
	v_or_b32_e32 v80, s1, v248
	v_readlane_b32 s1, v254, 59
	s_lshl_b32 s1, s1, 1
	s_add_u32 s8, s12, s1
	v_lshlrev_b32_e32 v82, 3, v247
	s_addc_u32 s9, s13, 0
	v_ashrrev_i32_e32 v83, 31, v82
	v_lshl_add_u64 v[82:83], v[82:83], 1, s[8:9]
	v_mad_i64_i32 v[86:87], s[8:9], s0, v80, 0
	v_lshl_add_u64 v[86:87], v[86:87], 1, v[82:83]
	v_cvt_pk_bf16_f32 v136, v132, v133
	v_cvt_pk_bf16_f32 v137, v134, v135
	v_cvt_pk_bf16_f32 v138, v128, v129
	v_cvt_pk_bf16_f32 v139, v130, v131
	global_store_dwordx4 v[86:87], v[136:139], off sc1
	v_or_b32_e32 v85, 16, v80
	s_nop 0
	v_cvt_pk_bf16_f32 v136, v116, v117
	v_cvt_pk_bf16_f32 v137, v118, v119
	v_cvt_pk_bf16_f32 v138, v112, v113
	v_cvt_pk_bf16_f32 v139, v114, v115
	global_store_dwordx4 v[86:87], v[136:139], off offset:256 sc1
	v_mad_i64_i32 v[86:87], s[8:9], s0, v85, 0
	v_lshl_add_u64 v[86:87], v[86:87], 1, v[82:83]
	v_cvt_pk_bf16_f32 v136, v124, v125
	v_cvt_pk_bf16_f32 v137, v126, v127
	v_cvt_pk_bf16_f32 v138, v120, v121
	v_cvt_pk_bf16_f32 v139, v122, v123
	global_store_dwordx4 v[86:87], v[136:139], off sc1
	v_or_b32_e32 v85, 32, v80
	s_nop 0
	v_cvt_pk_bf16_f32 v136, v100, v101
	v_cvt_pk_bf16_f32 v137, v102, v103
	v_cvt_pk_bf16_f32 v138, v96, v97
	v_cvt_pk_bf16_f32 v139, v98, v99
	global_store_dwordx4 v[86:87], v[136:139], off offset:256 sc1
	v_mad_i64_i32 v[86:87], s[8:9], s0, v85, 0
	v_lshl_add_u64 v[86:87], v[86:87], 1, v[82:83]
	v_cvt_pk_bf16_f32 v136, v108, v109
	v_cvt_pk_bf16_f32 v137, v110, v111
	v_cvt_pk_bf16_f32 v138, v104, v105
	v_cvt_pk_bf16_f32 v139, v106, v107
	global_store_dwordx4 v[86:87], v[136:139], off sc1
	v_or_b32_e32 v85, 48, v80
	s_nop 0
	v_cvt_pk_bf16_f32 v136, v76, v77
	v_cvt_pk_bf16_f32 v137, v78, v79
	v_cvt_pk_bf16_f32 v138, v72, v73
	v_cvt_pk_bf16_f32 v139, v74, v75
	global_store_dwordx4 v[86:87], v[136:139], off offset:256 sc1
	v_mad_i64_i32 v[86:87], s[8:9], s0, v85, 0
	v_lshl_add_u64 v[86:87], v[86:87], 1, v[82:83]
	v_cvt_pk_bf16_f32 v136, v92, v93
	v_cvt_pk_bf16_f32 v137, v94, v95
	v_cvt_pk_bf16_f32 v138, v88, v89
	v_cvt_pk_bf16_f32 v139, v90, v91
	global_store_dwordx4 v[86:87], v[136:139], off sc1
	v_add_u32_e32 v85, 0x80, v80
	s_nop 0
	v_cvt_pk_bf16_f32 v136, v68, v69
	v_cvt_pk_bf16_f32 v137, v70, v71
	v_cvt_pk_bf16_f32 v138, v60, v61
	v_cvt_pk_bf16_f32 v139, v62, v63
	global_store_dwordx4 v[86:87], v[136:139], off offset:256 sc1
	v_mad_i64_i32 v[86:87], s[8:9], s0, v85, 0
	v_lshl_add_u64 v[86:87], v[86:87], 1, v[82:83]
	v_cvt_pk_bf16_f32 v136, v64, v65
	v_cvt_pk_bf16_f32 v137, v66, v67
	v_cvt_pk_bf16_f32 v138, v56, v57
	v_cvt_pk_bf16_f32 v139, v58, v59
	global_store_dwordx4 v[86:87], v[136:139], off sc1
	v_add_u32_e32 v85, 0x90, v80
	s_nop 0
	v_cvt_pk_bf16_f32 v136, v44, v45
	v_cvt_pk_bf16_f32 v137, v46, v47
	v_cvt_pk_bf16_f32 v138, v40, v41
	v_cvt_pk_bf16_f32 v139, v42, v43
	global_store_dwordx4 v[86:87], v[136:139], off offset:256 sc1
	v_mad_i64_i32 v[86:87], s[8:9], s0, v85, 0
	v_lshl_add_u64 v[86:87], v[86:87], 1, v[82:83]
	v_cvt_pk_bf16_f32 v136, v52, v53
	v_cvt_pk_bf16_f32 v137, v54, v55
	v_cvt_pk_bf16_f32 v138, v48, v49
	v_cvt_pk_bf16_f32 v139, v50, v51
	global_store_dwordx4 v[86:87], v[136:139], off sc1
	v_add_u32_e32 v85, 0xa0, v80
	v_add_u32_e32 v80, 0xb0, v80
	v_cvt_pk_bf16_f32 v136, v28, v29
	v_cvt_pk_bf16_f32 v137, v30, v31
	v_cvt_pk_bf16_f32 v138, v24, v25
	v_cvt_pk_bf16_f32 v139, v26, v27
	global_store_dwordx4 v[86:87], v[136:139], off offset:256 sc1
	v_mad_i64_i32 v[86:87], s[8:9], s0, v85, 0
	v_lshl_add_u64 v[86:87], v[86:87], 1, v[82:83]
	v_cvt_pk_bf16_f32 v136, v36, v37
	v_cvt_pk_bf16_f32 v137, v38, v39
	v_cvt_pk_bf16_f32 v138, v32, v33
	v_cvt_pk_bf16_f32 v139, v34, v35
	global_store_dwordx4 v[86:87], v[136:139], off sc1
	s_nop 1
	v_cvt_pk_bf16_f32 v136, v12, v13
	v_cvt_pk_bf16_f32 v137, v14, v15
	v_cvt_pk_bf16_f32 v138, v8, v9
	v_cvt_pk_bf16_f32 v139, v10, v11
	global_store_dwordx4 v[86:87], v[136:139], off offset:256 sc1
	v_mad_i64_i32 v[86:87], s[0:1], s0, v80, 0
	v_lshl_add_u64 v[82:83], v[86:87], 1, v[82:83]
	v_cvt_pk_bf16_f32 v136, v20, v21
	v_cvt_pk_bf16_f32 v137, v22, v23
	v_cvt_pk_bf16_f32 v138, v16, v17
	v_cvt_pk_bf16_f32 v139, v18, v19
	global_store_dwordx4 v[82:83], v[136:139], off sc1
	s_nop 1
	v_cvt_pk_bf16_f32 v136, v4, v5
	v_cvt_pk_bf16_f32 v137, v6, v7
	v_cvt_pk_bf16_f32 v138, v0, v1
	v_cvt_pk_bf16_f32 v139, v2, v3
	global_store_dwordx4 v[82:83], v[136:139], off offset:256 sc1

; __device__ __forceinline__ u32x4 pack8(const f32x4& a, const f32x4& b) { u32x4 w; w.x = cvt_pk_bf16(a[0], a[1]); w.y = cvt_pk_bf16(a[2], a[3]); w.z = cvt_pk_bf16(b[0], b[1]); w.w = cvt_pk_bf16(b[2], b[3]); return w; }
; __device__ __forceinline__ void epi_rope(const f32x4 (&acc)[2][2][4][2], const Job& J, int rowt, int colb, int wr, int wc, int fr, int fq) {
;     bf16_t* O = (bf16_t*)J.out; const float* TC = J.aux; const float* TS = J.aux + 1024;
;     const bool anyrope = (rowt < MX) && (colb < 640); const int half = wc & 1, j0 = 8 * (fq & 1); const float sgn = fq < 2 ? -1.f : 1.f;
;     f32x4 tb[2][4];
; #pragma unroll
;     for (int q = 0; q < 4; ++q) tb[0][q] = tb[1][q] = (q < 2) ? (f32x4){1.f, 1.f, 1.f, 1.f} : (f32x4){0.f, 0.f, 0.f, 0.f};
;     auto ldtab = [&](int g, f32x4 (&t)[4]) {
;         const int grow = rowt + (g >> 2) * HALF + wr * 64 + (g & 3) * 16 + fr;
;         const int tt = grow & (SEQ - 1), pos = half ? (tt & 63) : (tt >> 6);
;         t[0] = *(const f32x4*)(TC + pos * 16 + j0); t[1] = *(const f32x4*)(TC + pos * 16 + j0 + 4);
;         t[2] = *(const f32x4*)(TS + pos * 16 + j0); t[3] = *(const f32x4*)(TS + pos * 16 + j0 + 4);
;     };
;     if (anyrope) ldtab(0, tb[0]);
; #pragma unroll
;     for (int g = 0; g < 8; ++g) {
;         const int ai = g >> 2, m = g & 3;
;         const int grow = rowt + ai * HALF + wr * 64 + m * 16 + fr;
;         if (anyrope && g + 1 < 8) ldtab(g + 1, tb[(g + 1) & 1]);
;         __builtin_amdgcn_sched_barrier(0);
;         const f32x4 c0 = tb[g & 1][0], c1 = tb[g & 1][1], s0 = tb[g & 1][2], s1 = tb[g & 1][3];
; #pragma unroll
;         for (int bj = 0; bj < 2; ++bj) {
;             const int cs = colb + bj * HALF; const bool isq = cs < 512, isk = (cs >= 512) && (cs < 640);
;             f32x4 v0 = acc[ai][bj][m][0], v1 = acc[ai][bj][m][1];
;             if ((isq || isk) && anyrope) {
;                 f32x4 p0, p1;
; #pragma unroll
;                 for (int e = 0; e < 4; ++e) { p0[e] = __shfl_xor(v0[e], 32); p1[e] = __shfl_xor(v1[e], 32); }
;                 v0 = v0 * c0 + (p0 * sgn) * s0; v1 = v1 * c1 + (p1 * sgn) * s1;
;             }
;             if (isq) { v0 = v0 * QSCALE; v1 = v1 * QSCALE; }
;             *(u32x4*)(O + (size_t)grow * J.ldc + cs + wc * 32 + 8 * fq) = pack8(v0, v1);
;         }
;         __builtin_amdgcn_sched_barrier(0);
;     }
; }
.LBB0_445:
	s_cmpk_lt_i32 s0, 0x200
	s_mov_b32 s8, 0x3e38aa3b
	v_pk_mul_f32 v[86:87], v[170:171], s[8:9] op_sel_hi:[1,0]
	v_pk_mul_f32 v[184:185], v[168:169], s[8:9] op_sel_hi:[1,0]
	s_cselect_b64 s[40:41], -1, 0
	v_pk_mul_f32 v[186:187], v[174:175], s[8:9] op_sel_hi:[1,0]
	v_pk_mul_f32 v[188:189], v[172:173], s[8:9] op_sel_hi:[1,0]
	v_cndmask_b32_e64 v87, v171, v87, s[40:41]
	v_cndmask_b32_e64 v86, v170, v86, s[40:41]
	v_cndmask_b32_e64 v169, v169, v185, s[40:41]
	v_cndmask_b32_e64 v168, v168, v184, s[40:41]
	v_ashrrev_i32_e32 v80, 31, v182
	v_cndmask_b32_e64 v85, v175, v187, s[40:41]
	v_cndmask_b32_e64 v174, v174, v186, s[40:41]
	v_cndmask_b32_e64 v173, v173, v189, s[40:41]
	v_cndmask_b32_e64 v172, v172, v188, s[40:41]
	v_cvt_pk_bf16_f32 v168, v168, v169
	v_cvt_pk_bf16_f32 v169, v86, v87
	v_mad_u64_u32 v[86:87], s[8:9], s2, v182, 0
	v_cvt_pk_bf16_f32 v170, v172, v173
	v_cvt_pk_bf16_f32 v171, v174, v85
	v_mul_lo_u32 v172, s3, v182
	v_mul_lo_u32 v85, s2, v80
	v_readlane_b32 s8, v254, 23
	v_add3_u32 v87, v87, v85, v172
	v_readlane_b32 s9, v254, 24
	s_ashr_i32 s1, s0, 31
	v_ashrrev_i32_e32 v177, 31, v176
	v_lshl_add_u64 v[86:87], v[86:87], 1, s[8:9]
	v_readlane_b32 s8, v254, 59
	v_lshl_add_u64 v[86:87], s[0:1], 1, v[86:87]
	s_lshl_b32 s8, s8, 1
	s_mov_b32 s9, s29
	v_lshl_add_u64 v[86:87], v[86:87], 0, s[8:9]
	v_lshl_add_u64 v[86:87], v[176:177], 1, v[86:87]
	s_and_b64 s[12:13], s[40:41], s[42:43]
	global_store_dwordx4 v[86:87], v[168:171], off sc1
	v_cndmask_b32_e64 v80, 0, 1, s[12:13]
	v_mov_b64_e32 v[174:175], v[114:115]
	v_mov_b64_e32 v[170:171], v[118:119]
	v_cmp_ne_u32_e64 s[44:45], 1, v80
	s_andn2_b64 vcc, exec, s[12:13]
	v_mov_b64_e32 v[172:173], v[112:113]
	v_mov_b64_e32 v[168:169], v[116:117]
	s_cbranch_vccnz .LBB0_447
	v_and_b32_e32 v168, 64, v231
	v_xor_b32_e32 v80, 32, v231
	v_add_u32_e32 v168, 64, v168
	v_cmp_lt_i32_e32 vcc, v80, v168
	v_mov_b32_e32 v184, v82
	v_mov_b32_e32 v185, v82
	v_cndmask_b32_e32 v80, v231, v80, vcc
	v_lshlrev_b32_e32 v80, 2, v80
	ds_bpermute_b32 v168, v80, v116
	ds_bpermute_b32 v172, v80, v112
	ds_bpermute_b32 v169, v80, v117
	ds_bpermute_b32 v173, v80, v113
	ds_bpermute_b32 v170, v80, v118
	ds_bpermute_b32 v171, v80, v119
	ds_bpermute_b32 v174, v80, v114
	ds_bpermute_b32 v175, v80, v115
	s_waitcnt lgkmcnt(0)
	v_pk_mul_f32 v[168:169], v[82:83], v[168:169]
	v_pk_mul_f32 v[172:173], v[82:83], v[172:173]
	v_pk_mul_f32 v[170:171], v[184:185], v[170:171]
	s_waitcnt vmcnt(0)
	v_pk_mul_f32 v[168:169], v[164:165], v[168:169]
	v_pk_mul_f32 v[174:175], v[184:185], v[174:175]
	v_pk_mul_f32 v[170:171], v[166:167], v[170:171]
	v_pk_mul_f32 v[172:173], v[160:161], v[172:173]
	v_pk_mul_f32 v[174:175], v[162:163], v[174:175]
	v_pk_fma_f32 v[170:171], v[118:119], v[158:159], v[170:171]
	v_pk_fma_f32 v[168:169], v[116:117], v[156:157], v[168:169]
	v_pk_fma_f32 v[174:175], v[114:115], v[154:155], v[174:175]
	v_pk_fma_f32 v[172:173], v[112:113], v[152:153], v[172:173]
.LBB0_447:
	s_cmpk_lt_i32 s0, 0x180
	s_mov_b32 s12, 0x3e38aa3b
	v_pk_mul_f32 v[184:185], v[170:171], s[12:13] op_sel_hi:[1,0]
	v_pk_mul_f32 v[186:187], v[168:169], s[12:13] op_sel_hi:[1,0]
	v_pk_mul_f32 v[188:189], v[174:175], s[12:13] op_sel_hi:[1,0]
	v_pk_mul_f32 v[190:191], v[172:173], s[12:13] op_sel_hi:[1,0]
	s_cselect_b64 s[42:43], -1, 0
	v_cndmask_b32_e64 v80, v175, v189, s[42:43]
	v_cndmask_b32_e64 v174, v174, v188, s[42:43]
	v_cndmask_b32_e64 v173, v173, v191, s[42:43]
	v_cndmask_b32_e64 v172, v172, v190, s[42:43]
	v_cndmask_b32_e64 v171, v171, v185, s[42:43]
	v_cndmask_b32_e64 v170, v170, v184, s[42:43]
	v_cndmask_b32_e64 v169, v169, v187, s[42:43]
	v_cndmask_b32_e64 v168, v168, v186, s[42:43]
	v_cvt_pk_bf16_f32 v168, v168, v169
	v_cvt_pk_bf16_f32 v169, v170, v171
	v_cvt_pk_bf16_f32 v170, v172, v173
	v_cvt_pk_bf16_f32 v171, v174, v80
	global_store_dwordx4 v[86:87], v[168:171], off offset:256 sc1
	s_and_b64 vcc, exec, s[38:39]
	s_cbranch_vccnz .LBB0_449
	v_readlane_b32 s12, v254, 60
	v_or_b32_e32 v80, 32, v248
	v_readlane_b32 s13, v254, 61
	s_nop 1
	v_cndmask_b32_e64 v80, v80, v183, s[12:13]
	v_lshlrev_b32_e32 v80, 6, v80
	v_lshl_add_u64 v[86:87], v[180:181], 0, v[80:81]
	global_load_dwordx4 v[152:155], v[86:87], off offset:16
	global_load_dwordx4 v[156:159], v[86:87], off
	v_lshl_add_u64 v[86:87], v[178:179], 0, v[80:81]
	global_load_dwordx4 v[160:163], v[86:87], off offset:16
	global_load_dwordx4 v[164:167], v[86:87], off

; __device__ __forceinline__ u32x4 pack8(const f32x4& a, const f32x4& b) { u32x4 w; w.x = cvt_pk_bf16(a[0], a[1]); w.y = cvt_pk_bf16(a[2], a[3]); w.z = cvt_pk_bf16(b[0], b[1]); w.w = cvt_pk_bf16(b[2], b[3]); return w; }
; __device__ __forceinline__ void epi_rope(const f32x4 (&acc)[2][2][4][2], const Job& J, int rowt, int colb, int wr, int wc, int fr, int fq) {
;     bf16_t* O = (bf16_t*)J.out; const float* TC = J.aux; const float* TS = J.aux + 1024;
;     const bool anyrope = (rowt < MX) && (colb < 640); const int half = wc & 1, j0 = 8 * (fq & 1); const float sgn = fq < 2 ? -1.f : 1.f;
;     f32x4 tb[2][4];
; #pragma unroll
;     for (int q = 0; q < 4; ++q) tb[0][q] = tb[1][q] = (q < 2) ? (f32x4){1.f, 1.f, 1.f, 1.f} : (f32x4){0.f, 0.f, 0.f, 0.f};
;     auto ldtab = [&](int g, f32x4 (&t)[4]) {
;         const int grow = rowt + (g >> 2) * HALF + wr * 64 + (g & 3) * 16 + fr;
;         const int tt = grow & (SEQ - 1), pos = half ? (tt & 63) : (tt >> 6);
;         t[0] = *(const f32x4*)(TC + pos * 16 + j0); t[1] = *(const f32x4*)(TC + pos * 16 + j0 + 4);
;         t[2] = *(const f32x4*)(TS + pos * 16 + j0); t[3] = *(const f32x4*)(TS + pos * 16 + j0 + 4);
;     };
;     if (anyrope) ldtab(0, tb[0]);
; #pragma unroll
;     for (int g = 0; g < 8; ++g) {
;         const int ai = g >> 2, m = g & 3;
;         const int grow = rowt + ai * HALF + wr * 64 + m * 16 + fr;
;         if (anyrope && g + 1 < 8) ldtab(g + 1, tb[(g + 1) & 1]);
;         __builtin_amdgcn_sched_barrier(0);
;         const f32x4 c0 = tb[g & 1][0], c1 = tb[g & 1][1], s0 = tb[g & 1][2], s1 = tb[g & 1][3];
; #pragma unroll
;         for (int bj = 0; bj < 2; ++bj) {
;             const int cs = colb + bj * HALF; const bool isq = cs < 512, isk = (cs >= 512) && (cs < 640);
;             f32x4 v0 = acc[ai][bj][m][0], v1 = acc[ai][bj][m][1];
;             if ((isq || isk) && anyrope) {
;                 f32x4 p0, p1;
; #pragma unroll
;                 for (int e = 0; e < 4; ++e) { p0[e] = __shfl_xor(v0[e], 32); p1[e] = __shfl_xor(v1[e], 32); }
;                 v0 = v0 * c0 + (p0 * sgn) * s0; v1 = v1 * c1 + (p1 * sgn) * s1;
;             }
;             if (isq) { v0 = v0 * QSCALE; v1 = v1 * QSCALE; }
;             *(u32x4*)(O + (size_t)grow * J.ldc + cs + wc * 32 + 8 * fq) = pack8(v0, v1);
;         }
;         __builtin_amdgcn_sched_barrier(0);
;     }
; }
.LBB0_451:
	s_mov_b32 s12, 0x3e38aa3b
	v_pk_mul_f32 v[86:87], v[170:171], s[12:13] op_sel_hi:[1,0]
	v_pk_mul_f32 v[184:185], v[168:169], s[12:13] op_sel_hi:[1,0]
	v_or_b32_e32 v80, 16, v182
	v_pk_mul_f32 v[188:189], v[172:173], s[12:13] op_sel_hi:[1,0]
	v_cndmask_b32_e64 v87, v171, v87, s[40:41]
	v_cndmask_b32_e64 v86, v170, v86, s[40:41]
	v_cndmask_b32_e64 v169, v169, v185, s[40:41]
	v_cndmask_b32_e64 v168, v168, v184, s[40:41]
	v_pk_mul_f32 v[186:187], v[174:175], s[12:13] op_sel_hi:[1,0]
	v_cndmask_b32_e64 v173, v173, v189, s[40:41]
	v_cndmask_b32_e64 v172, v172, v188, s[40:41]
	v_cvt_pk_bf16_f32 v168, v168, v169
	v_cvt_pk_bf16_f32 v169, v86, v87
	v_mad_u64_u32 v[86:87], s[12:13], s2, v80, 0
	v_cvt_pk_bf16_f32 v170, v172, v173
	v_mul_lo_u32 v172, s3, v80
	v_readlane_b32 s12, v254, 23
	v_add3_u32 v87, v87, v85, v172
	v_readlane_b32 s13, v254, 24
	s_mov_b32 s9, s29
	v_cndmask_b32_e64 v175, v175, v187, s[40:41]
	v_lshl_add_u64 v[86:87], v[86:87], 1, s[12:13]
	v_lshl_add_u64 v[86:87], s[0:1], 1, v[86:87]
	v_cndmask_b32_e64 v174, v174, v186, s[40:41]
	v_lshl_add_u64 v[86:87], v[86:87], 0, s[8:9]
	v_cvt_pk_bf16_f32 v171, v174, v175
	v_lshl_add_u64 v[86:87], v[176:177], 1, v[86:87]
	global_store_dwordx4 v[86:87], v[168:171], off sc1
	v_mov_b64_e32 v[174:175], v[98:99]
	s_and_b64 vcc, exec, s[44:45]
	v_mov_b64_e32 v[170:171], v[102:103]
	v_mov_b64_e32 v[172:173], v[96:97]
	v_mov_b64_e32 v[168:169], v[100:101]
	s_cbranch_vccnz .LBB0_453
	v_and_b32_e32 v168, 64, v231
	v_xor_b32_e32 v80, 32, v231
	v_add_u32_e32 v168, 64, v168
	v_cmp_lt_i32_e32 vcc, v80, v168
	v_mov_b32_e32 v184, v82
	v_mov_b32_e32 v185, v82
	v_cndmask_b32_e32 v80, v231, v80, vcc
	v_lshlrev_b32_e32 v80, 2, v80
	ds_bpermute_b32 v168, v80, v100
	ds_bpermute_b32 v172, v80, v96
	ds_bpermute_b32 v169, v80, v101
	ds_bpermute_b32 v173, v80, v97
	ds_bpermute_b32 v170, v80, v102
	ds_bpermute_b32 v171, v80, v103
	ds_bpermute_b32 v174, v80, v98
	ds_bpermute_b32 v175, v80, v99
	s_waitcnt lgkmcnt(0)
	v_pk_mul_f32 v[168:169], v[82:83], v[168:169]
	v_pk_mul_f32 v[172:173], v[82:83], v[172:173]
	v_pk_mul_f32 v[170:171], v[184:185], v[170:171]
	s_waitcnt vmcnt(0)
	v_pk_mul_f32 v[168:169], v[148:149], v[168:169]
	v_pk_mul_f32 v[174:175], v[184:185], v[174:175]
	v_pk_mul_f32 v[170:171], v[150:151], v[170:171]
	v_pk_mul_f32 v[172:173], v[144:145], v[172:173]
	v_pk_mul_f32 v[174:175], v[146:147], v[174:175]
	v_pk_fma_f32 v[170:171], v[102:103], v[142:143], v[170:171]
	v_pk_fma_f32 v[168:169], v[100:101], v[140:141], v[168:169]
	v_pk_fma_f32 v[174:175], v[98:99], v[138:139], v[174:175]
	v_pk_fma_f32 v[172:173], v[96:97], v[136:137], v[172:173]
.LBB0_453:
	s_mov_b32 s12, 0x3e38aa3b
	v_pk_mul_f32 v[184:185], v[170:171], s[12:13] op_sel_hi:[1,0]
	v_pk_mul_f32 v[186:187], v[168:169], s[12:13] op_sel_hi:[1,0]
	v_pk_mul_f32 v[188:189], v[174:175], s[12:13] op_sel_hi:[1,0]
	v_pk_mul_f32 v[190:191], v[172:173], s[12:13] op_sel_hi:[1,0]
	v_cndmask_b32_e64 v80, v175, v189, s[42:43]
	v_cndmask_b32_e64 v174, v174, v188, s[42:43]
	v_cndmask_b32_e64 v173, v173, v191, s[42:43]
	v_cndmask_b32_e64 v172, v172, v190, s[42:43]
	v_cndmask_b32_e64 v171, v171, v185, s[42:43]
	v_cndmask_b32_e64 v170, v170, v184, s[42:43]
	v_cndmask_b32_e64 v169, v169, v187, s[42:43]
	v_cndmask_b32_e64 v168, v168, v186, s[42:43]
	v_cvt_pk_bf16_f32 v168, v168, v169
	v_cvt_pk_bf16_f32 v169, v170, v171
	v_cvt_pk_bf16_f32 v170, v172, v173
	v_cvt_pk_bf16_f32 v171, v174, v80
	global_store_dwordx4 v[86:87], v[168:171], off offset:256 sc1
	s_and_b64 vcc, exec, s[38:39]
	s_cbranch_vccnz .LBB0_455
	v_readlane_b32 s12, v254, 60
	v_or_b32_e32 v80, 48, v248
	v_readlane_b32 s13, v254, 61
	s_nop 1
	v_cndmask_b32_e64 v80, v80, v183, s[12:13]
	v_lshlrev_b32_e32 v80, 6, v80
	v_lshl_add_u64 v[86:87], v[180:181], 0, v[80:81]
	global_load_dwordx4 v[136:139], v[86:87], off offset:16
	global_load_dwordx4 v[140:143], v[86:87], off
	v_lshl_add_u64 v[86:87], v[178:179], 0, v[80:81]
	global_load_dwordx4 v[144:147], v[86:87], off offset:16
	global_load_dwordx4 v[148:151], v[86:87], off

; __device__ __forceinline__ u32x4 pack8(const f32x4& a, const f32x4& b) { u32x4 w; w.x = cvt_pk_bf16(a[0], a[1]); w.y = cvt_pk_bf16(a[2], a[3]); w.z = cvt_pk_bf16(b[0], b[1]); w.w = cvt_pk_bf16(b[2], b[3]); return w; }
; __device__ __forceinline__ void epi_rope(const f32x4 (&acc)[2][2][4][2], const Job& J, int rowt, int colb, int wr, int wc, int fr, int fq) {
;     bf16_t* O = (bf16_t*)J.out; const float* TC = J.aux; const float* TS = J.aux + 1024;
;     const bool anyrope = (rowt < MX) && (colb < 640); const int half = wc & 1, j0 = 8 * (fq & 1); const float sgn = fq < 2 ? -1.f : 1.f;
;     f32x4 tb[2][4];
; #pragma unroll
;     for (int q = 0; q < 4; ++q) tb[0][q] = tb[1][q] = (q < 2) ? (f32x4){1.f, 1.f, 1.f, 1.f} : (f32x4){0.f, 0.f, 0.f, 0.f};
;     auto ldtab = [&](int g, f32x4 (&t)[4]) {
;         const int grow = rowt + (g >> 2) * HALF + wr * 64 + (g & 3) * 16 + fr;
;         const int tt = grow & (SEQ - 1), pos = half ? (tt & 63) : (tt >> 6);
;         t[0] = *(const f32x4*)(TC + pos * 16 + j0); t[1] = *(const f32x4*)(TC + pos * 16 + j0 + 4);
;         t[2] = *(const f32x4*)(TS + pos * 16 + j0); t[3] = *(const f32x4*)(TS + pos * 16 + j0 + 4);
;     };
;     if (anyrope) ldtab(0, tb[0]);
; #pragma unroll
;     for (int g = 0; g < 8; ++g) {
;         const int ai = g >> 2, m = g & 3;
;         const int grow = rowt + ai * HALF + wr * 64 + m * 16 + fr;
;         if (anyrope && g + 1 < 8) ldtab(g + 1, tb[(g + 1) & 1]);
;         __builtin_amdgcn_sched_barrier(0);
;         const f32x4 c0 = tb[g & 1][0], c1 = tb[g & 1][1], s0 = tb[g & 1][2], s1 = tb[g & 1][3];
; #pragma unroll
;         for (int bj = 0; bj < 2; ++bj) {
;             const int cs = colb + bj * HALF; const bool isq = cs < 512, isk = (cs >= 512) && (cs < 640);
;             f32x4 v0 = acc[ai][bj][m][0], v1 = acc[ai][bj][m][1];
;             if ((isq || isk) && anyrope) {
;                 f32x4 p0, p1;
; #pragma unroll
;                 for (int e = 0; e < 4; ++e) { p0[e] = __shfl_xor(v0[e], 32); p1[e] = __shfl_xor(v1[e], 32); }
;                 v0 = v0 * c0 + (p0 * sgn) * s0; v1 = v1 * c1 + (p1 * sgn) * s1;
;             }
;             if (isq) { v0 = v0 * QSCALE; v1 = v1 * QSCALE; }
;             *(u32x4*)(O + (size_t)grow * J.ldc + cs + wc * 32 + 8 * fq) = pack8(v0, v1);
;         }
;         __builtin_amdgcn_sched_barrier(0);
;     }
; }
.LBB0_457:
	s_mov_b32 s12, 0x3e38aa3b
	v_pk_mul_f32 v[86:87], v[170:171], s[12:13] op_sel_hi:[1,0]
	v_pk_mul_f32 v[184:185], v[168:169], s[12:13] op_sel_hi:[1,0]
	v_or_b32_e32 v80, 32, v182
	v_pk_mul_f32 v[188:189], v[172:173], s[12:13] op_sel_hi:[1,0]
	v_cndmask_b32_e64 v87, v171, v87, s[40:41]
	v_cndmask_b32_e64 v86, v170, v86, s[40:41]
	v_cndmask_b32_e64 v169, v169, v185, s[40:41]
	v_cndmask_b32_e64 v168, v168, v184, s[40:41]
	v_pk_mul_f32 v[186:187], v[174:175], s[12:13] op_sel_hi:[1,0]
	v_cndmask_b32_e64 v173, v173, v189, s[40:41]
	v_cndmask_b32_e64 v172, v172, v188, s[40:41]
	v_cvt_pk_bf16_f32 v168, v168, v169
	v_cvt_pk_bf16_f32 v169, v86, v87
	v_mad_u64_u32 v[86:87], s[12:13], s2, v80, 0
	v_cvt_pk_bf16_f32 v170, v172, v173
	v_mul_lo_u32 v172, s3, v80
	v_readlane_b32 s12, v254, 23
	v_add3_u32 v87, v87, v85, v172
	v_readlane_b32 s13, v254, 24
	s_mov_b32 s9, s29
	v_cndmask_b32_e64 v175, v175, v187, s[40:41]
	v_lshl_add_u64 v[86:87], v[86:87], 1, s[12:13]
	v_lshl_add_u64 v[86:87], s[0:1], 1, v[86:87]
	v_cndmask_b32_e64 v174, v174, v186, s[40:41]
	v_lshl_add_u64 v[86:87], v[86:87], 0, s[8:9]
	v_cvt_pk_bf16_f32 v171, v174, v175
	v_lshl_add_u64 v[86:87], v[176:177], 1, v[86:87]
	global_store_dwordx4 v[86:87], v[168:171], off sc1
	v_mov_b64_e32 v[174:175], v[74:75]
	s_and_b64 vcc, exec, s[44:45]
	v_mov_b64_e32 v[170:171], v[78:79]
	v_mov_b64_e32 v[172:173], v[72:73]
	v_mov_b64_e32 v[168:169], v[76:77]
	s_cbranch_vccnz .LBB0_459
	v_and_b32_e32 v168, 64, v231
	v_xor_b32_e32 v80, 32, v231
	v_add_u32_e32 v168, 64, v168
	v_cmp_lt_i32_e32 vcc, v80, v168
	v_mov_b32_e32 v184, v82
	v_mov_b32_e32 v185, v82
	v_cndmask_b32_e32 v80, v231, v80, vcc
	v_lshlrev_b32_e32 v80, 2, v80
	ds_bpermute_b32 v168, v80, v76
	ds_bpermute_b32 v172, v80, v72
	ds_bpermute_b32 v169, v80, v77
	ds_bpermute_b32 v173, v80, v73
	ds_bpermute_b32 v170, v80, v78
	ds_bpermute_b32 v171, v80, v79
	ds_bpermute_b32 v174, v80, v74
	ds_bpermute_b32 v175, v80, v75
	s_waitcnt lgkmcnt(0)
	v_pk_mul_f32 v[168:169], v[82:83], v[168:169]
	v_pk_mul_f32 v[172:173], v[82:83], v[172:173]
	v_pk_mul_f32 v[170:171], v[184:185], v[170:171]
	s_waitcnt vmcnt(0)
	v_pk_mul_f32 v[168:169], v[164:165], v[168:169]
	v_pk_mul_f32 v[174:175], v[184:185], v[174:175]
	v_pk_mul_f32 v[170:171], v[166:167], v[170:171]
	v_pk_mul_f32 v[172:173], v[160:161], v[172:173]
	v_pk_mul_f32 v[174:175], v[162:163], v[174:175]
	v_pk_fma_f32 v[170:171], v[78:79], v[158:159], v[170:171]
	v_pk_fma_f32 v[168:169], v[76:77], v[156:157], v[168:169]
	v_pk_fma_f32 v[174:175], v[74:75], v[154:155], v[174:175]
	v_pk_fma_f32 v[172:173], v[72:73], v[152:153], v[172:173]
.LBB0_459:
	s_mov_b32 s12, 0x3e38aa3b
	v_pk_mul_f32 v[184:185], v[170:171], s[12:13] op_sel_hi:[1,0]
	v_pk_mul_f32 v[186:187], v[168:169], s[12:13] op_sel_hi:[1,0]
	v_pk_mul_f32 v[188:189], v[174:175], s[12:13] op_sel_hi:[1,0]
	v_pk_mul_f32 v[190:191], v[172:173], s[12:13] op_sel_hi:[1,0]
	v_cndmask_b32_e64 v80, v175, v189, s[42:43]
	v_cndmask_b32_e64 v174, v174, v188, s[42:43]
	v_cndmask_b32_e64 v173, v173, v191, s[42:43]
	v_cndmask_b32_e64 v172, v172, v190, s[42:43]
	v_cndmask_b32_e64 v171, v171, v185, s[42:43]
	v_cndmask_b32_e64 v170, v170, v184, s[42:43]
	v_cndmask_b32_e64 v169, v169, v187, s[42:43]
	v_cndmask_b32_e64 v168, v168, v186, s[42:43]
	v_cvt_pk_bf16_f32 v168, v168, v169
	v_cvt_pk_bf16_f32 v169, v170, v171
	v_cvt_pk_bf16_f32 v170, v172, v173
	v_cvt_pk_bf16_f32 v171, v174, v80
	global_store_dwordx4 v[86:87], v[168:171], off offset:256 sc1
	s_and_b64 vcc, exec, s[38:39]
	v_add_u32_e32 v184, 0x80, v182
	s_cbranch_vccnz .LBB0_461
	v_readlane_b32 s12, v254, 60
	v_bfe_u32 v80, v184, 6, 5
	v_readlane_b32 s13, v254, 61
	s_nop 1
	v_cndmask_b32_e64 v80, v248, v80, s[12:13]
	v_lshlrev_b32_e32 v80, 6, v80
	v_lshl_add_u64 v[86:87], v[180:181], 0, v[80:81]
	global_load_dwordx4 v[152:155], v[86:87], off offset:16
	global_load_dwordx4 v[156:159], v[86:87], off
	v_lshl_add_u64 v[86:87], v[178:179], 0, v[80:81]
	global_load_dwordx4 v[160:163], v[86:87], off offset:16
	global_load_dwordx4 v[164:167], v[86:87], off

; __device__ __forceinline__ u32x4 pack8(const f32x4& a, const f32x4& b) { u32x4 w; w.x = cvt_pk_bf16(a[0], a[1]); w.y = cvt_pk_bf16(a[2], a[3]); w.z = cvt_pk_bf16(b[0], b[1]); w.w = cvt_pk_bf16(b[2], b[3]); return w; }
; __device__ __forceinline__ void epi_rope(const f32x4 (&acc)[2][2][4][2], const Job& J, int rowt, int colb, int wr, int wc, int fr, int fq) {
;     bf16_t* O = (bf16_t*)J.out; const float* TC = J.aux; const float* TS = J.aux + 1024;
;     const bool anyrope = (rowt < MX) && (colb < 640); const int half = wc & 1, j0 = 8 * (fq & 1); const float sgn = fq < 2 ? -1.f : 1.f;
;     f32x4 tb[2][4];
; #pragma unroll
;     for (int q = 0; q < 4; ++q) tb[0][q] = tb[1][q] = (q < 2) ? (f32x4){1.f, 1.f, 1.f, 1.f} : (f32x4){0.f, 0.f, 0.f, 0.f};
;     auto ldtab = [&](int g, f32x4 (&t)[4]) {
;         const int grow = rowt + (g >> 2) * HALF + wr * 64 + (g & 3) * 16 + fr;
;         const int tt = grow & (SEQ - 1), pos = half ? (tt & 63) : (tt >> 6);
;         t[0] = *(const f32x4*)(TC + pos * 16 + j0); t[1] = *(const f32x4*)(TC + pos * 16 + j0 + 4);
;         t[2] = *(const f32x4*)(TS + pos * 16 + j0); t[3] = *(const f32x4*)(TS + pos * 16 + j0 + 4);
;     };
;     if (anyrope) ldtab(0, tb[0]);
; #pragma unroll
;     for (int g = 0; g < 8; ++g) {
;         const int ai = g >> 2, m = g & 3;
;         const int grow = rowt + ai * HALF + wr * 64 + m * 16 + fr;
;         if (anyrope && g + 1 < 8) ldtab(g + 1, tb[(g + 1) & 1]);
;         __builtin_amdgcn_sched_barrier(0);
;         const f32x4 c0 = tb[g & 1][0], c1 = tb[g & 1][1], s0 = tb[g & 1][2], s1 = tb[g & 1][3];
; #pragma unroll
;         for (int bj = 0; bj < 2; ++bj) {
;             const int cs = colb + bj * HALF; const bool isq = cs < 512, isk = (cs >= 512) && (cs < 640);
;             f32x4 v0 = acc[ai][bj][m][0], v1 = acc[ai][bj][m][1];
;             if ((isq || isk) && anyrope) {
;                 f32x4 p0, p1;
; #pragma unroll
;                 for (int e = 0; e < 4; ++e) { p0[e] = __shfl_xor(v0[e], 32); p1[e] = __shfl_xor(v1[e], 32); }
;                 v0 = v0 * c0 + (p0 * sgn) * s0; v1 = v1 * c1 + (p1 * sgn) * s1;
;             }
;             if (isq) { v0 = v0 * QSCALE; v1 = v1 * QSCALE; }
;             *(u32x4*)(O + (size_t)grow * J.ldc + cs + wc * 32 + 8 * fq) = pack8(v0, v1);
;         }
;         __builtin_amdgcn_sched_barrier(0);
;     }
; }
.LBB0_463:
	s_mov_b32 s12, 0x3e38aa3b
	v_pk_mul_f32 v[86:87], v[170:171], s[12:13] op_sel_hi:[1,0]
	v_pk_mul_f32 v[186:187], v[168:169], s[12:13] op_sel_hi:[1,0]
	v_or_b32_e32 v80, 48, v182
	v_pk_mul_f32 v[190:191], v[172:173], s[12:13] op_sel_hi:[1,0]
	v_cndmask_b32_e64 v87, v171, v87, s[40:41]
	v_cndmask_b32_e64 v86, v170, v86, s[40:41]
	v_cndmask_b32_e64 v169, v169, v187, s[40:41]
	v_cndmask_b32_e64 v168, v168, v186, s[40:41]
	v_pk_mul_f32 v[188:189], v[174:175], s[12:13] op_sel_hi:[1,0]
	v_cndmask_b32_e64 v173, v173, v191, s[40:41]
	v_cndmask_b32_e64 v172, v172, v190, s[40:41]
	v_cvt_pk_bf16_f32 v168, v168, v169
	v_cvt_pk_bf16_f32 v169, v86, v87
	v_mad_u64_u32 v[86:87], s[12:13], s2, v80, 0
	v_cvt_pk_bf16_f32 v170, v172, v173
	v_mul_lo_u32 v172, s3, v80
	v_readlane_b32 s12, v254, 23
	v_add3_u32 v87, v87, v85, v172
	v_readlane_b32 s13, v254, 24
	s_mov_b32 s9, s29
	v_cndmask_b32_e64 v175, v175, v189, s[40:41]
	v_lshl_add_u64 v[86:87], v[86:87], 1, s[12:13]
	v_lshl_add_u64 v[86:87], s[0:1], 1, v[86:87]
	v_cndmask_b32_e64 v174, v174, v188, s[40:41]
	v_lshl_add_u64 v[86:87], v[86:87], 0, s[8:9]
	v_cvt_pk_bf16_f32 v171, v174, v175
	v_lshl_add_u64 v[86:87], v[176:177], 1, v[86:87]
	global_store_dwordx4 v[86:87], v[168:171], off sc1
	v_mov_b64_e32 v[174:175], v[62:63]
	s_and_b64 vcc, exec, s[44:45]
	v_mov_b64_e32 v[170:171], v[70:71]
	v_mov_b64_e32 v[172:173], v[60:61]
	v_mov_b64_e32 v[168:169], v[68:69]
	s_cbranch_vccnz .LBB0_465
	v_and_b32_e32 v85, 64, v231
	v_xor_b32_e32 v80, 32, v231
	v_add_u32_e32 v85, 64, v85
	v_cmp_lt_i32_e32 vcc, v80, v85
	v_mov_b32_e32 v186, v82
	v_mov_b32_e32 v187, v82
	v_cndmask_b32_e32 v80, v231, v80, vcc
	v_lshlrev_b32_e32 v80, 2, v80
	ds_bpermute_b32 v168, v80, v68
	ds_bpermute_b32 v172, v80, v60
	ds_bpermute_b32 v169, v80, v69
	ds_bpermute_b32 v173, v80, v61
	ds_bpermute_b32 v170, v80, v70
	ds_bpermute_b32 v171, v80, v71
	ds_bpermute_b32 v174, v80, v62
	ds_bpermute_b32 v175, v80, v63
	s_waitcnt lgkmcnt(0)
	v_pk_mul_f32 v[168:169], v[82:83], v[168:169]
	v_pk_mul_f32 v[172:173], v[82:83], v[172:173]
	v_pk_mul_f32 v[170:171], v[186:187], v[170:171]
	s_waitcnt vmcnt(0)
	v_pk_mul_f32 v[168:169], v[148:149], v[168:169]
	v_pk_mul_f32 v[174:175], v[186:187], v[174:175]
	v_pk_mul_f32 v[170:171], v[150:151], v[170:171]
	v_pk_mul_f32 v[172:173], v[144:145], v[172:173]
	v_pk_mul_f32 v[174:175], v[146:147], v[174:175]
	v_pk_fma_f32 v[170:171], v[70:71], v[142:143], v[170:171]
	v_pk_fma_f32 v[168:169], v[68:69], v[140:141], v[168:169]
	v_pk_fma_f32 v[174:175], v[62:63], v[138:139], v[174:175]
	v_pk_fma_f32 v[172:173], v[60:61], v[136:137], v[172:173]
.LBB0_465:
	s_mov_b32 s12, 0x3e38aa3b
	v_pk_mul_f32 v[186:187], v[170:171], s[12:13] op_sel_hi:[1,0]
	v_pk_mul_f32 v[188:189], v[168:169], s[12:13] op_sel_hi:[1,0]
	v_pk_mul_f32 v[190:191], v[174:175], s[12:13] op_sel_hi:[1,0]
	v_pk_mul_f32 v[192:193], v[172:173], s[12:13] op_sel_hi:[1,0]
	v_cndmask_b32_e64 v80, v175, v191, s[42:43]
	v_cndmask_b32_e64 v85, v174, v190, s[42:43]
	v_cndmask_b32_e64 v173, v173, v193, s[42:43]
	v_cndmask_b32_e64 v172, v172, v192, s[42:43]
	v_cndmask_b32_e64 v171, v171, v187, s[42:43]
	v_cndmask_b32_e64 v170, v170, v186, s[42:43]
	v_cndmask_b32_e64 v169, v169, v189, s[42:43]
	v_cndmask_b32_e64 v168, v168, v188, s[42:43]
	v_cvt_pk_bf16_f32 v168, v168, v169
	v_cvt_pk_bf16_f32 v169, v170, v171
	v_cvt_pk_bf16_f32 v170, v172, v173
	v_cvt_pk_bf16_f32 v171, v85, v80
	global_store_dwordx4 v[86:87], v[168:171], off offset:256 sc1
	s_and_b64 vcc, exec, s[38:39]
	v_add_u32_e32 v183, 0x90, v182
	s_cbranch_vccnz .LBB0_467
	v_readlane_b32 s12, v254, 60
	v_lshrrev_b32_e32 v80, 6, v183
	v_readlane_b32 s13, v254, 61
	s_nop 1
	v_cndmask_b32_e64 v80, v183, v80, s[12:13]
	v_lshlrev_b32_e32 v80, 6, v80
	v_and_b32_e32 v80, 0x7c0, v80
	v_lshl_add_u64 v[86:87], v[180:181], 0, v[80:81]
	global_load_dwordx4 v[136:139], v[86:87], off offset:16
	global_load_dwordx4 v[140:143], v[86:87], off
	v_lshl_add_u64 v[86:87], v[178:179], 0, v[80:81]
	global_load_dwordx4 v[144:147], v[86:87], off offset:16
	global_load_dwordx4 v[148:151], v[86:87], off

; __device__ __forceinline__ u32x4 pack8(const f32x4& a, const f32x4& b) { u32x4 w; w.x = cvt_pk_bf16(a[0], a[1]); w.y = cvt_pk_bf16(a[2], a[3]); w.z = cvt_pk_bf16(b[0], b[1]); w.w = cvt_pk_bf16(b[2], b[3]); return w; }
; __device__ __forceinline__ void epi_rope(const f32x4 (&acc)[2][2][4][2], const Job& J, int rowt, int colb, int wr, int wc, int fr, int fq) {
;     bf16_t* O = (bf16_t*)J.out; const float* TC = J.aux; const float* TS = J.aux + 1024;
;     const bool anyrope = (rowt < MX) && (colb < 640); const int half = wc & 1, j0 = 8 * (fq & 1); const float sgn = fq < 2 ? -1.f : 1.f;
;     f32x4 tb[2][4];
; #pragma unroll
;     for (int q = 0; q < 4; ++q) tb[0][q] = tb[1][q] = (q < 2) ? (f32x4){1.f, 1.f, 1.f, 1.f} : (f32x4){0.f, 0.f, 0.f, 0.f};
;     auto ldtab = [&](int g, f32x4 (&t)[4]) {
;         const int grow = rowt + (g >> 2) * HALF + wr * 64 + (g & 3) * 16 + fr;
;         const int tt = grow & (SEQ - 1), pos = half ? (tt & 63) : (tt >> 6);
;         t[0] = *(const f32x4*)(TC + pos * 16 + j0); t[1] = *(const f32x4*)(TC + pos * 16 + j0 + 4);
;         t[2] = *(const f32x4*)(TS + pos * 16 + j0); t[3] = *(const f32x4*)(TS + pos * 16 + j0 + 4);
;     };
;     if (anyrope) ldtab(0, tb[0]);
; #pragma unroll
;     for (int g = 0; g < 8; ++g) {
;         const int ai = g >> 2, m = g & 3;
;         const int grow = rowt + ai * HALF + wr * 64 + m * 16 + fr;
;         if (anyrope && g + 1 < 8) ldtab(g + 1, tb[(g + 1) & 1]);
;         __builtin_amdgcn_sched_barrier(0);
;         const f32x4 c0 = tb[g & 1][0], c1 = tb[g & 1][1], s0 = tb[g & 1][2], s1 = tb[g & 1][3];
; #pragma unroll
;         for (int bj = 0; bj < 2; ++bj) {
;             const int cs = colb + bj * HALF; const bool isq = cs < 512, isk = (cs >= 512) && (cs < 640);
;             f32x4 v0 = acc[ai][bj][m][0], v1 = acc[ai][bj][m][1];
;             if ((isq || isk) && anyrope) {
;                 f32x4 p0, p1;
; #pragma unroll
;                 for (int e = 0; e < 4; ++e) { p0[e] = __shfl_xor(v0[e], 32); p1[e] = __shfl_xor(v1[e], 32); }
;                 v0 = v0 * c0 + (p0 * sgn) * s0; v1 = v1 * c1 + (p1 * sgn) * s1;
;             }
;             if (isq) { v0 = v0 * QSCALE; v1 = v1 * QSCALE; }
;             *(u32x4*)(O + (size_t)grow * J.ldc + cs + wc * 32 + 8 * fq) = pack8(v0, v1);
;         }
;         __builtin_amdgcn_sched_barrier(0);
;     }
; }
.LBB0_469:
	s_mov_b32 s12, 0x3e38aa3b
	v_pk_mul_f32 v[86:87], v[170:171], s[12:13] op_sel_hi:[1,0]
	v_pk_mul_f32 v[186:187], v[168:169], s[12:13] op_sel_hi:[1,0]
	v_pk_mul_f32 v[188:189], v[174:175], s[12:13] op_sel_hi:[1,0]
	v_cndmask_b32_e64 v87, v171, v87, s[40:41]
	v_cndmask_b32_e64 v86, v170, v86, s[40:41]
	v_cndmask_b32_e64 v169, v169, v187, s[40:41]
	v_cndmask_b32_e64 v168, v168, v186, s[40:41]
	v_ashrrev_i32_e32 v80, 31, v184
	v_pk_mul_f32 v[190:191], v[172:173], s[12:13] op_sel_hi:[1,0]
	v_cndmask_b32_e64 v85, v175, v189, s[40:41]
	v_cndmask_b32_e64 v174, v174, v188, s[40:41]
	v_cvt_pk_bf16_f32 v168, v168, v169
	v_cvt_pk_bf16_f32 v169, v86, v87
	v_mad_u64_u32 v[86:87], s[12:13], s2, v184, 0
	v_cvt_pk_bf16_f32 v171, v174, v85
	v_mul_lo_u32 v80, s2, v80
	v_mul_lo_u32 v85, s3, v184
	v_readlane_b32 s12, v254, 23
	v_add3_u32 v87, v87, v80, v85
	v_readlane_b32 s13, v254, 24
	s_mov_b32 s9, s29
	v_cndmask_b32_e64 v173, v173, v191, s[40:41]
	v_lshl_add_u64 v[86:87], v[86:87], 1, s[12:13]
	v_lshl_add_u64 v[86:87], s[0:1], 1, v[86:87]
	v_cndmask_b32_e64 v172, v172, v190, s[40:41]
	v_lshl_add_u64 v[86:87], v[86:87], 0, s[8:9]
	v_cvt_pk_bf16_f32 v170, v172, v173
	v_lshl_add_u64 v[86:87], v[176:177], 1, v[86:87]
	global_store_dwordx4 v[86:87], v[168:171], off sc1
	v_mov_b64_e32 v[174:175], v[42:43]
	s_and_b64 vcc, exec, s[44:45]
	v_mov_b64_e32 v[170:171], v[46:47]
	v_mov_b64_e32 v[172:173], v[40:41]
	v_mov_b64_e32 v[168:169], v[44:45]
	s_cbranch_vccnz .LBB0_471
	v_and_b32_e32 v85, 64, v231
	v_xor_b32_e32 v80, 32, v231
	v_add_u32_e32 v85, 64, v85
	v_cmp_lt_i32_e32 vcc, v80, v85
	v_mov_b32_e32 v184, v82
	v_mov_b32_e32 v185, v82
	v_cndmask_b32_e32 v80, v231, v80, vcc
	v_lshlrev_b32_e32 v80, 2, v80
	ds_bpermute_b32 v168, v80, v44
	ds_bpermute_b32 v172, v80, v40
	ds_bpermute_b32 v169, v80, v45
	ds_bpermute_b32 v173, v80, v41
	ds_bpermute_b32 v170, v80, v46
	ds_bpermute_b32 v171, v80, v47
	ds_bpermute_b32 v174, v80, v42
	ds_bpermute_b32 v175, v80, v43
	s_waitcnt lgkmcnt(0)
	v_pk_mul_f32 v[168:169], v[82:83], v[168:169]
	v_pk_mul_f32 v[172:173], v[82:83], v[172:173]
	v_pk_mul_f32 v[170:171], v[184:185], v[170:171]
	s_waitcnt vmcnt(0)
	v_pk_mul_f32 v[168:169], v[164:165], v[168:169]
	v_pk_mul_f32 v[174:175], v[184:185], v[174:175]
	v_pk_mul_f32 v[170:171], v[166:167], v[170:171]
	v_pk_mul_f32 v[172:173], v[160:161], v[172:173]
	v_pk_mul_f32 v[174:175], v[162:163], v[174:175]
	v_pk_fma_f32 v[170:171], v[46:47], v[158:159], v[170:171]
	v_pk_fma_f32 v[168:169], v[44:45], v[156:157], v[168:169]
	v_pk_fma_f32 v[174:175], v[42:43], v[154:155], v[174:175]
	v_pk_fma_f32 v[172:173], v[40:41], v[152:153], v[172:173]
.LBB0_471:
	s_mov_b32 s12, 0x3e38aa3b
	v_pk_mul_f32 v[184:185], v[170:171], s[12:13] op_sel_hi:[1,0]
	v_pk_mul_f32 v[186:187], v[168:169], s[12:13] op_sel_hi:[1,0]
	v_pk_mul_f32 v[188:189], v[174:175], s[12:13] op_sel_hi:[1,0]
	v_pk_mul_f32 v[190:191], v[172:173], s[12:13] op_sel_hi:[1,0]
	v_cndmask_b32_e64 v80, v175, v189, s[42:43]
	v_cndmask_b32_e64 v85, v174, v188, s[42:43]
	v_cndmask_b32_e64 v173, v173, v191, s[42:43]
	v_cndmask_b32_e64 v172, v172, v190, s[42:43]
	v_cndmask_b32_e64 v171, v171, v185, s[42:43]
	v_cndmask_b32_e64 v170, v170, v184, s[42:43]
	v_cndmask_b32_e64 v169, v169, v187, s[42:43]
	v_cndmask_b32_e64 v168, v168, v186, s[42:43]
	v_cvt_pk_bf16_f32 v168, v168, v169
	v_cvt_pk_bf16_f32 v169, v170, v171
	v_cvt_pk_bf16_f32 v170, v172, v173
	v_cvt_pk_bf16_f32 v171, v85, v80
	global_store_dwordx4 v[86:87], v[168:171], off offset:256 sc1
	s_and_b64 vcc, exec, s[38:39]
	v_add_u32_e32 v85, 0xa0, v182
	s_cbranch_vccnz .LBB0_473
	v_readlane_b32 s12, v254, 60
	v_and_b32_e32 v80, 47, v85
	v_bfe_u32 v86, v85, 6, 5
	v_readlane_b32 s13, v254, 61
	s_nop 1
	v_cndmask_b32_e64 v80, v80, v86, s[12:13]
	v_lshlrev_b32_e32 v80, 6, v80
	v_lshl_add_u64 v[86:87], v[180:181], 0, v[80:81]
	global_load_dwordx4 v[152:155], v[86:87], off offset:16
	global_load_dwordx4 v[156:159], v[86:87], off
	v_lshl_add_u64 v[86:87], v[178:179], 0, v[80:81]
	global_load_dwordx4 v[160:163], v[86:87], off offset:16
	global_load_dwordx4 v[164:167], v[86:87], off

; __device__ __forceinline__ u32x4 pack8(const f32x4& a, const f32x4& b) { u32x4 w; w.x = cvt_pk_bf16(a[0], a[1]); w.y = cvt_pk_bf16(a[2], a[3]); w.z = cvt_pk_bf16(b[0], b[1]); w.w = cvt_pk_bf16(b[2], b[3]); return w; }
; __device__ __forceinline__ void epi_rope(const f32x4 (&acc)[2][2][4][2], const Job& J, int rowt, int colb, int wr, int wc, int fr, int fq) {
;     bf16_t* O = (bf16_t*)J.out; const float* TC = J.aux; const float* TS = J.aux + 1024;
;     const bool anyrope = (rowt < MX) && (colb < 640); const int half = wc & 1, j0 = 8 * (fq & 1); const float sgn = fq < 2 ? -1.f : 1.f;
;     f32x4 tb[2][4];
; #pragma unroll
;     for (int q = 0; q < 4; ++q) tb[0][q] = tb[1][q] = (q < 2) ? (f32x4){1.f, 1.f, 1.f, 1.f} : (f32x4){0.f, 0.f, 0.f, 0.f};
;     auto ldtab = [&](int g, f32x4 (&t)[4]) {
;         const int grow = rowt + (g >> 2) * HALF + wr * 64 + (g & 3) * 16 + fr;
;         const int tt = grow & (SEQ - 1), pos = half ? (tt & 63) : (tt >> 6);
;         t[0] = *(const f32x4*)(TC + pos * 16 + j0); t[1] = *(const f32x4*)(TC + pos * 16 + j0 + 4);
;         t[2] = *(const f32x4*)(TS + pos * 16 + j0); t[3] = *(const f32x4*)(TS + pos * 16 + j0 + 4);
;     };
;     if (anyrope) ldtab(0, tb[0]);
; #pragma unroll
;     for (int g = 0; g < 8; ++g) {
;         const int ai = g >> 2, m = g & 3;
;         const int grow = rowt + ai * HALF + wr * 64 + m * 16 + fr;
;         if (anyrope && g + 1 < 8) ldtab(g + 1, tb[(g + 1) & 1]);
;         __builtin_amdgcn_sched_barrier(0);
;         const f32x4 c0 = tb[g & 1][0], c1 = tb[g & 1][1], s0 = tb[g & 1][2], s1 = tb[g & 1][3];
; #pragma unroll
;         for (int bj = 0; bj < 2; ++bj) {
;             const int cs = colb + bj * HALF; const bool isq = cs < 512, isk = (cs >= 512) && (cs < 640);
;             f32x4 v0 = acc[ai][bj][m][0], v1 = acc[ai][bj][m][1];
;             if ((isq || isk) && anyrope) {
;                 f32x4 p0, p1;
; #pragma unroll
;                 for (int e = 0; e < 4; ++e) { p0[e] = __shfl_xor(v0[e], 32); p1[e] = __shfl_xor(v1[e], 32); }
;                 v0 = v0 * c0 + (p0 * sgn) * s0; v1 = v1 * c1 + (p1 * sgn) * s1;
;             }
;             if (isq) { v0 = v0 * QSCALE; v1 = v1 * QSCALE; }
;             *(u32x4*)(O + (size_t)grow * J.ldc + cs + wc * 32 + 8 * fq) = pack8(v0, v1);
;         }
;         __builtin_amdgcn_sched_barrier(0);
;     }
; }
.LBB0_475:
	s_mov_b32 s12, 0x3e38aa3b
	v_pk_mul_f32 v[86:87], v[170:171], s[12:13] op_sel_hi:[1,0]
	v_pk_mul_f32 v[184:185], v[168:169], s[12:13] op_sel_hi:[1,0]
	v_pk_mul_f32 v[188:189], v[172:173], s[12:13] op_sel_hi:[1,0]
	v_cndmask_b32_e64 v87, v171, v87, s[40:41]
	v_cndmask_b32_e64 v86, v170, v86, s[40:41]
	v_cndmask_b32_e64 v169, v169, v185, s[40:41]
	v_cndmask_b32_e64 v168, v168, v184, s[40:41]
	v_ashrrev_i32_e32 v80, 31, v183
	v_pk_mul_f32 v[186:187], v[174:175], s[12:13] op_sel_hi:[1,0]
	v_cndmask_b32_e64 v173, v173, v189, s[40:41]
	v_cndmask_b32_e64 v172, v172, v188, s[40:41]
	v_cvt_pk_bf16_f32 v168, v168, v169
	v_cvt_pk_bf16_f32 v169, v86, v87
	v_mad_u64_u32 v[86:87], s[12:13], s2, v183, 0
	v_cvt_pk_bf16_f32 v170, v172, v173
	v_mul_lo_u32 v80, s2, v80
	v_mul_lo_u32 v172, s3, v183
	v_readlane_b32 s12, v254, 23
	v_add3_u32 v87, v87, v80, v172
	v_readlane_b32 s13, v254, 24
	s_mov_b32 s9, s29
	v_cndmask_b32_e64 v175, v175, v187, s[40:41]
	v_lshl_add_u64 v[86:87], v[86:87], 1, s[12:13]
	v_lshl_add_u64 v[86:87], s[0:1], 1, v[86:87]
	v_cndmask_b32_e64 v174, v174, v186, s[40:41]
	v_lshl_add_u64 v[86:87], v[86:87], 0, s[8:9]
	v_cvt_pk_bf16_f32 v171, v174, v175
	v_lshl_add_u64 v[86:87], v[176:177], 1, v[86:87]
	global_store_dwordx4 v[86:87], v[168:171], off sc1
	v_mov_b64_e32 v[174:175], v[26:27]
	s_and_b64 vcc, exec, s[44:45]
	v_mov_b64_e32 v[170:171], v[30:31]
	v_mov_b64_e32 v[172:173], v[24:25]
	v_mov_b64_e32 v[168:169], v[28:29]
	s_cbranch_vccnz .LBB0_477
	v_and_b32_e32 v168, 64, v231
	v_xor_b32_e32 v80, 32, v231
	v_add_u32_e32 v168, 64, v168
	v_cmp_lt_i32_e32 vcc, v80, v168
	v_mov_b32_e32 v184, v82
	v_mov_b32_e32 v185, v82
	v_cndmask_b32_e32 v80, v231, v80, vcc
	v_lshlrev_b32_e32 v80, 2, v80
	ds_bpermute_b32 v168, v80, v28
	ds_bpermute_b32 v172, v80, v24
	ds_bpermute_b32 v169, v80, v29
	ds_bpermute_b32 v173, v80, v25
	ds_bpermute_b32 v170, v80, v30
	ds_bpermute_b32 v171, v80, v31
	ds_bpermute_b32 v174, v80, v26
	ds_bpermute_b32 v175, v80, v27
	s_waitcnt lgkmcnt(0)
	v_pk_mul_f32 v[168:169], v[82:83], v[168:169]
	v_pk_mul_f32 v[172:173], v[82:83], v[172:173]
	v_pk_mul_f32 v[170:171], v[184:185], v[170:171]
	s_waitcnt vmcnt(0)
	v_pk_mul_f32 v[168:169], v[148:149], v[168:169]
	v_pk_mul_f32 v[174:175], v[184:185], v[174:175]
	v_pk_mul_f32 v[170:171], v[150:151], v[170:171]
	v_pk_mul_f32 v[172:173], v[144:145], v[172:173]
	v_pk_mul_f32 v[174:175], v[146:147], v[174:175]
	v_pk_fma_f32 v[170:171], v[30:31], v[142:143], v[170:171]
	v_pk_fma_f32 v[168:169], v[28:29], v[140:141], v[168:169]
	v_pk_fma_f32 v[174:175], v[26:27], v[138:139], v[174:175]
	v_pk_fma_f32 v[172:173], v[24:25], v[136:137], v[172:173]
.LBB0_477:
	s_mov_b32 s12, 0x3e38aa3b
	v_pk_mul_f32 v[184:185], v[170:171], s[12:13] op_sel_hi:[1,0]
	v_pk_mul_f32 v[186:187], v[168:169], s[12:13] op_sel_hi:[1,0]
	v_pk_mul_f32 v[188:189], v[174:175], s[12:13] op_sel_hi:[1,0]
	v_pk_mul_f32 v[190:191], v[172:173], s[12:13] op_sel_hi:[1,0]
	v_cndmask_b32_e64 v80, v175, v189, s[42:43]
	v_cndmask_b32_e64 v174, v174, v188, s[42:43]
	v_cndmask_b32_e64 v173, v173, v191, s[42:43]
	v_cndmask_b32_e64 v172, v172, v190, s[42:43]
	v_cndmask_b32_e64 v171, v171, v185, s[42:43]
	v_cndmask_b32_e64 v170, v170, v184, s[42:43]
	v_cndmask_b32_e64 v169, v169, v187, s[42:43]
	v_cndmask_b32_e64 v168, v168, v186, s[42:43]
	v_cvt_pk_bf16_f32 v168, v168, v169
	v_cvt_pk_bf16_f32 v169, v170, v171
	v_cvt_pk_bf16_f32 v170, v172, v173
	v_cvt_pk_bf16_f32 v171, v174, v80
	global_store_dwordx4 v[86:87], v[168:171], off offset:256 sc1
	s_and_b64 vcc, exec, s[38:39]
	v_add_u32_e32 v182, 0xb0, v182
	s_cbranch_vccnz .LBB0_479
	v_readlane_b32 s12, v254, 60
	v_and_b32_e32 v80, 63, v182
	v_bfe_u32 v86, v182, 6, 5
	v_readlane_b32 s13, v254, 61
	s_nop 1
	v_cndmask_b32_e64 v80, v80, v86, s[12:13]
	v_lshlrev_b32_e32 v80, 6, v80
	v_lshl_add_u64 v[86:87], v[180:181], 0, v[80:81]
	global_load_dwordx4 v[136:139], v[86:87], off offset:16
	global_load_dwordx4 v[140:143], v[86:87], off
	v_lshl_add_u64 v[86:87], v[178:179], 0, v[80:81]
	global_load_dwordx4 v[144:147], v[86:87], off offset:16
	global_load_dwordx4 v[148:151], v[86:87], off

; __device__ __forceinline__ u32x4 pack8(const f32x4& a, const f32x4& b) { u32x4 w; w.x = cvt_pk_bf16(a[0], a[1]); w.y = cvt_pk_bf16(a[2], a[3]); w.z = cvt_pk_bf16(b[0], b[1]); w.w = cvt_pk_bf16(b[2], b[3]); return w; }
; __device__ __forceinline__ void epi_rope(const f32x4 (&acc)[2][2][4][2], const Job& J, int rowt, int colb, int wr, int wc, int fr, int fq) {
;     bf16_t* O = (bf16_t*)J.out; const float* TC = J.aux; const float* TS = J.aux + 1024;
;     const bool anyrope = (rowt < MX) && (colb < 640); const int half = wc & 1, j0 = 8 * (fq & 1); const float sgn = fq < 2 ? -1.f : 1.f;
;     f32x4 tb[2][4];
; #pragma unroll
;     for (int q = 0; q < 4; ++q) tb[0][q] = tb[1][q] = (q < 2) ? (f32x4){1.f, 1.f, 1.f, 1.f} : (f32x4){0.f, 0.f, 0.f, 0.f};
;     auto ldtab = [&](int g, f32x4 (&t)[4]) {
;         const int grow = rowt + (g >> 2) * HALF + wr * 64 + (g & 3) * 16 + fr;
;         const int tt = grow & (SEQ - 1), pos = half ? (tt & 63) : (tt >> 6);
;         t[0] = *(const f32x4*)(TC + pos * 16 + j0); t[1] = *(const f32x4*)(TC + pos * 16 + j0 + 4);
;         t[2] = *(const f32x4*)(TS + pos * 16 + j0); t[3] = *(const f32x4*)(TS + pos * 16 + j0 + 4);
;     };
;     if (anyrope) ldtab(0, tb[0]);
; #pragma unroll
;     for (int g = 0; g < 8; ++g) {
;         const int ai = g >> 2, m = g & 3;
;         const int grow = rowt + ai * HALF + wr * 64 + m * 16 + fr;
;         if (anyrope && g + 1 < 8) ldtab(g + 1, tb[(g + 1) & 1]);
;         __builtin_amdgcn_sched_barrier(0);
;         const f32x4 c0 = tb[g & 1][0], c1 = tb[g & 1][1], s0 = tb[g & 1][2], s1 = tb[g & 1][3];
; #pragma unroll
;         for (int bj = 0; bj < 2; ++bj) {
;             const int cs = colb + bj * HALF; const bool isq = cs < 512, isk = (cs >= 512) && (cs < 640);
;             f32x4 v0 = acc[ai][bj][m][0], v1 = acc[ai][bj][m][1];
;             if ((isq || isk) && anyrope) {
;                 f32x4 p0, p1;
; #pragma unroll
;                 for (int e = 0; e < 4; ++e) { p0[e] = __shfl_xor(v0[e], 32); p1[e] = __shfl_xor(v1[e], 32); }
;                 v0 = v0 * c0 + (p0 * sgn) * s0; v1 = v1 * c1 + (p1 * sgn) * s1;
;             }
;             if (isq) { v0 = v0 * QSCALE; v1 = v1 * QSCALE; }
;             *(u32x4*)(O + (size_t)grow * J.ldc + cs + wc * 32 + 8 * fq) = pack8(v0, v1);
;         }
;         __builtin_amdgcn_sched_barrier(0);
;     }
; }
.LBB0_481:
	s_mov_b32 s12, 0x3e38aa3b
	v_pk_mul_f32 v[86:87], v[170:171], s[12:13] op_sel_hi:[1,0]
	v_pk_mul_f32 v[178:179], v[168:169], s[12:13] op_sel_hi:[1,0]
	v_pk_mul_f32 v[184:185], v[172:173], s[12:13] op_sel_hi:[1,0]
	v_cndmask_b32_e64 v87, v171, v87, s[40:41]
	v_cndmask_b32_e64 v86, v170, v86, s[40:41]
	v_cndmask_b32_e64 v169, v169, v179, s[40:41]
	v_cndmask_b32_e64 v168, v168, v178, s[40:41]
	v_ashrrev_i32_e32 v80, 31, v85
	v_pk_mul_f32 v[180:181], v[174:175], s[12:13] op_sel_hi:[1,0]
	v_cndmask_b32_e64 v173, v173, v185, s[40:41]
	v_cndmask_b32_e64 v172, v172, v184, s[40:41]
	v_cvt_pk_bf16_f32 v168, v168, v169
	v_cvt_pk_bf16_f32 v169, v86, v87
	v_mad_u64_u32 v[86:87], s[12:13], s2, v85, 0
	v_cvt_pk_bf16_f32 v170, v172, v173
	v_mul_lo_u32 v80, s2, v80
	v_mul_lo_u32 v172, s3, v85
	v_readlane_b32 s12, v254, 23
	v_add3_u32 v87, v87, v80, v172
	v_readlane_b32 s13, v254, 24
	s_mov_b32 s9, s29
	v_cndmask_b32_e64 v175, v175, v181, s[40:41]
	v_lshl_add_u64 v[86:87], v[86:87], 1, s[12:13]
	v_lshl_add_u64 v[86:87], s[0:1], 1, v[86:87]
	v_cndmask_b32_e64 v174, v174, v180, s[40:41]
	v_lshl_add_u64 v[86:87], v[86:87], 0, s[8:9]
	v_cvt_pk_bf16_f32 v171, v174, v175
	v_lshl_add_u64 v[86:87], v[176:177], 1, v[86:87]
	global_store_dwordx4 v[86:87], v[168:171], off sc1
	v_mov_b64_e32 v[174:175], v[10:11]
	s_and_b64 vcc, exec, s[44:45]
	v_mov_b64_e32 v[170:171], v[14:15]
	v_mov_b64_e32 v[172:173], v[8:9]
	v_mov_b64_e32 v[168:169], v[12:13]
	s_cbranch_vccnz .LBB0_483
	v_and_b32_e32 v85, 64, v231
	v_xor_b32_e32 v80, 32, v231
	v_add_u32_e32 v85, 64, v85
	v_cmp_lt_i32_e32 vcc, v80, v85
	v_mov_b32_e32 v178, v82
	v_mov_b32_e32 v179, v82
	v_cndmask_b32_e32 v80, v231, v80, vcc
	v_lshlrev_b32_e32 v80, 2, v80
	ds_bpermute_b32 v168, v80, v12
	ds_bpermute_b32 v169, v80, v13
	ds_bpermute_b32 v170, v80, v14
	ds_bpermute_b32 v171, v80, v15
	ds_bpermute_b32 v172, v80, v8
	ds_bpermute_b32 v173, v80, v9
	ds_bpermute_b32 v174, v80, v10
	ds_bpermute_b32 v175, v80, v11
	s_waitcnt lgkmcnt(0)
	v_pk_mul_f32 v[170:171], v[178:179], v[170:171]
	v_pk_mul_f32 v[168:169], v[82:83], v[168:169]
	s_waitcnt vmcnt(0)
	v_pk_mul_f32 v[166:167], v[166:167], v[170:171]
	v_pk_mul_f32 v[164:165], v[164:165], v[168:169]
	v_pk_fma_f32 v[170:171], v[14:15], v[158:159], v[166:167]
	v_pk_fma_f32 v[168:169], v[12:13], v[156:157], v[164:165]
	v_pk_mul_f32 v[156:157], v[178:179], v[174:175]
	v_pk_mul_f32 v[158:159], v[82:83], v[172:173]
	v_pk_mul_f32 v[156:157], v[162:163], v[156:157]
	v_pk_mul_f32 v[158:159], v[160:161], v[158:159]
	v_pk_fma_f32 v[174:175], v[10:11], v[154:155], v[156:157]
	v_pk_fma_f32 v[172:173], v[8:9], v[152:153], v[158:159]
.LBB0_483:
	s_mov_b32 s12, 0x3e38aa3b
	s_waitcnt vmcnt(0)
	v_pk_mul_f32 v[152:153], v[170:171], s[12:13] op_sel_hi:[1,0]
	v_pk_mul_f32 v[154:155], v[168:169], s[12:13] op_sel_hi:[1,0]
	v_pk_mul_f32 v[156:157], v[174:175], s[12:13] op_sel_hi:[1,0]
	v_pk_mul_f32 v[158:159], v[172:173], s[12:13] op_sel_hi:[1,0]
	v_cndmask_b32_e64 v80, v175, v157, s[42:43]
	v_cndmask_b32_e64 v85, v174, v156, s[42:43]
	v_cndmask_b32_e64 v156, v173, v159, s[42:43]
	v_cndmask_b32_e64 v157, v172, v158, s[42:43]
	v_cndmask_b32_e64 v153, v171, v153, s[42:43]
	v_cndmask_b32_e64 v158, v170, v152, s[42:43]
	v_cndmask_b32_e64 v152, v169, v155, s[42:43]
	v_cndmask_b32_e64 v154, v168, v154, s[42:43]
	v_cvt_pk_bf16_f32 v152, v154, v152
	v_cvt_pk_bf16_f32 v153, v158, v153
	v_cvt_pk_bf16_f32 v154, v157, v156
	v_cvt_pk_bf16_f32 v155, v85, v80
	global_store_dwordx4 v[86:87], v[152:155], off offset:256 sc1
	v_mov_b64_e32 v[158:159], v[18:19]
	s_nop 0
	v_mov_b64_e32 v[154:155], v[22:23]
	s_and_b64 vcc, exec, s[38:39]
	v_mov_b64_e32 v[156:157], v[16:17]
	v_mov_b64_e32 v[152:153], v[20:21]
	s_cbranch_vccnz .LBB0_485
	v_and_b32_e32 v85, 64, v231
	v_xor_b32_e32 v80, 32, v231
	v_add_u32_e32 v85, 64, v85
	v_cmp_lt_i32_e32 vcc, v80, v85
	v_mov_b32_e32 v160, v82
	v_mov_b32_e32 v161, v82
	v_cndmask_b32_e32 v80, v231, v80, vcc
	v_lshlrev_b32_e32 v80, 2, v80
	ds_bpermute_b32 v86, v80, v20
	ds_bpermute_b32 v87, v80, v21
	ds_bpermute_b32 v152, v80, v22
	ds_bpermute_b32 v153, v80, v23
	ds_bpermute_b32 v156, v80, v16
	ds_bpermute_b32 v157, v80, v17
	ds_bpermute_b32 v158, v80, v18
	ds_bpermute_b32 v159, v80, v19
	s_waitcnt lgkmcnt(4)
	v_pk_mul_f32 v[152:153], v[160:161], v[152:153]
	v_pk_mul_f32 v[86:87], v[82:83], v[86:87]
	v_pk_mul_f32 v[152:153], v[150:151], v[152:153]
	v_pk_mul_f32 v[86:87], v[148:149], v[86:87]
	v_pk_fma_f32 v[154:155], v[22:23], v[142:143], v[152:153]
	v_pk_fma_f32 v[152:153], v[20:21], v[140:141], v[86:87]
	s_waitcnt lgkmcnt(0)
	v_pk_mul_f32 v[86:87], v[160:161], v[158:159]
	v_pk_mul_f32 v[156:157], v[82:83], v[156:157]
	v_pk_mul_f32 v[86:87], v[146:147], v[86:87]
	v_pk_mul_f32 v[156:157], v[144:145], v[156:157]
	v_pk_fma_f32 v[158:159], v[18:19], v[138:139], v[86:87]
	v_pk_fma_f32 v[156:157], v[16:17], v[136:137], v[156:157]
; __device__ __forceinline__ u32x4 pack8(const f32x4& a, const f32x4& b) { u32x4 w; w.x = cvt_pk_bf16(a[0], a[1]); w.y = cvt_pk_bf16(a[2], a[3]); w.z = cvt_pk_bf16(b[0], b[1]); w.w = cvt_pk_bf16(b[2], b[3]); return w; }
; __device__ __forceinline__ void epi_rope(const f32x4 (&acc)[2][2][4][2], const Job& J, int rowt, int colb, int wr, int wc, int fr, int fq) {
;     bf16_t* O = (bf16_t*)J.out; const float* TC = J.aux; const float* TS = J.aux + 1024;
;     const bool anyrope = (rowt < MX) && (colb < 640); const int half = wc & 1, j0 = 8 * (fq & 1); const float sgn = fq < 2 ? -1.f : 1.f;
;     f32x4 tb[2][4];
; #pragma unroll
;     for (int q = 0; q < 4; ++q) tb[0][q] = tb[1][q] = (q < 2) ? (f32x4){1.f, 1.f, 1.f, 1.f} : (f32x4){0.f, 0.f, 0.f, 0.f};
;     auto ldtab = [&](int g, f32x4 (&t)[4]) {
;         const int grow = rowt + (g >> 2) * HALF + wr * 64 + (g & 3) * 16 + fr;
;         const int tt = grow & (SEQ - 1), pos = half ? (tt & 63) : (tt >> 6);
;         t[0] = *(const f32x4*)(TC + pos * 16 + j0); t[1] = *(const f32x4*)(TC + pos * 16 + j0 + 4);
;         t[2] = *(const f32x4*)(TS + pos * 16 + j0); t[3] = *(const f32x4*)(TS + pos * 16 + j0 + 4);
;     };
;     if (anyrope) ldtab(0, tb[0]);
; #pragma unroll
;     for (int g = 0; g < 8; ++g) {
;         const int ai = g >> 2, m = g & 3;
;         const int grow = rowt + ai * HALF + wr * 64 + m * 16 + fr;
;         if (anyrope && g + 1 < 8) ldtab(g + 1, tb[(g + 1) & 1]);
;         __builtin_amdgcn_sched_barrier(0);
;         const f32x4 c0 = tb[g & 1][0], c1 = tb[g & 1][1], s0 = tb[g & 1][2], s1 = tb[g & 1][3];
; #pragma unroll
;         for (int bj = 0; bj < 2; ++bj) {
;             const int cs = colb + bj * HALF; const bool isq = cs < 512, isk = (cs >= 512) && (cs < 640);
;             f32x4 v0 = acc[ai][bj][m][0], v1 = acc[ai][bj][m][1];
;             if ((isq || isk) && anyrope) {
;                 f32x4 p0, p1;
; #pragma unroll
;                 for (int e = 0; e < 4; ++e) { p0[e] = __shfl_xor(v0[e], 32); p1[e] = __shfl_xor(v1[e], 32); }
;                 v0 = v0 * c0 + (p0 * sgn) * s0; v1 = v1 * c1 + (p1 * sgn) * s1;
;             }
;             if (isq) { v0 = v0 * QSCALE; v1 = v1 * QSCALE; }
;             *(u32x4*)(O + (size_t)grow * J.ldc + cs + wc * 32 + 8 * fq) = pack8(v0, v1);
;         }
;         __builtin_amdgcn_sched_barrier(0);
;     }
; }
.LBB0_485:
	v_pk_mul_f32 v[86:87], v[154:155], s[12:13] op_sel_hi:[1,0]
	v_pk_mul_f32 v[160:161], v[152:153], s[12:13] op_sel_hi:[1,0]
	v_pk_mul_f32 v[162:163], v[158:159], s[12:13] op_sel_hi:[1,0]
	v_cndmask_b32_e64 v87, v155, v87, s[40:41]
	v_cndmask_b32_e64 v86, v154, v86, s[40:41]
	v_cndmask_b32_e64 v153, v153, v161, s[40:41]
	v_cndmask_b32_e64 v152, v152, v160, s[40:41]
	v_ashrrev_i32_e32 v80, 31, v182
	v_pk_mul_f32 v[164:165], v[156:157], s[12:13] op_sel_hi:[1,0]
	v_cndmask_b32_e64 v85, v159, v163, s[40:41]
	v_cndmask_b32_e64 v158, v158, v162, s[40:41]
	v_cvt_pk_bf16_f32 v152, v152, v153
	v_cvt_pk_bf16_f32 v153, v86, v87
	v_mad_u64_u32 v[86:87], s[12:13], s2, v182, 0
	v_cvt_pk_bf16_f32 v155, v158, v85
	v_mul_lo_u32 v80, s2, v80
	v_mul_lo_u32 v85, s3, v182
	v_readlane_b32 s12, v254, 23
	v_add3_u32 v87, v87, v80, v85
	v_readlane_b32 s13, v254, 24
	s_mov_b32 s9, s29
	v_cndmask_b32_e64 v157, v157, v165, s[40:41]
	v_lshl_add_u64 v[86:87], v[86:87], 1, s[12:13]
	v_lshl_add_u64 v[86:87], s[0:1], 1, v[86:87]
	v_cndmask_b32_e64 v156, v156, v164, s[40:41]
	v_lshl_add_u64 v[86:87], v[86:87], 0, s[8:9]
	v_cvt_pk_bf16_f32 v154, v156, v157
	v_lshl_add_u64 v[86:87], v[176:177], 1, v[86:87]
	global_store_dwordx4 v[86:87], v[152:155], off sc1
	v_mov_b64_e32 v[158:159], v[2:3]
	s_and_b64 vcc, exec, s[44:45]
	v_mov_b64_e32 v[154:155], v[6:7]
	v_mov_b64_e32 v[156:157], v[0:1]
	v_mov_b64_e32 v[152:153], v[4:5]
	s_cbranch_vccnz .LBB0_487
	v_and_b32_e32 v85, 64, v231
	v_xor_b32_e32 v80, 32, v231
	v_add_u32_e32 v85, 64, v85
	v_cmp_lt_i32_e32 vcc, v80, v85
	v_mov_b32_e32 v160, v82
	v_mov_b32_e32 v161, v82
	v_cndmask_b32_e32 v80, v231, v80, vcc
	v_lshlrev_b32_e32 v80, 2, v80
	ds_bpermute_b32 v152, v80, v4
	ds_bpermute_b32 v153, v80, v5
	ds_bpermute_b32 v156, v80, v0
	ds_bpermute_b32 v157, v80, v1
	ds_bpermute_b32 v154, v80, v6
	ds_bpermute_b32 v155, v80, v7
	ds_bpermute_b32 v158, v80, v2
	ds_bpermute_b32 v159, v80, v3
	s_waitcnt lgkmcnt(6)
	v_pk_mul_f32 v[152:153], v[82:83], v[152:153]
	s_waitcnt lgkmcnt(4)
	v_pk_mul_f32 v[82:83], v[82:83], v[156:157]
	v_pk_mul_f32 v[148:149], v[148:149], v[152:153]
	s_waitcnt lgkmcnt(2)
	v_pk_mul_f32 v[154:155], v[160:161], v[154:155]
	v_pk_fma_f32 v[152:153], v[4:5], v[140:141], v[148:149]
	s_waitcnt lgkmcnt(0)
	v_pk_mul_f32 v[140:141], v[160:161], v[158:159]
	v_pk_mul_f32 v[150:151], v[150:151], v[154:155]
	v_pk_mul_f32 v[82:83], v[144:145], v[82:83]
	v_pk_mul_f32 v[140:141], v[146:147], v[140:141]
	v_pk_fma_f32 v[154:155], v[6:7], v[142:143], v[150:151]
	v_pk_fma_f32 v[158:159], v[2:3], v[138:139], v[140:141]
	v_pk_fma_f32 v[156:157], v[0:1], v[136:137], v[82:83]
.LBB0_487:
	s_mov_b32 s0, 0x3e38aa3b
	v_pk_mul_f32 v[82:83], v[154:155], s[0:1] op_sel_hi:[1,0]
	v_pk_mul_f32 v[136:137], v[152:153], s[0:1] op_sel_hi:[1,0]
	v_pk_mul_f32 v[138:139], v[158:159], s[0:1] op_sel_hi:[1,0]
	v_pk_mul_f32 v[140:141], v[156:157], s[0:1] op_sel_hi:[1,0]
	v_cndmask_b32_e64 v80, v159, v139, s[42:43]
	v_cndmask_b32_e64 v85, v158, v138, s[42:43]
	v_cndmask_b32_e64 v138, v157, v141, s[42:43]
	v_cndmask_b32_e64 v139, v156, v140, s[42:43]
	v_cndmask_b32_e64 v83, v155, v83, s[42:43]
	v_cndmask_b32_e64 v82, v154, v82, s[42:43]
	v_cndmask_b32_e64 v137, v153, v137, s[42:43]
	v_cndmask_b32_e64 v136, v152, v136, s[42:43]
	v_cvt_pk_bf16_f32 v136, v136, v137
	v_cvt_pk_bf16_f32 v137, v82, v83
	v_cvt_pk_bf16_f32 v138, v139, v138
	v_cvt_pk_bf16_f32 v139, v85, v80
	global_store_dwordx4 v[86:87], v[136:139], off offset:256 sc1

; __device__ __forceinline__ u32x4 pack8(const f32x4& a, const f32x4& b) { u32x4 w; w.x = cvt_pk_bf16(a[0], a[1]); w.y = cvt_pk_bf16(a[2], a[3]); w.z = cvt_pk_bf16(b[0], b[1]); w.w = cvt_pk_bf16(b[2], b[3]); return w; }
; __device__ __forceinline__ void epi_plain(const f32x4 (&acc)[2][2][4][2], const Job& J, int rowt, int colb, int wr, int wc, int fr, int fq) {
;     bf16_t* O = (bf16_t*)J.out;
; #pragma unroll
;     for (int ai = 0; ai < 2; ++ai)
; #pragma unroll
;         for (int m = 0; m < 4; ++m) {
;             bf16_t* rowp = O + (size_t)(rowt + ai * HALF + wr * 64 + m * 16 + fr) * J.ldc + colb + wc * 32 + 8 * fq;
; #pragma unroll
;             for (int bj = 0; bj < 2; ++bj) *(u32x4*)(rowp + bj * HALF) = pack8(acc[ai][bj][m][0], acc[ai][bj][m][1]);
;         }
; }
; __device__ __forceinline__ void epilogue(const f32x4 (&acc)[2][2][4][2], const Call& C, const Unit& u, int wr, int wc, int fr_, int fq_, int lane, int wid, const Args& a, LAS unsigned char* pst) {
;     ...
;     else if (J.kind == K_DFT) epi_plain(acc, J, J.row0 + ((u.pn >> 1) * J.p0 + u.pm) * BM, J.col0 + (u.pn & 1) * BM, wr, wc, fr, fq);
.LBB0_489:
	s_andn2_b64 vcc, exec, s[0:1]
	s_cbranch_vccnz .LBB0_494
	s_mov_b64 s[0:1], -1
	s_cmp_gt_i32 s55, 0
	v_cvt_pk_bf16_f32 v196, v132, v133
	v_cvt_pk_bf16_f32 v197, v134, v135
	v_cvt_pk_bf16_f32 v198, v128, v129
	v_cvt_pk_bf16_f32 v199, v130, v131
	v_cvt_pk_bf16_f32 v192, v116, v117
	v_cvt_pk_bf16_f32 v193, v118, v119
	v_cvt_pk_bf16_f32 v194, v112, v113
	v_cvt_pk_bf16_f32 v195, v114, v115
	v_cvt_pk_bf16_f32 v188, v124, v125
	v_cvt_pk_bf16_f32 v189, v126, v127
	v_cvt_pk_bf16_f32 v190, v120, v121
	v_cvt_pk_bf16_f32 v191, v122, v123
	v_cvt_pk_bf16_f32 v184, v100, v101
	v_cvt_pk_bf16_f32 v185, v102, v103
	v_cvt_pk_bf16_f32 v186, v96, v97
	v_cvt_pk_bf16_f32 v187, v98, v99
	v_cvt_pk_bf16_f32 v180, v108, v109
	v_cvt_pk_bf16_f32 v181, v110, v111
	v_cvt_pk_bf16_f32 v182, v104, v105
	v_cvt_pk_bf16_f32 v183, v106, v107
	v_cvt_pk_bf16_f32 v176, v76, v77
	v_cvt_pk_bf16_f32 v177, v78, v79
	v_cvt_pk_bf16_f32 v178, v72, v73
	v_cvt_pk_bf16_f32 v179, v74, v75
	v_cvt_pk_bf16_f32 v172, v92, v93
	v_cvt_pk_bf16_f32 v173, v94, v95
	v_cvt_pk_bf16_f32 v174, v88, v89
	v_cvt_pk_bf16_f32 v175, v90, v91
	v_cvt_pk_bf16_f32 v168, v68, v69
	v_cvt_pk_bf16_f32 v169, v70, v71
	v_cvt_pk_bf16_f32 v170, v60, v61
	v_cvt_pk_bf16_f32 v171, v62, v63
	v_cvt_pk_bf16_f32 v164, v64, v65
	v_cvt_pk_bf16_f32 v165, v66, v67
	v_cvt_pk_bf16_f32 v166, v56, v57
	v_cvt_pk_bf16_f32 v167, v58, v59
	v_cvt_pk_bf16_f32 v160, v44, v45
	v_cvt_pk_bf16_f32 v161, v46, v47
	v_cvt_pk_bf16_f32 v162, v40, v41
	v_cvt_pk_bf16_f32 v163, v42, v43
	v_cvt_pk_bf16_f32 v156, v52, v53
	v_cvt_pk_bf16_f32 v157, v54, v55
	v_cvt_pk_bf16_f32 v158, v48, v49
	v_cvt_pk_bf16_f32 v159, v50, v51
	v_cvt_pk_bf16_f32 v152, v28, v29
	v_cvt_pk_bf16_f32 v153, v30, v31
	v_cvt_pk_bf16_f32 v154, v24, v25
	v_cvt_pk_bf16_f32 v155, v26, v27
	v_cvt_pk_bf16_f32 v148, v36, v37
	v_cvt_pk_bf16_f32 v149, v38, v39
	v_cvt_pk_bf16_f32 v150, v32, v33
	v_cvt_pk_bf16_f32 v151, v34, v35
	v_cvt_pk_bf16_f32 v144, v12, v13
	v_cvt_pk_bf16_f32 v145, v14, v15
	v_cvt_pk_bf16_f32 v146, v8, v9
	v_cvt_pk_bf16_f32 v147, v10, v11
	v_cvt_pk_bf16_f32 v140, v20, v21
	v_cvt_pk_bf16_f32 v141, v22, v23
	v_cvt_pk_bf16_f32 v142, v16, v17
	v_cvt_pk_bf16_f32 v143, v18, v19
	v_cvt_pk_bf16_f32 v136, v4, v5
	v_cvt_pk_bf16_f32 v137, v6, v7
	v_cvt_pk_bf16_f32 v138, v0, v1
	v_cvt_pk_bf16_f32 v139, v2, v3
	s_cbranch_scc0 .LBB0_492
	s_lshr_b32 s0, s78, 1
	v_readlane_b32 s1, v254, 39
	s_mul_i32 s0, s0, s1
	s_add_i32 s0, s0, s90
	s_lshl_b32 s1, s0, 8
	s_lshl_b32 s0, s78, 8
	s_and_b32 s0, s0, 0x100
	v_readlane_b32 s8, v254, 30
	s_or_b32 s0, s0, s8
	v_readlane_b32 s8, v255, 9
	s_add_i32 s8, s8, s1
	s_mov_b32 s1, s29
	s_lshl_b64 s[0:1], s[0:1], 1
	v_readlane_b32 s9, v255, 2
	s_add_u32 s0, s9, s0
	v_readlane_b32 s9, v255, 3
	v_lshlrev_b32_e32 v82, 3, v247
	s_addc_u32 s1, s9, s1
	v_ashrrev_i32_e32 v83, 31, v82
	v_or_b32_e32 v80, s8, v248
	v_lshl_add_u64 v[82:83], v[82:83], 1, s[0:1]
	s_ashr_i32 s0, s8, 31
	s_mul_i32 s8, s2, s0
	v_mul_lo_u32 v85, s3, v80
	v_mad_u64_u32 v[86:87], s[0:1], s2, v80, 0
	v_add3_u32 v87, v87, s8, v85
	v_lshl_add_u64 v[86:87], v[86:87], 1, v[82:83]
	v_or_b32_e32 v85, 16, v80
	global_store_dwordx4 v[86:87], v[196:199], off sc1
	global_store_dwordx4 v[86:87], v[192:195], off offset:256 sc1
	v_mul_lo_u32 v200, s3, v85
	v_mad_u64_u32 v[86:87], s[0:1], s2, v85, 0
	v_add3_u32 v87, v87, s8, v200
	v_lshl_add_u64 v[86:87], v[86:87], 1, v[82:83]
	v_or_b32_e32 v85, 32, v80
	global_store_dwordx4 v[86:87], v[188:191], off sc1
	global_store_dwordx4 v[86:87], v[184:187], off offset:256 sc1
	v_mul_lo_u32 v200, s3, v85
	v_mad_u64_u32 v[86:87], s[0:1], s2, v85, 0
	v_add3_u32 v87, v87, s8, v200
	v_lshl_add_u64 v[86:87], v[86:87], 1, v[82:83]
	v_or_b32_e32 v85, 48, v80
	global_store_dwordx4 v[86:87], v[180:183], off sc1
	global_store_dwordx4 v[86:87], v[176:179], off offset:256 sc1
	v_mul_lo_u32 v200, s3, v85
	v_mad_u64_u32 v[86:87], s[0:1], s2, v85, 0
	v_add3_u32 v87, v87, s8, v200
	v_lshl_add_u64 v[86:87], v[86:87], 1, v[82:83]
	v_add_u32_e32 v85, 0x80, v80
	global_store_dwordx4 v[86:87], v[172:175], off sc1
	global_store_dwordx4 v[86:87], v[168:171], off offset:256 sc1
	v_ashrrev_i32_e32 v86, 31, v85
	v_mul_lo_u32 v200, s2, v86
	v_mul_lo_u32 v201, s3, v85
	v_mad_u64_u32 v[86:87], s[0:1], s2, v85, 0
	v_add3_u32 v87, v87, v200, v201
	v_lshl_add_u64 v[86:87], v[86:87], 1, v[82:83]
	v_add_u32_e32 v85, 0x90, v80
	global_store_dwordx4 v[86:87], v[164:167], off sc1
	global_store_dwordx4 v[86:87], v[160:163], off offset:256 sc1
	v_ashrrev_i32_e32 v86, 31, v85
	v_mul_lo_u32 v200, s2, v86
	v_mul_lo_u32 v201, s3, v85
	v_mad_u64_u32 v[86:87], s[0:1], s2, v85, 0
	v_add3_u32 v87, v87, v200, v201
	v_lshl_add_u64 v[86:87], v[86:87], 1, v[82:83]
	v_add_u32_e32 v85, 0xa0, v80
	global_store_dwordx4 v[86:87], v[156:159], off sc1
	global_store_dwordx4 v[86:87], v[152:155], off offset:256 sc1
	v_ashrrev_i32_e32 v86, 31, v85
	v_mul_lo_u32 v200, s2, v86
	v_mul_lo_u32 v201, s3, v85
	v_mad_u64_u32 v[86:87], s[0:1], s2, v85, 0
	v_add3_u32 v87, v87, v200, v201
	v_add_u32_e32 v80, 0xb0, v80
	v_lshl_add_u64 v[86:87], v[86:87], 1, v[82:83]
	v_ashrrev_i32_e32 v85, 31, v80
	global_store_dwordx4 v[86:87], v[148:151], off sc1
	global_store_dwordx4 v[86:87], v[144:147], off offset:256 sc1
	v_mul_lo_u32 v85, s2, v85
	v_mul_lo_u32 v200, s3, v80
	v_mad_u64_u32 v[86:87], s[0:1], s2, v80, 0
	v_add3_u32 v87, v87, v85, v200
	v_lshl_add_u64 v[82:83], v[86:87], 1, v[82:83]
	global_store_dwordx4 v[82:83], v[140:143], off sc1
	global_store_dwordx4 v[82:83], v[136:139], off offset:256 sc1
	s_mov_b64 s[0:1], 0
; __device__ __forceinline__ u32x4 pack8(const f32x4& a, const f32x4& b) { u32x4 w; w.x = cvt_pk_bf16(a[0], a[1]); w.y = cvt_pk_bf16(a[2], a[3]); w.z = cvt_pk_bf16(b[0], b[1]); w.w = cvt_pk_bf16(b[2], b[3]); return w; }
; __device__ __forceinline__ void epi_plain(const f32x4 (&acc)[2][2][4][2], const Job& J, int rowt, int colb, int wr, int wc, int fr, int fq) {
;     bf16_t* O = (bf16_t*)J.out;
; #pragma unroll
;     for (int ai = 0; ai < 2; ++ai)
; #pragma unroll
;         for (int m = 0; m < 4; ++m) {
;             bf16_t* rowp = O + (size_t)(rowt + ai * HALF + wr * 64 + m * 16 + fr) * J.ldc + colb + wc * 32 + 8 * fq;
; #pragma unroll
;             for (int bj = 0; bj < 2; ++bj) *(u32x4*)(rowp + bj * HALF) = pack8(acc[ai][bj][m][0], acc[ai][bj][m][1]);
;         }
; }
; __device__ __forceinline__ void epilogue(const f32x4 (&acc)[2][2][4][2], const Call& C, const Unit& u, int wr, int wc, int fr_, int fq_, int lane, int wid, const Args& a, LAS unsigned char* pst) {
;     ...
;     else if (J.kind == K_PLAIN) epi_plain(acc, J, J.row0 + u.pm * BM, J.col0 + u.pn * BM, wr, wc, fr, fq);
.LBB0_492:
	s_andn2_b64 vcc, exec, s[0:1]
	s_cbranch_vccnz .LBB0_494
	s_lshl_b32 s0, s78, 8
	v_readlane_b32 s8, v254, 30
	s_lshl_b32 s1, s90, 8
	s_add_i32 s0, s0, s8
	v_readlane_b32 s8, v255, 9
	s_add_i32 s8, s8, s1
	s_ashr_i32 s1, s0, 31
	s_lshl_b64 s[0:1], s[0:1], 1
	v_readlane_b32 s9, v255, 2
	s_add_u32 s0, s9, s0
	v_readlane_b32 s9, v255, 3
	v_lshlrev_b32_e32 v82, 3, v247
	s_addc_u32 s1, s9, s1
	v_ashrrev_i32_e32 v83, 31, v82
	v_or_b32_e32 v80, s8, v248
	v_lshl_add_u64 v[82:83], v[82:83], 1, s[0:1]
	s_ashr_i32 s0, s8, 31
	s_mul_i32 s8, s2, s0
	v_mul_lo_u32 v85, s3, v80
	v_mad_u64_u32 v[86:87], s[0:1], s2, v80, 0
	v_add3_u32 v87, v87, s8, v85
	v_lshl_add_u64 v[86:87], v[86:87], 1, v[82:83]
	v_or_b32_e32 v85, 16, v80
	global_store_dwordx4 v[86:87], v[196:199], off sc1
	global_store_dwordx4 v[86:87], v[192:195], off offset:256 sc1
	v_mad_u64_u32 v[86:87], s[0:1], s2, v85, 0
	s_nop 0
	v_mul_lo_u32 v192, s3, v85
	v_add3_u32 v87, v87, s8, v192
	v_lshl_add_u64 v[86:87], v[86:87], 1, v[82:83]
	v_or_b32_e32 v85, 32, v80
	global_store_dwordx4 v[86:87], v[188:191], off sc1
	global_store_dwordx4 v[86:87], v[184:187], off offset:256 sc1
	v_mad_u64_u32 v[86:87], s[0:1], s2, v85, 0
	s_nop 0
	v_mul_lo_u32 v184, s3, v85
	v_add3_u32 v87, v87, s8, v184
	v_lshl_add_u64 v[86:87], v[86:87], 1, v[82:83]
	v_or_b32_e32 v85, 48, v80
	global_store_dwordx4 v[86:87], v[180:183], off sc1
	global_store_dwordx4 v[86:87], v[176:179], off offset:256 sc1
	v_mad_u64_u32 v[86:87], s[0:1], s2, v85, 0
	s_nop 0
	v_mul_lo_u32 v176, s3, v85
	v_add3_u32 v87, v87, s8, v176
	v_lshl_add_u64 v[86:87], v[86:87], 1, v[82:83]
	v_add_u32_e32 v85, 0x80, v80
	global_store_dwordx4 v[86:87], v[172:175], off sc1
	global_store_dwordx4 v[86:87], v[168:171], off offset:256 sc1
	v_ashrrev_i32_e32 v86, 31, v85
	s_nop 0
	v_mul_lo_u32 v168, s2, v86
	v_mul_lo_u32 v169, s3, v85
	v_mad_u64_u32 v[86:87], s[0:1], s2, v85, 0
	v_add3_u32 v87, v87, v168, v169
	v_lshl_add_u64 v[86:87], v[86:87], 1, v[82:83]
	v_add_u32_e32 v85, 0x90, v80
	global_store_dwordx4 v[86:87], v[164:167], off sc1
	global_store_dwordx4 v[86:87], v[160:163], off offset:256 sc1
	v_ashrrev_i32_e32 v86, 31, v85
	s_nop 0
	v_mul_lo_u32 v160, s2, v86
	v_mul_lo_u32 v161, s3, v85
	v_mad_u64_u32 v[86:87], s[0:1], s2, v85, 0
	v_add3_u32 v87, v87, v160, v161
	v_lshl_add_u64 v[86:87], v[86:87], 1, v[82:83]
	v_add_u32_e32 v85, 0xa0, v80
	global_store_dwordx4 v[86:87], v[156:159], off sc1
	global_store_dwordx4 v[86:87], v[152:155], off offset:256 sc1
	v_ashrrev_i32_e32 v86, 31, v85
	v_add_u32_e32 v80, 0xb0, v80
	v_mul_lo_u32 v152, s2, v86
	v_mul_lo_u32 v153, s3, v85
	v_mad_u64_u32 v[86:87], s[0:1], s2, v85, 0
	v_add3_u32 v87, v87, v152, v153
	v_lshl_add_u64 v[86:87], v[86:87], 1, v[82:83]
	v_ashrrev_i32_e32 v85, 31, v80
	global_store_dwordx4 v[86:87], v[148:151], off sc1
	global_store_dwordx4 v[86:87], v[144:147], off offset:256 sc1
	v_mul_lo_u32 v85, s2, v85
	v_mad_u64_u32 v[86:87], s[0:1], s2, v80, 0
	v_mul_lo_u32 v144, s3, v80
	v_add3_u32 v87, v87, v85, v144
	v_lshl_add_u64 v[82:83], v[86:87], 1, v[82:83]
	global_store_dwordx4 v[82:83], v[140:143], off sc1
	global_store_dwordx4 v[82:83], v[136:139], off offset:256 sc1

; #define LAS __attribute__((address_space(3)))
; #define LDS_WAIT() asm volatile("s_waitcnt lgkmcnt(0)" ::: "memory")
; __device__ __forceinline__ unsigned cvt_pk_bf16(float lo, float hi) { f32x2_t v = {lo, hi}; bf16x2_t b = __builtin_convertvector(v, bf16x2_t); return __builtin_bit_cast(unsigned, b); }
; __device__ __forceinline__ void tr_load(const float* src, int ldn, int lane, f32x4 (&v)[8]) {
;     const int r8 = lane >> 3, c4 = lane & 7;
; #pragma unroll
;     for (int i = 0; i < 8; ++i) v[i] = __builtin_nontemporal_load((const f32x4*)(src + (size_t)(8 * i + r8) * ldn + 4 * c4));
; }
;     const int r8 = lane >> 3, c4 = lane & 7;
; #pragma unroll
;     for (int i = 0; i < 8; ++i) { LAS float* w = scr + (8 * i + r8) * 33 + 4 * c4; w[0] = v[i][0]; w[1] = v[i][1]; w[2] = v[i][2]; w[3] = v[i][3]; }
;     LDS_WAIT(); asm volatile("" ::: "memory");
;     const int c = lane & 7;
; #pragma unroll
;     for (int j = 0; j < 4; ++j) { const int n = (lane >> 3) + 8 * j; const LAS float* sp = scr + (8 * c) * 33 + n;
;         u32x4 o; o.x = cvt_pk_bf16(sp[0 * 33] * s, sp[1 * 33] * s); o.y = cvt_pk_bf16(sp[2 * 33] * s, sp[3 * 33] * s); o.z = cvt_pk_bf16(sp[4 * 33] * s, sp[5 * 33] * s); o.w = cvt_pk_bf16(sp[6 * 33] * s, sp[7 * 33] * s);
;         *(u32x4*)(dst + (size_t)n * ldk + 8 * c) = o; if (dst2) *(u32x4*)(dst2 + (size_t)n * ldk + 8 * c) = o; }
;     LDS_WAIT(); asm volatile("" ::: "memory");
; }
;     LAS float* scr = (LAS float*)(lds + wave * 8448);
;     const int n1 = (l & 1) == 0 ? 16 * 72 : 16 * 16, n2 = (l & 1) == 0 ? 16 * 32 : 8 * 32, nU = 16 * 176, nD = 44 * 32;
;     const int I0 = part <= 1 ? 0 : (part == 2 ? n1 : n1 + n2 + nU), NIT = part == 0 ? n1 + n2 + nU + nD : (part == 1 ? n1 : (part == 2 ? n1 + n2 + nU : n1 + n2 + nU + nD));
;     for (int it = I0 + wr; it < NIT; it += 2 * nw) {
;         const bool two = it + nw < NIT;
;         const TrDesc d0 = tr_decode(a, l, it), d1 = tr_decode(a, l, two ? it + nw : it);
;         f32x4 v0[8], v1[8];
;         tr_load(d0.src, d0.ldn, lane, v0); tr_load(d1.src, d1.ldn, lane, v1);
;         tr_finish(v0, d0.dst, d0.dst2, d0.ldk, scr, lane, d0.scale);
;         if (two) tr_finish(v1, d1.dst, d1.dst2, d1.ldk, scr, lane, d1.scale);
;     }
.LBB0_530:
	v_mov_b32_e32 v39, v81
	v_mul_u32_u24_e32 v2, s44, v37
	s_lshl_b32 s12, s44, 3
	v_lshl_add_u64 v[0:1], s[34:35], 0, v[38:39]
	v_lshlrev_b32_e32 v80, 2, v2
	s_ashr_i32 s13, s12, 31
	v_lshl_add_u64 v[2:3], v[0:1], 0, v[80:81]
	s_lshl_b64 s[34:35], s[12:13], 2
	global_load_dwordx4 v[42:45], v[2:3], off nt
	v_lshl_add_u64 v[2:3], v[2:3], 0, s[34:35]
	global_load_dwordx4 v[46:49], v[2:3], off nt
	v_lshl_add_u64 v[2:3], v[2:3], 0, s[34:35]
	s_add_i32 s13, s12, s12
	global_load_dwordx4 v[50:53], v[2:3], off nt
	v_lshl_add_u64 v[2:3], v[2:3], 0, s[34:35]
	s_add_i32 s13, s13, s13
	global_load_dwordx4 v[54:57], v[2:3], off nt
	v_mov_b32_e32 v2, s13
	v_mad_u32_u24 v80, s44, v37, v2
	v_lshl_add_u64 v[2:3], v[80:81], 2, v[0:1]
	v_add_u32_e32 v80, s12, v80
	global_load_dwordx4 v[58:61], v[2:3], off nt
	v_lshl_add_u64 v[2:3], v[80:81], 2, v[0:1]
	v_add_u32_e32 v80, s12, v80
	global_load_dwordx4 v[62:65], v[2:3], off nt
	v_lshl_add_u64 v[2:3], v[80:81], 2, v[0:1]
	v_add_u32_e32 v80, s12, v80
	v_lshl_add_u64 v[0:1], v[80:81], 2, v[0:1]
	global_load_dwordx4 v[66:69], v[2:3], off nt
	global_load_dwordx4 v[32:35], v[0:1], off nt
	s_lshl_b32 s12, s28, 3
	s_ashr_i32 s13, s12, 31
	s_lshl_b64 s[34:35], s[12:13], 2
	s_add_i32 s13, s12, s12
	v_mul_u32_u24_e32 v0, s28, v37
	s_add_i32 s13, s13, s13
	v_lshl_add_u64 v[28:29], s[36:37], 0, v[38:39]
	v_lshlrev_b32_e32 v80, 2, v0
	v_mov_b32_e32 v16, s13
	v_lshl_add_u64 v[4:5], v[28:29], 0, v[80:81]
	v_mad_u32_u24 v80, s28, v37, v16
	v_lshl_add_u64 v[16:17], v[80:81], 2, v[28:29]
	v_add_u32_e32 v80, s12, v80
	s_waitcnt lgkmcnt(0)
	v_lshl_add_u64 v[8:9], v[4:5], 0, s[34:35]
	v_lshl_add_u64 v[20:21], v[80:81], 2, v[28:29]
	v_add_u32_e32 v80, s12, v80
	v_lshl_add_u64 v[12:13], v[8:9], 0, s[34:35]
	v_lshl_add_u64 v[24:25], v[80:81], 2, v[28:29]
	v_add_u32_e32 v80, s12, v80
	global_load_dwordx4 v[0:3], v[4:5], off nt
	v_lshl_add_u64 v[28:29], v[80:81], 2, v[28:29]
	global_load_dwordx4 v[16:19], v[16:17], off nt
	v_add_u32_e32 v39, 0x420, v41
	global_load_dwordx4 v[4:7], v[8:9], off nt
	v_lshlrev_b32_e32 v80, 1, v36
	global_load_dwordx4 v[20:23], v[20:21], off nt
	s_lshl_b32 s12, s43, 3
	global_load_dwordx4 v[8:11], v[12:13], off nt
	s_ashr_i32 s13, s12, 31
	global_load_dwordx4 v[24:27], v[24:25], off nt
	v_lshl_add_u64 v[12:13], v[12:13], 0, s[34:35]
	global_load_dwordx4 v[12:15], v[12:13], off nt
	s_andn2_b64 vcc, exec, s[20:21]
	global_load_dwordx4 v[28:31], v[28:29], off nt
	s_waitcnt vmcnt(0)
	ds_write2_b32 v41, v42, v43 offset1:1
	ds_write2_b32 v41, v44, v45 offset0:2 offset1:3
	v_add_u32_e32 v44, 0x848, v41
	v_add_u32_e32 v42, 0x428, v41
	v_add_u32_e32 v43, 0x840, v41
	ds_write2_b32 v39, v46, v47 offset1:1
	ds_write2_b32 v44, v52, v53 offset1:1
	v_add_u32_e32 v53, 0x1ce0, v41
	ds_write2_b32 v42, v48, v49 offset1:1
	ds_write2_b32 v43, v50, v51 offset1:1
	v_add_u32_e32 v45, 0xc60, v41
	v_add_u32_e32 v46, 0xc68, v41
	v_add_u32_e32 v47, 0x1080, v41
	v_add_u32_e32 v48, 0x1088, v41
	v_add_u32_e32 v49, 0x14a0, v41
	v_add_u32_e32 v50, 0x14a8, v41
	v_add_u32_e32 v51, 0x18c0, v41
	v_add_u32_e32 v52, 0x18c8, v41
	ds_write2_b32 v45, v54, v55 offset1:1
	ds_write2_b32 v46, v56, v57 offset1:1
	ds_write2_b32 v47, v58, v59 offset1:1
	ds_write2_b32 v48, v60, v61 offset1:1
	ds_write2_b32 v53, v32, v33 offset1:1
	v_add_u32_e32 v32, 0x1ce8, v41
	ds_write2_b32 v49, v62, v63 offset1:1
	ds_write2_b32 v50, v64, v65 offset1:1
	ds_write2_b32 v51, v66, v67 offset1:1
	ds_write2_b32 v52, v68, v69 offset1:1
	ds_write2_b32 v32, v34, v35 offset1:1
	s_waitcnt lgkmcnt(0)
	ds_read2_b32 v[58:59], v40 offset0:33 offset1:41
	ds_read2_b32 v[60:61], v40 offset1:8
	ds_read2_b32 v[62:63], v40 offset0:66 offset1:74
	ds_read2_b32 v[64:65], v40 offset0:99 offset1:107
	ds_read2_b32 v[66:67], v40 offset0:132 offset1:140
	ds_read2_b32 v[68:69], v40 offset0:165 offset1:173
	ds_read2_b32 v[70:71], v40 offset0:198 offset1:206
	ds_read2_b32 v[72:73], v40 offset0:231 offset1:239
	s_waitcnt lgkmcnt(7)
	v_mov_b32_e32 v55, v58
	s_waitcnt lgkmcnt(6)
	v_mov_b32_e32 v54, v60
	s_waitcnt lgkmcnt(5)
	v_mov_b32_e32 v56, v62
	s_waitcnt lgkmcnt(4)
	v_mov_b32_e32 v57, v64
	v_pk_mul_f32 v[54:55], s[8:9], v[54:55] op_sel_hi:[0,1]
	v_pk_mul_f32 v[56:57], s[8:9], v[56:57] op_sel_hi:[0,1]
	v_cvt_pk_bf16_f32 v54, v54, v55
	v_cvt_pk_bf16_f32 v55, v56, v57
	s_waitcnt lgkmcnt(3)
	v_mov_b32_e32 v56, v66
	s_waitcnt lgkmcnt(2)
	v_mov_b32_e32 v57, v68
	s_waitcnt lgkmcnt(1)
	v_mov_b32_e32 v74, v70
	s_waitcnt lgkmcnt(0)
	v_mov_b32_e32 v75, v72
	v_pk_mul_f32 v[56:57], s[8:9], v[56:57] op_sel_hi:[0,1]
	v_pk_mul_f32 v[74:75], s[8:9], v[74:75] op_sel_hi:[0,1]
	v_mul_u32_u24_e32 v33, s43, v37
	v_lshl_add_u64 v[34:35], s[26:27], 0, v[80:81]
	v_cvt_pk_bf16_f32 v56, v56, v57
	v_cvt_pk_bf16_f32 v57, v74, v75
	v_lshlrev_b32_e32 v74, 1, v33
	v_mov_b32_e32 v75, v81
	v_lshl_add_u64 v[34:35], v[34:35], 0, v[74:75]
	v_mov_b32_e32 v58, v61
	v_mov_b32_e32 v64, v63
	global_store_dwordx4 v[34:35], v[54:57], off sc1
	v_mov_b32_e32 v68, v67
	v_mov_b32_e32 v72, v71
	v_pk_mul_f32 v[54:55], s[8:9], v[58:59] op_sel_hi:[0,1]
	v_pk_mul_f32 v[56:57], s[8:9], v[64:65] op_sel_hi:[0,1]
	v_cvt_pk_bf16_f32 v54, v54, v55
	v_cvt_pk_bf16_f32 v55, v56, v57
	v_pk_mul_f32 v[56:57], s[8:9], v[68:69] op_sel_hi:[0,1]
	v_pk_mul_f32 v[58:59], s[8:9], v[72:73] op_sel_hi:[0,1]
	s_lshl_b64 s[26:27], s[12:13], 1
	v_cvt_pk_bf16_f32 v56, v56, v57
	v_cvt_pk_bf16_f32 v57, v58, v59
	v_lshl_add_u64 v[34:35], v[34:35], 0, s[26:27]
	global_store_dwordx4 v[34:35], v[54:57], off sc1
	ds_read2_b32 v[58:59], v40 offset0:16 offset1:24
	ds_read2_b32 v[60:61], v40 offset0:49 offset1:57
	ds_read2_b32 v[62:63], v40 offset0:82 offset1:90
	ds_read2_b32 v[64:65], v40 offset0:115 offset1:123
	ds_read2_b32 v[66:67], v40 offset0:148 offset1:156
	ds_read2_b32 v[68:69], v40 offset0:181 offset1:189
	ds_read2_b32 v[70:71], v40 offset0:214 offset1:222
	ds_read2_b32 v[72:73], v40 offset0:247 offset1:255
	s_waitcnt lgkmcnt(7)
; #define LAS __attribute__((address_space(3)))
; #define LDS_WAIT() asm volatile("s_waitcnt lgkmcnt(0)" ::: "memory")
; __device__ __forceinline__ unsigned cvt_pk_bf16(float lo, float hi) { f32x2_t v = {lo, hi}; bf16x2_t b = __builtin_convertvector(v, bf16x2_t); return __builtin_bit_cast(unsigned, b); }
; __device__ __forceinline__ void tr_load(const float* src, int ldn, int lane, f32x4 (&v)[8]) {
;     const int r8 = lane >> 3, c4 = lane & 7;
; #pragma unroll
;     for (int i = 0; i < 8; ++i) v[i] = __builtin_nontemporal_load((const f32x4*)(src + (size_t)(8 * i + r8) * ldn + 4 * c4));
; }
;     const int r8 = lane >> 3, c4 = lane & 7;
; #pragma unroll
;     for (int i = 0; i < 8; ++i) { LAS float* w = scr + (8 * i + r8) * 33 + 4 * c4; w[0] = v[i][0]; w[1] = v[i][1]; w[2] = v[i][2]; w[3] = v[i][3]; }
;     LDS_WAIT(); asm volatile("" ::: "memory");
;     const int c = lane & 7;
; #pragma unroll
;     for (int j = 0; j < 4; ++j) { const int n = (lane >> 3) + 8 * j; const LAS float* sp = scr + (8 * c) * 33 + n;
;         u32x4 o; o.x = cvt_pk_bf16(sp[0 * 33] * s, sp[1 * 33] * s); o.y = cvt_pk_bf16(sp[2 * 33] * s, sp[3 * 33] * s); o.z = cvt_pk_bf16(sp[4 * 33] * s, sp[5 * 33] * s); o.w = cvt_pk_bf16(sp[6 * 33] * s, sp[7 * 33] * s);
;         *(u32x4*)(dst + (size_t)n * ldk + 8 * c) = o; if (dst2) *(u32x4*)(dst2 + (size_t)n * ldk + 8 * c) = o; }
;     LDS_WAIT(); asm volatile("" ::: "memory");
; }
;     LAS float* scr = (LAS float*)(lds + wave * 8448);
;     const int n1 = (l & 1) == 0 ? 16 * 72 : 16 * 16, n2 = (l & 1) == 0 ? 16 * 32 : 8 * 32, nU = 16 * 176, nD = 44 * 32;
;     const int I0 = part <= 1 ? 0 : (part == 2 ? n1 : n1 + n2 + nU), NIT = part == 0 ? n1 + n2 + nU + nD : (part == 1 ? n1 : (part == 2 ? n1 + n2 + nU : n1 + n2 + nU + nD));
;     for (int it = I0 + wr; it < NIT; it += 2 * nw) {
;         const bool two = it + nw < NIT;
;         const TrDesc d0 = tr_decode(a, l, it), d1 = tr_decode(a, l, two ? it + nw : it);
;         f32x4 v0[8], v1[8];
;         tr_load(d0.src, d0.ldn, lane, v0); tr_load(d1.src, d1.ldn, lane, v1);
;         tr_finish(v0, d0.dst, d0.dst2, d0.ldk, scr, lane, d0.scale);
;         if (two) tr_finish(v1, d1.dst, d1.dst2, d1.ldk, scr, lane, d1.scale);
;     }
	v_mov_b32_e32 v54, v58
	s_waitcnt lgkmcnt(6)
	v_mov_b32_e32 v55, v60
	s_waitcnt lgkmcnt(5)
	v_mov_b32_e32 v56, v62
	s_waitcnt lgkmcnt(4)
	v_mov_b32_e32 v57, v64
	v_pk_mul_f32 v[54:55], s[8:9], v[54:55] op_sel_hi:[0,1]
	v_pk_mul_f32 v[56:57], s[8:9], v[56:57] op_sel_hi:[0,1]
	v_cvt_pk_bf16_f32 v54, v54, v55
	v_cvt_pk_bf16_f32 v55, v56, v57
	s_waitcnt lgkmcnt(3)
	v_mov_b32_e32 v56, v66
	s_waitcnt lgkmcnt(2)
	v_mov_b32_e32 v57, v68
	s_waitcnt lgkmcnt(1)
	v_mov_b32_e32 v74, v70
	s_waitcnt lgkmcnt(0)
	v_mov_b32_e32 v75, v72
	v_pk_mul_f32 v[56:57], s[8:9], v[56:57] op_sel_hi:[0,1]
	v_pk_mul_f32 v[74:75], s[8:9], v[74:75] op_sel_hi:[0,1]
	v_cvt_pk_bf16_f32 v56, v56, v57
	v_cvt_pk_bf16_f32 v57, v74, v75
	v_lshl_add_u64 v[34:35], v[34:35], 0, s[26:27]
	v_mov_b32_e32 v60, v59
	v_mov_b32_e32 v64, v63
	global_store_dwordx4 v[34:35], v[54:57], off sc1
	v_mov_b32_e32 v68, v67
	v_mov_b32_e32 v72, v71
	v_pk_mul_f32 v[54:55], s[8:9], v[60:61] op_sel_hi:[0,1]
	v_pk_mul_f32 v[56:57], s[8:9], v[64:65] op_sel_hi:[0,1]
	v_cvt_pk_bf16_f32 v54, v54, v55
	v_cvt_pk_bf16_f32 v55, v56, v57
	v_pk_mul_f32 v[56:57], s[8:9], v[68:69] op_sel_hi:[0,1]
	v_pk_mul_f32 v[58:59], s[8:9], v[72:73] op_sel_hi:[0,1]
	v_cvt_pk_bf16_f32 v56, v56, v57
	v_cvt_pk_bf16_f32 v57, v58, v59
	v_lshl_add_u64 v[34:35], v[34:35], 0, s[26:27]
	global_store_dwordx4 v[34:35], v[54:57], off sc1
	s_waitcnt lgkmcnt(0)
	s_cbranch_vccnz .LBB0_507
	ds_write2_b32 v41, v0, v1 offset1:1
	ds_write2_b32 v41, v2, v3 offset0:2 offset1:3
	ds_write2_b32 v39, v4, v5 offset1:1
	ds_write2_b32 v42, v6, v7 offset1:1
	ds_write2_b32 v43, v8, v9 offset1:1
	ds_write2_b32 v44, v10, v11 offset1:1
	ds_write2_b32 v45, v12, v13 offset1:1
	ds_write2_b32 v46, v14, v15 offset1:1
	ds_write2_b32 v47, v16, v17 offset1:1
	ds_write2_b32 v48, v18, v19 offset1:1
	ds_write2_b32 v49, v20, v21 offset1:1
	ds_write2_b32 v50, v22, v23 offset1:1
	ds_write2_b32 v51, v24, v25 offset1:1
	ds_write2_b32 v52, v26, v27 offset1:1
	ds_write2_b32 v53, v28, v29 offset1:1
	ds_write2_b32 v32, v30, v31 offset1:1
	s_waitcnt lgkmcnt(0)
	ds_read2_b32 v[4:5], v40 offset1:8
	ds_read2_b32 v[6:7], v40 offset0:33 offset1:41
	ds_read2_b32 v[10:11], v40 offset0:66 offset1:74
	ds_read2_b32 v[12:13], v40 offset0:99 offset1:107
	ds_read2_b32 v[14:15], v40 offset0:132 offset1:140
	ds_read2_b32 v[16:17], v40 offset0:165 offset1:173
	ds_read2_b32 v[18:19], v40 offset0:198 offset1:206
	ds_read2_b32 v[20:21], v40 offset0:231 offset1:239
	s_waitcnt lgkmcnt(7)
	v_mov_b32_e32 v0, v4
	s_waitcnt lgkmcnt(6)
	v_mov_b32_e32 v1, v6
	s_waitcnt lgkmcnt(5)
	v_mov_b32_e32 v2, v10
	s_waitcnt lgkmcnt(4)
	v_mov_b32_e32 v3, v12
	v_pk_mul_f32 v[0:1], s[16:17], v[0:1] op_sel_hi:[0,1]
	v_pk_mul_f32 v[2:3], s[16:17], v[2:3] op_sel_hi:[0,1]
	v_cvt_pk_bf16_f32 v0, v0, v1
	v_cvt_pk_bf16_f32 v1, v2, v3
	s_waitcnt lgkmcnt(3)
	v_mov_b32_e32 v2, v14
	s_waitcnt lgkmcnt(2)
	v_mov_b32_e32 v3, v16
	s_waitcnt lgkmcnt(1)
	v_mov_b32_e32 v22, v18
	s_waitcnt lgkmcnt(0)
	v_mov_b32_e32 v23, v20
	v_mul_u32_u24_e32 v4, s9, v37
	v_lshl_add_u64 v[8:9], s[22:23], 0, v[80:81]
	v_pk_mul_f32 v[2:3], s[16:17], v[2:3] op_sel_hi:[0,1]
	v_pk_mul_f32 v[22:23], s[16:17], v[22:23] op_sel_hi:[0,1]
	v_lshlrev_b32_e32 v80, 1, v4
	v_cvt_pk_bf16_f32 v2, v2, v3
	v_cvt_pk_bf16_f32 v3, v22, v23
	v_lshl_add_u64 v[8:9], v[8:9], 0, v[80:81]
	v_mov_b32_e32 v6, v5
	v_mov_b32_e32 v12, v11
	s_lshl_b32 s8, s9, 3
	global_store_dwordx4 v[8:9], v[0:3], off sc1
	v_mov_b32_e32 v16, v15
	v_mov_b32_e32 v20, v19
	v_pk_mul_f32 v[0:1], s[16:17], v[6:7] op_sel_hi:[0,1]
	v_pk_mul_f32 v[2:3], s[16:17], v[12:13] op_sel_hi:[0,1]
	s_ashr_i32 s9, s8, 31
	v_cvt_pk_bf16_f32 v0, v0, v1
	v_cvt_pk_bf16_f32 v1, v2, v3
	v_pk_mul_f32 v[2:3], s[16:17], v[16:17] op_sel_hi:[0,1]
	v_pk_mul_f32 v[4:5], s[16:17], v[20:21] op_sel_hi:[0,1]
	s_lshl_b64 s[8:9], s[8:9], 1
	v_cvt_pk_bf16_f32 v2, v2, v3
	v_cvt_pk_bf16_f32 v3, v4, v5
	ds_read2_b32 v[4:5], v40 offset0:16 offset1:24
	ds_read2_b32 v[6:7], v40 offset0:49 offset1:57
	v_lshl_add_u64 v[8:9], v[8:9], 0, s[8:9]
	ds_read2_b32 v[10:11], v40 offset0:82 offset1:90
	ds_read2_b32 v[12:13], v40 offset0:115 offset1:123
	global_store_dwordx4 v[8:9], v[0:3], off sc1
	ds_read2_b32 v[14:15], v40 offset0:148 offset1:156
	ds_read2_b32 v[16:17], v40 offset0:181 offset1:189
	ds_read2_b32 v[18:19], v40 offset0:214 offset1:222
	ds_read2_b32 v[20:21], v40 offset0:247 offset1:255
	s_waitcnt lgkmcnt(7)
	v_mov_b32_e32 v0, v4
	s_waitcnt lgkmcnt(6)
	v_mov_b32_e32 v1, v6
	s_waitcnt lgkmcnt(5)
	v_mov_b32_e32 v2, v10
	s_waitcnt lgkmcnt(4)
	v_mov_b32_e32 v3, v12
	v_pk_mul_f32 v[0:1], s[16:17], v[0:1] op_sel_hi:[0,1]
	v_pk_mul_f32 v[2:3], s[16:17], v[2:3] op_sel_hi:[0,1]
	v_cvt_pk_bf16_f32 v0, v0, v1
	v_cvt_pk_bf16_f32 v1, v2, v3
	s_waitcnt lgkmcnt(3)
	v_mov_b32_e32 v2, v14
	s_waitcnt lgkmcnt(2)
	v_mov_b32_e32 v3, v16
	s_waitcnt lgkmcnt(1)
	v_mov_b32_e32 v22, v18
	s_waitcnt lgkmcnt(0)
	v_mov_b32_e32 v23, v20
	v_pk_mul_f32 v[2:3], s[16:17], v[2:3] op_sel_hi:[0,1]
	v_pk_mul_f32 v[22:23], s[16:17], v[22:23] op_sel_hi:[0,1]
	v_cvt_pk_bf16_f32 v2, v2, v3
	v_cvt_pk_bf16_f32 v3, v22, v23
	v_lshl_add_u64 v[8:9], v[8:9], 0, s[8:9]
	v_mov_b32_e32 v6, v5
	v_mov_b32_e32 v12, v11
	global_store_dwordx4 v[8:9], v[0:3], off sc1
	v_mov_b32_e32 v16, v15
	v_mov_b32_e32 v20, v19
	v_pk_mul_f32 v[0:1], s[16:17], v[6:7] op_sel_hi:[0,1]
	v_pk_mul_f32 v[2:3], s[16:17], v[12:13] op_sel_hi:[0,1]
	v_cvt_pk_bf16_f32 v0, v0, v1
	v_cvt_pk_bf16_f32 v1, v2, v3
	v_pk_mul_f32 v[2:3], s[16:17], v[16:17] op_sel_hi:[0,1]
	v_pk_mul_f32 v[4:5], s[16:17], v[20:21] op_sel_hi:[0,1]
	v_cvt_pk_bf16_f32 v2, v2, v3
	v_cvt_pk_bf16_f32 v3, v4, v5
	v_lshl_add_u64 v[4:5], v[8:9], 0, s[8:9]
	global_store_dwordx4 v[4:5], v[0:3], off sc1
	s_waitcnt lgkmcnt(0)
	s_branch .LBB0_507

; #define LAS __attribute__((address_space(3)))
; #define LDS_WAIT() asm volatile("s_waitcnt lgkmcnt(0)" ::: "memory")
; __device__ __forceinline__ unsigned cvt_pk_bf16(float lo, float hi) { f32x2_t v = {lo, hi}; bf16x2_t b = __builtin_convertvector(v, bf16x2_t); return __builtin_bit_cast(unsigned, b); }
; __device__ __forceinline__ void tr_load(const float* src, int ldn, int lane, f32x4 (&v)[8]) {
;     const int r8 = lane >> 3, c4 = lane & 7;
; #pragma unroll
;     for (int i = 0; i < 8; ++i) v[i] = __builtin_nontemporal_load((const f32x4*)(src + (size_t)(8 * i + r8) * ldn + 4 * c4));
; }
;     const int r8 = lane >> 3, c4 = lane & 7;
; #pragma unroll
;     for (int i = 0; i < 8; ++i) { LAS float* w = scr + (8 * i + r8) * 33 + 4 * c4; w[0] = v[i][0]; w[1] = v[i][1]; w[2] = v[i][2]; w[3] = v[i][3]; }
;     LDS_WAIT(); asm volatile("" ::: "memory");
;     const int c = lane & 7;
; #pragma unroll
;     for (int j = 0; j < 4; ++j) { const int n = (lane >> 3) + 8 * j; const LAS float* sp = scr + (8 * c) * 33 + n;
;         u32x4 o; o.x = cvt_pk_bf16(sp[0 * 33] * s, sp[1 * 33] * s); o.y = cvt_pk_bf16(sp[2 * 33] * s, sp[3 * 33] * s); o.z = cvt_pk_bf16(sp[4 * 33] * s, sp[5 * 33] * s); o.w = cvt_pk_bf16(sp[6 * 33] * s, sp[7 * 33] * s);
;         *(u32x4*)(dst + (size_t)n * ldk + 8 * c) = o; if (dst2) *(u32x4*)(dst2 + (size_t)n * ldk + 8 * c) = o; }
;     LDS_WAIT(); asm volatile("" ::: "memory");
; }
;     LAS float* scr = (LAS float*)(lds + wave * 8448);
;     const int n1 = (l & 1) == 0 ? 16 * 72 : 16 * 16, n2 = (l & 1) == 0 ? 16 * 32 : 8 * 32, nU = 16 * 176, nD = 44 * 32;
;     const int I0 = part <= 1 ? 0 : (part == 2 ? n1 : n1 + n2 + nU), NIT = part == 0 ? n1 + n2 + nU + nD : (part == 1 ? n1 : (part == 2 ? n1 + n2 + nU : n1 + n2 + nU + nD));
;     for (int it = I0 + wr; it < NIT; it += 2 * nw) {
;         const bool two = it + nw < NIT;
;         const TrDesc d0 = tr_decode(a, l, it), d1 = tr_decode(a, l, two ? it + nw : it);
;         f32x4 v0[8], v1[8];
;         tr_load(d0.src, d0.ldn, lane, v0); tr_load(d1.src, d1.ldn, lane, v1);
;         tr_finish(v0, d0.dst, d0.dst2, d0.ldk, scr, lane, d0.scale);
;         if (two) tr_finish(v1, d1.dst, d1.dst2, d1.ldk, scr, lane, d1.scale);
;     }
.LBB0_576:
	v_mov_b32_e32 v39, v81
	v_mul_u32_u24_e32 v2, s92, v37
	s_lshl_b32 s12, s92, 3
	v_lshl_add_u64 v[0:1], s[36:37], 0, v[38:39]
	v_lshlrev_b32_e32 v80, 2, v2
	s_ashr_i32 s13, s12, 31
	v_lshl_add_u64 v[2:3], v[0:1], 0, v[80:81]
	s_lshl_b64 s[34:35], s[12:13], 2
	global_load_dwordx4 v[42:45], v[2:3], off nt
	v_lshl_add_u64 v[2:3], v[2:3], 0, s[34:35]
	global_load_dwordx4 v[46:49], v[2:3], off nt
	v_lshl_add_u64 v[2:3], v[2:3], 0, s[34:35]
	s_add_i32 s13, s12, s12
	global_load_dwordx4 v[50:53], v[2:3], off nt
	v_lshl_add_u64 v[2:3], v[2:3], 0, s[34:35]
	s_add_i32 s13, s13, s13
	global_load_dwordx4 v[54:57], v[2:3], off nt
	v_mov_b32_e32 v2, s13
	v_mad_u32_u24 v80, s92, v37, v2
	v_lshl_add_u64 v[2:3], v[80:81], 2, v[0:1]
	v_add_u32_e32 v80, s12, v80
	global_load_dwordx4 v[58:61], v[2:3], off nt
	v_lshl_add_u64 v[2:3], v[80:81], 2, v[0:1]
	v_add_u32_e32 v80, s12, v80
	global_load_dwordx4 v[62:65], v[2:3], off nt
	v_lshl_add_u64 v[2:3], v[80:81], 2, v[0:1]
	v_add_u32_e32 v80, s12, v80
	v_lshl_add_u64 v[0:1], v[80:81], 2, v[0:1]
	global_load_dwordx4 v[66:69], v[2:3], off nt
	global_load_dwordx4 v[32:35], v[0:1], off nt
	s_lshl_b32 s12, s28, 3
	s_ashr_i32 s13, s12, 31
	s_lshl_b64 s[34:35], s[12:13], 2
	s_add_i32 s13, s12, s12
	v_mul_u32_u24_e32 v0, s28, v37
	s_add_i32 s13, s13, s13
	v_lshl_add_u64 v[28:29], s[38:39], 0, v[38:39]
	v_lshlrev_b32_e32 v80, 2, v0
	v_mov_b32_e32 v16, s13
	v_lshl_add_u64 v[4:5], v[28:29], 0, v[80:81]
	v_mad_u32_u24 v80, s28, v37, v16
	v_lshl_add_u64 v[16:17], v[80:81], 2, v[28:29]
	v_add_u32_e32 v80, s12, v80
	s_waitcnt lgkmcnt(0)
	v_lshl_add_u64 v[8:9], v[4:5], 0, s[34:35]
	v_lshl_add_u64 v[20:21], v[80:81], 2, v[28:29]
	v_add_u32_e32 v80, s12, v80
	v_lshl_add_u64 v[12:13], v[8:9], 0, s[34:35]
	v_lshl_add_u64 v[24:25], v[80:81], 2, v[28:29]
	v_add_u32_e32 v80, s12, v80
	global_load_dwordx4 v[0:3], v[4:5], off nt
	v_lshl_add_u64 v[28:29], v[80:81], 2, v[28:29]
	global_load_dwordx4 v[16:19], v[16:17], off nt
	v_add_u32_e32 v39, 0x420, v41
	global_load_dwordx4 v[4:7], v[8:9], off nt
	v_lshlrev_b32_e32 v80, 1, v36
	global_load_dwordx4 v[20:23], v[20:21], off nt
	s_lshl_b32 s12, s9, 3
	global_load_dwordx4 v[8:11], v[12:13], off nt
	s_ashr_i32 s13, s12, 31
	global_load_dwordx4 v[24:27], v[24:25], off nt
	v_lshl_add_u64 v[12:13], v[12:13], 0, s[34:35]
	global_load_dwordx4 v[12:15], v[12:13], off nt
	s_andn2_b64 vcc, exec, s[16:17]
	global_load_dwordx4 v[28:31], v[28:29], off nt
	s_waitcnt vmcnt(0)
	ds_write2_b32 v41, v42, v43 offset1:1
	ds_write2_b32 v41, v44, v45 offset0:2 offset1:3
	v_add_u32_e32 v44, 0x848, v41
	v_add_u32_e32 v42, 0x428, v41
	v_add_u32_e32 v43, 0x840, v41
	ds_write2_b32 v39, v46, v47 offset1:1
	ds_write2_b32 v44, v52, v53 offset1:1
	v_add_u32_e32 v53, 0x1ce0, v41
	ds_write2_b32 v42, v48, v49 offset1:1
	ds_write2_b32 v43, v50, v51 offset1:1
	v_add_u32_e32 v45, 0xc60, v41
	v_add_u32_e32 v46, 0xc68, v41
	v_add_u32_e32 v47, 0x1080, v41
	v_add_u32_e32 v48, 0x1088, v41
	v_add_u32_e32 v49, 0x14a0, v41
	v_add_u32_e32 v50, 0x14a8, v41
	v_add_u32_e32 v51, 0x18c0, v41
	v_add_u32_e32 v52, 0x18c8, v41
	ds_write2_b32 v45, v54, v55 offset1:1
	ds_write2_b32 v46, v56, v57 offset1:1
	ds_write2_b32 v47, v58, v59 offset1:1
	ds_write2_b32 v48, v60, v61 offset1:1
	ds_write2_b32 v53, v32, v33 offset1:1
	v_add_u32_e32 v32, 0x1ce8, v41
	ds_write2_b32 v49, v62, v63 offset1:1
	ds_write2_b32 v50, v64, v65 offset1:1
	ds_write2_b32 v51, v66, v67 offset1:1
	ds_write2_b32 v52, v68, v69 offset1:1
	ds_write2_b32 v32, v34, v35 offset1:1
	s_waitcnt lgkmcnt(0)
	ds_read2_b32 v[58:59], v40 offset0:33 offset1:41
	ds_read2_b32 v[60:61], v40 offset1:8
	ds_read2_b32 v[62:63], v40 offset0:66 offset1:74
	ds_read2_b32 v[64:65], v40 offset0:99 offset1:107
	ds_read2_b32 v[66:67], v40 offset0:132 offset1:140
	ds_read2_b32 v[68:69], v40 offset0:165 offset1:173
	ds_read2_b32 v[70:71], v40 offset0:198 offset1:206
	ds_read2_b32 v[72:73], v40 offset0:231 offset1:239
	s_waitcnt lgkmcnt(7)
	v_mov_b32_e32 v55, v58
	s_waitcnt lgkmcnt(6)
	v_mov_b32_e32 v54, v60
	s_waitcnt lgkmcnt(5)
	v_mov_b32_e32 v56, v62
	s_waitcnt lgkmcnt(4)
	v_mov_b32_e32 v57, v64
	v_pk_mul_f32 v[54:55], s[8:9], v[54:55] op_sel_hi:[0,1]
	v_pk_mul_f32 v[56:57], s[8:9], v[56:57] op_sel_hi:[0,1]
	v_cvt_pk_bf16_f32 v54, v54, v55
	v_cvt_pk_bf16_f32 v55, v56, v57
	s_waitcnt lgkmcnt(3)
	v_mov_b32_e32 v56, v66
	s_waitcnt lgkmcnt(2)
	v_mov_b32_e32 v57, v68
	s_waitcnt lgkmcnt(1)
	v_mov_b32_e32 v74, v70
	s_waitcnt lgkmcnt(0)
	v_mov_b32_e32 v75, v72
	v_pk_mul_f32 v[56:57], s[8:9], v[56:57] op_sel_hi:[0,1]
	v_pk_mul_f32 v[74:75], s[8:9], v[74:75] op_sel_hi:[0,1]
	v_mul_u32_u24_e32 v33, s9, v37
	v_lshl_add_u64 v[34:35], s[22:23], 0, v[80:81]
	v_cvt_pk_bf16_f32 v56, v56, v57
	v_cvt_pk_bf16_f32 v57, v74, v75
	v_lshlrev_b32_e32 v74, 1, v33
	v_mov_b32_e32 v75, v81
	v_lshl_add_u64 v[34:35], v[34:35], 0, v[74:75]
	v_mov_b32_e32 v58, v61
	v_mov_b32_e32 v64, v63
	global_store_dwordx4 v[34:35], v[54:57], off sc1
	v_mov_b32_e32 v68, v67
	v_mov_b32_e32 v72, v71
	v_pk_mul_f32 v[54:55], s[8:9], v[58:59] op_sel_hi:[0,1]
	v_pk_mul_f32 v[56:57], s[8:9], v[64:65] op_sel_hi:[0,1]
	v_cvt_pk_bf16_f32 v54, v54, v55
	v_cvt_pk_bf16_f32 v55, v56, v57
	v_pk_mul_f32 v[56:57], s[8:9], v[68:69] op_sel_hi:[0,1]
	v_pk_mul_f32 v[58:59], s[8:9], v[72:73] op_sel_hi:[0,1]
	s_lshl_b64 s[22:23], s[12:13], 1
	v_cvt_pk_bf16_f32 v56, v56, v57
	v_cvt_pk_bf16_f32 v57, v58, v59
	v_lshl_add_u64 v[34:35], v[34:35], 0, s[22:23]
	global_store_dwordx4 v[34:35], v[54:57], off sc1
	ds_read2_b32 v[58:59], v40 offset0:16 offset1:24
	ds_read2_b32 v[60:61], v40 offset0:49 offset1:57
	ds_read2_b32 v[62:63], v40 offset0:82 offset1:90
	ds_read2_b32 v[64:65], v40 offset0:115 offset1:123
	ds_read2_b32 v[66:67], v40 offset0:148 offset1:156
	ds_read2_b32 v[68:69], v40 offset0:181 offset1:189
	ds_read2_b32 v[70:71], v40 offset0:214 offset1:222
	ds_read2_b32 v[72:73], v40 offset0:247 offset1:255
	s_waitcnt lgkmcnt(7)
; #define LAS __attribute__((address_space(3)))
; #define LDS_WAIT() asm volatile("s_waitcnt lgkmcnt(0)" ::: "memory")
; __device__ __forceinline__ unsigned cvt_pk_bf16(float lo, float hi) { f32x2_t v = {lo, hi}; bf16x2_t b = __builtin_convertvector(v, bf16x2_t); return __builtin_bit_cast(unsigned, b); }
; __device__ __forceinline__ void tr_load(const float* src, int ldn, int lane, f32x4 (&v)[8]) {
;     const int r8 = lane >> 3, c4 = lane & 7;
; #pragma unroll
;     for (int i = 0; i < 8; ++i) v[i] = __builtin_nontemporal_load((const f32x4*)(src + (size_t)(8 * i + r8) * ldn + 4 * c4));
; }
;     const int r8 = lane >> 3, c4 = lane & 7;
; #pragma unroll
;     for (int i = 0; i < 8; ++i) { LAS float* w = scr + (8 * i + r8) * 33 + 4 * c4; w[0] = v[i][0]; w[1] = v[i][1]; w[2] = v[i][2]; w[3] = v[i][3]; }
;     LDS_WAIT(); asm volatile("" ::: "memory");
;     const int c = lane & 7;
; #pragma unroll
;     for (int j = 0; j < 4; ++j) { const int n = (lane >> 3) + 8 * j; const LAS float* sp = scr + (8 * c) * 33 + n;
;         u32x4 o; o.x = cvt_pk_bf16(sp[0 * 33] * s, sp[1 * 33] * s); o.y = cvt_pk_bf16(sp[2 * 33] * s, sp[3 * 33] * s); o.z = cvt_pk_bf16(sp[4 * 33] * s, sp[5 * 33] * s); o.w = cvt_pk_bf16(sp[6 * 33] * s, sp[7 * 33] * s);
;         *(u32x4*)(dst + (size_t)n * ldk + 8 * c) = o; if (dst2) *(u32x4*)(dst2 + (size_t)n * ldk + 8 * c) = o; }
;     LDS_WAIT(); asm volatile("" ::: "memory");
; }
;     LAS float* scr = (LAS float*)(lds + wave * 8448);
;     const int n1 = (l & 1) == 0 ? 16 * 72 : 16 * 16, n2 = (l & 1) == 0 ? 16 * 32 : 8 * 32, nU = 16 * 176, nD = 44 * 32;
;     const int I0 = part <= 1 ? 0 : (part == 2 ? n1 : n1 + n2 + nU), NIT = part == 0 ? n1 + n2 + nU + nD : (part == 1 ? n1 : (part == 2 ? n1 + n2 + nU : n1 + n2 + nU + nD));
;     for (int it = I0 + wr; it < NIT; it += 2 * nw) {
;         const bool two = it + nw < NIT;
;         const TrDesc d0 = tr_decode(a, l, it), d1 = tr_decode(a, l, two ? it + nw : it);
;         f32x4 v0[8], v1[8];
;         tr_load(d0.src, d0.ldn, lane, v0); tr_load(d1.src, d1.ldn, lane, v1);
;         tr_finish(v0, d0.dst, d0.dst2, d0.ldk, scr, lane, d0.scale);
;         if (two) tr_finish(v1, d1.dst, d1.dst2, d1.ldk, scr, lane, d1.scale);
;     }
	v_mov_b32_e32 v54, v58
	s_waitcnt lgkmcnt(6)
	v_mov_b32_e32 v55, v60
	s_waitcnt lgkmcnt(5)
	v_mov_b32_e32 v56, v62
	s_waitcnt lgkmcnt(4)
	v_mov_b32_e32 v57, v64
	v_pk_mul_f32 v[54:55], s[8:9], v[54:55] op_sel_hi:[0,1]
	v_pk_mul_f32 v[56:57], s[8:9], v[56:57] op_sel_hi:[0,1]
	v_cvt_pk_bf16_f32 v54, v54, v55
	v_cvt_pk_bf16_f32 v55, v56, v57
	s_waitcnt lgkmcnt(3)
	v_mov_b32_e32 v56, v66
	s_waitcnt lgkmcnt(2)
	v_mov_b32_e32 v57, v68
	s_waitcnt lgkmcnt(1)
	v_mov_b32_e32 v74, v70
	s_waitcnt lgkmcnt(0)
	v_mov_b32_e32 v75, v72
	v_pk_mul_f32 v[56:57], s[8:9], v[56:57] op_sel_hi:[0,1]
	v_pk_mul_f32 v[74:75], s[8:9], v[74:75] op_sel_hi:[0,1]
	v_cvt_pk_bf16_f32 v56, v56, v57
	v_cvt_pk_bf16_f32 v57, v74, v75
	v_lshl_add_u64 v[34:35], v[34:35], 0, s[22:23]
	v_mov_b32_e32 v60, v59
	v_mov_b32_e32 v64, v63
	global_store_dwordx4 v[34:35], v[54:57], off sc1
	v_mov_b32_e32 v68, v67
	v_mov_b32_e32 v72, v71
	v_pk_mul_f32 v[54:55], s[8:9], v[60:61] op_sel_hi:[0,1]
	v_pk_mul_f32 v[56:57], s[8:9], v[64:65] op_sel_hi:[0,1]
	v_cvt_pk_bf16_f32 v54, v54, v55
	v_cvt_pk_bf16_f32 v55, v56, v57
	v_pk_mul_f32 v[56:57], s[8:9], v[68:69] op_sel_hi:[0,1]
	v_pk_mul_f32 v[58:59], s[8:9], v[72:73] op_sel_hi:[0,1]
	v_cvt_pk_bf16_f32 v56, v56, v57
	v_cvt_pk_bf16_f32 v57, v58, v59
	v_lshl_add_u64 v[34:35], v[34:35], 0, s[22:23]
	global_store_dwordx4 v[34:35], v[54:57], off sc1
	s_waitcnt lgkmcnt(0)
	s_cbranch_vccnz .LBB0_537
	ds_write2_b32 v41, v0, v1 offset1:1
	ds_write2_b32 v41, v2, v3 offset0:2 offset1:3
	ds_write2_b32 v39, v4, v5 offset1:1
	ds_write2_b32 v42, v6, v7 offset1:1
	ds_write2_b32 v43, v8, v9 offset1:1
	ds_write2_b32 v44, v10, v11 offset1:1
	ds_write2_b32 v45, v12, v13 offset1:1
	ds_write2_b32 v46, v14, v15 offset1:1
	ds_write2_b32 v47, v16, v17 offset1:1
	ds_write2_b32 v48, v18, v19 offset1:1
	ds_write2_b32 v49, v20, v21 offset1:1
	ds_write2_b32 v50, v22, v23 offset1:1
	ds_write2_b32 v51, v24, v25 offset1:1
	ds_write2_b32 v52, v26, v27 offset1:1
	ds_write2_b32 v53, v28, v29 offset1:1
	ds_write2_b32 v32, v30, v31 offset1:1
	s_waitcnt lgkmcnt(0)
	ds_read2_b32 v[4:5], v40 offset1:8
	ds_read2_b32 v[6:7], v40 offset0:33 offset1:41
	ds_read2_b32 v[10:11], v40 offset0:66 offset1:74
	ds_read2_b32 v[12:13], v40 offset0:99 offset1:107
	ds_read2_b32 v[14:15], v40 offset0:132 offset1:140
	ds_read2_b32 v[16:17], v40 offset0:165 offset1:173
	ds_read2_b32 v[18:19], v40 offset0:198 offset1:206
	ds_read2_b32 v[20:21], v40 offset0:231 offset1:239
	s_waitcnt lgkmcnt(7)
	v_mov_b32_e32 v0, v4
	s_waitcnt lgkmcnt(6)
	v_mov_b32_e32 v1, v6
	s_waitcnt lgkmcnt(5)
	v_mov_b32_e32 v2, v10
	s_waitcnt lgkmcnt(4)
	v_mov_b32_e32 v3, v12
	v_pk_mul_f32 v[0:1], s[20:21], v[0:1] op_sel_hi:[0,1]
	v_pk_mul_f32 v[2:3], s[20:21], v[2:3] op_sel_hi:[0,1]
	v_cvt_pk_bf16_f32 v0, v0, v1
	v_cvt_pk_bf16_f32 v1, v2, v3
	s_waitcnt lgkmcnt(3)
	v_mov_b32_e32 v2, v14
	s_waitcnt lgkmcnt(2)
	v_mov_b32_e32 v3, v16
	s_waitcnt lgkmcnt(1)
	v_mov_b32_e32 v22, v18
	s_waitcnt lgkmcnt(0)
	v_mov_b32_e32 v23, v20
	v_mul_u32_u24_e32 v4, s21, v37
	v_lshl_add_u64 v[8:9], s[26:27], 0, v[80:81]
	v_pk_mul_f32 v[2:3], s[20:21], v[2:3] op_sel_hi:[0,1]
	v_pk_mul_f32 v[22:23], s[20:21], v[22:23] op_sel_hi:[0,1]
	v_lshlrev_b32_e32 v80, 1, v4
	v_cvt_pk_bf16_f32 v2, v2, v3
	v_cvt_pk_bf16_f32 v3, v22, v23
	v_lshl_add_u64 v[8:9], v[8:9], 0, v[80:81]
	v_mov_b32_e32 v6, v5
	v_mov_b32_e32 v12, v11
	s_lshl_b32 s8, s21, 3
	global_store_dwordx4 v[8:9], v[0:3], off sc1
	v_mov_b32_e32 v16, v15
	v_mov_b32_e32 v20, v19
	v_pk_mul_f32 v[0:1], s[20:21], v[6:7] op_sel_hi:[0,1]
	v_pk_mul_f32 v[2:3], s[20:21], v[12:13] op_sel_hi:[0,1]
	s_ashr_i32 s9, s8, 31
	v_cvt_pk_bf16_f32 v0, v0, v1
	v_cvt_pk_bf16_f32 v1, v2, v3
	v_pk_mul_f32 v[2:3], s[20:21], v[16:17] op_sel_hi:[0,1]
	v_pk_mul_f32 v[4:5], s[20:21], v[20:21] op_sel_hi:[0,1]
	s_lshl_b64 s[8:9], s[8:9], 1
	v_cvt_pk_bf16_f32 v2, v2, v3
	v_cvt_pk_bf16_f32 v3, v4, v5
	ds_read2_b32 v[4:5], v40 offset0:16 offset1:24
	ds_read2_b32 v[6:7], v40 offset0:49 offset1:57
	v_lshl_add_u64 v[8:9], v[8:9], 0, s[8:9]
	ds_read2_b32 v[10:11], v40 offset0:82 offset1:90
	ds_read2_b32 v[12:13], v40 offset0:115 offset1:123
	global_store_dwordx4 v[8:9], v[0:3], off sc1
	ds_read2_b32 v[14:15], v40 offset0:148 offset1:156
	ds_read2_b32 v[16:17], v40 offset0:181 offset1:189
	ds_read2_b32 v[18:19], v40 offset0:214 offset1:222
	ds_read2_b32 v[20:21], v40 offset0:247 offset1:255
	s_waitcnt lgkmcnt(7)
	v_mov_b32_e32 v0, v4
	s_waitcnt lgkmcnt(6)
	v_mov_b32_e32 v1, v6
	s_waitcnt lgkmcnt(5)
	v_mov_b32_e32 v2, v10
	s_waitcnt lgkmcnt(4)
	v_mov_b32_e32 v3, v12
	v_pk_mul_f32 v[0:1], s[20:21], v[0:1] op_sel_hi:[0,1]
	v_pk_mul_f32 v[2:3], s[20:21], v[2:3] op_sel_hi:[0,1]
	v_cvt_pk_bf16_f32 v0, v0, v1
	v_cvt_pk_bf16_f32 v1, v2, v3
	s_waitcnt lgkmcnt(3)
	v_mov_b32_e32 v2, v14
	s_waitcnt lgkmcnt(2)
	v_mov_b32_e32 v3, v16
	s_waitcnt lgkmcnt(1)
	v_mov_b32_e32 v22, v18
	s_waitcnt lgkmcnt(0)
	v_mov_b32_e32 v23, v20
	v_pk_mul_f32 v[2:3], s[20:21], v[2:3] op_sel_hi:[0,1]
	v_pk_mul_f32 v[22:23], s[20:21], v[22:23] op_sel_hi:[0,1]
	v_cvt_pk_bf16_f32 v2, v2, v3
	v_cvt_pk_bf16_f32 v3, v22, v23
	v_lshl_add_u64 v[8:9], v[8:9], 0, s[8:9]
	v_mov_b32_e32 v6, v5
	v_mov_b32_e32 v12, v11
	global_store_dwordx4 v[8:9], v[0:3], off sc1
	v_mov_b32_e32 v16, v15
	v_mov_b32_e32 v20, v19
	v_pk_mul_f32 v[0:1], s[20:21], v[6:7] op_sel_hi:[0,1]
	v_pk_mul_f32 v[2:3], s[20:21], v[12:13] op_sel_hi:[0,1]
	v_cvt_pk_bf16_f32 v0, v0, v1
	v_cvt_pk_bf16_f32 v1, v2, v3
	v_pk_mul_f32 v[2:3], s[20:21], v[16:17] op_sel_hi:[0,1]
	v_pk_mul_f32 v[4:5], s[20:21], v[20:21] op_sel_hi:[0,1]
	v_cvt_pk_bf16_f32 v2, v2, v3
	v_cvt_pk_bf16_f32 v3, v4, v5
	v_lshl_add_u64 v[4:5], v[8:9], 0, s[8:9]
	global_store_dwordx4 v[4:5], v[0:3], off sc1
	s_waitcnt lgkmcnt(0)
	s_branch .LBB0_537

; #define LAS __attribute__((address_space(3)))
; #define LDS_WAIT() asm volatile("s_waitcnt lgkmcnt(0)" ::: "memory")
; __device__ __forceinline__ unsigned cvt_pk_bf16(float lo, float hi) { f32x2_t v = {lo, hi}; bf16x2_t b = __builtin_convertvector(v, bf16x2_t); return __builtin_bit_cast(unsigned, b); }
; __device__ __forceinline__ void tr_load(const float* src, int ldn, int lane, f32x4 (&v)[8]) {
;     const int r8 = lane >> 3, c4 = lane & 7;
; #pragma unroll
;     for (int i = 0; i < 8; ++i) v[i] = __builtin_nontemporal_load((const f32x4*)(src + (size_t)(8 * i + r8) * ldn + 4 * c4));
; }
;     const int r8 = lane >> 3, c4 = lane & 7;
; #pragma unroll
;     for (int i = 0; i < 8; ++i) { LAS float* w = scr + (8 * i + r8) * 33 + 4 * c4; w[0] = v[i][0]; w[1] = v[i][1]; w[2] = v[i][2]; w[3] = v[i][3]; }
;     LDS_WAIT(); asm volatile("" ::: "memory");
;     const int c = lane & 7;
; #pragma unroll
;     for (int j = 0; j < 4; ++j) { const int n = (lane >> 3) + 8 * j; const LAS float* sp = scr + (8 * c) * 33 + n;
;         u32x4 o; o.x = cvt_pk_bf16(sp[0 * 33] * s, sp[1 * 33] * s); o.y = cvt_pk_bf16(sp[2 * 33] * s, sp[3 * 33] * s); o.z = cvt_pk_bf16(sp[4 * 33] * s, sp[5 * 33] * s); o.w = cvt_pk_bf16(sp[6 * 33] * s, sp[7 * 33] * s);
;         *(u32x4*)(dst + (size_t)n * ldk + 8 * c) = o; if (dst2) *(u32x4*)(dst2 + (size_t)n * ldk + 8 * c) = o; }
;     LDS_WAIT(); asm volatile("" ::: "memory");
; }
;     LAS float* scr = (LAS float*)(lds + wave * 8448);
;     const int n1 = (l & 1) == 0 ? 16 * 72 : 16 * 16, n2 = (l & 1) == 0 ? 16 * 32 : 8 * 32, nU = 16 * 176, nD = 44 * 32;
;     const int I0 = part <= 1 ? 0 : (part == 2 ? n1 : n1 + n2 + nU), NIT = part == 0 ? n1 + n2 + nU + nD : (part == 1 ? n1 : (part == 2 ? n1 + n2 + nU : n1 + n2 + nU + nD));
;     for (int it = I0 + wr; it < NIT; it += 2 * nw) {
;         const bool two = it + nw < NIT;
;         const TrDesc d0 = tr_decode(a, l, it), d1 = tr_decode(a, l, two ? it + nw : it);
;         f32x4 v0[8], v1[8];
;         tr_load(d0.src, d0.ldn, lane, v0); tr_load(d1.src, d1.ldn, lane, v1);
;         tr_finish(v0, d0.dst, d0.dst2, d0.ldk, scr, lane, d0.scale);
;         if (two) tr_finish(v1, d1.dst, d1.dst2, d1.ldk, scr, lane, d1.scale);
;     }
.LBB0_605:
	v_mov_b32_e32 v51, v81
	v_mul_u32_u24_e32 v2, s39, v49
	s_lshl_b32 s12, s39, 3
	v_lshl_add_u64 v[0:1], s[22:23], 0, v[50:51]
	v_lshlrev_b32_e32 v80, 2, v2
	s_ashr_i32 s13, s12, 31
	v_lshl_add_u64 v[2:3], v[0:1], 0, v[80:81]
	s_lshl_b64 s[22:23], s[12:13], 2
	global_load_dwordx4 v[62:65], v[2:3], off nt
	v_lshl_add_u64 v[2:3], v[2:3], 0, s[22:23]
	global_load_dwordx4 v[66:69], v[2:3], off nt
	v_lshl_add_u64 v[2:3], v[2:3], 0, s[22:23]
	s_add_i32 s13, s12, s12
	global_load_dwordx4 v[70:73], v[2:3], off nt
	v_lshl_add_u64 v[2:3], v[2:3], 0, s[22:23]
	s_add_i32 s13, s13, s13
	global_load_dwordx4 v[74:77], v[2:3], off nt
	v_mov_b32_e32 v2, s13
	v_mad_u32_u24 v80, s39, v49, v2
	v_lshl_add_u64 v[2:3], v[80:81], 2, v[0:1]
	v_add_u32_e32 v80, s12, v80
	global_load_dwordx4 v[44:47], v[2:3], off nt
	v_lshl_add_u64 v[2:3], v[80:81], 2, v[0:1]
	v_add_u32_e32 v80, s12, v80
	global_load_dwordx4 v[40:43], v[2:3], off nt
	v_lshl_add_u64 v[2:3], v[80:81], 2, v[0:1]
	v_add_u32_e32 v80, s12, v80
	global_load_dwordx4 v[36:39], v[2:3], off nt
	v_lshl_add_u64 v[0:1], v[80:81], 2, v[0:1]
	global_load_dwordx4 v[32:35], v[0:1], off nt
	s_lshl_b32 s12, s28, 3
	s_ashr_i32 s13, s12, 31
	s_lshl_b64 s[22:23], s[12:13], 2
	s_add_i32 s13, s12, s12
	v_mul_u32_u24_e32 v0, s28, v49
	s_add_i32 s13, s13, s13
	v_lshl_add_u64 v[28:29], s[26:27], 0, v[50:51]
	v_lshlrev_b32_e32 v80, 2, v0
	v_mov_b32_e32 v16, s13
	v_lshl_add_u64 v[4:5], v[28:29], 0, v[80:81]
	v_mad_u32_u24 v80, s28, v49, v16
	v_lshl_add_u64 v[16:17], v[80:81], 2, v[28:29]
	v_add_u32_e32 v80, s12, v80
	s_waitcnt lgkmcnt(0)
	v_lshl_add_u64 v[8:9], v[4:5], 0, s[22:23]
	v_lshl_add_u64 v[20:21], v[80:81], 2, v[28:29]
	v_add_u32_e32 v80, s12, v80
	v_lshl_add_u64 v[12:13], v[8:9], 0, s[22:23]
	v_lshl_add_u64 v[24:25], v[80:81], 2, v[28:29]
	v_add_u32_e32 v80, s12, v80
	global_load_dwordx4 v[0:3], v[4:5], off nt
	v_lshl_add_u64 v[28:29], v[80:81], 2, v[28:29]
	global_load_dwordx4 v[16:19], v[16:17], off nt
	v_add_u32_e32 v51, 0x420, v61
	global_load_dwordx4 v[4:7], v[8:9], off nt
	v_lshlrev_b32_e32 v80, 1, v48
	global_load_dwordx4 v[20:23], v[20:21], off nt
	v_mov_b32_e32 v53, v81
	global_load_dwordx4 v[8:11], v[12:13], off nt
	v_mov_b32_e32 v55, v81
	global_load_dwordx4 v[24:27], v[24:25], off nt
	v_lshl_add_u64 v[12:13], v[12:13], 0, s[22:23]
	global_load_dwordx4 v[12:15], v[12:13], off nt
	v_mov_b32_e32 v57, v81
	global_load_dwordx4 v[28:31], v[28:29], off nt
	v_mov_b32_e32 v59, v81
	s_andn2_b64 vcc, exec, s[8:9]
	s_waitcnt vmcnt(0)
	ds_write2_b32 v61, v62, v63 offset1:1
	ds_write2_b32 v61, v64, v65 offset0:2 offset1:3
	v_add_u32_e32 v62, 0x428, v61
	ds_write2_b32 v51, v66, v67 offset1:1
	v_add_u32_e32 v67, 0x1080, v61
	v_add_u32_e32 v63, 0x840, v61
	v_add_u32_e32 v64, 0x848, v61
	v_add_u32_e32 v65, 0xc60, v61
	v_add_u32_e32 v66, 0xc68, v61
	ds_write2_b32 v62, v68, v69 offset1:1
	ds_write2_b32 v63, v70, v71 offset1:1
	ds_write2_b32 v64, v72, v73 offset1:1
	ds_write2_b32 v65, v74, v75 offset1:1
	ds_write2_b32 v66, v76, v77 offset1:1
	ds_write2_b32 v67, v44, v45 offset1:1
	v_add_u32_e32 v45, 0x14a0, v61
	v_add_u32_e32 v44, 0x1088, v61
	ds_write2_b32 v45, v40, v41 offset1:1
	v_add_u32_e32 v41, 0x18c0, v61
	v_add_u32_e32 v40, 0x14a8, v61
	ds_write2_b32 v41, v36, v37 offset1:1
	v_add_u32_e32 v37, 0x1ce0, v61
	v_add_u32_e32 v36, 0x18c8, v61
	ds_write2_b32 v37, v32, v33 offset1:1
	v_add_u32_e32 v32, 0x1ce8, v61
	ds_write2_b32 v44, v46, v47 offset1:1
	ds_write2_b32 v40, v42, v43 offset1:1
	ds_write2_b32 v36, v38, v39 offset1:1
	ds_write2_b32 v32, v34, v35 offset1:1
	s_waitcnt lgkmcnt(0)
	ds_read2_b32 v[38:39], v60 offset0:33 offset1:41
	ds_read2_b32 v[42:43], v60 offset1:8
	ds_read2_b32 v[46:47], v60 offset0:66 offset1:74
	ds_read2_b32 v[72:73], v60 offset0:99 offset1:107
	ds_read2_b32 v[74:75], v60 offset0:132 offset1:140
	ds_read2_b32 v[76:77], v60 offset0:165 offset1:173
	ds_read2_b32 v[78:79], v60 offset0:198 offset1:206
	ds_read2_b32 v[82:83], v60 offset0:231 offset1:239
	v_lshl_add_u64 v[34:35], s[20:21], 0, v[80:81]
	s_waitcnt lgkmcnt(6)
	v_cvt_pk_bf16_f32 v68, v42, v38
	s_waitcnt lgkmcnt(4)
	v_cvt_pk_bf16_f32 v69, v46, v72
	s_waitcnt lgkmcnt(2)
	v_cvt_pk_bf16_f32 v70, v74, v76
	s_waitcnt lgkmcnt(0)
	v_cvt_pk_bf16_f32 v71, v78, v82
	v_lshl_add_u64 v[86:87], v[34:35], 0, v[52:53]
	global_store_dwordx4 v[86:87], v[68:71], off sc1
	v_lshl_add_u64 v[86:87], v[34:35], 0, v[56:57]
	s_nop 0
	v_cvt_pk_bf16_f32 v68, v43, v39
	v_cvt_pk_bf16_f32 v69, v47, v73
	v_cvt_pk_bf16_f32 v70, v75, v77
	v_cvt_pk_bf16_f32 v71, v79, v83
	v_lshl_add_u64 v[38:39], v[34:35], 0, v[54:55]
	global_store_dwordx4 v[38:39], v[68:71], off sc1
	ds_read2_b32 v[38:39], v60 offset0:49 offset1:57
	ds_read2_b32 v[42:43], v60 offset0:16 offset1:24
	ds_read2_b32 v[46:47], v60 offset0:82 offset1:90
	ds_read2_b32 v[72:73], v60 offset0:115 offset1:123
	ds_read2_b32 v[74:75], v60 offset0:148 offset1:156
	ds_read2_b32 v[76:77], v60 offset0:181 offset1:189
	ds_read2_b32 v[78:79], v60 offset0:214 offset1:222
	ds_read2_b32 v[82:83], v60 offset0:247 offset1:255
	v_lshl_add_u64 v[34:35], v[34:35], 0, v[58:59]
	s_waitcnt lgkmcnt(6)
	v_cvt_pk_bf16_f32 v68, v42, v38
	s_waitcnt lgkmcnt(4)
	v_cvt_pk_bf16_f32 v69, v46, v72
	s_waitcnt lgkmcnt(2)
	v_cvt_pk_bf16_f32 v70, v74, v76
	s_waitcnt lgkmcnt(0)
	v_cvt_pk_bf16_f32 v71, v78, v82
	global_store_dwordx4 v[86:87], v[68:71], off sc1
	s_nop 1
	v_cvt_pk_bf16_f32 v68, v43, v39
	v_cvt_pk_bf16_f32 v69, v47, v73
	v_cvt_pk_bf16_f32 v70, v75, v77
	v_cvt_pk_bf16_f32 v71, v79, v83
	global_store_dwordx4 v[34:35], v[68:71], off sc1
	s_waitcnt lgkmcnt(0)
	s_cbranch_vccnz .LBB0_585
; #define LAS __attribute__((address_space(3)))
; #define LDS_WAIT() asm volatile("s_waitcnt lgkmcnt(0)" ::: "memory")
; __device__ __forceinline__ unsigned cvt_pk_bf16(float lo, float hi) { f32x2_t v = {lo, hi}; bf16x2_t b = __builtin_convertvector(v, bf16x2_t); return __builtin_bit_cast(unsigned, b); }
; __device__ __forceinline__ void tr_load(const float* src, int ldn, int lane, f32x4 (&v)[8]) {
;     const int r8 = lane >> 3, c4 = lane & 7;
; #pragma unroll
;     for (int i = 0; i < 8; ++i) v[i] = __builtin_nontemporal_load((const f32x4*)(src + (size_t)(8 * i + r8) * ldn + 4 * c4));
; }
;     const int r8 = lane >> 3, c4 = lane & 7;
; #pragma unroll
;     for (int i = 0; i < 8; ++i) { LAS float* w = scr + (8 * i + r8) * 33 + 4 * c4; w[0] = v[i][0]; w[1] = v[i][1]; w[2] = v[i][2]; w[3] = v[i][3]; }
;     LDS_WAIT(); asm volatile("" ::: "memory");
;     const int c = lane & 7;
; #pragma unroll
;     for (int j = 0; j < 4; ++j) { const int n = (lane >> 3) + 8 * j; const LAS float* sp = scr + (8 * c) * 33 + n;
;         u32x4 o; o.x = cvt_pk_bf16(sp[0 * 33] * s, sp[1 * 33] * s); o.y = cvt_pk_bf16(sp[2 * 33] * s, sp[3 * 33] * s); o.z = cvt_pk_bf16(sp[4 * 33] * s, sp[5 * 33] * s); o.w = cvt_pk_bf16(sp[6 * 33] * s, sp[7 * 33] * s);
;         *(u32x4*)(dst + (size_t)n * ldk + 8 * c) = o; if (dst2) *(u32x4*)(dst2 + (size_t)n * ldk + 8 * c) = o; }
;     LDS_WAIT(); asm volatile("" ::: "memory");
; }
;     LAS float* scr = (LAS float*)(lds + wave * 8448);
;     const int n1 = (l & 1) == 0 ? 16 * 72 : 16 * 16, n2 = (l & 1) == 0 ? 16 * 32 : 8 * 32, nU = 16 * 176, nD = 44 * 32;
;     const int I0 = part <= 1 ? 0 : (part == 2 ? n1 : n1 + n2 + nU), NIT = part == 0 ? n1 + n2 + nU + nD : (part == 1 ? n1 : (part == 2 ? n1 + n2 + nU : n1 + n2 + nU + nD));
;     for (int it = I0 + wr; it < NIT; it += 2 * nw) {
;         const bool two = it + nw < NIT;
;         const TrDesc d0 = tr_decode(a, l, it), d1 = tr_decode(a, l, two ? it + nw : it);
;         f32x4 v0[8], v1[8];
;         tr_load(d0.src, d0.ldn, lane, v0); tr_load(d1.src, d1.ldn, lane, v1);
;         tr_finish(v0, d0.dst, d0.dst2, d0.ldk, scr, lane, d0.scale);
;         if (two) tr_finish(v1, d1.dst, d1.dst2, d1.ldk, scr, lane, d1.scale);
;     }
	ds_write2_b32 v61, v0, v1 offset1:1
	ds_write2_b32 v61, v2, v3 offset0:2 offset1:3
	ds_write2_b32 v51, v4, v5 offset1:1
	ds_write2_b32 v62, v6, v7 offset1:1
	ds_write2_b32 v63, v8, v9 offset1:1
	ds_write2_b32 v64, v10, v11 offset1:1
	ds_write2_b32 v65, v12, v13 offset1:1
	ds_write2_b32 v66, v14, v15 offset1:1
	ds_write2_b32 v67, v16, v17 offset1:1
	ds_write2_b32 v44, v18, v19 offset1:1
	ds_write2_b32 v45, v20, v21 offset1:1
	ds_write2_b32 v40, v22, v23 offset1:1
	ds_write2_b32 v41, v24, v25 offset1:1
	ds_write2_b32 v36, v26, v27 offset1:1
	ds_write2_b32 v37, v28, v29 offset1:1
	ds_write2_b32 v32, v30, v31 offset1:1
	s_waitcnt lgkmcnt(0)
	ds_read2_b32 v[4:5], v60 offset1:8
	ds_read2_b32 v[6:7], v60 offset0:33 offset1:41
	ds_read2_b32 v[10:11], v60 offset0:66 offset1:74
	ds_read2_b32 v[12:13], v60 offset0:99 offset1:107
	ds_read2_b32 v[14:15], v60 offset0:132 offset1:140
	ds_read2_b32 v[16:17], v60 offset0:165 offset1:173
	ds_read2_b32 v[18:19], v60 offset0:198 offset1:206
	ds_read2_b32 v[20:21], v60 offset0:231 offset1:239
	s_waitcnt lgkmcnt(7)
	v_mov_b32_e32 v0, v4
	s_waitcnt lgkmcnt(6)
	v_mov_b32_e32 v1, v6
	s_waitcnt lgkmcnt(5)
	v_mov_b32_e32 v2, v10
	s_waitcnt lgkmcnt(4)
	v_mov_b32_e32 v3, v12
	v_pk_mul_f32 v[0:1], s[0:1], v[0:1] op_sel_hi:[0,1]
	v_pk_mul_f32 v[2:3], s[0:1], v[2:3] op_sel_hi:[0,1]
	v_cvt_pk_bf16_f32 v0, v0, v1
	v_cvt_pk_bf16_f32 v1, v2, v3
	s_waitcnt lgkmcnt(3)
	v_mov_b32_e32 v2, v14
	s_waitcnt lgkmcnt(2)
	v_mov_b32_e32 v3, v16
	s_waitcnt lgkmcnt(1)
	v_mov_b32_e32 v22, v18
	s_waitcnt lgkmcnt(0)
	v_mov_b32_e32 v23, v20
	v_mul_u32_u24_e32 v4, s1, v49
	v_lshl_add_u64 v[8:9], s[16:17], 0, v[80:81]
	v_pk_mul_f32 v[2:3], s[0:1], v[2:3] op_sel_hi:[0,1]
	v_pk_mul_f32 v[22:23], s[0:1], v[22:23] op_sel_hi:[0,1]
	v_lshlrev_b32_e32 v80, 1, v4
	v_cvt_pk_bf16_f32 v2, v2, v3
	v_cvt_pk_bf16_f32 v3, v22, v23
	v_lshl_add_u64 v[8:9], v[8:9], 0, v[80:81]
	v_mov_b32_e32 v6, v5
	v_mov_b32_e32 v12, v11
	s_lshl_b32 s8, s1, 3
	global_store_dwordx4 v[8:9], v[0:3], off sc1
	v_mov_b32_e32 v16, v15
	v_mov_b32_e32 v20, v19
	v_pk_mul_f32 v[0:1], s[0:1], v[6:7] op_sel_hi:[0,1]
	v_pk_mul_f32 v[2:3], s[0:1], v[12:13] op_sel_hi:[0,1]
	s_ashr_i32 s9, s8, 31
	v_cvt_pk_bf16_f32 v0, v0, v1
	v_cvt_pk_bf16_f32 v1, v2, v3
	v_pk_mul_f32 v[2:3], s[0:1], v[16:17] op_sel_hi:[0,1]
	v_pk_mul_f32 v[4:5], s[0:1], v[20:21] op_sel_hi:[0,1]
	s_lshl_b64 s[8:9], s[8:9], 1
	v_cvt_pk_bf16_f32 v2, v2, v3
	v_cvt_pk_bf16_f32 v3, v4, v5
	ds_read2_b32 v[4:5], v60 offset0:16 offset1:24
	ds_read2_b32 v[6:7], v60 offset0:49 offset1:57
	v_lshl_add_u64 v[8:9], v[8:9], 0, s[8:9]
	ds_read2_b32 v[10:11], v60 offset0:82 offset1:90
	ds_read2_b32 v[12:13], v60 offset0:115 offset1:123
	global_store_dwordx4 v[8:9], v[0:3], off sc1
	ds_read2_b32 v[14:15], v60 offset0:148 offset1:156
	ds_read2_b32 v[16:17], v60 offset0:181 offset1:189
	ds_read2_b32 v[18:19], v60 offset0:214 offset1:222
	ds_read2_b32 v[20:21], v60 offset0:247 offset1:255
	s_waitcnt lgkmcnt(7)
	v_mov_b32_e32 v0, v4
	s_waitcnt lgkmcnt(6)
	v_mov_b32_e32 v1, v6
	s_waitcnt lgkmcnt(5)
	v_mov_b32_e32 v2, v10
	s_waitcnt lgkmcnt(4)
	v_mov_b32_e32 v3, v12
	v_pk_mul_f32 v[0:1], s[0:1], v[0:1] op_sel_hi:[0,1]
	v_pk_mul_f32 v[2:3], s[0:1], v[2:3] op_sel_hi:[0,1]
	v_cvt_pk_bf16_f32 v0, v0, v1
	v_cvt_pk_bf16_f32 v1, v2, v3
	s_waitcnt lgkmcnt(3)
	v_mov_b32_e32 v2, v14
	s_waitcnt lgkmcnt(2)
	v_mov_b32_e32 v3, v16
	s_waitcnt lgkmcnt(1)
	v_mov_b32_e32 v22, v18
	s_waitcnt lgkmcnt(0)
	v_mov_b32_e32 v23, v20
	v_pk_mul_f32 v[2:3], s[0:1], v[2:3] op_sel_hi:[0,1]
	v_pk_mul_f32 v[22:23], s[0:1], v[22:23] op_sel_hi:[0,1]
	v_cvt_pk_bf16_f32 v2, v2, v3
	v_cvt_pk_bf16_f32 v3, v22, v23
	v_lshl_add_u64 v[8:9], v[8:9], 0, s[8:9]
	v_mov_b32_e32 v6, v5
	v_mov_b32_e32 v12, v11
	global_store_dwordx4 v[8:9], v[0:3], off sc1
	v_mov_b32_e32 v16, v15
	v_mov_b32_e32 v20, v19
	v_pk_mul_f32 v[0:1], s[0:1], v[6:7] op_sel_hi:[0,1]
	v_pk_mul_f32 v[2:3], s[0:1], v[12:13] op_sel_hi:[0,1]
	v_cvt_pk_bf16_f32 v0, v0, v1
	v_cvt_pk_bf16_f32 v1, v2, v3
	v_pk_mul_f32 v[2:3], s[0:1], v[16:17] op_sel_hi:[0,1]
	v_pk_mul_f32 v[4:5], s[0:1], v[20:21] op_sel_hi:[0,1]
	v_cvt_pk_bf16_f32 v2, v2, v3
	v_cvt_pk_bf16_f32 v3, v4, v5
	v_lshl_add_u64 v[4:5], v[8:9], 0, s[8:9]
	global_store_dwordx4 v[4:5], v[0:3], off sc1
	s_waitcnt lgkmcnt(0)
	s_branch .LBB0_585

; #define LAS __attribute__((address_space(3)))
; __device__ __forceinline__ unsigned cvt_pk_bf16(float lo, float hi) { f32x2_t v = {lo, hi}; bf16x2_t b = __builtin_convertvector(v, bf16x2_t); return __builtin_bit_cast(unsigned, b); }
; __device__ __forceinline__ void fold_out_item(LAS unsigned char* lds, const Args& a, int item, int tid) {
;     ...
;     const int lane = tid & 63, wv = tid >> 6, i32 = lane & 31, hi = lane >> 5, cb = wv & 3, nb = wv >> 2;
;     f32x16 dd;
; #pragma unroll
;     for (int r = 0; r < 16; ++r) dd[r] = 0.f;
;     const LAS float* arow = Wg + (32 * cb + i32) * 129 + hi; const LAS float* bcol = Wo + hi * 65 + 32 * nb + i32;
; #pragma unroll 8
;     for (int st = 0; st < 64; ++st) dd = __builtin_amdgcn_mfma_f32_32x32x2f32(arow[2 * st], bcol[2 * st * 65], dd, 0, 0, 0);
;     bf16_t* op = WMO + (size_t)(64 * nc + 32 * nb + i32) * WMOLD + 128 * g + 32 * cb + 4 * hi;
; #pragma unroll
;     for (int q = 0; q < 4; ++q) { u32x2 w; w.x = cvt_pk_bf16(dd[4 * q], dd[4 * q + 1]); w.y = cvt_pk_bf16(dd[4 * q + 2], dd[4 * q + 3]); *(u32x2*)(op + 8 * q) = w; }
;     __syncthreads();
.LBB0_625:
	v_add_u32_e32 v20, 0, v17
	ds_read2_b32 v[18:19], v20 offset1:2
	v_add_u32_e32 v21, 0, v16
	v_add_u32_e32 v22, 0x10400, v21
	ds_read_b32 v22, v22
	s_add_i32 s20, s20, -8
	v_add_u32_e32 v17, 64, v17
	s_cmp_lg_u32 s20, 0
	v_add_u32_e32 v16, 0x1040, v16
	s_waitcnt lgkmcnt(0)
	v_mfma_f32_32x32x2_f32 v[0:15], v18, v22, v[0:15]
	v_add_u32_e32 v18, 0x10608, v21
	ds_read_b32 v18, v18
	v_add_u32_e32 v22, 0x10810, v21
	ds_read_b32 v22, v22
	s_waitcnt lgkmcnt(1)
	v_mfma_f32_32x32x2_f32 v[0:15], v19, v18, v[0:15]
	ds_read2_b32 v[18:19], v20 offset0:4 offset1:6
	s_waitcnt lgkmcnt(0)
	v_mfma_f32_32x32x2_f32 v[0:15], v18, v22, v[0:15]
	v_add_u32_e32 v18, 0x10a18, v21
	ds_read_b32 v18, v18
	v_add_u32_e32 v22, 0x10c20, v21
	ds_read_b32 v22, v22
	s_waitcnt lgkmcnt(1)
	v_mfma_f32_32x32x2_f32 v[0:15], v19, v18, v[0:15]
	ds_read2_b32 v[18:19], v20 offset0:8 offset1:10
	s_waitcnt lgkmcnt(0)
	v_mfma_f32_32x32x2_f32 v[0:15], v18, v22, v[0:15]
	v_add_u32_e32 v18, 0x10e28, v21
	ds_read_b32 v18, v18
	s_waitcnt lgkmcnt(0)
	v_mfma_f32_32x32x2_f32 v[0:15], v19, v18, v[0:15]
	ds_read2_b32 v[18:19], v20 offset0:12 offset1:14
	v_add_u32_e32 v20, 0x11030, v21
	ds_read_b32 v20, v20
	s_waitcnt lgkmcnt(0)
	v_mfma_f32_32x32x2_f32 v[0:15], v18, v20, v[0:15]
	v_add_u32_e32 v18, 0x11238, v21
	ds_read_b32 v18, v18
	s_waitcnt lgkmcnt(0)
	v_mfma_f32_32x32x2_f32 v[0:15], v19, v18, v[0:15]
	s_cbranch_scc1 .LBB0_625
	s_lshl_b64 s[0:1], s[0:1], 21
	v_readlane_b32 s4, v252, 42
	v_add_u32_e32 v16, s17, v72
	s_add_u32 s0, s4, s0
	v_readlane_b32 s4, v252, 43
	v_ashrrev_i32_e32 v17, 31, v16
	s_addc_u32 s1, s4, s1
	v_lshlrev_b64 v[16:17], 11, v[16:17]
	v_lshl_add_u64 v[16:17], s[0:1], 0, v[16:17]
	s_lshl_b32 s28, s16, 1
	v_lshl_add_u64 v[16:17], v[16:17], 0, s[28:29]
	v_mov_b32_e32 v71, v81
	v_lshl_add_u64 v[16:17], v[16:17], 0, v[70:71]
	v_lshlrev_b32_e32 v18, 1, v66
	v_mov_b32_e32 v19, v81
	v_lshl_add_u64 v[16:17], v[16:17], 0, v[18:19]
	s_nop 0
	v_cvt_pk_bf16_f32 v0, v0, v1
	v_cvt_pk_bf16_f32 v1, v2, v3
	global_store_dwordx2 v[16:17], v[0:1], off sc1
	v_cvt_pk_bf16_f32 v0, v4, v5
	v_cvt_pk_bf16_f32 v1, v6, v7
	global_store_dwordx2 v[16:17], v[0:1], off offset:16 sc1
	v_cvt_pk_bf16_f32 v0, v8, v9
	v_cvt_pk_bf16_f32 v1, v10, v11
	global_store_dwordx2 v[16:17], v[0:1], off offset:32 sc1
	v_cvt_pk_bf16_f32 v0, v12, v13
	v_cvt_pk_bf16_f32 v1, v14, v15
	v_readlane_b32 s21, v254, 50
	global_store_dwordx2 v[16:17], v[0:1], off offset:48 sc1
	s_barrier
	s_branch .LBB0_622

; #define LAS __attribute__((address_space(3)))
; __device__ __forceinline__ unsigned cvt_pk_bf16(float lo, float hi) { f32x2_t v = {lo, hi}; bf16x2_t b = __builtin_convertvector(v, bf16x2_t); return __builtin_bit_cast(unsigned, b); }
; __device__ __forceinline__ void fold_in_item(LAS unsigned char* lds, const Args& a, int item, int tid) {
;     ...
;     const int lane = tid & 63, wv = tid >> 6, i32 = lane & 31, hi = lane >> 5, kh = wv >> 2, jb = wv & 3, jp = 32 * jb + i32;
;     f32x16 dc, ds;
; #pragma unroll
;     for (int r = 0; r < 16; ++r) { dc[r] = 0.f; ds[r] = 0.f; }
;     const LAS float* arow = Wl + (32 * kh + i32) * 129 + hi;
; #pragma unroll 8
;     for (int st = 0; st < 64; ++st) {
;         const float av = arow[2 * st]; const int ph = ((2 * st + hi) * jp) & 127;
;         dc = __builtin_amdgcn_mfma_f32_32x32x2f32(av, tc[ph], dc, 0, 0, 0);
;         ds = __builtin_amdgcn_mfma_f32_32x32x2f32(av, ts[ph], ds, 0, 0, 0);
;     }
;     bf16_t* oc = WMI + (size_t)(512 + 128 * g + jp) * DM + 64 * kc + 32 * kh + 4 * hi; bf16_t* os = oc + (size_t)512 * DM;
; #pragma unroll
;     for (int q = 0; q < 4; ++q) {
;         u32x2 wc, ws_; wc.x = cvt_pk_bf16(dc[4 * q], dc[4 * q + 1]); wc.y = cvt_pk_bf16(dc[4 * q + 2], dc[4 * q + 3]); ws_.x = cvt_pk_bf16(ds[4 * q], ds[4 * q + 1]); ws_.y = cvt_pk_bf16(ds[4 * q + 2], ds[4 * q + 3]);
;         *(u32x2*)(oc + 8 * q) = wc; *(u32x2*)(os + 8 * q) = ws_;
;     }
.LBB0_631:
	v_add_u32_e32 v71, s16, v94
	ds_read2_b32 v[112:113], v71 offset1:2
	v_add_u32_e32 v114, v93, v69
	v_and_b32_e32 v114, 0x7f, v114
	v_lshl_add_u32 v114, v114, 2, 0
	ds_read2st64_b32 v[114:115], v114 offset0:129 offset1:131
	s_add_i32 s16, s16, 64
	s_cmpk_lg_i32 s16, 0x200
	s_waitcnt lgkmcnt(0)
	v_mfma_f32_32x32x2_f32 v[0:15], v112, v114, v[0:15]
	v_mfma_f32_32x32x2_f32 v[16:31], v112, v115, v[16:31]
	v_add_u32_e32 v112, v92, v69
	v_and_b32_e32 v112, 0x7f, v112
	v_lshl_add_u32 v112, v112, 2, 0
	ds_read2st64_b32 v[114:115], v112 offset0:129 offset1:131
	s_waitcnt lgkmcnt(0)
	v_mfma_f32_32x32x2_f32 v[0:15], v113, v114, v[0:15]
	v_add_u32_e32 v114, v91, v69
	v_and_b32_e32 v114, 0x7f, v114
	v_lshl_add_u32 v114, v114, 2, 0
	v_mfma_f32_32x32x2_f32 v[16:31], v113, v115, v[16:31]
	ds_read2_b32 v[112:113], v71 offset0:4 offset1:6
	ds_read2st64_b32 v[114:115], v114 offset0:129 offset1:131
	s_waitcnt lgkmcnt(0)
	v_mfma_f32_32x32x2_f32 v[0:15], v112, v114, v[0:15]
	v_mfma_f32_32x32x2_f32 v[16:31], v112, v115, v[16:31]
	v_add_u32_e32 v112, v90, v69
	v_and_b32_e32 v112, 0x7f, v112
	v_lshl_add_u32 v112, v112, 2, 0
	ds_read2st64_b32 v[114:115], v112 offset0:129 offset1:131
	s_waitcnt lgkmcnt(0)
	v_mfma_f32_32x32x2_f32 v[0:15], v113, v114, v[0:15]
	v_add_u32_e32 v114, v89, v69
	v_and_b32_e32 v114, 0x7f, v114
	v_lshl_add_u32 v114, v114, 2, 0
	v_mfma_f32_32x32x2_f32 v[16:31], v113, v115, v[16:31]
	ds_read2_b32 v[112:113], v71 offset0:8 offset1:10
	ds_read2st64_b32 v[114:115], v114 offset0:129 offset1:131
	s_waitcnt lgkmcnt(0)
	v_mfma_f32_32x32x2_f32 v[0:15], v112, v114, v[0:15]
	v_mfma_f32_32x32x2_f32 v[16:31], v112, v115, v[16:31]
	v_add_u32_e32 v112, v88, v69
	v_and_b32_e32 v112, 0x7f, v112
	v_lshl_add_u32 v112, v112, 2, 0
	ds_read2st64_b32 v[114:115], v112 offset0:129 offset1:131
	s_waitcnt lgkmcnt(0)
	v_mfma_f32_32x32x2_f32 v[0:15], v113, v114, v[0:15]
	v_add_u32_e32 v114, v87, v69
	v_mfma_f32_32x32x2_f32 v[16:31], v113, v115, v[16:31]
	ds_read2_b32 v[112:113], v71 offset0:12 offset1:14
	v_and_b32_e32 v71, 0x7f, v114
	v_lshl_add_u32 v71, v71, 2, 0
	ds_read2st64_b32 v[114:115], v71 offset0:129 offset1:131
	v_add_u32_e32 v71, v85, v69
	v_and_b32_e32 v71, 0x7f, v71
	v_lshl_add_u32 v71, v71, 2, 0
	v_add_u32_e32 v69, v69, v86
	s_waitcnt lgkmcnt(0)
	v_mfma_f32_32x32x2_f32 v[0:15], v112, v114, v[0:15]
	v_mfma_f32_32x32x2_f32 v[16:31], v112, v115, v[16:31]
	ds_read2st64_b32 v[114:115], v71 offset0:129 offset1:131
	s_waitcnt lgkmcnt(0)
	v_mfma_f32_32x32x2_f32 v[0:15], v113, v114, v[0:15]
	v_mfma_f32_32x32x2_f32 v[16:31], v113, v115, v[16:31]
	s_cbranch_scc1 .LBB0_631
	s_mul_hi_i32 s17, s0, 0x300000
	s_mul_i32 s0, s0, 0x300000
	s_add_u32 s16, s86, s0
	s_addc_u32 s17, s87, s17
	v_lshl_or_b32 v112, s13, 18, v111
	v_mov_b32_e32 v113, v81
	v_lshl_add_u64 v[112:113], s[16:17], 0, v[112:113]
	s_lshl_b32 s28, s1, 1
	v_lshl_add_u64 v[112:113], v[112:113], 0, s[28:29]
	v_lshl_add_u64 v[112:113], v[64:65], 1, v[112:113]
	v_lshlrev_b32_e32 v114, 1, v66
	v_mov_b32_e32 v115, v81
	v_lshl_add_u64 v[112:113], v[112:113], 0, v[114:115]
	s_mov_b64 s[0:1], 0x1200000
	v_lshl_add_u64 v[114:115], v[112:113], 0, s[0:1]
	s_mov_b32 s0, 0x1200000
	v_cvt_pk_bf16_f32 v0, v0, v1
	v_cvt_pk_bf16_f32 v1, v2, v3
	v_cvt_pk_bf16_f32 v2, v16, v17
	v_add_co_u32_e32 v16, vcc, s0, v112
	s_mov_b32 s0, 0x1300000
	s_nop 0
	v_addc_co_u32_e32 v17, vcc, 0, v113, vcc
	global_store_dwordx2 v[16:17], v[0:1], off sc1
	v_add_co_u32_e32 v0, vcc, s0, v112
	v_cvt_pk_bf16_f32 v3, v18, v19
	s_nop 0
	v_addc_co_u32_e32 v1, vcc, 0, v113, vcc
	global_store_dwordx2 v[0:1], v[2:3], off sc1
	v_cvt_pk_bf16_f32 v2, v4, v5
	v_cvt_pk_bf16_f32 v3, v6, v7
	v_cvt_pk_bf16_f32 v4, v20, v21
	v_cvt_pk_bf16_f32 v5, v22, v23
	global_store_dwordx2 v[114:115], v[2:3], off offset:16 sc1
	global_store_dwordx2 v[0:1], v[4:5], off offset:16 sc1
	v_cvt_pk_bf16_f32 v2, v8, v9
	v_cvt_pk_bf16_f32 v3, v10, v11
	v_cvt_pk_bf16_f32 v4, v24, v25
	v_cvt_pk_bf16_f32 v5, v26, v27
	global_store_dwordx2 v[114:115], v[2:3], off offset:32 sc1
	global_store_dwordx2 v[0:1], v[4:5], off offset:32 sc1
	v_cvt_pk_bf16_f32 v2, v12, v13
	v_cvt_pk_bf16_f32 v3, v14, v15
	v_cvt_pk_bf16_f32 v4, v28, v29
	v_cvt_pk_bf16_f32 v5, v30, v31
	global_store_dwordx2 v[114:115], v[2:3], off offset:48 sc1
	global_store_dwordx2 v[0:1], v[4:5], off offset:48 sc1
	s_barrier
	s_branch .LBB0_622

; __device__ __forceinline__ unsigned cvt_pk_bf16(float lo, float hi) { f32x2_t v = {lo, hi}; bf16x2_t b = __builtin_convertvector(v, bf16x2_t); return __builtin_bit_cast(unsigned, b); }
; __device__ __forceinline__ void fold_layer(LAS unsigned char* lds, const Args& a, int o, int rk, int n, int tid) {
;     ...
;         for (int idx = gt; idx < 2048 * 256; idx += NT) {
;             const int k = idx >> 8, t0 = (idx & 255) * 8, ph0 = (k * t0) & 2047;
;             float c = tab[ph0], sn = tab[(ph0 - 512) & 2047]; const float dc = tab[k], dsn = tab[(k - 512) & 2047];
;             float vc[8], vs[8];
; #pragma unroll
;             for (int e = 0; e < 8; ++e) { vc[e] = c * (1.0f / 512.0f); vs[e] = sn * (-1.0f / 512.0f); const float c2 = c * dc - sn * dsn; sn = sn * dc + c * dsn; c = c2; }
;             u32x4 w; w.x = cvt_pk_bf16(vc[0], vc[1]); w.y = cvt_pk_bf16(vc[2], vc[3]); w.z = cvt_pk_bf16(vc[4], vc[5]); w.w = cvt_pk_bf16(vc[6], vc[7]);
;             *(u32x4*)(FM + (size_t)k * 4096 + t0) = w;
;             w.x = cvt_pk_bf16(vs[0], vs[1]); w.y = cvt_pk_bf16(vs[2], vs[3]); w.z = cvt_pk_bf16(vs[4], vs[5]); w.w = cvt_pk_bf16(vs[6], vs[7]);
;             *(u32x4*)(FM + (size_t)k * 4096 + 2048 + t0) = w;
;         }
.LBB0_636:
	v_add_u32_e32 v0, s13, v20
	v_ashrrev_i32_e32 v0, 8, v0
	v_mul_lo_u32 v1, v0, v21
	v_and_b32_e32 v2, 0x7f8, v1
	v_add_u32_e32 v1, 0x600, v1
	s_add_i32 s14, 0, 0x1e000
	v_and_b32_e32 v1, 0x7f8, v1
	v_lshl_add_u32 v2, v2, 2, s14
	v_lshl_add_u32 v1, v1, 2, s14
	ds_read_b32 v2, v2
	ds_read_b32 v3, v1
	v_lshl_add_u32 v1, v0, 2, s14
	ds_read_b32 v14, v1
	v_add_u32_e32 v1, 0x600, v0
	v_and_b32_e32 v1, 0x7ff, v1
	v_lshl_add_u32 v1, v1, 2, s14
	ds_read_b32 v15, v1
	v_ashrrev_i32_e32 v1, 31, v0
	v_lshlrev_b64 v[0:1], 13, v[0:1]
	v_lshl_add_u64 v[0:1], s[16:17], 0, v[0:1]
	s_add_i32 s13, s13, s12
	s_waitcnt lgkmcnt(0)
	v_mul_f32_e32 v4, v3, v15
	v_pk_fma_f32 v[6:7], v[2:3], v[14:15], v[4:5] op_sel_hi:[1,1,0] neg_lo:[0,0,1] neg_hi:[0,0,1]
	v_mov_b32_e32 v4, v3
	v_mov_b32_e32 v5, v2
	v_mul_f32_e32 v8, v2, v15
	v_pk_fma_f32 v[8:9], v[4:5], v[14:15], v[8:9] op_sel_hi:[1,1,0]
	v_mov_b32_e32 v16, v15
	v_mov_b32_e32 v7, v8
	v_mov_b32_e32 v5, v6
	v_mov_b32_e32 v9, v6
	v_pk_mul_f32 v[6:7], v[16:17], v[6:7] op_sel_hi:[0,1]
	v_pk_fma_f32 v[10:11], v[14:15], v[8:9], v[6:7] op_sel_hi:[0,1,1]
	v_pk_fma_f32 v[6:7], v[14:15], v[8:9], v[6:7] op_sel_hi:[0,1,1] neg_lo:[0,0,1] neg_hi:[0,0,1]
	v_pk_mov_b32 v[12:13], v[6:7], v[10:11] op_sel:[1,0]
	v_mov_b32_e32 v4, v2
	v_mov_b32_e32 v2, v3
	v_mov_b32_e32 v3, v8
	v_mov_b32_e32 v8, v10
	v_mov_b32_e32 v9, v7
	v_pk_mul_f32 v[12:13], v[16:17], v[12:13] op_sel_hi:[0,1]
	v_pk_fma_f32 v[22:23], v[14:15], v[8:9], v[12:13] op_sel_hi:[0,1,1]
	v_pk_fma_f32 v[12:13], v[14:15], v[8:9], v[12:13] op_sel_hi:[0,1,1] neg_lo:[0,0,1] neg_hi:[0,0,1]
	v_mov_b32_e32 v6, v7
	v_mov_b32_e32 v7, v13
	v_mov_b32_e32 v11, v22
	v_pk_mul_f32 v[8:9], v[6:7], s[20:21] op_sel_hi:[1,0]
	v_pk_mul_f32 v[6:7], v[10:11], s[22:23] op_sel_hi:[1,0]
	v_pk_mov_b32 v[10:11], v[12:13], v[22:23] op_sel:[1,0]
	v_mov_b32_e32 v24, v22
	v_mov_b32_e32 v25, v13
	v_pk_mul_f32 v[10:11], v[16:17], v[10:11] op_sel_hi:[0,1]
	v_pk_fma_f32 v[22:23], v[14:15], v[24:25], v[10:11] op_sel_hi:[0,1,1]
	v_pk_fma_f32 v[10:11], v[14:15], v[24:25], v[10:11] op_sel_hi:[0,1,1] neg_lo:[0,0,1] neg_hi:[0,0,1]
	v_pk_mov_b32 v[24:25], v[10:11], v[22:23] op_sel:[1,0]
	v_mov_b32_e32 v12, v22
	v_mov_b32_e32 v13, v11
	v_pk_mul_f32 v[24:25], v[16:17], v[24:25] op_sel_hi:[0,1]
	v_pk_fma_f32 v[26:27], v[14:15], v[12:13], v[24:25] op_sel_hi:[0,1,1]
	v_pk_fma_f32 v[24:25], v[14:15], v[12:13], v[24:25] op_sel_hi:[0,1,1] neg_lo:[0,0,1] neg_hi:[0,0,1]
	v_mov_b32_e32 v10, v11
	v_mov_b32_e32 v11, v25
	v_mov_b32_e32 v23, v26
	v_pk_mul_f32 v[12:13], v[10:11], s[20:21] op_sel_hi:[1,0]
	v_pk_mul_f32 v[10:11], v[22:23], s[22:23] op_sel_hi:[1,0]
	v_pk_mov_b32 v[22:23], v[24:25], v[26:27] op_sel:[1,0]
	v_mov_b32_e32 v28, v26
	v_mov_b32_e32 v29, v25
	v_pk_mul_f32 v[16:17], v[16:17], v[22:23] op_sel_hi:[0,1]
	v_pk_fma_f32 v[22:23], v[14:15], v[28:29], v[16:17] op_sel_hi:[0,1,1]
	v_pk_fma_f32 v[16:17], v[14:15], v[28:29], v[16:17] op_sel_hi:[0,1,1] neg_lo:[0,0,1] neg_hi:[0,0,1]
	v_mov_b32_e32 v23, v17
	v_mov_b32_e32 v24, v15
	v_mov_b32_e32 v25, v14
	v_mul_f32_e32 v16, v15, v22
	v_pk_fma_f32 v[24:25], v[24:25], v[22:23], v[16:17] op_sel_hi:[1,1,0] neg_lo:[0,0,1] neg_hi:[0,0,1]
	v_and_b32_e32 v26, 0x7f8, v21
	v_mov_b32_e32 v24, v17
	v_pk_mul_f32 v[16:17], v[24:25], s[20:21] op_sel_hi:[1,0]
	v_mul_f32_e32 v24, v14, v22
	v_pk_fma_f32 v[14:15], v[14:15], v[22:23], v[24:25] op_sel_hi:[1,1,0]
	v_pk_mul_f32 v[4:5], v[4:5], s[20:21] op_sel_hi:[1,0]
	v_mov_b32_e32 v23, v15
	v_lshlrev_b32_e32 v80, 1, v26
	v_pk_mul_f32 v[14:15], v[22:23], s[22:23] op_sel_hi:[1,0]
	v_cvt_pk_bf16_f32 v22, v4, v5
	v_cvt_pk_bf16_f32 v23, v8, v9
	v_cvt_pk_bf16_f32 v24, v12, v13
	v_cvt_pk_bf16_f32 v25, v16, v17
	v_lshl_add_u64 v[4:5], v[0:1], 0, v[80:81]
	v_pk_mul_f32 v[2:3], v[2:3], s[22:23] op_sel_hi:[1,0]
	global_store_dwordx4 v[4:5], v[22:25], off sc1
	v_add_co_u32_e32 v4, vcc, 0x1000, v4
	v_cvt_pk_bf16_f32 v0, v2, v3
	v_cvt_pk_bf16_f32 v1, v6, v7
	v_cvt_pk_bf16_f32 v2, v10, v11
	v_cvt_pk_bf16_f32 v3, v14, v15
	v_addc_co_u32_e32 v5, vcc, 0, v5, vcc
	global_store_dwordx4 v[4:5], v[0:3], off sc1
	v_add_u32_e32 v21, s5, v21
	s_nop 0
	v_add_u32_e32 v0, s13, v20
	v_cmp_lt_i32_e32 vcc, s4, v0
	s_or_b64 s[8:9], vcc, s[8:9]
	s_andn2_b64 exec, exec, s[8:9]
	s_cbranch_execnz .LBB0_636

; __device__ __forceinline__ unsigned cvt_pk_bf16(float lo, float hi) { f32x2_t v = {lo, hi}; bf16x2_t b = __builtin_convertvector(v, bf16x2_t); return __builtin_bit_cast(unsigned, b); }
; __device__ __forceinline__ void fold_layer(LAS unsigned char* lds, const Args& a, int o, int rk, int n, int tid) {
;     ...
;         for (int idx = gt; idx < 256 * 64; idx += NT) {
;             const int k = idx >> 6, ch = idx & 63, s = ch >> 5, t0 = (ch & 31) * 8; float v[8];
; #pragma unroll
;             for (int e = 0; e < 8; ++e) { const int ph = ((k * (t0 + e)) & 255) * 8; v[e] = s ? -tab[(ph - 512) & 2047] * nc : tab[ph] * nc; }
;             u32x4 w; w.x = cvt_pk_bf16(v[0], v[1]); w.y = cvt_pk_bf16(v[2], v[3]); w.z = cvt_pk_bf16(v[4], v[5]); w.w = cvt_pk_bf16(v[6], v[7]);
;             *(u32x4*)(FC + (size_t)k * 512 + ch * 8) = w;
;         }
.LBB0_639:
	v_add_u32_e32 v5, s5, v4
	v_ashrrev_i32_e32 v10, 6, v5
	v_lshlrev_b32_e32 v5, 3, v10
	v_mul_lo_u32 v7, v5, v18
	v_add_u32_e32 v6, 0x600, v7
	v_add_u32_e32 v8, v7, v5
	v_cndmask_b32_e32 v6, v6, v7, vcc
	v_add_u32_e32 v7, 0x600, v8
	v_add_u32_e32 v9, v8, v5
	v_cndmask_b32_e32 v7, v7, v8, vcc
	v_add_u32_e32 v8, 0x600, v9
	v_add_u32_e32 v11, v9, v5
	v_cndmask_b32_e32 v8, v8, v9, vcc
	v_add_u32_e32 v9, 0x600, v11
	v_cndmask_b32_e32 v9, v9, v11, vcc
	v_add_u32_e32 v11, v11, v5
	v_add_u32_e32 v12, 0x600, v11
	v_cndmask_b32_e32 v12, v12, v11, vcc
	v_add_u32_e32 v11, v11, v5
	v_add_u32_e32 v13, 0x600, v11
	v_cndmask_b32_e32 v13, v13, v11, vcc
	v_add_u32_e32 v11, v11, v5
	v_add_u32_e32 v14, 0x600, v11
	v_add_u32_e32 v5, v11, v5
	v_cndmask_b32_e32 v14, v14, v11, vcc
	v_add_u32_e32 v11, 0x600, v5
	v_cndmask_b32_e32 v5, v11, v5, vcc
	v_and_b32_e32 v6, 0x7c0, v6
	s_add_i32 s13, 0, 0x1e000
	v_and_b32_e32 v7, 0x7f8, v7
	v_and_b32_e32 v8, 0x7f0, v8
	v_and_b32_e32 v9, 0x7f8, v9
	v_and_b32_e32 v12, 0x7e0, v12
	v_and_b32_e32 v13, 0x7f8, v13
	v_and_b32_e32 v14, 0x7f0, v14
	v_and_b32_e32 v5, 0x7f8, v5
	v_lshl_add_u32 v6, v6, 2, s13
	v_lshl_add_u32 v7, v7, 2, s13
	v_lshl_add_u32 v8, v8, 2, s13
	v_lshl_add_u32 v9, v9, 2, s13
	v_lshl_add_u32 v12, v12, 2, s13
	v_lshl_add_u32 v13, v13, 2, s13
	v_lshl_add_u32 v14, v14, 2, s13
	v_lshl_add_u32 v5, v5, 2, s13
	ds_read_b32 v6, v6
	ds_read_b32 v7, v7
	ds_read_b32 v8, v8
	ds_read_b32 v9, v9
	ds_read_b32 v12, v12
	ds_read_b32 v13, v13
	ds_read_b32 v14, v14
	ds_read_b32 v15, v5
	s_add_i32 s5, s5, s12
	v_ashrrev_i32_e32 v11, 31, v10
	v_add_u32_e32 v5, s5, v4
	s_movk_i32 s13, 0x3fff
	s_waitcnt lgkmcnt(6)
	v_pk_mul_f32 v[6:7], v[2:3], v[6:7]
	s_waitcnt lgkmcnt(4)
	v_pk_mul_f32 v[8:9], v[2:3], v[8:9]
	s_waitcnt lgkmcnt(2)
	v_pk_mul_f32 v[12:13], v[2:3], v[12:13]
	s_waitcnt lgkmcnt(0)
	v_pk_mul_f32 v[14:15], v[2:3], v[14:15]
	v_lshlrev_b64 v[10:11], 10, v[10:11]
	v_cmp_lt_i32_e64 s[34:35], s13, v5
	v_cvt_pk_bf16_f32 v6, v6, v7
	v_cvt_pk_bf16_f32 v7, v8, v9
	v_cvt_pk_bf16_f32 v8, v12, v13
	v_cvt_pk_bf16_f32 v9, v14, v15
	v_lshl_add_u64 v[10:11], v[0:1], 0, v[10:11]
	v_add_u32_e32 v18, s4, v18
	s_or_b64 s[8:9], s[34:35], s[8:9]
	global_store_dwordx4 v[10:11], v[6:9], off sc1
	s_andn2_b64 exec, exec, s[8:9]
	s_cbranch_execnz .LBB0_639

; #define GAS __attribute__((address_space(1)))
; __device__ __forceinline__ void row_finish(RowRegs& R, const RowCtx& c, int row, const f32x4 (&gA)[4], const f32x4 (&gB)[4], GAS float* xo, GAS bf16_t* ho) {
;     const int lane = c.lane;
;     if (c.which != 0) {
;         const float rsy = row_rs(R.y);
; #pragma unroll
;         for (int j = 0; j < 4; ++j) { R.x[j] = R.x[j] + R.gt[j] * (R.y[j] * rsy * gA[j]); *(GAS f32x4*)(xo + 4 * lane + 256 * j) = R.x[j]; }
;     }
;     if (c.which == 0 && row < MX) {
;         typedef _Float16 h4 __attribute__((ext_vector_type(4))); GAS _Float16* xh = (GAS _Float16*)c.xh + (size_t)row * DM;
; #pragma unroll
;         for (int j = 0; j < 4; ++j) *(GAS h4*)(xh + 4 * lane + 256 * j) = __builtin_convertvector(R.x[j], h4);
;     }
.LBB0_673:
	s_and_b64 vcc, exec, s[36:37]
	s_cbranch_vccnz .LBB0_675
	v_pk_mul_f32 v[200:201], v[182:183], v[182:183]
	v_pk_mul_f32 v[202:203], v[178:179], v[178:179]
	s_lshl_b64 s[12:13], s[8:9], 12
	v_pk_mov_b32 v[212:213], v[202:203], v[200:201] op_sel:[1,0]
	v_mov_b32_e32 v203, v201
	v_pk_add_f32 v[200:201], v[212:213], v[202:203]
	v_pk_mul_f32 v[202:203], v[190:191], v[190:191]
	v_pk_add_f32 v[200:201], v[200:201], v[200:201] op_sel_hi:[0,1]
	v_pk_mul_f32 v[212:213], v[186:187], v[186:187]
	v_mul_f32_e32 v200, v194, v194
	v_pk_mov_b32 v[214:215], v[212:213], v[202:203] op_sel:[1,0]
	v_mov_b32_e32 v213, v203
	v_pk_add_f32 v[202:203], v[214:215], v[212:213]
	v_pk_fma_f32 v[212:213], v[194:195], v[194:195], v[200:201] op_sel_hi:[1,1,0]
	v_mul_f32_e32 v200, v198, v198
	v_pk_add_f32 v[202:203], v[202:203], v[202:203] op_sel_hi:[0,1]
	v_pk_fma_f32 v[214:215], v[198:199], v[198:199], v[200:201] op_sel_hi:[1,1,0]
	v_mul_f32_e32 v212, v206, v206
	v_mul_f32_e32 v214, v207, v207
	v_mul_f32_e32 v202, v210, v210
	v_mul_f32_e32 v200, v211, v211
	v_pk_add_f32 v[212:213], v[212:213], v[214:215]
	v_pk_add_f32 v[200:201], v[202:203], v[200:201]
	v_xor_b32_e32 v202, 1, v231
	v_pk_add_f32 v[200:201], v[212:213], v[200:201]
	v_readlane_b32 s24, v252, 23
	v_add_f32_e32 v200, v200, v201
	v_and_b32_e32 v201, 64, v231
	v_add_u32_e32 v201, 64, v201
	v_cmp_lt_i32_e32 vcc, v202, v201
	s_add_u32 s24, s24, s12
	v_readlane_b32 s12, v252, 20
	v_cndmask_b32_e32 v202, v231, v202, vcc
	v_lshlrev_b32_e32 v202, 2, v202
	ds_bpermute_b32 v202, v202, v200
	s_addc_u32 s25, s12, s13
	s_lshl_b64 s[12:13], s[22:23], 12
	v_readlane_b32 s22, v252, 16
	v_readlane_b32 s23, v252, 17
	s_waitcnt lgkmcnt(0)
	v_add_f32_e32 v200, v200, v202
	v_xor_b32_e32 v202, 2, v231
	v_cmp_lt_i32_e32 vcc, v202, v201
	s_add_u32 s22, s22, s12
	s_addc_u32 s23, s23, s13
	v_cndmask_b32_e32 v202, v231, v202, vcc
	v_lshlrev_b32_e32 v202, 2, v202
	ds_bpermute_b32 v202, v202, v200
	s_and_b64 s[12:13], s[20:21], exec
	s_cselect_b32 s23, s25, s23
	s_cselect_b32 s22, s24, s22
	s_waitcnt lgkmcnt(0)
	v_add_f32_e32 v200, v200, v202
	v_xor_b32_e32 v202, 4, v231
	v_cmp_lt_i32_e32 vcc, v202, v201
	s_nop 1
	v_cndmask_b32_e32 v202, v231, v202, vcc
	v_lshlrev_b32_e32 v202, 2, v202
	ds_bpermute_b32 v202, v202, v200
	s_waitcnt lgkmcnt(0)
	v_add_f32_e32 v200, v200, v202
	v_xor_b32_e32 v202, 8, v231
	v_cmp_lt_i32_e32 vcc, v202, v201
	s_nop 1
	v_cndmask_b32_e32 v202, v231, v202, vcc
	v_lshlrev_b32_e32 v202, 2, v202
	ds_bpermute_b32 v202, v202, v200
	s_waitcnt lgkmcnt(0)
	v_add_f32_e32 v200, v200, v202
	v_xor_b32_e32 v202, 16, v231
	v_cmp_lt_i32_e32 vcc, v202, v201
	s_nop 1
	v_cndmask_b32_e32 v202, v231, v202, vcc
	v_lshlrev_b32_e32 v202, 2, v202
	ds_bpermute_b32 v202, v202, v200
	s_waitcnt lgkmcnt(0)
	v_add_f32_e32 v200, v200, v202
	v_xor_b32_e32 v202, 32, v231
	v_cmp_lt_i32_e32 vcc, v202, v201
	s_nop 1
	v_cndmask_b32_e32 v201, v231, v202, vcc
	v_lshlrev_b32_e32 v201, 2, v201
	ds_bpermute_b32 v201, v201, v200
	s_waitcnt lgkmcnt(0)
	v_add_f32_e32 v200, v200, v201
	v_fmamk_f32 v200, v200, 0x3a800000, v236
	v_rsq_f32_e32 v200, v200
	s_nop 0
	v_pk_mul_f32 v[202:203], v[200:201], v[182:183] op_sel_hi:[0,1]
	s_waitcnt vmcnt(0)
	v_pk_mul_f32 v[202:203], v[2:3], v[202:203]
	v_pk_mul_f32 v[212:213], v[200:201], v[178:179] op_sel_hi:[0,1]
	v_pk_fma_f32 v[148:149], v[50:51], v[202:203], v[148:149]
	v_pk_mul_f32 v[202:203], v[200:201], v[190:191] op_sel_hi:[0,1]
	v_pk_mul_f32 v[212:213], v[0:1], v[212:213]
	v_pk_mul_f32 v[202:203], v[6:7], v[202:203]
	v_pk_fma_f32 v[146:147], v[48:49], v[212:213], v[146:147]
	v_pk_mul_f32 v[212:213], v[200:201], v[186:187] op_sel_hi:[0,1]
	v_pk_fma_f32 v[144:145], v[54:55], v[202:203], v[144:145]
	v_pk_mul_f32 v[202:203], v[200:201], v[198:199] op_sel_hi:[0,1]
	v_pk_mul_f32 v[212:213], v[4:5], v[212:213]
	v_pk_mul_f32 v[202:203], v[18:19], v[202:203]
	v_pk_fma_f32 v[142:143], v[52:53], v[212:213], v[142:143]
	v_pk_mul_f32 v[212:213], v[200:201], v[194:195] op_sel_hi:[0,1]
	v_pk_fma_f32 v[140:141], v[58:59], v[202:203], v[140:141]
	v_pk_mul_f32 v[202:203], v[200:201], v[210:211] op_sel_hi:[0,1]
	v_pk_mul_f32 v[200:201], v[200:201], v[206:207] op_sel_hi:[0,1]
	v_pk_mul_f32 v[212:213], v[16:17], v[212:213]
	v_pk_mul_f32 v[200:201], v[20:21], v[200:201]
	v_pk_mul_f32 v[202:203], v[22:23], v[202:203]
	v_pk_fma_f32 v[138:139], v[56:57], v[212:213], v[138:139]
	v_pk_fma_f32 v[136:137], v[62:63], v[202:203], v[136:137]
	v_pk_fma_f32 v[134:135], v[60:61], v[200:201], v[134:135]
	global_store_dwordx4 v80, v[146:149], s[22:23] sc1
	global_store_dwordx4 v80, v[142:145], s[22:23] offset:1024 sc1
	global_store_dwordx4 v80, v[138:141], s[22:23] offset:2048 sc1
	global_store_dwordx4 v80, v[134:137], s[22:23] offset:3072 sc1
.LBB0_675:
	v_readlane_b32 s12, v254, 32
	v_readlane_b32 s13, v254, 33
	s_and_b64 s[12:13], s[12:13], s[20:21]
	s_andn2_b64 vcc, exec, s[12:13]
	s_lshl_b64 s[8:9], s[8:9], 11
	s_cbranch_vccnz .LBB0_678
	v_lshl_add_u64 v[200:201], v[168:169], 0, s[8:9]
	s_waitcnt vmcnt(0)
	v_cvt_pk_f16_f32 v203, v148, v149
	v_cvt_pk_f16_f32 v202, v146, v147
	global_store_dwordx2 v[200:201], v[202:203], off sc1
	v_cvt_pk_f16_f32 v203, v144, v145
	v_cvt_pk_f16_f32 v202, v142, v143
	global_store_dwordx2 v[200:201], v[202:203], off offset:512 sc1
	v_cvt_pk_f16_f32 v203, v140, v141
	v_cvt_pk_f16_f32 v202, v138, v139
	global_store_dwordx2 v[200:201], v[202:203], off offset:1024 sc1
	v_cvt_pk_f16_f32 v203, v136, v137
	v_cvt_pk_f16_f32 v202, v134, v135
	global_store_dwordx2 v[200:201], v[202:203], off offset:1536 sc1
	s_and_b64 vcc, exec, s[34:35]
	s_cbranch_vccz .LBB0_679

; #define GAS __attribute__((address_space(1)))
; __device__ __forceinline__ unsigned cvt_pk_bf16(float lo, float hi) { f32x2_t v = {lo, hi}; bf16x2_t b = __builtin_convertvector(v, bf16x2_t); return __builtin_bit_cast(unsigned, b); }
; __device__ __forceinline__ void row_finish(RowRegs& R, const RowCtx& c, int row, const f32x4 (&gA)[4], const f32x4 (&gB)[4], GAS float* xo, GAS bf16_t* ho) {
;     ...
;     if (c.do_norm) {
;         const float rs = row_rs(R.x);
; #pragma unroll
;         for (int j = 0; j < 4; ++j) {
;     ...
;             u32x2 w; w.x = cvt_pk_bf16(h[0], h[1]); w.y = cvt_pk_bf16(h[2], h[3]);
;             *(GAS u32x2*)(ho + 4 * lane + 256 * j) = w;
;         }
;     }
.LBB0_679:
	s_waitcnt vmcnt(0)
	v_pk_mul_f32 v[200:201], v[148:149], v[148:149]
	v_pk_mul_f32 v[202:203], v[146:147], v[146:147]
	s_nop 0
	v_pk_mov_b32 v[212:213], v[202:203], v[200:201] op_sel:[1,0]
	v_mov_b32_e32 v203, v201
	v_pk_add_f32 v[200:201], v[212:213], v[202:203]
	v_pk_mul_f32 v[202:203], v[144:145], v[144:145]
	v_pk_add_f32 v[200:201], v[200:201], v[200:201] op_sel_hi:[0,1]
	v_pk_mul_f32 v[212:213], v[142:143], v[142:143]
	v_mul_f32_e32 v200, v138, v138
	v_pk_mov_b32 v[214:215], v[212:213], v[202:203] op_sel:[1,0]
	v_mov_b32_e32 v213, v203
	v_pk_add_f32 v[202:203], v[214:215], v[212:213]
	v_pk_fma_f32 v[212:213], v[138:139], v[138:139], v[200:201] op_sel_hi:[1,1,0]
	v_mul_f32_e32 v200, v140, v140
	v_pk_add_f32 v[202:203], v[202:203], v[202:203] op_sel_hi:[0,1]
	v_pk_fma_f32 v[214:215], v[140:141], v[140:141], v[200:201] op_sel_hi:[1,1,0]
	v_mul_f32_e32 v212, v134, v134
	v_mul_f32_e32 v214, v135, v135
	v_mul_f32_e32 v202, v136, v136
	v_mul_f32_e32 v200, v137, v137
	v_pk_add_f32 v[212:213], v[212:213], v[214:215]
	v_pk_add_f32 v[200:201], v[202:203], v[200:201]
	v_xor_b32_e32 v202, 1, v231
	v_pk_add_f32 v[200:201], v[212:213], v[200:201]
	v_pk_add_f32 v[212:213], v[96:97], 1.0 op_sel_hi:[1,0]
	v_add_f32_e32 v200, v200, v201
	v_and_b32_e32 v201, 64, v231
	v_add_u32_e32 v201, 64, v201
	v_cmp_lt_i32_e32 vcc, v202, v201
	v_pk_add_f32 v[214:215], v[94:95], 1.0 op_sel_hi:[1,0]
	s_nop 0
	v_cndmask_b32_e32 v202, v231, v202, vcc
	v_lshlrev_b32_e32 v202, 2, v202
	ds_bpermute_b32 v202, v202, v200
	s_waitcnt lgkmcnt(0)
	v_add_f32_e32 v200, v200, v202
	v_xor_b32_e32 v202, 2, v231
	v_cmp_lt_i32_e32 vcc, v202, v201
	s_nop 1
	v_cndmask_b32_e32 v202, v231, v202, vcc
	v_lshlrev_b32_e32 v202, 2, v202
	ds_bpermute_b32 v202, v202, v200
	s_waitcnt lgkmcnt(0)
	v_add_f32_e32 v200, v200, v202
	v_xor_b32_e32 v202, 4, v231
	v_cmp_lt_i32_e32 vcc, v202, v201
	s_nop 1
	v_cndmask_b32_e32 v202, v231, v202, vcc
	v_lshlrev_b32_e32 v202, 2, v202
	ds_bpermute_b32 v202, v202, v200
	s_waitcnt lgkmcnt(0)
	v_add_f32_e32 v200, v200, v202
	v_xor_b32_e32 v202, 8, v231
	v_cmp_lt_i32_e32 vcc, v202, v201
	s_nop 1
	v_cndmask_b32_e32 v202, v231, v202, vcc
	v_lshlrev_b32_e32 v202, 2, v202
	ds_bpermute_b32 v202, v202, v200
	s_waitcnt lgkmcnt(0)
	v_add_f32_e32 v200, v200, v202
	v_xor_b32_e32 v202, 16, v231
	v_cmp_lt_i32_e32 vcc, v202, v201
	s_nop 1
	v_cndmask_b32_e32 v202, v231, v202, vcc
	v_lshlrev_b32_e32 v202, 2, v202
	ds_bpermute_b32 v202, v202, v200
	s_waitcnt lgkmcnt(0)
	v_add_f32_e32 v200, v200, v202
	v_xor_b32_e32 v202, 32, v231
	v_cmp_lt_i32_e32 vcc, v202, v201
	s_nop 1
	v_cndmask_b32_e32 v201, v231, v202, vcc
	v_lshlrev_b32_e32 v201, 2, v201
	ds_bpermute_b32 v201, v201, v200
	v_lshl_add_u64 v[202:203], v[170:171], 0, s[8:9]
	s_waitcnt lgkmcnt(0)
	v_add_f32_e32 v200, v200, v201
	v_fmamk_f32 v200, v200, 0x3a800000, v236
	v_rsq_f32_e32 v200, v200
	s_nop 0
	v_pk_mul_f32 v[148:149], v[148:149], v[200:201] op_sel_hi:[1,0]
	v_pk_mul_f32 v[146:147], v[146:147], v[200:201] op_sel_hi:[1,0]
	v_pk_mul_f32 v[148:149], v[10:11], v[148:149]
	v_pk_mul_f32 v[146:147], v[8:9], v[146:147]
	v_pk_fma_f32 v[148:149], v[212:213], v[148:149], v[112:113]
	v_pk_fma_f32 v[146:147], v[214:215], v[146:147], v[110:111]
	v_pk_mul_f32 v[144:145], v[144:145], v[200:201] op_sel_hi:[1,0]
	v_cvt_pk_bf16_f32 v146, v146, v147
	v_cvt_pk_bf16_f32 v147, v148, v149
	v_pk_mul_f32 v[142:143], v[142:143], v[200:201] op_sel_hi:[1,0]
	global_store_dwordx2 v[202:203], v[146:147], off sc1
	v_pk_mul_f32 v[142:143], v[12:13], v[142:143]
	v_pk_mul_f32 v[144:145], v[14:15], v[144:145]
	v_pk_add_f32 v[146:147], v[104:105], 1.0 op_sel_hi:[1,0]
	v_pk_add_f32 v[148:149], v[102:103], 1.0 op_sel_hi:[1,0]
	v_pk_fma_f32 v[144:145], v[146:147], v[144:145], v[120:121]
	v_pk_fma_f32 v[142:143], v[148:149], v[142:143], v[118:119]
	v_pk_mul_f32 v[140:141], v[140:141], v[200:201] op_sel_hi:[1,0]
	v_cvt_pk_bf16_f32 v142, v142, v143
	v_cvt_pk_bf16_f32 v143, v144, v145
	v_pk_mul_f32 v[138:139], v[138:139], v[200:201] op_sel_hi:[1,0]
	global_store_dwordx2 v[202:203], v[142:143], off offset:512 sc1
	v_pk_mul_f32 v[138:139], v[24:25], v[138:139]
	v_pk_mul_f32 v[140:141], v[26:27], v[140:141]
	v_pk_add_f32 v[142:143], v[116:117], 1.0 op_sel_hi:[1,0]
	v_pk_add_f32 v[144:145], v[114:115], 1.0 op_sel_hi:[1,0]
	v_pk_fma_f32 v[140:141], v[142:143], v[140:141], v[128:129]
	v_pk_fma_f32 v[138:139], v[144:145], v[138:139], v[126:127]
	v_pk_mul_f32 v[136:137], v[136:137], v[200:201] op_sel_hi:[1,0]
	v_cvt_pk_bf16_f32 v138, v138, v139
	v_cvt_pk_bf16_f32 v139, v140, v141
	v_pk_mul_f32 v[134:135], v[134:135], v[200:201] op_sel_hi:[1,0]
	global_store_dwordx2 v[202:203], v[138:139], off offset:1024 sc1
	v_pk_mul_f32 v[134:135], v[28:29], v[134:135]
	v_pk_mul_f32 v[136:137], v[30:31], v[136:137]
	v_pk_add_f32 v[138:139], v[124:125], 1.0 op_sel_hi:[1,0]
	v_pk_add_f32 v[140:141], v[122:123], 1.0 op_sel_hi:[1,0]
	v_pk_fma_f32 v[136:137], v[138:139], v[136:137], v[132:133]
	v_pk_fma_f32 v[134:135], v[140:141], v[134:135], v[130:131]
	s_nop 0
	v_cvt_pk_bf16_f32 v134, v134, v135
	v_cvt_pk_bf16_f32 v135, v136, v137
	global_store_dwordx2 v[202:203], v[134:135], off offset:1536 sc1
	s_andn2_b64 vcc, exec, s[40:41]
	s_cbranch_vccnz .LBB0_651
; #define GAS __attribute__((address_space(1)))
; __device__ __forceinline__ void row_finish(RowRegs& R, const RowCtx& c, int row, const f32x4 (&gA)[4], const f32x4 (&gB)[4], GAS float* xo, GAS bf16_t* ho) {
;     const int lane = c.lane;
;     if (c.which != 0) {
;         const float rsy = row_rs(R.y);
; #pragma unroll
;         for (int j = 0; j < 4; ++j) { R.x[j] = R.x[j] + R.gt[j] * (R.y[j] * rsy * gA[j]); *(GAS f32x4*)(xo + 4 * lane + 256 * j) = R.x[j]; }
;     }
;     if (c.which == 0 && row < MX) {
;         typedef _Float16 h4 __attribute__((ext_vector_type(4))); GAS _Float16* xh = (GAS _Float16*)c.xh + (size_t)row * DM;
; #pragma unroll
;         for (int j = 0; j < 4; ++j) *(GAS h4*)(xh + 4 * lane + 256 * j) = __builtin_convertvector(R.x[j], h4);
;     }
.LBB0_680:
	s_and_b64 vcc, exec, s[36:37]
	s_cbranch_vccnz .LBB0_682
	s_waitcnt vmcnt(0)
	v_pk_mul_f32 v[134:135], v[180:181], v[180:181]
	v_pk_mul_f32 v[136:137], v[174:175], v[174:175]
	s_lshl_b64 s[8:9], s[26:27], 12
	v_pk_mov_b32 v[138:139], v[136:137], v[134:135] op_sel:[1,0]
	v_mov_b32_e32 v137, v135
	v_pk_add_f32 v[134:135], v[138:139], v[136:137]
	v_pk_mul_f32 v[136:137], v[188:189], v[188:189]
	v_pk_add_f32 v[134:135], v[134:135], v[134:135] op_sel_hi:[0,1]
	v_pk_mul_f32 v[138:139], v[176:177], v[176:177]
	v_mul_f32_e32 v134, v184, v184
	v_pk_mov_b32 v[140:141], v[138:139], v[136:137] op_sel:[1,0]
	v_mov_b32_e32 v139, v137
	v_pk_add_f32 v[136:137], v[140:141], v[138:139]
	v_pk_fma_f32 v[138:139], v[184:185], v[184:185], v[134:135] op_sel_hi:[1,1,0]
	v_mul_f32_e32 v134, v196, v196
	v_pk_add_f32 v[136:137], v[136:137], v[136:137] op_sel_hi:[0,1]
	v_pk_fma_f32 v[140:141], v[196:197], v[196:197], v[134:135] op_sel_hi:[1,1,0]
	v_mul_f32_e32 v138, v192, v192
	v_mul_f32_e32 v140, v193, v193
	v_mul_f32_e32 v136, v208, v208
	v_mul_f32_e32 v134, v209, v209
	v_pk_add_f32 v[138:139], v[138:139], v[140:141]
	v_pk_add_f32 v[134:135], v[136:137], v[134:135]
	v_xor_b32_e32 v136, 1, v231
	v_pk_add_f32 v[134:135], v[138:139], v[134:135]
	v_readlane_b32 s12, v252, 23
	v_add_f32_e32 v134, v134, v135
	v_and_b32_e32 v135, 64, v231
	v_add_u32_e32 v135, 64, v135
	v_cmp_lt_i32_e32 vcc, v136, v135
	s_add_u32 s12, s12, s8
	v_readlane_b32 s8, v252, 20
	v_cndmask_b32_e32 v136, v231, v136, vcc
	v_lshlrev_b32_e32 v136, 2, v136
	ds_bpermute_b32 v136, v136, v134
	s_addc_u32 s13, s8, s9
	s_lshl_b64 s[8:9], s[28:29], 12
	v_readlane_b32 s20, v252, 16
	v_readlane_b32 s21, v252, 17
	s_waitcnt lgkmcnt(0)
	v_add_f32_e32 v134, v134, v136
	v_xor_b32_e32 v136, 2, v231
	v_cmp_lt_i32_e32 vcc, v136, v135
	s_add_u32 s20, s20, s8
	s_addc_u32 s21, s21, s9
	v_cndmask_b32_e32 v136, v231, v136, vcc
	v_lshlrev_b32_e32 v136, 2, v136
	ds_bpermute_b32 v136, v136, v134
	s_and_b64 s[8:9], s[38:39], exec
	s_cselect_b32 s9, s13, s21
	s_cselect_b32 s8, s12, s20
	s_waitcnt lgkmcnt(0)
	v_add_f32_e32 v134, v134, v136
	v_xor_b32_e32 v136, 4, v231
	v_cmp_lt_i32_e32 vcc, v136, v135
	s_nop 1
	v_cndmask_b32_e32 v136, v231, v136, vcc
	v_lshlrev_b32_e32 v136, 2, v136
	ds_bpermute_b32 v136, v136, v134
	s_waitcnt lgkmcnt(0)
	v_add_f32_e32 v134, v134, v136
	v_xor_b32_e32 v136, 8, v231
	v_cmp_lt_i32_e32 vcc, v136, v135
	s_nop 1
	v_cndmask_b32_e32 v136, v231, v136, vcc
	v_lshlrev_b32_e32 v136, 2, v136
	ds_bpermute_b32 v136, v136, v134
	s_waitcnt lgkmcnt(0)
	v_add_f32_e32 v134, v134, v136
	v_xor_b32_e32 v136, 16, v231
	v_cmp_lt_i32_e32 vcc, v136, v135
	s_nop 1
	v_cndmask_b32_e32 v136, v231, v136, vcc
	v_lshlrev_b32_e32 v136, 2, v136
	ds_bpermute_b32 v136, v136, v134
	s_waitcnt lgkmcnt(0)
	v_add_f32_e32 v134, v134, v136
	v_xor_b32_e32 v136, 32, v231
	v_cmp_lt_i32_e32 vcc, v136, v135
	s_nop 1
	v_cndmask_b32_e32 v135, v231, v136, vcc
	v_lshlrev_b32_e32 v135, 2, v135
	ds_bpermute_b32 v135, v135, v134
	s_waitcnt lgkmcnt(0)
	v_add_f32_e32 v134, v134, v135
	v_fmamk_f32 v134, v134, 0x3a800000, v236
	v_rsq_f32_e32 v134, v134
	s_nop 0
	v_pk_mul_f32 v[136:137], v[134:135], v[180:181] op_sel_hi:[0,1]
	v_pk_mul_f32 v[136:137], v[2:3], v[136:137]
	v_pk_mul_f32 v[138:139], v[134:135], v[174:175] op_sel_hi:[0,1]
	v_pk_fma_f32 v[164:165], v[34:35], v[136:137], v[164:165]
	v_pk_mul_f32 v[136:137], v[134:135], v[188:189] op_sel_hi:[0,1]
	v_pk_mul_f32 v[138:139], v[0:1], v[138:139]
	v_pk_mul_f32 v[136:137], v[6:7], v[136:137]
	v_pk_fma_f32 v[162:163], v[32:33], v[138:139], v[162:163]
	v_pk_mul_f32 v[138:139], v[134:135], v[176:177] op_sel_hi:[0,1]
	v_pk_fma_f32 v[160:161], v[38:39], v[136:137], v[160:161]
	v_pk_mul_f32 v[136:137], v[134:135], v[196:197] op_sel_hi:[0,1]
	v_pk_mul_f32 v[138:139], v[4:5], v[138:139]
	v_pk_mul_f32 v[136:137], v[18:19], v[136:137]
	v_pk_fma_f32 v[158:159], v[36:37], v[138:139], v[158:159]
	v_pk_mul_f32 v[138:139], v[134:135], v[184:185] op_sel_hi:[0,1]
	v_pk_fma_f32 v[156:157], v[42:43], v[136:137], v[156:157]
	v_pk_mul_f32 v[136:137], v[134:135], v[208:209] op_sel_hi:[0,1]
	v_pk_mul_f32 v[134:135], v[134:135], v[192:193] op_sel_hi:[0,1]
	v_pk_mul_f32 v[138:139], v[16:17], v[138:139]
	v_pk_mul_f32 v[134:135], v[20:21], v[134:135]
	v_pk_mul_f32 v[136:137], v[22:23], v[136:137]
	v_pk_fma_f32 v[154:155], v[40:41], v[138:139], v[154:155]
	v_pk_fma_f32 v[152:153], v[46:47], v[136:137], v[152:153]
	v_pk_fma_f32 v[150:151], v[44:45], v[134:135], v[150:151]
	global_store_dwordx4 v80, v[162:165], s[8:9] sc1
	global_store_dwordx4 v80, v[158:161], s[8:9] offset:1024 sc1
	global_store_dwordx4 v80, v[154:157], s[8:9] offset:2048 sc1
	global_store_dwordx4 v80, v[150:153], s[8:9] offset:3072 sc1
.LBB0_682:
	v_readlane_b32 s8, v254, 32
	v_readlane_b32 s9, v254, 33
	s_and_b64 s[8:9], s[8:9], s[38:39]
	s_andn2_b64 vcc, exec, s[8:9]
	s_lshl_b64 s[8:9], s[26:27], 11
	s_cbranch_vccnz .LBB0_684
	s_waitcnt vmcnt(0)
	v_lshl_add_u64 v[134:135], v[168:169], 0, s[8:9]
	v_cvt_pk_f16_f32 v137, v164, v165
	v_cvt_pk_f16_f32 v136, v162, v163
	global_store_dwordx2 v[134:135], v[136:137], off sc1
	v_cvt_pk_f16_f32 v137, v160, v161
	v_cvt_pk_f16_f32 v136, v158, v159
	global_store_dwordx2 v[134:135], v[136:137], off offset:512 sc1
	v_cvt_pk_f16_f32 v137, v156, v157
	v_cvt_pk_f16_f32 v136, v154, v155
	global_store_dwordx2 v[134:135], v[136:137], off offset:1024 sc1
	v_cvt_pk_f16_f32 v137, v152, v153
	v_cvt_pk_f16_f32 v136, v150, v151
	global_store_dwordx2 v[134:135], v[136:137], off offset:1536 sc1
; #define GAS __attribute__((address_space(1)))
; __device__ __forceinline__ unsigned cvt_pk_bf16(float lo, float hi) { f32x2_t v = {lo, hi}; bf16x2_t b = __builtin_convertvector(v, bf16x2_t); return __builtin_bit_cast(unsigned, b); }
; __device__ __forceinline__ void row_finish(RowRegs& R, const RowCtx& c, int row, const f32x4 (&gA)[4], const f32x4 (&gB)[4], GAS float* xo, GAS bf16_t* ho) {
;     ...
;     if (c.do_norm) {
;         const float rs = row_rs(R.x);
; #pragma unroll
;         for (int j = 0; j < 4; ++j) {
;     ...
;             u32x2 w; w.x = cvt_pk_bf16(h[0], h[1]); w.y = cvt_pk_bf16(h[2], h[3]);
;             *(GAS u32x2*)(ho + 4 * lane + 256 * j) = w;
;         }
;     }
.LBB0_684:
	s_and_b64 vcc, exec, s[34:35]
	s_cbranch_vccnz .LBB0_651
	s_waitcnt vmcnt(0)
	v_pk_mul_f32 v[134:135], v[164:165], v[164:165]
	v_pk_mul_f32 v[136:137], v[162:163], v[162:163]
	v_mul_f32_e32 v80, v154, v154
	v_pk_mov_b32 v[138:139], v[136:137], v[134:135] op_sel:[1,0]
	v_mov_b32_e32 v137, v135
	v_pk_add_f32 v[134:135], v[138:139], v[136:137]
	v_pk_mul_f32 v[136:137], v[160:161], v[160:161]
	v_pk_mul_f32 v[138:139], v[158:159], v[158:159]
	v_pk_add_f32 v[134:135], v[134:135], v[134:135] op_sel_hi:[0,1]
	v_pk_mov_b32 v[140:141], v[138:139], v[136:137] op_sel:[1,0]
	v_mov_b32_e32 v139, v137
	v_pk_add_f32 v[136:137], v[140:141], v[138:139]
	v_pk_fma_f32 v[138:139], v[154:155], v[154:155], v[80:81] op_sel_hi:[1,1,0]
	v_mul_f32_e32 v80, v156, v156
	v_pk_add_f32 v[136:137], v[136:137], v[136:137] op_sel_hi:[0,1]
	v_pk_fma_f32 v[140:141], v[156:157], v[156:157], v[80:81] op_sel_hi:[1,1,0]
	v_mul_f32_e32 v138, v150, v150
	v_mul_f32_e32 v140, v151, v151
	v_mul_f32_e32 v136, v152, v152
	v_mul_f32_e32 v134, v153, v153
	v_pk_add_f32 v[138:139], v[138:139], v[140:141]
	v_pk_add_f32 v[134:135], v[136:137], v[134:135]
	v_pk_add_f32 v[140:141], v[66:67], 1.0 op_sel_hi:[1,0]
	v_pk_add_f32 v[134:135], v[138:139], v[134:135]
	v_pk_add_f32 v[142:143], v[64:65], 1.0 op_sel_hi:[1,0]
	v_add_f32_e32 v80, v134, v135
	v_and_b32_e32 v134, 64, v231
	v_add_u32_e32 v134, 64, v134
	v_xor_b32_e32 v135, 1, v231
	v_cmp_lt_i32_e32 vcc, v135, v134
	s_nop 1
	v_cndmask_b32_e32 v135, v231, v135, vcc
	v_lshlrev_b32_e32 v135, 2, v135
	ds_bpermute_b32 v135, v135, v80
	s_waitcnt lgkmcnt(0)
	v_add_f32_e32 v80, v80, v135
	v_xor_b32_e32 v135, 2, v231
	v_cmp_lt_i32_e32 vcc, v135, v134
	s_nop 1
	v_cndmask_b32_e32 v135, v231, v135, vcc
	v_lshlrev_b32_e32 v135, 2, v135
	ds_bpermute_b32 v135, v135, v80
	s_waitcnt lgkmcnt(0)
	v_add_f32_e32 v80, v80, v135
	v_xor_b32_e32 v135, 4, v231
	v_cmp_lt_i32_e32 vcc, v135, v134
	s_nop 1
	v_cndmask_b32_e32 v135, v231, v135, vcc
	v_lshlrev_b32_e32 v135, 2, v135
	ds_bpermute_b32 v135, v135, v80
	s_waitcnt lgkmcnt(0)
	v_add_f32_e32 v80, v80, v135
	v_xor_b32_e32 v135, 8, v231
	v_cmp_lt_i32_e32 vcc, v135, v134
	s_nop 1
	v_cndmask_b32_e32 v135, v231, v135, vcc
	v_lshlrev_b32_e32 v135, 2, v135
	ds_bpermute_b32 v135, v135, v80
	s_waitcnt lgkmcnt(0)
	v_add_f32_e32 v80, v80, v135
	v_xor_b32_e32 v135, 16, v231
	v_cmp_lt_i32_e32 vcc, v135, v134
	s_nop 1
	v_cndmask_b32_e32 v135, v231, v135, vcc
	v_lshlrev_b32_e32 v135, 2, v135
	ds_bpermute_b32 v135, v135, v80
	s_waitcnt lgkmcnt(0)
	v_add_f32_e32 v80, v80, v135
	v_xor_b32_e32 v135, 32, v231
	v_cmp_lt_i32_e32 vcc, v135, v134
	s_nop 1
	v_cndmask_b32_e32 v134, v231, v135, vcc
	v_lshlrev_b32_e32 v134, 2, v134
	ds_bpermute_b32 v134, v134, v80
	s_waitcnt lgkmcnt(0)
	v_add_f32_e32 v80, v80, v134
	v_fmamk_f32 v80, v80, 0x3a800000, v236
	v_rsq_f32_e32 v80, v80
	v_lshl_add_u64 v[134:135], v[170:171], 0, s[8:9]
	v_pk_mul_f32 v[136:137], v[164:165], v[80:81] op_sel_hi:[1,0]
	v_pk_mul_f32 v[138:139], v[162:163], v[80:81] op_sel_hi:[1,0]
	v_pk_mul_f32 v[136:137], v[10:11], v[136:137]
	v_pk_mul_f32 v[138:139], v[8:9], v[138:139]
	v_pk_fma_f32 v[136:137], v[140:141], v[136:137], v[78:79]
	v_pk_fma_f32 v[138:139], v[142:143], v[138:139], v[76:77]
	v_pk_add_f32 v[140:141], v[70:71], 1.0 op_sel_hi:[1,0]
	v_cvt_pk_bf16_f32 v138, v138, v139
	v_cvt_pk_bf16_f32 v139, v136, v137
	global_store_dwordx2 v[134:135], v[138:139], off sc1
	v_pk_mul_f32 v[136:137], v[160:161], v[80:81] op_sel_hi:[1,0]
	v_pk_mul_f32 v[138:139], v[158:159], v[80:81] op_sel_hi:[1,0]
	v_pk_mul_f32 v[136:137], v[14:15], v[136:137]
	v_pk_mul_f32 v[138:139], v[12:13], v[138:139]
	v_pk_add_f32 v[142:143], v[68:69], 1.0 op_sel_hi:[1,0]
	v_pk_fma_f32 v[136:137], v[140:141], v[136:137], v[88:89]
	v_pk_fma_f32 v[138:139], v[142:143], v[138:139], v[86:87]
	v_pk_add_f32 v[140:141], v[74:75], 1.0 op_sel_hi:[1,0]
	v_cvt_pk_bf16_f32 v138, v138, v139
	v_cvt_pk_bf16_f32 v139, v136, v137
	global_store_dwordx2 v[134:135], v[138:139], off offset:512 sc1
	v_pk_mul_f32 v[136:137], v[156:157], v[80:81] op_sel_hi:[1,0]
	v_pk_mul_f32 v[138:139], v[154:155], v[80:81] op_sel_hi:[1,0]
	v_pk_mul_f32 v[136:137], v[26:27], v[136:137]
	v_pk_mul_f32 v[138:139], v[24:25], v[138:139]
	v_pk_add_f32 v[142:143], v[72:73], 1.0 op_sel_hi:[1,0]
	v_pk_fma_f32 v[136:137], v[140:141], v[136:137], v[100:101]
	v_pk_fma_f32 v[138:139], v[142:143], v[138:139], v[98:99]
	v_pk_add_f32 v[140:141], v[92:93], 1.0 op_sel_hi:[1,0]
	v_cvt_pk_bf16_f32 v138, v138, v139
	v_cvt_pk_bf16_f32 v139, v136, v137
	global_store_dwordx2 v[134:135], v[138:139], off offset:1024 sc1
	v_pk_mul_f32 v[136:137], v[152:153], v[80:81] op_sel_hi:[1,0]
	v_pk_mul_f32 v[138:139], v[150:151], v[80:81] op_sel_hi:[1,0]
	v_pk_mul_f32 v[136:137], v[30:31], v[136:137]
	v_pk_mul_f32 v[138:139], v[28:29], v[138:139]
	v_pk_add_f32 v[142:143], v[90:91], 1.0 op_sel_hi:[1,0]
	v_pk_fma_f32 v[136:137], v[140:141], v[136:137], v[108:109]
	v_pk_fma_f32 v[138:139], v[142:143], v[138:139], v[106:107]
	s_nop 0
	v_cvt_pk_bf16_f32 v138, v138, v139
	v_cvt_pk_bf16_f32 v139, v136, v137
	global_store_dwordx2 v[134:135], v[138:139], off offset:1536 sc1
	s_branch .LBB0_651

; #define GAS __attribute__((address_space(1)))
; __device__ __forceinline__ void row_finish(RowRegs& R, const RowCtx& c, int row, const f32x4 (&gA)[4], const f32x4 (&gB)[4], GAS float* xo, GAS bf16_t* ho) {
;     const int lane = c.lane;
;     if (c.which != 0) {
;         const float rsy = row_rs(R.y);
; #pragma unroll
;         for (int j = 0; j < 4; ++j) { R.x[j] = R.x[j] + R.gt[j] * (R.y[j] * rsy * gA[j]); *(GAS f32x4*)(xo + 4 * lane + 256 * j) = R.x[j]; }
;     }
;     if (c.which == 0 && row < MX) {
;         typedef _Float16 h4 __attribute__((ext_vector_type(4))); GAS _Float16* xh = (GAS _Float16*)c.xh + (size_t)row * DM;
; #pragma unroll
;         for (int j = 0; j < 4; ++j) *(GAS h4*)(xh + 4 * lane + 256 * j) = __builtin_convertvector(R.x[j], h4);
;     }
.LBB0_700:
	s_and_b64 vcc, exec, s[36:37]
	s_cbranch_vccnz .LBB0_702
	v_pk_mul_f32 v[122:123], v[108:109], v[108:109]
	v_pk_mul_f32 v[124:125], v[106:107], v[106:107]
	s_ashr_i32 s25, s28, 31
	v_pk_mov_b32 v[126:127], v[124:125], v[122:123] op_sel:[1,0]
	v_mov_b32_e32 v125, v123
	v_pk_add_f32 v[122:123], v[126:127], v[124:125]
	v_pk_mul_f32 v[124:125], v[112:113], v[112:113]
	v_pk_add_f32 v[122:123], v[122:123], v[122:123] op_sel_hi:[0,1]
	v_pk_mul_f32 v[126:127], v[110:111], v[110:111]
	v_mul_f32_e32 v122, v114, v114
	v_pk_mov_b32 v[128:129], v[126:127], v[124:125] op_sel:[1,0]
	v_mov_b32_e32 v127, v125
	v_pk_add_f32 v[124:125], v[128:129], v[126:127]
	v_pk_fma_f32 v[126:127], v[114:115], v[114:115], v[122:123] op_sel_hi:[1,1,0]
	v_mul_f32_e32 v122, v116, v116
	v_pk_add_f32 v[124:125], v[124:125], v[124:125] op_sel_hi:[0,1]
	v_pk_fma_f32 v[128:129], v[116:117], v[116:117], v[122:123] op_sel_hi:[1,1,0]
	v_mul_f32_e32 v126, v120, v120
	v_mul_f32_e32 v128, v121, v121
	v_mul_f32_e32 v124, v118, v118
	v_mul_f32_e32 v122, v119, v119
	v_pk_add_f32 v[126:127], v[126:127], v[128:129]
	v_pk_add_f32 v[122:123], v[124:125], v[122:123]
	v_xor_b32_e32 v124, 1, v231
	v_pk_add_f32 v[122:123], v[126:127], v[122:123]
	s_mov_b32 s24, s28
	v_add_f32_e32 v122, v122, v123
	v_and_b32_e32 v123, 64, v231
	v_add_u32_e32 v123, 64, v123
	v_cmp_lt_i32_e32 vcc, v124, v123
	s_lshl_b64 s[24:25], s[24:25], 12
	s_nop 0
	v_cndmask_b32_e32 v124, v231, v124, vcc
	v_lshlrev_b32_e32 v124, 2, v124
	ds_bpermute_b32 v124, v124, v122
	s_waitcnt lgkmcnt(0)
	v_add_f32_e32 v122, v122, v124
	v_xor_b32_e32 v124, 2, v231
	v_cmp_lt_i32_e32 vcc, v124, v123
	s_nop 1
	v_cndmask_b32_e32 v124, v231, v124, vcc
	v_lshlrev_b32_e32 v124, 2, v124
	ds_bpermute_b32 v124, v124, v122
	s_waitcnt lgkmcnt(0)
	v_add_f32_e32 v122, v122, v124
	v_xor_b32_e32 v124, 4, v231
	v_cmp_lt_i32_e32 vcc, v124, v123
	s_nop 1
	v_cndmask_b32_e32 v124, v231, v124, vcc
	v_lshlrev_b32_e32 v124, 2, v124
	ds_bpermute_b32 v124, v124, v122
	s_waitcnt lgkmcnt(0)
	v_add_f32_e32 v122, v122, v124
	v_xor_b32_e32 v124, 8, v231
	v_cmp_lt_i32_e32 vcc, v124, v123
	s_nop 1
	v_cndmask_b32_e32 v124, v231, v124, vcc
	v_lshlrev_b32_e32 v124, 2, v124
	ds_bpermute_b32 v124, v124, v122
	s_waitcnt lgkmcnt(0)
	v_add_f32_e32 v122, v122, v124
	v_xor_b32_e32 v124, 16, v231
	v_cmp_lt_i32_e32 vcc, v124, v123
	s_nop 1
	v_cndmask_b32_e32 v124, v231, v124, vcc
	v_lshlrev_b32_e32 v124, 2, v124
	ds_bpermute_b32 v124, v124, v122
	s_waitcnt lgkmcnt(0)
	v_add_f32_e32 v122, v122, v124
	v_xor_b32_e32 v124, 32, v231
	v_cmp_lt_i32_e32 vcc, v124, v123
	s_nop 1
	v_cndmask_b32_e32 v123, v231, v124, vcc
	v_lshlrev_b32_e32 v123, 2, v123
	ds_bpermute_b32 v123, v123, v122
	v_lshl_add_u64 v[124:125], v[102:103], 0, s[24:25]
	s_waitcnt lgkmcnt(0)
	v_add_f32_e32 v122, v122, v123
	v_fmamk_f32 v122, v122, 0x3a800000, v236
	v_rsq_f32_e32 v122, v122
	s_nop 0
	v_pk_mul_f32 v[126:127], v[122:123], v[108:109] op_sel_hi:[0,1]
	v_pk_mul_f32 v[126:127], v[2:3], v[126:127]
	v_pk_mul_f32 v[128:129], v[122:123], v[106:107] op_sel_hi:[0,1]
	s_waitcnt vmcnt(3)
	v_pk_fma_f32 v[100:101], v[34:35], v[126:127], v[100:101]
	v_pk_mul_f32 v[126:127], v[122:123], v[112:113] op_sel_hi:[0,1]
	v_pk_mul_f32 v[128:129], v[0:1], v[128:129]
	v_pk_mul_f32 v[126:127], v[6:7], v[126:127]
	v_pk_fma_f32 v[98:99], v[32:33], v[128:129], v[98:99]
	v_pk_mul_f32 v[128:129], v[122:123], v[110:111] op_sel_hi:[0,1]
	s_waitcnt vmcnt(2)
	v_pk_fma_f32 v[96:97], v[38:39], v[126:127], v[96:97]
	v_pk_mul_f32 v[126:127], v[122:123], v[116:117] op_sel_hi:[0,1]
	v_pk_mul_f32 v[128:129], v[4:5], v[128:129]
	v_pk_mul_f32 v[126:127], v[18:19], v[126:127]
	v_pk_fma_f32 v[94:95], v[36:37], v[128:129], v[94:95]
	v_pk_mul_f32 v[128:129], v[122:123], v[114:115] op_sel_hi:[0,1]
	s_waitcnt vmcnt(1)
	v_pk_fma_f32 v[92:93], v[42:43], v[126:127], v[92:93]
	v_pk_mul_f32 v[126:127], v[122:123], v[118:119] op_sel_hi:[0,1]
	v_pk_mul_f32 v[122:123], v[122:123], v[120:121] op_sel_hi:[0,1]
	v_pk_mul_f32 v[128:129], v[16:17], v[128:129]
	v_pk_mul_f32 v[122:123], v[20:21], v[122:123]
	v_pk_mul_f32 v[126:127], v[22:23], v[126:127]
	v_pk_fma_f32 v[90:91], v[40:41], v[128:129], v[90:91]
	s_waitcnt vmcnt(0)
	v_pk_fma_f32 v[88:89], v[46:47], v[126:127], v[88:89]
	v_pk_fma_f32 v[86:87], v[44:45], v[122:123], v[86:87]
	global_store_dwordx4 v[124:125], v[98:101], off sc1
	global_store_dwordx4 v[124:125], v[94:97], off offset:1024 sc1
	global_store_dwordx4 v[124:125], v[90:93], off offset:2048 sc1
	global_store_dwordx4 v[124:125], v[86:89], off offset:3072 sc1
.LBB0_702:
	v_readlane_b32 s24, v254, 32
	v_readlane_b32 s25, v254, 33
	s_and_b64 s[22:23], s[24:25], s[22:23]
	s_andn2_b64 vcc, exec, s[22:23]
	s_cbranch_vccnz .LBB0_704
	s_waitcnt vmcnt(3)
	v_cvt_pk_f16_f32 v123, v100, v101
	v_cvt_pk_f16_f32 v122, v98, v99
	global_store_dwordx2 v[104:105], v[122:123], off offset:-1536 sc1
	s_waitcnt vmcnt(3)
	v_cvt_pk_f16_f32 v123, v96, v97
	v_cvt_pk_f16_f32 v122, v94, v95
	global_store_dwordx2 v[104:105], v[122:123], off offset:-1024 sc1
	s_waitcnt vmcnt(3)
	v_cvt_pk_f16_f32 v123, v92, v93
	v_cvt_pk_f16_f32 v122, v90, v91
	global_store_dwordx2 v[104:105], v[122:123], off offset:-512 sc1
	s_waitcnt vmcnt(3)
	v_cvt_pk_f16_f32 v123, v88, v89
	v_cvt_pk_f16_f32 v122, v86, v87
	global_store_dwordx2 v[104:105], v[122:123], off sc1
; #define GAS __attribute__((address_space(1)))
; __device__ __forceinline__ unsigned cvt_pk_bf16(float lo, float hi) { f32x2_t v = {lo, hi}; bf16x2_t b = __builtin_convertvector(v, bf16x2_t); return __builtin_bit_cast(unsigned, b); }
; __device__ __forceinline__ void row_finish(RowRegs& R, const RowCtx& c, int row, const f32x4 (&gA)[4], const f32x4 (&gB)[4], GAS float* xo, GAS bf16_t* ho) {
;     ...
;     if (c.do_norm) {
;         const float rs = row_rs(R.x);
; #pragma unroll
;         for (int j = 0; j < 4; ++j) {
;     ...
;             u32x2 w; w.x = cvt_pk_bf16(h[0], h[1]); w.y = cvt_pk_bf16(h[2], h[3]);
;             *(GAS u32x2*)(ho + 4 * lane + 256 * j) = w;
;         }
;     }
.LBB0_704:
	s_and_b64 vcc, exec, s[34:35]
	s_cbranch_vccnz .LBB0_690
	s_waitcnt vmcnt(3)
	v_pk_mul_f32 v[122:123], v[100:101], v[100:101]
	v_pk_mul_f32 v[124:125], v[98:99], v[98:99]
	s_mov_b32 s1, 0xf2500000
	v_pk_mov_b32 v[126:127], v[124:125], v[122:123] op_sel:[1,0]
	v_mov_b32_e32 v125, v123
	v_pk_add_f32 v[122:123], v[126:127], v[124:125]
	s_waitcnt vmcnt(2)
	v_pk_mul_f32 v[124:125], v[96:97], v[96:97]
	v_pk_add_f32 v[122:123], v[122:123], v[122:123] op_sel_hi:[0,1]
	v_pk_mul_f32 v[126:127], v[94:95], v[94:95]
	s_waitcnt vmcnt(1)
	v_mul_f32_e32 v122, v90, v90
	v_pk_mov_b32 v[128:129], v[126:127], v[124:125] op_sel:[1,0]
	v_mov_b32_e32 v127, v125
	v_pk_add_f32 v[124:125], v[128:129], v[126:127]
	v_pk_fma_f32 v[126:127], v[90:91], v[90:91], v[122:123] op_sel_hi:[1,1,0]
	v_mul_f32_e32 v122, v92, v92
	v_pk_add_f32 v[124:125], v[124:125], v[124:125] op_sel_hi:[0,1]
	v_pk_fma_f32 v[128:129], v[92:93], v[92:93], v[122:123] op_sel_hi:[1,1,0]
	s_waitcnt vmcnt(0)
	v_mul_f32_e32 v126, v86, v86
	v_mul_f32_e32 v128, v87, v87
	v_mul_f32_e32 v124, v88, v88
	v_mul_f32_e32 v122, v89, v89
	v_pk_add_f32 v[126:127], v[126:127], v[128:129]
	v_pk_add_f32 v[122:123], v[124:125], v[122:123]
	v_xor_b32_e32 v124, 1, v231
	v_pk_add_f32 v[122:123], v[126:127], v[122:123]
	v_pk_add_f32 v[126:127], v[48:49], 1.0 op_sel_hi:[1,0]
	v_add_f32_e32 v122, v122, v123
	v_and_b32_e32 v123, 64, v231
	v_add_u32_e32 v123, 64, v123
	v_cmp_lt_i32_e32 vcc, v124, v123
	s_nop 1
	v_cndmask_b32_e32 v124, v231, v124, vcc
	v_lshlrev_b32_e32 v124, 2, v124
	ds_bpermute_b32 v124, v124, v122
	s_waitcnt lgkmcnt(0)
	v_add_f32_e32 v122, v122, v124
	v_xor_b32_e32 v124, 2, v231
	v_cmp_lt_i32_e32 vcc, v124, v123
	s_nop 1
	v_cndmask_b32_e32 v124, v231, v124, vcc
	v_lshlrev_b32_e32 v124, 2, v124
	ds_bpermute_b32 v124, v124, v122
	s_waitcnt lgkmcnt(0)
	v_add_f32_e32 v122, v122, v124
	v_xor_b32_e32 v124, 4, v231
	v_cmp_lt_i32_e32 vcc, v124, v123
	s_nop 1
	v_cndmask_b32_e32 v124, v231, v124, vcc
	v_lshlrev_b32_e32 v124, 2, v124
	ds_bpermute_b32 v124, v124, v122
	s_waitcnt lgkmcnt(0)
	v_add_f32_e32 v122, v122, v124
	v_xor_b32_e32 v124, 8, v231
	v_cmp_lt_i32_e32 vcc, v124, v123
	s_nop 1
	v_cndmask_b32_e32 v124, v231, v124, vcc
	v_lshlrev_b32_e32 v124, 2, v124
	ds_bpermute_b32 v124, v124, v122
	s_waitcnt lgkmcnt(0)
	v_add_f32_e32 v122, v122, v124
	v_xor_b32_e32 v124, 16, v231
	v_cmp_lt_i32_e32 vcc, v124, v123
	s_nop 1
	v_cndmask_b32_e32 v124, v231, v124, vcc
	v_lshlrev_b32_e32 v124, 2, v124
	ds_bpermute_b32 v124, v124, v122
	s_waitcnt lgkmcnt(0)
	v_add_f32_e32 v122, v122, v124
	v_xor_b32_e32 v124, 32, v231
	v_cmp_lt_i32_e32 vcc, v124, v123
	s_nop 1
	v_cndmask_b32_e32 v123, v231, v124, vcc
	v_lshlrev_b32_e32 v123, 2, v123
	ds_bpermute_b32 v123, v123, v122
	v_pk_add_f32 v[124:125], v[50:51], 1.0 op_sel_hi:[1,0]
	s_waitcnt lgkmcnt(0)
	v_add_f32_e32 v122, v122, v123
	v_fmamk_f32 v122, v122, 0x3a800000, v236
	v_rsq_f32_e32 v122, v122
	s_nop 0
	v_pk_mul_f32 v[100:101], v[100:101], v[122:123] op_sel_hi:[1,0]
	v_pk_mul_f32 v[98:99], v[98:99], v[122:123] op_sel_hi:[1,0]
	v_pk_mul_f32 v[100:101], v[10:11], v[100:101]
	v_pk_mul_f32 v[98:99], v[8:9], v[98:99]
	v_pk_fma_f32 v[100:101], v[124:125], v[100:101], v[58:59]
	v_pk_fma_f32 v[98:99], v[126:127], v[98:99], v[56:57]
	v_pk_mul_f32 v[96:97], v[96:97], v[122:123] op_sel_hi:[1,0]
	v_cvt_pk_bf16_f32 v98, v98, v99
	v_cvt_pk_bf16_f32 v99, v100, v101
	v_add_co_u32_e32 v100, vcc, s1, v104
	v_pk_mul_f32 v[94:95], v[94:95], v[122:123] op_sel_hi:[1,0]
	s_nop 0
	v_addc_co_u32_e32 v101, vcc, -1, v105, vcc
	global_store_dwordx2 v[100:101], v[98:99], off offset:-1536 sc1
	v_pk_mul_f32 v[94:95], v[12:13], v[94:95]
	v_pk_mul_f32 v[96:97], v[14:15], v[96:97]
	v_pk_add_f32 v[98:99], v[54:55], 1.0 op_sel_hi:[1,0]
	v_pk_add_f32 v[124:125], v[52:53], 1.0 op_sel_hi:[1,0]
	v_pk_fma_f32 v[96:97], v[98:99], v[96:97], v[66:67]
	v_pk_fma_f32 v[94:95], v[124:125], v[94:95], v[64:65]
	v_pk_mul_f32 v[92:93], v[92:93], v[122:123] op_sel_hi:[1,0]
	v_cvt_pk_bf16_f32 v94, v94, v95
	v_cvt_pk_bf16_f32 v95, v96, v97
	v_pk_mul_f32 v[90:91], v[90:91], v[122:123] op_sel_hi:[1,0]
	global_store_dwordx2 v[100:101], v[94:95], off offset:-1024 sc1
	v_pk_mul_f32 v[90:91], v[24:25], v[90:91]
	v_pk_mul_f32 v[92:93], v[26:27], v[92:93]
	v_pk_add_f32 v[94:95], v[62:63], 1.0 op_sel_hi:[1,0]
	v_pk_add_f32 v[96:97], v[60:61], 1.0 op_sel_hi:[1,0]
	v_pk_fma_f32 v[92:93], v[94:95], v[92:93], v[74:75]
	v_pk_fma_f32 v[90:91], v[96:97], v[90:91], v[72:73]
	v_pk_mul_f32 v[88:89], v[88:89], v[122:123] op_sel_hi:[1,0]
	v_cvt_pk_bf16_f32 v90, v90, v91
	v_cvt_pk_bf16_f32 v91, v92, v93
	v_pk_mul_f32 v[86:87], v[86:87], v[122:123] op_sel_hi:[1,0]
	global_store_dwordx2 v[100:101], v[90:91], off offset:-512 sc1
	v_pk_mul_f32 v[86:87], v[28:29], v[86:87]
	v_pk_mul_f32 v[88:89], v[30:31], v[88:89]
	v_pk_add_f32 v[90:91], v[70:71], 1.0 op_sel_hi:[1,0]
	v_pk_add_f32 v[92:93], v[68:69], 1.0 op_sel_hi:[1,0]
	v_pk_fma_f32 v[88:89], v[90:91], v[88:89], v[78:79]
	v_pk_fma_f32 v[86:87], v[92:93], v[86:87], v[76:77]
	s_nop 0
	v_cvt_pk_bf16_f32 v86, v86, v87
	v_cvt_pk_bf16_f32 v87, v88, v89
	global_store_dwordx2 v[100:101], v[86:87], off sc1
	s_branch .LBB0_690

; __device__ __forceinline__ void mod_item(LAS unsigned char* lds, const Args& a, int item, int tid) {
;     ...
;     for (int idx = tid; idx < 9 * 96; idx += NTHR) {
;         const int r = idx / 96, n = idx % 96; float s = mb[n0 + n];
;         for (int g = 0; g < 21; ++g) s += red[(g * 9 + r) * 96 + n];
;         if (r < 8) modx[((size_t)(l * 8 + r)) * 6144 + n0 + n] = s; else modc[(size_t)l * 6144 + n0 + n] = s;
;     }
.LBB0_737:
	s_mov_b32 s12, 0x2aaaaaab
	v_mul_hi_i32 v2, v0, s12
	v_lshrrev_b32_e32 v3, 31, v2
	v_ashrrev_i32_e32 v2, 4, v2
	v_add_u32_e32 v4, v2, v3
	s_movk_i32 s12, 0xffa0
	v_mad_u64_u32 v[2:3], s[12:13], v4, s12, v[0:1]
	v_add_u32_e32 v6, s14, v2
	v_ashrrev_i32_e32 v7, 31, v6
	v_lshl_add_u64 v[6:7], v[6:7], 2, s[2:3]
	global_load_dword v3, v[6:7], off
	ds_read_b32 v5, v1 offset:40960
	s_movk_i32 s12, 0x2ff
	v_cmp_lt_i32_e32 vcc, s12, v0
	s_waitcnt vmcnt(0) lgkmcnt(0)
	v_add_f32_e32 v3, v3, v5
	ds_read_b32 v5, v1 offset:44416
	s_waitcnt lgkmcnt(0)
	v_add_f32_e32 v3, v3, v5
	ds_read_b32 v5, v1 offset:47872
	s_waitcnt lgkmcnt(0)
	v_add_f32_e32 v3, v3, v5
	ds_read_b32 v5, v1 offset:51328
	s_waitcnt lgkmcnt(0)
	v_add_f32_e32 v3, v3, v5
	ds_read_b32 v5, v1 offset:54784
	s_waitcnt lgkmcnt(0)
	v_add_f32_e32 v3, v3, v5
	ds_read_b32 v5, v1 offset:58240
	s_waitcnt lgkmcnt(0)
	v_add_f32_e32 v3, v3, v5
	ds_read_b32 v5, v1 offset:61696
	s_waitcnt lgkmcnt(0)
	v_add_f32_e32 v3, v3, v5
	ds_read_b32 v5, v1 offset:65152
	s_waitcnt lgkmcnt(0)
	v_add_f32_e32 v3, v3, v5
	v_add_u32_e32 v5, 0x10c00, v1
	ds_read_b32 v5, v5
	s_waitcnt lgkmcnt(0)
	v_add_f32_e32 v3, v3, v5
	v_add_u32_e32 v5, 0x11980, v1
	ds_read_b32 v5, v5
	s_waitcnt lgkmcnt(0)
	v_add_f32_e32 v3, v3, v5
	v_add_u32_e32 v5, 0x12700, v1
	ds_read_b32 v5, v5
	s_waitcnt lgkmcnt(0)
	v_add_f32_e32 v3, v3, v5
	v_add_u32_e32 v5, 0x13480, v1
	ds_read_b32 v5, v5
	s_waitcnt lgkmcnt(0)
	v_add_f32_e32 v3, v3, v5
	v_add_u32_e32 v5, 0x14200, v1
	ds_read_b32 v5, v5
	s_waitcnt lgkmcnt(0)
	v_add_f32_e32 v3, v3, v5
	v_add_u32_e32 v5, 0x14f80, v1
	ds_read_b32 v5, v5
	s_waitcnt lgkmcnt(0)
	v_add_f32_e32 v3, v3, v5
	v_add_u32_e32 v5, 0x15d00, v1
	ds_read_b32 v5, v5
	s_waitcnt lgkmcnt(0)
	v_add_f32_e32 v3, v3, v5
	v_add_u32_e32 v5, 0x16a80, v1
	ds_read_b32 v5, v5
	s_waitcnt lgkmcnt(0)
	v_add_f32_e32 v3, v3, v5
	v_add_u32_e32 v5, 0x17800, v1
	ds_read_b32 v5, v5
	s_waitcnt lgkmcnt(0)
	v_add_f32_e32 v3, v3, v5
	v_add_u32_e32 v5, 0x18580, v1
	ds_read_b32 v5, v5
	s_waitcnt lgkmcnt(0)
	v_add_f32_e32 v3, v3, v5
	v_add_u32_e32 v5, 0x19300, v1
	ds_read_b32 v5, v5
	s_waitcnt lgkmcnt(0)
	v_add_f32_e32 v3, v3, v5
	v_add_u32_e32 v5, 0x1a080, v1
	ds_read_b32 v5, v5
	s_waitcnt lgkmcnt(0)
	v_add_f32_e32 v3, v3, v5
	v_add_u32_e32 v5, 0x1ae00, v1
	ds_read_b32 v5, v5
	s_waitcnt lgkmcnt(0)
	v_add_f32_e32 v5, v3, v5
	s_and_saveexec_b64 s[12:13], vcc
	s_xor_b64 s[12:13], exec, s[12:13]
	s_cbranch_execz .LBB0_739
	v_mov_b32_e32 v3, v81
	v_lshl_add_u64 v[2:3], v[2:3], 2, s[8:9]
	global_store_dword v[2:3], v5, off sc1
.LBB0_739:
	s_andn2_saveexec_b64 s[12:13], s[12:13]
	s_cbranch_execz .LBB0_736
	v_add_u32_e32 v4, s22, v4
	v_mov_b64_e32 v[6:7], s[16:17]
	v_ashrrev_i32_e32 v3, 31, v2
	v_mad_i64_i32 v[6:7], s[24:25], v4, s30, v[6:7]
	v_lshl_add_u64 v[2:3], v[2:3], 2, v[6:7]
	global_store_dword v[2:3], v5, off sc1
	s_branch .LBB0_736

; #define LAS __attribute__((address_space(3)))
; #define LDS_WAIT() asm volatile("s_waitcnt lgkmcnt(0)" ::: "memory")
; __device__ __forceinline__ unsigned cvt_pk_bf16(float lo, float hi) { f32x2_t v = {lo, hi}; bf16x2_t b = __builtin_convertvector(v, bf16x2_t); return __builtin_bit_cast(unsigned, b); }
; __device__ __forceinline__ void tr_load(const float* src, int ldn, int lane, f32x4 (&v)[8]) {
;     const int r8 = lane >> 3, c4 = lane & 7;
; #pragma unroll
;     for (int i = 0; i < 8; ++i) v[i] = __builtin_nontemporal_load((const f32x4*)(src + (size_t)(8 * i + r8) * ldn + 4 * c4));
; }
;     const int r8 = lane >> 3, c4 = lane & 7;
; #pragma unroll
;     for (int i = 0; i < 8; ++i) { LAS float* w = scr + (8 * i + r8) * 33 + 4 * c4; w[0] = v[i][0]; w[1] = v[i][1]; w[2] = v[i][2]; w[3] = v[i][3]; }
;     LDS_WAIT(); asm volatile("" ::: "memory");
;     const int c = lane & 7;
; #pragma unroll
;     for (int j = 0; j < 4; ++j) { const int n = (lane >> 3) + 8 * j; const LAS float* sp = scr + (8 * c) * 33 + n;
;         u32x4 o; o.x = cvt_pk_bf16(sp[0 * 33] * s, sp[1 * 33] * s); o.y = cvt_pk_bf16(sp[2 * 33] * s, sp[3 * 33] * s); o.z = cvt_pk_bf16(sp[4 * 33] * s, sp[5 * 33] * s); o.w = cvt_pk_bf16(sp[6 * 33] * s, sp[7 * 33] * s);
;         *(u32x4*)(dst + (size_t)n * ldk + 8 * c) = o; if (dst2) *(u32x4*)(dst2 + (size_t)n * ldk + 8 * c) = o; }
;     LDS_WAIT(); asm volatile("" ::: "memory");
; }
;     ...
;     for (int it = I0 + wr; it < NIT; it += 2 * nw) {
;         const bool two = it + nw < NIT;
;         const TrDesc d0 = tr_decode(a, l, it), d1 = tr_decode(a, l, two ? it + nw : it);
;         f32x4 v0[8], v1[8];
;         tr_load(d0.src, d0.ldn, lane, v0); tr_load(d1.src, d1.ldn, lane, v1);
;         tr_finish(v0, d0.dst, d0.dst2, d0.ldk, scr, lane, d0.scale);
.LBB0_755:
	s_mul_hi_i32 s12, s4, 0x38e38e39
	s_lshr_b32 s13, s12, 31
	s_ashr_i32 s12, s12, 4
	s_add_i32 s16, s12, s13
	s_lshl_b32 s12, s16, 6
	s_ashr_i32 s13, s12, 31
	s_mul_i32 s17, s16, 0x90000
	s_mul_hi_i32 s25, s12, 0x2400
	s_add_u32 s28, s70, s17
	s_mulk_i32 s16, 0xf700
	s_addc_u32 s25, s71, s25
	s_add_i32 s16, s22, s16
	s_ashr_i32 s17, s16, 31
	s_lshl_b64 s[26:27], s[16:17], 2
	s_add_u32 s26, s28, s26
	s_addc_u32 s27, s25, s27
	s_lshl_b64 s[16:17], s[16:17], 11
	v_readlane_b32 s25, v252, 27
	s_add_u32 s16, s25, s16
	v_readlane_b32 s25, v252, 28
	v_mov_b32_e32 v55, v81
	s_addc_u32 s17, s25, s17
	s_lshl_b64 s[12:13], s[12:13], 1
	s_waitcnt vmcnt(11)
	v_lshl_add_u64 v[0:1], s[26:27], 0, v[54:55]
	v_mov_b32_e32 v57, v81
	s_add_u32 s16, s16, s12
	v_lshl_add_u64 v[2:3], v[0:1], 0, v[56:57]
	s_mov_b32 s12, 0x12000
	s_waitcnt vmcnt(9)
	v_add_co_u32_e32 v4, vcc, s12, v2
	s_mov_b32 s12, 0x24000
	s_nop 0
	v_addc_co_u32_e32 v5, vcc, 0, v3, vcc
	global_load_dwordx4 v[76:79], v[2:3], off nt
	global_load_dwordx4 v[86:89], v[4:5], off nt
	v_add_co_u32_e32 v4, vcc, s12, v2
	s_mov_b32 s12, 0x36000
	s_nop 0
	v_addc_co_u32_e32 v5, vcc, 0, v3, vcc
	v_add_co_u32_e32 v2, vcc, s12, v2
	v_mov_b32_e32 v59, v81
	s_nop 0
	v_addc_co_u32_e32 v3, vcc, 0, v3, vcc
	global_load_dwordx4 v[90:93], v[4:5], off nt
	global_load_dwordx4 v[32:35], v[2:3], off nt
	v_lshl_add_u64 v[2:3], v[0:1], 0, v[58:59]
	v_mov_b32_e32 v61, v81
	global_load_dwordx4 v[36:39], v[2:3], off nt
	v_lshl_add_u64 v[2:3], v[0:1], 0, v[60:61]
	v_mov_b32_e32 v63, v81
	v_mov_b32_e32 v65, v81
	global_load_dwordx4 v[40:43], v[2:3], off nt
	v_lshl_add_u64 v[2:3], v[0:1], 0, v[62:63]
	v_lshl_add_u64 v[0:1], v[0:1], 0, v[64:65]
	global_load_dwordx4 v[44:47], v[2:3], off nt
	global_load_dwordx4 v[48:51], v[0:1], off nt
	s_addc_u32 s17, s17, s13
	s_lshl_b32 s12, s24, 3
	s_ashr_i32 s13, s12, 31
	s_waitcnt vmcnt(12)
	v_lshl_add_u64 v[28:29], s[20:21], 0, v[54:55]
	s_lshl_b64 s[20:21], s[12:13], 2
	s_add_i32 s13, s12, s12
	v_mul_u32_u24_e32 v0, s24, v53
	s_add_i32 s13, s13, s13
	v_lshlrev_b32_e32 v80, 2, v0
	v_mov_b32_e32 v16, s13
	v_lshl_add_u64 v[4:5], v[28:29], 0, v[80:81]
	v_mad_u32_u24 v80, s24, v53, v16
	v_lshl_add_u64 v[16:17], v[80:81], 2, v[28:29]
	v_add_u32_e32 v80, s12, v80
	s_waitcnt lgkmcnt(0)
	v_lshl_add_u64 v[8:9], v[4:5], 0, s[20:21]
	v_lshl_add_u64 v[20:21], v[80:81], 2, v[28:29]
	v_add_u32_e32 v80, s12, v80
	v_lshl_add_u64 v[12:13], v[8:9], 0, s[20:21]
	v_lshl_add_u64 v[24:25], v[80:81], 2, v[28:29]
	v_add_u32_e32 v80, s12, v80
	global_load_dwordx4 v[0:3], v[4:5], off nt
	v_lshl_add_u64 v[28:29], v[80:81], 2, v[28:29]
	global_load_dwordx4 v[16:19], v[16:17], off nt
	v_add_u32_e32 v63, 0xc60, v75
	global_load_dwordx4 v[4:7], v[8:9], off nt
	v_add_u32_e32 v55, 0x420, v75
	global_load_dwordx4 v[20:23], v[20:21], off nt
	v_add_u32_e32 v57, 0x428, v75
	global_load_dwordx4 v[8:11], v[12:13], off nt
	v_add_u32_e32 v59, 0x840, v75
	global_load_dwordx4 v[24:27], v[24:25], off nt
	v_lshl_add_u64 v[12:13], v[12:13], 0, s[20:21]
	global_load_dwordx4 v[12:15], v[12:13], off nt
	v_add_u32_e32 v61, 0x848, v75
	global_load_dwordx4 v[28:31], v[28:29], off nt
	s_waitcnt vmcnt(15)
	ds_write2_b32 v75, v76, v77 offset1:1
	ds_write2_b32 v75, v78, v79 offset0:2 offset1:3
	s_waitcnt vmcnt(14)
	ds_write2_b32 v55, v86, v87 offset1:1
	ds_write2_b32 v57, v88, v89 offset1:1
	v_lshlrev_b32_e32 v80, 1, v52
	v_mov_b32_e32 v67, v81
	v_mov_b32_e32 v69, v81
	v_mov_b32_e32 v71, v81
	v_mov_b32_e32 v73, v81
	s_andn2_b64 vcc, exec, s[2:3]
	s_waitcnt vmcnt(13)
	ds_write2_b32 v59, v90, v91 offset1:1
	s_waitcnt vmcnt(12)
	ds_write2_b32 v63, v32, v33 offset1:1
	v_add_u32_e32 v32, 0xc68, v75
	ds_write2_b32 v32, v34, v35 offset1:1
	v_add_u32_e32 v33, 0x1080, v75
	v_add_u32_e32 v34, 0x1088, v75
	v_add_u32_e32 v35, 0x14a0, v75
	s_waitcnt vmcnt(11)
	ds_write2_b32 v33, v36, v37 offset1:1
	ds_write2_b32 v34, v38, v39 offset1:1
	s_waitcnt vmcnt(10)
	ds_write2_b32 v35, v40, v41 offset1:1
	v_add_u32_e32 v36, 0x14a8, v75
	v_add_u32_e32 v37, 0x18c0, v75
	v_add_u32_e32 v38, 0x18c8, v75
	v_add_u32_e32 v39, 0x1ce0, v75
	v_add_u32_e32 v40, 0x1ce8, v75
	ds_write2_b32 v61, v92, v93 offset1:1
	ds_write2_b32 v36, v42, v43 offset1:1
	s_waitcnt vmcnt(9)
	ds_write2_b32 v37, v44, v45 offset1:1
	ds_write2_b32 v38, v46, v47 offset1:1
	s_waitcnt vmcnt(8)
	ds_write2_b32 v39, v48, v49 offset1:1
	ds_write2_b32 v40, v50, v51 offset1:1
	s_waitcnt lgkmcnt(0)
	ds_read2_b32 v[48:49], v74 offset0:33 offset1:41
	ds_read2_b32 v[50:51], v74 offset1:8
	ds_read2_b32 v[76:77], v74 offset0:66 offset1:74
	ds_read2_b32 v[78:79], v74 offset0:99 offset1:107
	ds_read2_b32 v[82:83], v74 offset0:132 offset1:140
	ds_read2_b32 v[86:87], v74 offset0:165 offset1:173
	ds_read2_b32 v[88:89], v74 offset0:198 offset1:206
	ds_read2_b32 v[90:91], v74 offset0:231 offset1:239
	v_lshl_add_u64 v[46:47], s[16:17], 0, v[80:81]
	s_waitcnt lgkmcnt(6)
	v_cvt_pk_bf16_f32 v42, v50, v48
	s_waitcnt lgkmcnt(4)
	v_cvt_pk_bf16_f32 v43, v76, v78
	s_waitcnt lgkmcnt(2)
	v_cvt_pk_bf16_f32 v44, v82, v86
	s_waitcnt lgkmcnt(0)
	v_cvt_pk_bf16_f32 v45, v88, v90
	v_lshl_add_u64 v[92:93], v[46:47], 0, v[66:67]
	global_store_dwordx4 v[92:93], v[42:45], off sc1
	v_lshl_add_u64 v[92:93], v[46:47], 0, v[70:71]
	s_nop 0
	v_cvt_pk_bf16_f32 v42, v51, v49
	v_cvt_pk_bf16_f32 v43, v77, v79
	v_cvt_pk_bf16_f32 v44, v83, v87
	v_cvt_pk_bf16_f32 v45, v89, v91
	v_lshl_add_u64 v[48:49], v[46:47], 0, v[68:69]
	global_store_dwordx4 v[48:49], v[42:45], off sc1
	ds_read2_b32 v[48:49], v74 offset0:49 offset1:57
	ds_read2_b32 v[50:51], v74 offset0:16 offset1:24
	ds_read2_b32 v[76:77], v74 offset0:82 offset1:90
	ds_read2_b32 v[78:79], v74 offset0:115 offset1:123
	ds_read2_b32 v[82:83], v74 offset0:148 offset1:156
	ds_read2_b32 v[86:87], v74 offset0:181 offset1:189
	ds_read2_b32 v[88:89], v74 offset0:214 offset1:222
	ds_read2_b32 v[90:91], v74 offset0:247 offset1:255
	v_lshl_add_u64 v[46:47], v[46:47], 0, v[72:73]
	s_waitcnt lgkmcnt(6)
	v_cvt_pk_bf16_f32 v42, v50, v48
	s_waitcnt lgkmcnt(4)
	v_cvt_pk_bf16_f32 v43, v76, v78
	s_waitcnt lgkmcnt(2)
	v_cvt_pk_bf16_f32 v44, v82, v86
	s_waitcnt lgkmcnt(0)
	v_cvt_pk_bf16_f32 v45, v88, v90
	global_store_dwordx4 v[92:93], v[42:45], off sc1
	s_nop 1
	v_cvt_pk_bf16_f32 v42, v51, v49
	v_cvt_pk_bf16_f32 v43, v77, v79
	v_cvt_pk_bf16_f32 v44, v83, v87
	v_cvt_pk_bf16_f32 v45, v89, v91
	global_store_dwordx4 v[46:47], v[42:45], off sc1
	s_waitcnt lgkmcnt(0)
	s_cbranch_vccnz .LBB0_743
; #define LAS __attribute__((address_space(3)))
; #define LDS_WAIT() asm volatile("s_waitcnt lgkmcnt(0)" ::: "memory")
; __device__ __forceinline__ unsigned cvt_pk_bf16(float lo, float hi) { f32x2_t v = {lo, hi}; bf16x2_t b = __builtin_convertvector(v, bf16x2_t); return __builtin_bit_cast(unsigned, b); }
;     const int r8 = lane >> 3, c4 = lane & 7;
; #pragma unroll
;     for (int i = 0; i < 8; ++i) { LAS float* w = scr + (8 * i + r8) * 33 + 4 * c4; w[0] = v[i][0]; w[1] = v[i][1]; w[2] = v[i][2]; w[3] = v[i][3]; }
;     LDS_WAIT(); asm volatile("" ::: "memory");
;     const int c = lane & 7;
; #pragma unroll
;     for (int j = 0; j < 4; ++j) { const int n = (lane >> 3) + 8 * j; const LAS float* sp = scr + (8 * c) * 33 + n;
;         u32x4 o; o.x = cvt_pk_bf16(sp[0 * 33] * s, sp[1 * 33] * s); o.y = cvt_pk_bf16(sp[2 * 33] * s, sp[3 * 33] * s); o.z = cvt_pk_bf16(sp[4 * 33] * s, sp[5 * 33] * s); o.w = cvt_pk_bf16(sp[6 * 33] * s, sp[7 * 33] * s);
;         *(u32x4*)(dst + (size_t)n * ldk + 8 * c) = o; if (dst2) *(u32x4*)(dst2 + (size_t)n * ldk + 8 * c) = o; }
;     LDS_WAIT(); asm volatile("" ::: "memory");
; }
	s_waitcnt vmcnt(11)
	ds_write2_b32 v75, v0, v1 offset1:1
	ds_write2_b32 v75, v2, v3 offset0:2 offset1:3
	s_waitcnt vmcnt(9)
	ds_write2_b32 v55, v4, v5 offset1:1
	ds_write2_b32 v57, v6, v7 offset1:1
	s_waitcnt vmcnt(7)
	ds_write2_b32 v59, v8, v9 offset1:1
	ds_write2_b32 v61, v10, v11 offset1:1
	s_waitcnt vmcnt(5)
	ds_write2_b32 v63, v12, v13 offset1:1
	ds_write2_b32 v32, v14, v15 offset1:1
	ds_write2_b32 v33, v16, v17 offset1:1
	ds_write2_b32 v34, v18, v19 offset1:1
	ds_write2_b32 v35, v20, v21 offset1:1
	ds_write2_b32 v36, v22, v23 offset1:1
	ds_write2_b32 v37, v24, v25 offset1:1
	ds_write2_b32 v38, v26, v27 offset1:1
	s_waitcnt vmcnt(4)
	ds_write2_b32 v39, v28, v29 offset1:1
	ds_write2_b32 v40, v30, v31 offset1:1
	s_waitcnt lgkmcnt(0)
	ds_read2_b32 v[4:5], v74 offset1:8
	ds_read2_b32 v[6:7], v74 offset0:33 offset1:41
	ds_read2_b32 v[10:11], v74 offset0:66 offset1:74
	ds_read2_b32 v[12:13], v74 offset0:99 offset1:107
	ds_read2_b32 v[14:15], v74 offset0:132 offset1:140
	ds_read2_b32 v[16:17], v74 offset0:165 offset1:173
	ds_read2_b32 v[18:19], v74 offset0:198 offset1:206
	ds_read2_b32 v[20:21], v74 offset0:231 offset1:239
	s_waitcnt lgkmcnt(7)
	v_mov_b32_e32 v0, v4
	s_waitcnt lgkmcnt(6)
	v_mov_b32_e32 v1, v6
	s_waitcnt lgkmcnt(5)
	v_mov_b32_e32 v2, v10
	s_waitcnt lgkmcnt(4)
	v_mov_b32_e32 v3, v12
	v_pk_mul_f32 v[0:1], s[0:1], v[0:1] op_sel_hi:[0,1]
	v_pk_mul_f32 v[2:3], s[0:1], v[2:3] op_sel_hi:[0,1]
	v_cvt_pk_bf16_f32 v0, v0, v1
	v_cvt_pk_bf16_f32 v1, v2, v3
	s_waitcnt lgkmcnt(3)
	v_mov_b32_e32 v2, v14
	s_waitcnt lgkmcnt(2)
	v_mov_b32_e32 v3, v16
	s_waitcnt lgkmcnt(1)
	v_mov_b32_e32 v22, v18
	s_waitcnt lgkmcnt(0)
	v_mov_b32_e32 v23, v20
	v_mul_u32_u24_e32 v4, s1, v53
	v_lshl_add_u64 v[8:9], s[8:9], 0, v[80:81]
	v_pk_mul_f32 v[2:3], s[0:1], v[2:3] op_sel_hi:[0,1]
	v_pk_mul_f32 v[22:23], s[0:1], v[22:23] op_sel_hi:[0,1]
	v_lshlrev_b32_e32 v80, 1, v4
	v_cvt_pk_bf16_f32 v2, v2, v3
	v_cvt_pk_bf16_f32 v3, v22, v23
	v_lshl_add_u64 v[8:9], v[8:9], 0, v[80:81]
	v_mov_b32_e32 v6, v5
	v_mov_b32_e32 v12, v11
	s_lshl_b32 s2, s1, 3
	global_store_dwordx4 v[8:9], v[0:3], off sc1
	v_mov_b32_e32 v16, v15
	v_mov_b32_e32 v20, v19
	v_pk_mul_f32 v[0:1], s[0:1], v[6:7] op_sel_hi:[0,1]
	v_pk_mul_f32 v[2:3], s[0:1], v[12:13] op_sel_hi:[0,1]
	s_ashr_i32 s3, s2, 31
	v_cvt_pk_bf16_f32 v0, v0, v1
	v_cvt_pk_bf16_f32 v1, v2, v3
	v_pk_mul_f32 v[2:3], s[0:1], v[16:17] op_sel_hi:[0,1]
	v_pk_mul_f32 v[4:5], s[0:1], v[20:21] op_sel_hi:[0,1]
	s_lshl_b64 s[2:3], s[2:3], 1
	v_cvt_pk_bf16_f32 v2, v2, v3
	v_cvt_pk_bf16_f32 v3, v4, v5
	ds_read2_b32 v[4:5], v74 offset0:16 offset1:24
	ds_read2_b32 v[6:7], v74 offset0:49 offset1:57
	v_lshl_add_u64 v[8:9], v[8:9], 0, s[2:3]
	ds_read2_b32 v[10:11], v74 offset0:82 offset1:90
	ds_read2_b32 v[12:13], v74 offset0:115 offset1:123
	global_store_dwordx4 v[8:9], v[0:3], off sc1
	ds_read2_b32 v[14:15], v74 offset0:148 offset1:156
	ds_read2_b32 v[16:17], v74 offset0:181 offset1:189
	ds_read2_b32 v[18:19], v74 offset0:214 offset1:222
	ds_read2_b32 v[20:21], v74 offset0:247 offset1:255
	s_waitcnt lgkmcnt(7)
	v_mov_b32_e32 v0, v4
	s_waitcnt lgkmcnt(6)
	v_mov_b32_e32 v1, v6
	s_waitcnt lgkmcnt(5)
	v_mov_b32_e32 v2, v10
	s_waitcnt lgkmcnt(4)
	v_mov_b32_e32 v3, v12
	v_pk_mul_f32 v[0:1], s[0:1], v[0:1] op_sel_hi:[0,1]
	v_pk_mul_f32 v[2:3], s[0:1], v[2:3] op_sel_hi:[0,1]
	v_cvt_pk_bf16_f32 v0, v0, v1
	v_cvt_pk_bf16_f32 v1, v2, v3
	s_waitcnt lgkmcnt(3)
	v_mov_b32_e32 v2, v14
	s_waitcnt lgkmcnt(2)
	v_mov_b32_e32 v3, v16
	s_waitcnt lgkmcnt(1)
	v_mov_b32_e32 v22, v18
	s_waitcnt lgkmcnt(0)
	v_mov_b32_e32 v23, v20
	v_pk_mul_f32 v[2:3], s[0:1], v[2:3] op_sel_hi:[0,1]
	v_pk_mul_f32 v[22:23], s[0:1], v[22:23] op_sel_hi:[0,1]
	v_cvt_pk_bf16_f32 v2, v2, v3
	v_cvt_pk_bf16_f32 v3, v22, v23
	v_lshl_add_u64 v[8:9], v[8:9], 0, s[2:3]
	v_mov_b32_e32 v6, v5
	v_mov_b32_e32 v12, v11
	global_store_dwordx4 v[8:9], v[0:3], off sc1
	v_mov_b32_e32 v16, v15
	v_mov_b32_e32 v20, v19
	v_pk_mul_f32 v[0:1], s[0:1], v[6:7] op_sel_hi:[0,1]
	v_pk_mul_f32 v[2:3], s[0:1], v[12:13] op_sel_hi:[0,1]
	v_cvt_pk_bf16_f32 v0, v0, v1
	v_cvt_pk_bf16_f32 v1, v2, v3
	v_pk_mul_f32 v[2:3], s[0:1], v[16:17] op_sel_hi:[0,1]
	v_pk_mul_f32 v[4:5], s[0:1], v[20:21] op_sel_hi:[0,1]
	v_cvt_pk_bf16_f32 v2, v2, v3
	v_cvt_pk_bf16_f32 v3, v4, v5
	v_lshl_add_u64 v[4:5], v[8:9], 0, s[2:3]
	global_store_dwordx4 v[4:5], v[0:3], off sc1
	s_waitcnt lgkmcnt(0)
	s_branch .LBB0_743

; __device__ __forceinline__ void prologue_a(LAS unsigned char* lds, const Args& a, int tid, int lane, int wave, int G) {
;     ...
;     { const int gt = bx * NTHR + tid, NT = G * NTHR; float* TC = (float*)(a.ws + WS_TAB); float* TS = TC + 1024;
;       for (int idx = gt; idx < 1024; idx += NT) { const int pos = idx >> 4, j = idx & 15; const float inv = powf(10000.0f, -(float)j / 16.0f); const float ang = (float)pos * inv; TC[idx] = cosf(ang); TS[idx] = sinf(ang); } }
.LBB0_760:
	s_or_b64 exec, exec, s[12:13]
	v_mul_f32_e32 v8, v7, v7
	v_fmamk_f32 v9, v8, 0xb94c1982, v227
	v_fmaak_f32 v9, v8, v9, 0xbe2aaa9d
	v_mul_f32_e32 v9, v8, v9
	v_fmac_f32_e32 v7, v7, v9
	v_fmamk_f32 v9, v8, 0x37d75334, v228
	v_fmaak_f32 v9, v8, v9, 0x3d2aabf7
	v_fmaak_f32 v9, v8, v9, 0xbf000004
	v_fma_f32 v8, v8, v9, 1.0
	v_and_b32_e32 v9, 1, v6
	v_lshlrev_b32_e32 v6, 30, v6
	v_cmp_eq_u32_e64 s[34:35], 0, v9
	v_and_b32_e32 v6, 0x80000000, v6
	v_xor_b32_e32 v1, v5, v1
	v_cndmask_b32_e64 v7, v8, v7, s[34:35]
	v_xor_b32_e32 v1, v1, v6
	v_xor_b32_e32 v1, v1, v7
	v_cndmask_b32_e32 v1, v241, v1, vcc
	v_add_co_u32_e32 v6, vcc, 0x1000, v2
	v_add_u32_e32 v0, s2, v0
	s_nop 0
	v_addc_co_u32_e32 v7, vcc, 0, v3, vcc
	s_movk_i32 s3, 0x3ff
	v_cmp_lt_i32_e32 vcc, s3, v0
	s_or_b64 s[16:17], vcc, s[16:17]
	v_lshl_add_u64 v[2:3], v[2:3], 0, s[8:9]
	global_store_dword v[6:7], v1, off sc1
	s_andn2_b64 exec, exec, s[16:17]
	s_cbranch_execz .LBB0_769

; __device__ __forceinline__ void prologue_a(LAS unsigned char* lds, const Args& a, int tid, int lane, int wave, int G) {
;     ...
;     { const int gt = bx * NTHR + tid, NT = G * NTHR; float* TC = (float*)(a.ws + WS_TAB); float* TS = TC + 1024;
;       for (int idx = gt; idx < 1024; idx += NT) { const int pos = idx >> 4, j = idx & 15; const float inv = powf(10000.0f, -(float)j / 16.0f); const float ang = (float)pos * inv; TC[idx] = cosf(ang); TS[idx] = sinf(ang); } }
.LBB0_765:
	s_or_b64 exec, exec, s[12:13]
	v_mul_f32_e32 v8, v7, v7
	v_fmamk_f32 v9, v8, 0xb94c1982, v227
	v_fmaak_f32 v9, v8, v9, 0xbe2aaa9d
	v_mul_f32_e32 v9, v8, v9
	v_fmac_f32_e32 v7, v7, v9
	v_fmamk_f32 v9, v8, 0x37d75334, v228
	v_fmaak_f32 v9, v8, v9, 0x3d2aabf7
	v_fmaak_f32 v9, v8, v9, 0xbf000004
	v_fma_f32 v8, v8, v9, 1.0
	v_and_b32_e32 v9, 1, v6
	v_cmp_eq_u32_e32 vcc, 0, v9
	v_lshlrev_b32_e32 v6, 30, v6
	s_brev_b32 s3, 1
	v_cndmask_b32_e64 v7, -v7, v8, vcc
	v_bitop3_b32 v6, v6, v7, s3 bitop3:0x6c
	s_movk_i32 s3, 0x1f8
	v_cmp_class_f32_e64 vcc, v1, s3
	s_nop 1
	v_cndmask_b32_e32 v6, v241, v6, vcc
	global_store_dword v[2:3], v6, off sc1
	s_and_saveexec_b64 s[4:5], s[20:21]
	s_xor_b64 s[20:21], exec, s[4:5]
	s_cbranch_execz .LBB0_767
	v_lshrrev_b32_e32 v6, 23, v5
	v_add_u32_e32 v6, 0xffffff88, v6
	v_cmp_lt_u32_e64 s[34:35], 63, v6
	s_mov_b32 s3, 0xfe5163ab
	s_nop 0
	v_cndmask_b32_e64 v7, 0, v217, s[34:35]
	v_add_u32_e32 v6, v7, v6
	v_cmp_lt_u32_e64 s[36:37], 31, v6
	s_nop 1
	v_cndmask_b32_e64 v7, 0, v239, s[36:37]
	v_add_u32_e32 v6, v7, v6
	v_cmp_lt_u32_e64 s[38:39], 31, v6
	s_nop 1
	v_cndmask_b32_e64 v7, 0, v239, s[38:39]
	v_add_u32_e32 v20, v7, v6
	v_and_b32_e32 v6, 0x7fffff, v5
	v_or_b32_e32 v18, 0x800000, v6
	v_mad_u64_u32 v[6:7], s[4:5], v18, s3, 0
	v_mov_b32_e32 v80, v7
	s_mov_b32 s3, 0x3c439041
	v_mad_u64_u32 v[8:9], s[4:5], v18, s3, v[80:81]
	v_mov_b32_e32 v80, v9
	s_mov_b32 s3, 0xdb629599
	v_mad_u64_u32 v[10:11], s[4:5], v18, s3, v[80:81]
	v_mov_b32_e32 v80, v11
	s_mov_b32 s3, 0xf534ddc0
	v_mad_u64_u32 v[12:13], s[4:5], v18, s3, v[80:81]
	v_mov_b32_e32 v80, v13
	s_mov_b32 s3, 0xfc2757d1
	v_mad_u64_u32 v[14:15], s[4:5], v18, s3, v[80:81]
	v_mov_b32_e32 v80, v15
	s_mov_b32 s3, 0x4e441529
	v_mad_u64_u32 v[16:17], s[4:5], v18, s3, v[80:81]
	v_mov_b32_e32 v80, v17
	s_mov_b32 s3, 0xa2f9836e
	v_mad_u64_u32 v[18:19], s[4:5], v18, s3, v[80:81]
	v_cndmask_b32_e64 v7, v16, v12, s[34:35]
	v_cndmask_b32_e64 v9, v18, v14, s[34:35]
	v_cndmask_b32_e64 v13, v19, v16, s[34:35]
	v_cndmask_b32_e64 v11, v9, v7, s[36:37]
	v_cndmask_b32_e64 v9, v13, v9, s[36:37]
	v_cndmask_b32_e64 v13, v14, v10, s[34:35]
	v_cndmask_b32_e64 v7, v7, v13, s[36:37]
	v_cndmask_b32_e64 v8, v12, v8, s[34:35]
	v_cndmask_b32_e64 v9, v9, v11, s[38:39]
	v_cndmask_b32_e64 v11, v11, v7, s[38:39]
	v_sub_u32_e32 v14, 32, v20
	v_cndmask_b32_e64 v12, v13, v8, s[36:37]
	v_alignbit_b32 v15, v9, v11, v14
	v_cmp_eq_u32_e64 s[40:41], 0, v20
	v_cndmask_b32_e64 v7, v7, v12, s[38:39]
	v_alignbit_b32 v13, v11, v7, v14
	v_cndmask_b32_e64 v9, v15, v9, s[40:41]
	v_cndmask_b32_e64 v6, v10, v6, s[34:35]
	v_cndmask_b32_e64 v11, v13, v11, s[40:41]
	v_bfe_u32 v16, v9, 29, 1
	v_cndmask_b32_e64 v6, v8, v6, s[36:37]
	v_alignbit_b32 v13, v9, v11, 30
	v_sub_u32_e32 v17, 0, v16
	v_cndmask_b32_e64 v6, v12, v6, s[38:39]
	v_xor_b32_e32 v13, v13, v17
	v_alignbit_b32 v8, v7, v6, v14
	v_cndmask_b32_e64 v7, v8, v7, s[40:41]
	v_ffbh_u32_e32 v10, v13
	v_alignbit_b32 v8, v11, v7, 30
	v_min_u32_e32 v10, 32, v10
	v_alignbit_b32 v6, v7, v6, 30
	v_xor_b32_e32 v8, v8, v17
	v_sub_u32_e32 v11, 31, v10
	v_xor_b32_e32 v6, v6, v17
	v_alignbit_b32 v12, v13, v8, v11
	v_alignbit_b32 v6, v8, v6, v11
	v_alignbit_b32 v7, v12, v6, 9
	v_ffbh_u32_e32 v8, v7
	v_min_u32_e32 v8, 32, v8
	v_lshrrev_b32_e32 v15, 29, v9
	v_not_b32_e32 v11, v8
	v_alignbit_b32 v6, v7, v6, v11
	v_lshlrev_b32_e32 v7, 31, v15
	v_or_b32_e32 v11, 0x33000000, v7
	v_add_lshl_u32 v8, v8, v10, 23
	v_lshrrev_b32_e32 v6, 9, v6
	v_sub_u32_e32 v8, v11, v8
	v_or_b32_e32 v7, 0.5, v7
	v_lshlrev_b32_e32 v10, 23, v10
	v_or_b32_e32 v6, v8, v6
	v_lshrrev_b32_e32 v8, 9, v12
	v_sub_u32_e32 v7, v7, v10
	v_or_b32_e32 v7, v8, v7
	v_mul_f32_e32 v8, 0x3fc90fda, v7
	s_mov_b32 s3, 0x3fc90fda
	v_fma_f32 v10, v7, s3, -v8
	v_fmac_f32_e32 v10, 0x33a22168, v7
	v_fmac_f32_e32 v10, 0x3fc90fda, v6
	v_lshrrev_b32_e32 v6, 30, v9
	v_add_f32_e32 v7, v8, v10
	v_add_u32_e32 v6, v16, v6

; __device__ __forceinline__ unsigned xb_add(unsigned* p, unsigned v) { return __hip_atomic_fetch_add(p, v, __ATOMIC_RELAXED, __HIP_MEMORY_SCOPE_AGENT); }
; __device__ __forceinline__ void xcd_barrier(const XcdBarrier& b) {
;     ...
;         __builtin_amdgcn_s_waitcnt(0);
;         unsigned nloc = b.st[0], nx = b.st[1];
;         if (nloc == 0u) { xcd_barrier_complete(bar, b.x, nloc, nx); b.st[0] = nloc; b.st[1] = nx; }
;         const unsigned target = b.st[2] + nx;
;         __builtin_amdgcn_fence(__ATOMIC_ACQUIRE, "agent");
;         const unsigned old = xb_add(&bar[XB_XSUB(b.x)], 1u);
;         const unsigned gen = old / nloc;
;         if (old + 1u == (gen + 1u) * nloc) {
;             __builtin_amdgcn_fence(__ATOMIC_RELEASE, "agent");
;             asm volatile("s_waitcnt vmcnt(0)" ::: "memory");
;             (void)xb_add(&bar[XB_TOP], 1u);
;         }
.LBB0_788:
	v_readlane_b32 s4, v253, 29
	s_nop 1
	v_mov_b32_e32 v2, s4
	v_readlane_b32 s4, v253, 24
	s_add_u32 s4, s8, s4
	s_addc_u32 s5, s9, 0
	v_mov_b32_e32 v3, s4
	v_add_co_u32_e32 v4, vcc, 0x1000, v3
	v_mov_b32_e32 v3, s5
	s_nop 0
	v_addc_co_u32_e32 v5, vcc, 0, v3, vcc
	ds_read_b32 v2, v2
	s_waitcnt vmcnt(0) lgkmcnt(0)
	buffer_inv sc1
	flat_atomic_add v3, v[4:5], v226 offset:1024 sc0
	v_cvt_f32_u32_e32 v4, v0
	v_sub_u32_e32 v5, 0, v0
	v_rcp_iflag_f32_e32 v4, v4
	s_nop 0
	v_mul_f32_e32 v4, 0x4f7ffffe, v4
	v_cvt_u32_f32_e32 v4, v4
	v_mul_lo_u32 v5, v5, v4
	v_mul_hi_u32 v5, v4, v5
	v_add_u32_e32 v4, v4, v5
	s_waitcnt vmcnt(0) lgkmcnt(0)
	v_mul_hi_u32 v4, v3, v4
	v_mul_lo_u32 v5, v4, v0
	v_sub_u32_e32 v5, v3, v5
	v_cmp_ge_u32_e32 vcc, v5, v0
	v_add_u32_e32 v6, 1, v4
	v_add_u32_e32 v3, 1, v3
	v_cndmask_b32_e32 v4, v4, v6, vcc
	v_sub_u32_e32 v6, v5, v0
	v_cndmask_b32_e32 v5, v5, v6, vcc
	v_cmp_ge_u32_e32 vcc, v5, v0
	v_add_u32_e32 v5, 1, v4
	s_nop 0
	v_cndmask_b32_e32 v4, v4, v5, vcc
	v_mad_u64_u32 v[4:5], s[4:5], v0, v4, v[0:1]
	v_cmp_eq_u32_e32 vcc, v3, v4
	s_and_saveexec_b64 s[12:13], vcc
	s_cbranch_execz .LBB0_790
	v_mov_b32_e32 v0, s8
	v_add_co_u32_e32 v4, vcc, 0x3000, v0
	v_mov_b32_e32 v0, s9
	v_addc_co_u32_e32 v5, vcc, 0, v0, vcc
	flat_atomic_add v[4:5], v226 offset:1024
